# v051 + leading half no longer waits (barrier E) for the trailing half's last MFMA block before its epilogue; trailing half skips the unit's last post-MFMA barrier to keep the pairing
# baseline (speedup 1.0000x reference)
; #define PG8_STAGE(bufoff, gbase, voff) do { _Pragma("unroll") for (int _i = 0; _i < 2; ++_i) \
;         __builtin_amdgcn_global_load_lds((const unsigned*)((const char*)(gbase) + (voff)[_i]), (PG8_LAS unsigned*)(lds + (bufoff) + ldsw + _i * 8192), 16, 0, AUX_A); } while (0)
; #define PG8_STAGEB(bufoff, gbase, voff) do { _Pragma("unroll") for (int _i = 0; _i < 2; ++_i) \
;         __builtin_amdgcn_global_load_lds((const unsigned*)((const char*)(gbase) + (voff)[_i]), (PG8_LAS unsigned*)(lds + (bufoff) + ldsw + _i * 8192), 16, 0, AUX_B); } while (0)
; #define PG8_LDA(dst, b, h) do { _Pragma("unroll") for (int m = 0; m < 4; ++m) _Pragma("unroll") for (int k = 0; k < 2; ++k) dst[m][k] = *(const PG8_LAS bf16x8*)(lds + PG8_SA(b, h) + aoff + m * 2048 + k * 1024); } while (0)
; #define PG8_LDB(dst, b, h) do { _Pragma("unroll") for (int n = 0; n < 2; ++n) _Pragma("unroll") for (int k = 0; k < 2; ++k) dst[n][k] = *(const PG8_LAS bf16x8*)(lds + PG8_SB(b, h) + boff + n * 2048 + k * 1024); } while (0)
; #define PG8_WAIT_V(n) asm volatile("s_waitcnt vmcnt(" #n ")" ::: "memory")
; #define PG8_WAIT_L(n) asm volatile("s_waitcnt lgkmcnt(" #n ")" ::: "memory")
; #define PG8_BAR __builtin_amdgcn_s_barrier()
; template <class Epi, class Sched, bool ALIGN_EPI = false, bool SP2 = false>
; __device__ __forceinline__ void gemm_phase(PG8_LAS unsigned char* lds, const Gemm g, const Sched& S, const Epi& E) {
;     ...
;         for (int t = 0; t < nt; t += 2) {
;             const bool last = (t == nt - 2);
;             const char* a1 = PG8_KP(cA, t + 1, rot, nt);
;             const char* a2 = last ? nAr : PG8_KP(cA, t + 2, rot, nt); const char* b2 = last ? nBr : PG8_KP(cB, t + 2, rot, nt);
;             const char* a3 = a2 + kstep; const char* b3 = b2 + kstep;
;             if (last && has_next) S.a_ready(nxt);
;             if constexpr (SP2) {
;             PG8_LDB(B0, 0, 0); PG8_LDB(B1, 0, 1); PG8_SCHED; PG8_LDA(At, 0, 0); PG8_STAGE(PG8_SA(1, 1), a1 + hstep, voffA);
;             PG8_WAIT_V(8); PG8_WAIT_L(0); PG8_BAR; PG8_MMA(0, 0, At, B0); PG8_MMA(0, 1, At, B1); PG8_BAR; PG8_SCHED;
;             PG8_LDA(At, 0, 1); PG8_STAGEB(PG8_SB(0, 0), b2, voffB); PG8_STAGEB(PG8_SB(0, 1), b2 + hstep, voffB); PG8_STAGE(PG8_SA(0, 0), a2, voffA);
;             PG8_WAIT_V(8); PG8_WAIT_L(0); PG8_BAR; PG8_MMA(1, 0, At, B0); PG8_MMA(1, 1, At, B1); PG8_BAR; PG8_SCHED;
.Lpk_270:
	s_add_i32 s81, s29, 2
	s_cmp_lt_u32 s29, 30
	s_cselect_b32 s0, 0, 0xffffffe0
	s_add_i32 s0, s81, s0
	s_ashr_i32 s1, s0, 31
	s_lshl_b64 s[0:1], s[0:1], 7
	s_add_u32 s42, s40, s0
	s_addc_u32 s43, s41, s1
	s_add_u32 s0, s38, s0
	s_addc_u32 s1, s39, s1
	s_cmp_eq_u32 s29, 30
	s_cselect_b32 s59, s49, s43
	s_cselect_b32 s58, s51, s42
	s_cselect_b32 s61, vcc_lo, s1
	s_cselect_b32 s60, vcc_hi, s0
	s_add_i32 s43, 0, 0x10000
	s_add_i32 s97, s43, s70
	s_add_i32 s46, 0, 0x14000
	s_add_i32 m0, s96, 0xc000
	s_add_i32 s69, s96, 0xe000
	s_add_i32 s84, s97, 0x2000
	s_add_u32 s62, s60, 0x80000
	s_addc_u32 s63, s61, 0
	s_add_i32 s4, s46, s70
	v_add_u32_e32 v148, s43, v221
	v_add_u32_e32 v164, s46, v221
	s_add_i32 s5, s4, 0x2000
	s_add_i32 s1, 0, 0x18000
	s_add_i32 s47, 0, 0x1c000
	ds_read_b128 v[136:139], v148
	ds_read_b128 v[140:143], v148 offset:1024
	ds_read_b128 v[144:147], v148 offset:2048
	ds_read_b128 v[148:151], v148 offset:3072
	ds_read_b128 v[152:155], v164
	ds_read_b128 v[156:159], v164 offset:1024
	ds_read_b128 v[160:163], v164 offset:2048
	ds_read_b128 v[164:167], v164 offset:3072
	s_add_u32 s56, s58, 0x80000
	s_addc_u32 s57, s59, 0
	s_add_i32 s0, s1, s70
	s_add_i32 s89, s0, 0x2000
	s_add_u32 s42, s60, 0x80080
	s_addc_u32 s43, s61, 0
	s_add_i32 s46, s47, s70
	s_add_i32 s92, s46, 0x2000
	s_cmp_gt_u32 s29, 29
	ds_read_b128 v[192:195], v222
	ds_read_b128 v[196:199], v222 offset:1024
	ds_read_b128 v[200:203], v222 offset:2048
	ds_read_b128 v[224:227], v222 offset:3072
	ds_read_b128 v[228:231], v222 offset:4096
	ds_read_b128 v[232:235], v222 offset:5120
	ds_read_b128 v[236:239], v222 offset:6144
	ds_read_b128 v[240:243], v222 offset:7168
	global_load_lds_dwordx4 v[134:135], off
	s_mov_b32 m0, s69
	s_nop 0
	global_load_lds_dwordx4 v[132:133], off
	s_waitcnt vmcnt(8)
	s_waitcnt lgkmcnt(0)
	s_setprio 1
	s_barrier
	v_mfma_f32_16x16x32_bf16 v[128:131], v[136:139], v[192:195], 0
	v_mfma_f32_16x16x32_bf16 v[128:131], v[140:143], v[196:199], v[128:131]
	v_mfma_f32_16x16x32_bf16 v[124:127], v[144:147], v[192:195], 0
	v_mfma_f32_16x16x32_bf16 v[124:127], v[148:151], v[196:199], v[124:127]
	v_mfma_f32_16x16x32_bf16 v[112:115], v[136:139], v[200:203], 0
	v_mfma_f32_16x16x32_bf16 v[112:115], v[140:143], v[224:227], v[112:115]
	v_mfma_f32_16x16x32_bf16 v[108:111], v[144:147], v[200:203], 0
	v_mfma_f32_16x16x32_bf16 v[108:111], v[148:151], v[224:227], v[108:111]
	v_mfma_f32_16x16x32_bf16 v[94:97], v[136:139], v[228:231], 0
	v_mfma_f32_16x16x32_bf16 v[94:97], v[140:143], v[232:235], v[94:97]
	v_mfma_f32_16x16x32_bf16 v[90:93], v[144:147], v[228:231], 0
	v_mfma_f32_16x16x32_bf16 v[90:93], v[148:151], v[232:235], v[90:93]
	v_mfma_f32_16x16x32_bf16 v[78:81], v[136:139], v[236:239], 0
	v_mfma_f32_16x16x32_bf16 v[78:81], v[140:143], v[240:243], v[78:81]
	v_mfma_f32_16x16x32_bf16 v[74:77], v[144:147], v[236:239], 0
	v_mfma_f32_16x16x32_bf16 v[74:77], v[148:151], v[240:243], v[74:77]
	s_setprio 0
	s_setprio 1
	v_mfma_f32_16x16x32_bf16 v[120:123], v[152:155], v[192:195], 0
	v_mfma_f32_16x16x32_bf16 v[120:123], v[156:159], v[196:199], v[120:123]
	v_mfma_f32_16x16x32_bf16 v[116:119], v[160:163], v[192:195], 0
	v_mfma_f32_16x16x32_bf16 v[116:119], v[164:167], v[196:199], v[116:119]
	v_mfma_f32_16x16x32_bf16 v[104:107], v[152:155], v[200:203], 0
	v_mfma_f32_16x16x32_bf16 v[104:107], v[156:159], v[224:227], v[104:107]
	v_mfma_f32_16x16x32_bf16 v[100:103], v[160:163], v[200:203], 0
	v_mfma_f32_16x16x32_bf16 v[100:103], v[164:167], v[224:227], v[100:103]
	v_mfma_f32_16x16x32_bf16 v[86:89], v[152:155], v[228:231], 0
	v_mfma_f32_16x16x32_bf16 v[86:89], v[156:159], v[232:235], v[86:89]
	v_mfma_f32_16x16x32_bf16 v[82:85], v[160:163], v[228:231], 0
	v_mfma_f32_16x16x32_bf16 v[82:85], v[164:167], v[232:235], v[82:85]
	v_mfma_f32_16x16x32_bf16 v[70:73], v[152:155], v[236:239], 0
	v_mfma_f32_16x16x32_bf16 v[70:73], v[156:159], v[240:243], v[70:73]
	s_setprio 2
	s_barrier
	v_mfma_f32_16x16x32_bf16 v[66:69], v[160:163], v[236:239], 0
	v_mfma_f32_16x16x32_bf16 v[66:69], v[164:167], v[240:243], v[66:69]
	s_setprio 0
	s_mov_b32 m0, s97
	v_lshl_add_u64 v[244:245], s[60:61], 0, v[184:185]
	ds_read_b128 v[192:195], v222 offset:16384
	ds_read_b128 v[196:199], v222 offset:17408
	ds_read_b128 v[200:203], v222 offset:18432
	ds_read_b128 v[224:227], v222 offset:19456
	ds_read_b128 v[228:231], v222 offset:20480
	ds_read_b128 v[232:235], v222 offset:21504
	ds_read_b128 v[236:239], v222 offset:22528
	ds_read_b128 v[240:243], v222 offset:23552
	global_load_lds_dwordx4 v[244:245], off
	v_lshl_add_u64 v[246:247], s[60:61], 0, v[180:181]
	s_mov_b32 m0, s84
	v_lshl_add_u64 v[212:213], s[62:63], 0, v[184:185]
	global_load_lds_dwordx4 v[246:247], off
	s_mov_b32 m0, s4
	v_lshl_add_u64 v[172:173], s[58:59], 0, v[182:183]
	global_load_lds_dwordx4 v[212:213], off
	v_lshl_add_u64 v[212:213], s[62:63], 0, v[180:181]
	s_mov_b32 m0, s5
	s_nop 0
	global_load_lds_dwordx4 v[212:213], off
	v_lshl_add_u64 v[212:213], s[58:59], 0, v[186:187]
	s_mov_b32 m0, s96
	s_nop 0
	global_load_lds_dwordx4 v[212:213], off
	s_mov_b32 m0, s71
	s_nop 0
	global_load_lds_dwordx4 v[172:173], off
	s_waitcnt vmcnt(8)
	s_waitcnt lgkmcnt(0)
	s_setprio 1
	s_barrier
; #define PG8_STAGE(bufoff, gbase, voff) do { _Pragma("unroll") for (int _i = 0; _i < 2; ++_i) \
;         __builtin_amdgcn_global_load_lds((const unsigned*)((const char*)(gbase) + (voff)[_i]), (PG8_LAS unsigned*)(lds + (bufoff) + ldsw + _i * 8192), 16, 0, AUX_A); } while (0)
; #define PG8_STAGEB(bufoff, gbase, voff) do { _Pragma("unroll") for (int _i = 0; _i < 2; ++_i) \
;         __builtin_amdgcn_global_load_lds((const unsigned*)((const char*)(gbase) + (voff)[_i]), (PG8_LAS unsigned*)(lds + (bufoff) + ldsw + _i * 8192), 16, 0, AUX_B); } while (0)
; #define PG8_LDA(dst, b, h) do { _Pragma("unroll") for (int m = 0; m < 4; ++m) _Pragma("unroll") for (int k = 0; k < 2; ++k) dst[m][k] = *(const PG8_LAS bf16x8*)(lds + PG8_SA(b, h) + aoff + m * 2048 + k * 1024); } while (0)
; #define PG8_LDB(dst, b, h) do { _Pragma("unroll") for (int n = 0; n < 2; ++n) _Pragma("unroll") for (int k = 0; k < 2; ++k) dst[n][k] = *(const PG8_LAS bf16x8*)(lds + PG8_SB(b, h) + boff + n * 2048 + k * 1024); } while (0)
; #define PG8_MMA(ai, bj, At, Bt) do { __builtin_amdgcn_s_setprio(1); _Pragma("unroll") for (int m = 0; m < 4; ++m) _Pragma("unroll") for (int n = 0; n < 2; ++n) _Pragma("unroll") for (int k = 0; k < 2; ++k) \
;         acc[ai][bj][m][n] = __builtin_amdgcn_mfma_f32_16x16x32_bf16(Bt[n][k], At[m][k], acc[ai][bj][m][n], 0, 0, 0); __builtin_amdgcn_s_setprio(0); } while (0)
; #define PG8_WAIT_V(n) asm volatile("s_waitcnt vmcnt(" #n ")" ::: "memory")
; #define PG8_WAIT_L(n) asm volatile("s_waitcnt lgkmcnt(" #n ")" ::: "memory")
; template <class Epi, class Sched, bool ALIGN_EPI = false, bool SP2 = false>
; __device__ __forceinline__ void gemm_phase(PG8_LAS unsigned char* lds, const Gemm g, const Sched& S, const Epi& E) {
;     ...
;             PG8_WAIT_V(8); PG8_WAIT_L(0); PG8_BAR; PG8_MMA(0, 0, At, B0); PG8_MMA(0, 1, At, B1); PG8_BAR; PG8_SCHED;
;             PG8_LDA(At, 0, 1); PG8_STAGEB(PG8_SB(0, 0), b2, voffB); PG8_STAGEB(PG8_SB(0, 1), b2 + hstep, voffB); PG8_STAGE(PG8_SA(0, 0), a2, voffA);
;             PG8_WAIT_V(8); PG8_WAIT_L(0); PG8_BAR; PG8_MMA(1, 0, At, B0); PG8_MMA(1, 1, At, B1); PG8_BAR; PG8_SCHED;
;             PG8_LDB(B0, 1, 0); PG8_LDB(B1, 1, 1); PG8_SCHED; PG8_LDA(At, 1, 0); PG8_STAGE(PG8_SA(0, 1), a2 + hstep, voffA);
;             PG8_WAIT_V(8); PG8_WAIT_L(0); PG8_BAR; PG8_MMA(0, 0, At, B0); PG8_MMA(0, 1, At, B1); PG8_BAR; PG8_SCHED;
	v_mfma_f32_16x16x32_bf16 v[62:65], v[136:139], v[192:195], 0
	v_mfma_f32_16x16x32_bf16 v[62:65], v[140:143], v[196:199], v[62:65]
	v_mfma_f32_16x16x32_bf16 v[58:61], v[144:147], v[192:195], 0
	v_mfma_f32_16x16x32_bf16 v[58:61], v[148:151], v[196:199], v[58:61]
	v_mfma_f32_16x16x32_bf16 v[46:49], v[136:139], v[200:203], 0
	v_mfma_f32_16x16x32_bf16 v[46:49], v[140:143], v[224:227], v[46:49]
	v_mfma_f32_16x16x32_bf16 v[42:45], v[144:147], v[200:203], 0
	v_mfma_f32_16x16x32_bf16 v[42:45], v[148:151], v[224:227], v[42:45]
	v_mfma_f32_16x16x32_bf16 v[30:33], v[136:139], v[228:231], 0
	v_mfma_f32_16x16x32_bf16 v[30:33], v[140:143], v[232:235], v[30:33]
	v_mfma_f32_16x16x32_bf16 v[26:29], v[144:147], v[228:231], 0
	v_mfma_f32_16x16x32_bf16 v[26:29], v[148:151], v[232:235], v[26:29]
	v_mfma_f32_16x16x32_bf16 v[14:17], v[136:139], v[236:239], 0
	v_mfma_f32_16x16x32_bf16 v[14:17], v[140:143], v[240:243], v[14:17]
	v_mfma_f32_16x16x32_bf16 v[10:13], v[144:147], v[236:239], 0
	v_mfma_f32_16x16x32_bf16 v[10:13], v[148:151], v[240:243], v[10:13]
	s_setprio 0
	s_setprio 1
	v_mfma_f32_16x16x32_bf16 v[54:57], v[152:155], v[192:195], 0
	v_mfma_f32_16x16x32_bf16 v[54:57], v[156:159], v[196:199], v[54:57]
	v_mfma_f32_16x16x32_bf16 v[50:53], v[160:163], v[192:195], 0
	v_mfma_f32_16x16x32_bf16 v[50:53], v[164:167], v[196:199], v[50:53]
	v_mfma_f32_16x16x32_bf16 v[38:41], v[152:155], v[200:203], 0
	v_mfma_f32_16x16x32_bf16 v[38:41], v[156:159], v[224:227], v[38:41]
	v_mfma_f32_16x16x32_bf16 v[34:37], v[160:163], v[200:203], 0
	v_mfma_f32_16x16x32_bf16 v[34:37], v[164:167], v[224:227], v[34:37]
	v_mfma_f32_16x16x32_bf16 v[22:25], v[152:155], v[228:231], 0
	v_mfma_f32_16x16x32_bf16 v[22:25], v[156:159], v[232:235], v[22:25]
	v_mfma_f32_16x16x32_bf16 v[18:21], v[160:163], v[228:231], 0
	v_mfma_f32_16x16x32_bf16 v[18:21], v[164:167], v[232:235], v[18:21]
	v_mfma_f32_16x16x32_bf16 v[6:9], v[152:155], v[236:239], 0
	v_mfma_f32_16x16x32_bf16 v[6:9], v[156:159], v[240:243], v[6:9]
	s_setprio 2
	s_barrier
	v_mfma_f32_16x16x32_bf16 v[2:5], v[160:163], v[236:239], 0
	v_mfma_f32_16x16x32_bf16 v[2:5], v[164:167], v[240:243], v[2:5]
	s_setprio 0
	v_add_u32_e32 v148, s1, v221
	v_add_u32_e32 v164, s47, v221
	ds_read_b128 v[136:139], v148
	ds_read_b128 v[140:143], v148 offset:1024
	ds_read_b128 v[144:147], v148 offset:2048
	ds_read_b128 v[148:151], v148 offset:3072
	ds_read_b128 v[152:155], v164
	ds_read_b128 v[156:159], v164 offset:1024
	ds_read_b128 v[160:163], v164 offset:2048
	ds_read_b128 v[164:167], v164 offset:3072
	s_mov_b32 m0, s33
	v_lshl_add_u64 v[168:169], s[56:57], 0, v[186:187]
	ds_read_b128 v[192:195], v222 offset:32768
	ds_read_b128 v[196:199], v222 offset:33792
	ds_read_b128 v[200:203], v222 offset:34816
	ds_read_b128 v[224:227], v222 offset:35840
	ds_read_b128 v[228:231], v222 offset:36864
	ds_read_b128 v[232:235], v222 offset:37888
	ds_read_b128 v[236:239], v222 offset:38912
	ds_read_b128 v[240:243], v222 offset:39936
	global_load_lds_dwordx4 v[168:169], off
	v_lshl_add_u64 v[168:169], s[56:57], 0, v[182:183]
	s_mov_b32 m0, s30
	s_nop 0
	global_load_lds_dwordx4 v[168:169], off
	s_waitcnt vmcnt(8)
	s_waitcnt lgkmcnt(0)
	s_setprio 1
	s_barrier
	v_mfma_f32_16x16x32_bf16 v[128:131], v[136:139], v[192:195], v[128:131]
	v_mfma_f32_16x16x32_bf16 v[128:131], v[140:143], v[196:199], v[128:131]
	v_mfma_f32_16x16x32_bf16 v[124:127], v[144:147], v[192:195], v[124:127]
	v_mfma_f32_16x16x32_bf16 v[124:127], v[148:151], v[196:199], v[124:127]
	v_mfma_f32_16x16x32_bf16 v[112:115], v[136:139], v[200:203], v[112:115]
	v_mfma_f32_16x16x32_bf16 v[112:115], v[140:143], v[224:227], v[112:115]
	v_mfma_f32_16x16x32_bf16 v[108:111], v[144:147], v[200:203], v[108:111]
	v_mfma_f32_16x16x32_bf16 v[108:111], v[148:151], v[224:227], v[108:111]
	v_mfma_f32_16x16x32_bf16 v[94:97], v[136:139], v[228:231], v[94:97]
	v_mfma_f32_16x16x32_bf16 v[94:97], v[140:143], v[232:235], v[94:97]
	v_mfma_f32_16x16x32_bf16 v[90:93], v[144:147], v[228:231], v[90:93]
	v_mfma_f32_16x16x32_bf16 v[90:93], v[148:151], v[232:235], v[90:93]
	v_mfma_f32_16x16x32_bf16 v[78:81], v[136:139], v[236:239], v[78:81]
	v_mfma_f32_16x16x32_bf16 v[78:81], v[140:143], v[240:243], v[78:81]
	v_mfma_f32_16x16x32_bf16 v[74:77], v[144:147], v[236:239], v[74:77]
	v_mfma_f32_16x16x32_bf16 v[74:77], v[148:151], v[240:243], v[74:77]
	s_setprio 0
	s_setprio 1
	v_mfma_f32_16x16x32_bf16 v[120:123], v[152:155], v[192:195], v[120:123]
	v_mfma_f32_16x16x32_bf16 v[120:123], v[156:159], v[196:199], v[120:123]
	v_mfma_f32_16x16x32_bf16 v[116:119], v[160:163], v[192:195], v[116:119]
	v_mfma_f32_16x16x32_bf16 v[116:119], v[164:167], v[196:199], v[116:119]
	v_mfma_f32_16x16x32_bf16 v[104:107], v[152:155], v[200:203], v[104:107]
	v_mfma_f32_16x16x32_bf16 v[104:107], v[156:159], v[224:227], v[104:107]
	v_mfma_f32_16x16x32_bf16 v[100:103], v[160:163], v[200:203], v[100:103]
	v_mfma_f32_16x16x32_bf16 v[100:103], v[164:167], v[224:227], v[100:103]
	v_mfma_f32_16x16x32_bf16 v[86:89], v[152:155], v[228:231], v[86:89]
	v_mfma_f32_16x16x32_bf16 v[86:89], v[156:159], v[232:235], v[86:89]
	v_mfma_f32_16x16x32_bf16 v[82:85], v[160:163], v[228:231], v[82:85]
	v_mfma_f32_16x16x32_bf16 v[82:85], v[164:167], v[232:235], v[82:85]
	v_mfma_f32_16x16x32_bf16 v[70:73], v[152:155], v[236:239], v[70:73]
	v_mfma_f32_16x16x32_bf16 v[70:73], v[156:159], v[240:243], v[70:73]
	s_setprio 2
	s_barrier
; #define PG8_STAGE(bufoff, gbase, voff) do { _Pragma("unroll") for (int _i = 0; _i < 2; ++_i) \
;         __builtin_amdgcn_global_load_lds((const unsigned*)((const char*)(gbase) + (voff)[_i]), (PG8_LAS unsigned*)(lds + (bufoff) + ldsw + _i * 8192), 16, 0, AUX_A); } while (0)
; #define PG8_STAGEB(bufoff, gbase, voff) do { _Pragma("unroll") for (int _i = 0; _i < 2; ++_i) \
;         __builtin_amdgcn_global_load_lds((const unsigned*)((const char*)(gbase) + (voff)[_i]), (PG8_LAS unsigned*)(lds + (bufoff) + ldsw + _i * 8192), 16, 0, AUX_B); } while (0)
; #define PG8_LDA(dst, b, h) do { _Pragma("unroll") for (int m = 0; m < 4; ++m) _Pragma("unroll") for (int k = 0; k < 2; ++k) dst[m][k] = *(const PG8_LAS bf16x8*)(lds + PG8_SA(b, h) + aoff + m * 2048 + k * 1024); } while (0)
; #define PG8_MMA(ai, bj, At, Bt) do { __builtin_amdgcn_s_setprio(1); _Pragma("unroll") for (int m = 0; m < 4; ++m) _Pragma("unroll") for (int n = 0; n < 2; ++n) _Pragma("unroll") for (int k = 0; k < 2; ++k) \
;         acc[ai][bj][m][n] = __builtin_amdgcn_mfma_f32_16x16x32_bf16(Bt[n][k], At[m][k], acc[ai][bj][m][n], 0, 0, 0); __builtin_amdgcn_s_setprio(0); } while (0)
; #define PG8_WAIT_V(n) asm volatile("s_waitcnt vmcnt(" #n ")" ::: "memory")
; #define PG8_WAIT_L(n) asm volatile("s_waitcnt lgkmcnt(" #n ")" ::: "memory")
; #define PG8_BAR __builtin_amdgcn_s_barrier()
; #define PG8_SCHED __builtin_amdgcn_sched_barrier(0)
; template <class Epi, class Sched, bool ALIGN_EPI = false, bool SP2 = false>
; __device__ __forceinline__ void gemm_phase(PG8_LAS unsigned char* lds, const Gemm g, const Sched& S, const Epi& E) {
;     ...
;             PG8_WAIT_V(8); PG8_WAIT_L(0); PG8_BAR; PG8_MMA(0, 0, At, B0); PG8_MMA(0, 1, At, B1); PG8_BAR; PG8_SCHED;
;             PG8_LDA(At, 1, 1); PG8_STAGEB(PG8_SB(1, 0), b3, voffB); PG8_STAGEB(PG8_SB(1, 1), b3 + hstep, voffB); PG8_STAGE(PG8_SA(1, 0), a3, voffA);
;             PG8_WAIT_V(8); PG8_WAIT_L(0); PG8_BAR; PG8_MMA(1, 0, At, B0); PG8_MMA(1, 1, At, B1); PG8_BAR; PG8_SCHED;
	v_mfma_f32_16x16x32_bf16 v[66:69], v[160:163], v[236:239], v[66:69]
	v_mfma_f32_16x16x32_bf16 v[66:69], v[164:167], v[240:243], v[66:69]
	s_setprio 0
	s_mov_b32 m0, s0
	v_lshl_add_u64 v[168:169], v[244:245], 0, s[76:77]
	ds_read_b128 v[192:195], v222 offset:49152
	ds_read_b128 v[196:199], v222 offset:50176
	ds_read_b128 v[200:203], v222 offset:51200
	ds_read_b128 v[224:227], v222 offset:52224
	ds_read_b128 v[228:231], v222 offset:53248
	ds_read_b128 v[232:235], v222 offset:54272
	ds_read_b128 v[236:239], v222 offset:55296
	ds_read_b128 v[240:243], v222 offset:56320
	global_load_lds_dwordx4 v[168:169], off
	v_lshl_add_u64 v[168:169], v[246:247], 0, s[76:77]
	s_mov_b32 m0, s89
	s_nop 0
	global_load_lds_dwordx4 v[168:169], off
	v_lshl_add_u64 v[168:169], s[42:43], 0, v[184:185]
	s_mov_b32 m0, s46
	s_nop 0
	global_load_lds_dwordx4 v[168:169], off
	v_lshl_add_u64 v[168:169], s[42:43], 0, v[180:181]
	s_mov_b32 m0, s92
	s_nop 0
	global_load_lds_dwordx4 v[168:169], off
	v_lshl_add_u64 v[168:169], v[212:213], 0, s[76:77]
	s_mov_b32 m0, s90
	s_nop 0
	global_load_lds_dwordx4 v[168:169], off
	v_lshl_add_u64 v[168:169], v[172:173], 0, s[76:77]
	s_mov_b32 m0, s91
	s_nop 0
	global_load_lds_dwordx4 v[168:169], off
	s_waitcnt vmcnt(8)
	s_waitcnt lgkmcnt(0)
	s_setprio 1
	s_barrier
	v_mfma_f32_16x16x32_bf16 v[62:65], v[136:139], v[192:195], v[62:65]
	v_mfma_f32_16x16x32_bf16 v[62:65], v[140:143], v[196:199], v[62:65]
	v_mfma_f32_16x16x32_bf16 v[58:61], v[144:147], v[192:195], v[58:61]
	v_mfma_f32_16x16x32_bf16 v[58:61], v[148:151], v[196:199], v[58:61]
	v_mfma_f32_16x16x32_bf16 v[46:49], v[136:139], v[200:203], v[46:49]
	v_mfma_f32_16x16x32_bf16 v[46:49], v[140:143], v[224:227], v[46:49]
	v_mfma_f32_16x16x32_bf16 v[42:45], v[144:147], v[200:203], v[42:45]
	v_mfma_f32_16x16x32_bf16 v[42:45], v[148:151], v[224:227], v[42:45]
	v_mfma_f32_16x16x32_bf16 v[30:33], v[136:139], v[228:231], v[30:33]
	v_mfma_f32_16x16x32_bf16 v[30:33], v[140:143], v[232:235], v[30:33]
	v_mfma_f32_16x16x32_bf16 v[26:29], v[144:147], v[228:231], v[26:29]
	v_mfma_f32_16x16x32_bf16 v[26:29], v[148:151], v[232:235], v[26:29]
	v_mfma_f32_16x16x32_bf16 v[14:17], v[136:139], v[236:239], v[14:17]
	v_mfma_f32_16x16x32_bf16 v[14:17], v[140:143], v[240:243], v[14:17]
	v_mfma_f32_16x16x32_bf16 v[10:13], v[144:147], v[236:239], v[10:13]
	v_mfma_f32_16x16x32_bf16 v[10:13], v[148:151], v[240:243], v[10:13]
	s_setprio 0
	s_setprio 1
	v_mfma_f32_16x16x32_bf16 v[54:57], v[152:155], v[192:195], v[54:57]
	v_mfma_f32_16x16x32_bf16 v[54:57], v[156:159], v[196:199], v[54:57]
	v_mfma_f32_16x16x32_bf16 v[50:53], v[160:163], v[192:195], v[50:53]
	v_mfma_f32_16x16x32_bf16 v[50:53], v[164:167], v[196:199], v[50:53]
	v_mfma_f32_16x16x32_bf16 v[38:41], v[152:155], v[200:203], v[38:41]
	v_mfma_f32_16x16x32_bf16 v[38:41], v[156:159], v[224:227], v[38:41]
	v_mfma_f32_16x16x32_bf16 v[34:37], v[160:163], v[200:203], v[34:37]
	v_mfma_f32_16x16x32_bf16 v[34:37], v[164:167], v[224:227], v[34:37]
	v_mfma_f32_16x16x32_bf16 v[22:25], v[152:155], v[228:231], v[22:25]
	v_mfma_f32_16x16x32_bf16 v[22:25], v[156:159], v[232:235], v[22:25]
	v_mfma_f32_16x16x32_bf16 v[18:21], v[160:163], v[228:231], v[18:21]
	v_mfma_f32_16x16x32_bf16 v[18:21], v[164:167], v[232:235], v[18:21]
	v_mfma_f32_16x16x32_bf16 v[6:9], v[152:155], v[236:239], v[6:9]
	v_mfma_f32_16x16x32_bf16 v[6:9], v[156:159], v[240:243], v[6:9]
	s_setprio 2
	s_cbranch_scc0 .Lq4b_270p
	v_cmp_ne_u32_e64 vcc, s10, 0
	s_cbranch_vccz .Lq4s_270p

; #define PG8_STAGE(bufoff, gbase, voff) do { _Pragma("unroll") for (int _i = 0; _i < 2; ++_i) \
;         __builtin_amdgcn_global_load_lds((const unsigned*)((const char*)(gbase) + (voff)[_i]), (PG8_LAS unsigned*)(lds + (bufoff) + ldsw + _i * 8192), 16, 0, AUX_A); } while (0)
; #define PG8_STAGEB(bufoff, gbase, voff) do { _Pragma("unroll") for (int _i = 0; _i < 2; ++_i) \
;         __builtin_amdgcn_global_load_lds((const unsigned*)((const char*)(gbase) + (voff)[_i]), (PG8_LAS unsigned*)(lds + (bufoff) + ldsw + _i * 8192), 16, 0, AUX_B); } while (0)
; #define PG8_LDA(dst, b, h) do { _Pragma("unroll") for (int m = 0; m < 4; ++m) _Pragma("unroll") for (int k = 0; k < 2; ++k) dst[m][k] = *(const PG8_LAS bf16x8*)(lds + PG8_SA(b, h) + aoff + m * 2048 + k * 1024); } while (0)
; #define PG8_LDB(dst, b, h) do { _Pragma("unroll") for (int n = 0; n < 2; ++n) _Pragma("unroll") for (int k = 0; k < 2; ++k) dst[n][k] = *(const PG8_LAS bf16x8*)(lds + PG8_SB(b, h) + boff + n * 2048 + k * 1024); } while (0)
; #define PG8_WAIT_V(n) asm volatile("s_waitcnt vmcnt(" #n ")" ::: "memory")
; #define PG8_WAIT_L(n) asm volatile("s_waitcnt lgkmcnt(" #n ")" ::: "memory")
; #define PG8_BAR __builtin_amdgcn_s_barrier()
; template <class Epi, class Sched, bool ALIGN_EPI = false, bool SP2 = false>
; __device__ __forceinline__ void gemm_phase(PG8_LAS unsigned char* lds, const Gemm g, const Sched& S, const Epi& E) {
;     ...
;         for (int t = 0; t < nt; t += 2) {
;             const bool last = (t == nt - 2);
;             const char* a1 = PG8_KP(cA, t + 1, rot, nt);
;             const char* a2 = last ? nAr : PG8_KP(cA, t + 2, rot, nt); const char* b2 = last ? nBr : PG8_KP(cB, t + 2, rot, nt);
;             const char* a3 = a2 + kstep; const char* b3 = b2 + kstep;
;             if (last && has_next) S.a_ready(nxt);
;             if constexpr (SP2) {
;             PG8_LDB(B0, 0, 0); PG8_LDB(B1, 0, 1); PG8_SCHED; PG8_LDA(At, 0, 0); PG8_STAGE(PG8_SA(1, 1), a1 + hstep, voffA);
;             PG8_WAIT_V(8); PG8_WAIT_L(0); PG8_BAR; PG8_MMA(0, 0, At, B0); PG8_MMA(0, 1, At, B1); PG8_BAR; PG8_SCHED;
;             PG8_LDA(At, 0, 1); PG8_STAGEB(PG8_SB(0, 0), b2, voffB); PG8_STAGEB(PG8_SB(0, 1), b2 + hstep, voffB); PG8_STAGE(PG8_SA(0, 0), a2, voffA);
;             PG8_WAIT_V(8); PG8_WAIT_L(0); PG8_BAR; PG8_MMA(1, 0, At, B0); PG8_MMA(1, 1, At, B1); PG8_BAR; PG8_SCHED;
.Lq4s_270p:
	v_mfma_f32_16x16x32_bf16 v[2:5], v[160:163], v[236:239], v[2:5]
	v_mfma_f32_16x16x32_bf16 v[2:5], v[164:167], v[240:243], v[2:5]
	s_setprio 0
	v_lshl_add_u64 v[132:133], v[132:133], 0, s[86:87]
	v_lshl_add_u64 v[134:135], v[134:135], 0, s[86:87]
	s_mov_b32 s29, s81
	s_cbranch_scc1 .Lpx_270
.LBB0_270:
	s_add_i32 s81, s29, 2
	s_cmp_lt_u32 s29, 30
	s_cselect_b32 s0, 0, 0xffffffe0
	s_add_i32 s0, s81, s0
	s_ashr_i32 s1, s0, 31
	s_lshl_b64 s[0:1], s[0:1], 7
	s_add_u32 s42, s40, s0
	s_addc_u32 s43, s41, s1
	s_add_u32 s0, s38, s0
	s_addc_u32 s1, s39, s1
	s_cmp_eq_u32 s29, 30
	s_cselect_b32 s59, s49, s43
	s_cselect_b32 s58, s51, s42
	s_cselect_b32 s61, vcc_lo, s1
	s_cselect_b32 s60, vcc_hi, s0
	s_add_i32 s43, 0, 0x10000
	s_add_i32 s97, s43, s70
	s_add_i32 s46, 0, 0x14000
	s_add_i32 m0, s96, 0xc000
	s_add_i32 s69, s96, 0xe000
	s_add_i32 s84, s97, 0x2000
	s_add_u32 s62, s60, 0x80000
	s_addc_u32 s63, s61, 0
	s_add_i32 s4, s46, s70
	v_add_u32_e32 v148, s43, v221
	v_add_u32_e32 v164, s46, v221
	s_add_i32 s5, s4, 0x2000
	s_add_i32 s1, 0, 0x18000
	s_add_i32 s47, 0, 0x1c000
	ds_read_b128 v[136:139], v148
	ds_read_b128 v[140:143], v148 offset:1024
	ds_read_b128 v[144:147], v148 offset:2048
	ds_read_b128 v[148:151], v148 offset:3072
	ds_read_b128 v[152:155], v164
	ds_read_b128 v[156:159], v164 offset:1024
	ds_read_b128 v[160:163], v164 offset:2048
	ds_read_b128 v[164:167], v164 offset:3072
	s_add_u32 s56, s58, 0x80000
	s_addc_u32 s57, s59, 0
	s_add_i32 s0, s1, s70
	s_add_i32 s89, s0, 0x2000
	s_add_u32 s42, s60, 0x80080
	s_addc_u32 s43, s61, 0
	s_add_i32 s46, s47, s70
	s_add_i32 s92, s46, 0x2000
	s_cmp_gt_u32 s29, 29
	ds_read_b128 v[192:195], v222
	ds_read_b128 v[196:199], v222 offset:1024
	ds_read_b128 v[200:203], v222 offset:2048
	ds_read_b128 v[224:227], v222 offset:3072
	ds_read_b128 v[228:231], v222 offset:4096
	ds_read_b128 v[232:235], v222 offset:5120
	ds_read_b128 v[236:239], v222 offset:6144
	ds_read_b128 v[240:243], v222 offset:7168
	global_load_lds_dwordx4 v[134:135], off
	s_mov_b32 m0, s69
	s_nop 0
	global_load_lds_dwordx4 v[132:133], off
	s_waitcnt vmcnt(8)
	s_waitcnt lgkmcnt(0)
	s_setprio 1
	s_barrier
	v_mfma_f32_16x16x32_bf16 v[128:131], v[136:139], v[192:195], v[128:131]
	v_mfma_f32_16x16x32_bf16 v[128:131], v[140:143], v[196:199], v[128:131]
	v_mfma_f32_16x16x32_bf16 v[124:127], v[144:147], v[192:195], v[124:127]
	v_mfma_f32_16x16x32_bf16 v[124:127], v[148:151], v[196:199], v[124:127]
	v_mfma_f32_16x16x32_bf16 v[112:115], v[136:139], v[200:203], v[112:115]
	v_mfma_f32_16x16x32_bf16 v[112:115], v[140:143], v[224:227], v[112:115]
	v_mfma_f32_16x16x32_bf16 v[108:111], v[144:147], v[200:203], v[108:111]
	v_mfma_f32_16x16x32_bf16 v[108:111], v[148:151], v[224:227], v[108:111]
	v_mfma_f32_16x16x32_bf16 v[94:97], v[136:139], v[228:231], v[94:97]
	v_mfma_f32_16x16x32_bf16 v[94:97], v[140:143], v[232:235], v[94:97]
	v_mfma_f32_16x16x32_bf16 v[90:93], v[144:147], v[228:231], v[90:93]
	v_mfma_f32_16x16x32_bf16 v[90:93], v[148:151], v[232:235], v[90:93]
	v_mfma_f32_16x16x32_bf16 v[78:81], v[136:139], v[236:239], v[78:81]
	v_mfma_f32_16x16x32_bf16 v[78:81], v[140:143], v[240:243], v[78:81]
	v_mfma_f32_16x16x32_bf16 v[74:77], v[144:147], v[236:239], v[74:77]
	v_mfma_f32_16x16x32_bf16 v[74:77], v[148:151], v[240:243], v[74:77]
	s_setprio 0
	s_setprio 1
	v_mfma_f32_16x16x32_bf16 v[120:123], v[152:155], v[192:195], v[120:123]
	v_mfma_f32_16x16x32_bf16 v[120:123], v[156:159], v[196:199], v[120:123]
	v_mfma_f32_16x16x32_bf16 v[116:119], v[160:163], v[192:195], v[116:119]
	v_mfma_f32_16x16x32_bf16 v[116:119], v[164:167], v[196:199], v[116:119]
	v_mfma_f32_16x16x32_bf16 v[104:107], v[152:155], v[200:203], v[104:107]
	v_mfma_f32_16x16x32_bf16 v[104:107], v[156:159], v[224:227], v[104:107]
	v_mfma_f32_16x16x32_bf16 v[100:103], v[160:163], v[200:203], v[100:103]
	v_mfma_f32_16x16x32_bf16 v[100:103], v[164:167], v[224:227], v[100:103]
	v_mfma_f32_16x16x32_bf16 v[86:89], v[152:155], v[228:231], v[86:89]
	v_mfma_f32_16x16x32_bf16 v[86:89], v[156:159], v[232:235], v[86:89]
	v_mfma_f32_16x16x32_bf16 v[82:85], v[160:163], v[228:231], v[82:85]
	v_mfma_f32_16x16x32_bf16 v[82:85], v[164:167], v[232:235], v[82:85]
	v_mfma_f32_16x16x32_bf16 v[70:73], v[152:155], v[236:239], v[70:73]
	v_mfma_f32_16x16x32_bf16 v[70:73], v[156:159], v[240:243], v[70:73]
	s_setprio 2
	s_barrier
	v_mfma_f32_16x16x32_bf16 v[66:69], v[160:163], v[236:239], v[66:69]
	v_mfma_f32_16x16x32_bf16 v[66:69], v[164:167], v[240:243], v[66:69]
	s_setprio 0
	s_mov_b32 m0, s97
	v_lshl_add_u64 v[244:245], s[60:61], 0, v[184:185]
	ds_read_b128 v[192:195], v222 offset:16384
	ds_read_b128 v[196:199], v222 offset:17408
	ds_read_b128 v[200:203], v222 offset:18432
	ds_read_b128 v[224:227], v222 offset:19456
	ds_read_b128 v[228:231], v222 offset:20480
	ds_read_b128 v[232:235], v222 offset:21504
	ds_read_b128 v[236:239], v222 offset:22528
	ds_read_b128 v[240:243], v222 offset:23552
	global_load_lds_dwordx4 v[244:245], off
	v_lshl_add_u64 v[246:247], s[60:61], 0, v[180:181]
	s_mov_b32 m0, s84
	v_lshl_add_u64 v[212:213], s[62:63], 0, v[184:185]
	global_load_lds_dwordx4 v[246:247], off
	s_mov_b32 m0, s4
	v_lshl_add_u64 v[172:173], s[58:59], 0, v[182:183]
	global_load_lds_dwordx4 v[212:213], off
	v_lshl_add_u64 v[212:213], s[62:63], 0, v[180:181]
	s_mov_b32 m0, s5
	s_nop 0
	global_load_lds_dwordx4 v[212:213], off
	v_lshl_add_u64 v[212:213], s[58:59], 0, v[186:187]
	s_mov_b32 m0, s96
	s_nop 0
	global_load_lds_dwordx4 v[212:213], off
	s_mov_b32 m0, s71
	s_nop 0
	global_load_lds_dwordx4 v[172:173], off
	s_waitcnt vmcnt(8)
	s_waitcnt lgkmcnt(0)
	s_setprio 1
	s_barrier
; #define PG8_STAGE(bufoff, gbase, voff) do { _Pragma("unroll") for (int _i = 0; _i < 2; ++_i) \
;         __builtin_amdgcn_global_load_lds((const unsigned*)((const char*)(gbase) + (voff)[_i]), (PG8_LAS unsigned*)(lds + (bufoff) + ldsw + _i * 8192), 16, 0, AUX_A); } while (0)
; #define PG8_STAGEB(bufoff, gbase, voff) do { _Pragma("unroll") for (int _i = 0; _i < 2; ++_i) \
;         __builtin_amdgcn_global_load_lds((const unsigned*)((const char*)(gbase) + (voff)[_i]), (PG8_LAS unsigned*)(lds + (bufoff) + ldsw + _i * 8192), 16, 0, AUX_B); } while (0)
; #define PG8_LDA(dst, b, h) do { _Pragma("unroll") for (int m = 0; m < 4; ++m) _Pragma("unroll") for (int k = 0; k < 2; ++k) dst[m][k] = *(const PG8_LAS bf16x8*)(lds + PG8_SA(b, h) + aoff + m * 2048 + k * 1024); } while (0)
; #define PG8_LDB(dst, b, h) do { _Pragma("unroll") for (int n = 0; n < 2; ++n) _Pragma("unroll") for (int k = 0; k < 2; ++k) dst[n][k] = *(const PG8_LAS bf16x8*)(lds + PG8_SB(b, h) + boff + n * 2048 + k * 1024); } while (0)
; #define PG8_MMA(ai, bj, At, Bt) do { __builtin_amdgcn_s_setprio(1); _Pragma("unroll") for (int m = 0; m < 4; ++m) _Pragma("unroll") for (int n = 0; n < 2; ++n) _Pragma("unroll") for (int k = 0; k < 2; ++k) \
;         acc[ai][bj][m][n] = __builtin_amdgcn_mfma_f32_16x16x32_bf16(Bt[n][k], At[m][k], acc[ai][bj][m][n], 0, 0, 0); __builtin_amdgcn_s_setprio(0); } while (0)
; #define PG8_WAIT_V(n) asm volatile("s_waitcnt vmcnt(" #n ")" ::: "memory")
; #define PG8_WAIT_L(n) asm volatile("s_waitcnt lgkmcnt(" #n ")" ::: "memory")
; template <class Epi, class Sched, bool ALIGN_EPI = false, bool SP2 = false>
; __device__ __forceinline__ void gemm_phase(PG8_LAS unsigned char* lds, const Gemm g, const Sched& S, const Epi& E) {
;     ...
;             PG8_WAIT_V(8); PG8_WAIT_L(0); PG8_BAR; PG8_MMA(0, 0, At, B0); PG8_MMA(0, 1, At, B1); PG8_BAR; PG8_SCHED;
;             PG8_LDA(At, 0, 1); PG8_STAGEB(PG8_SB(0, 0), b2, voffB); PG8_STAGEB(PG8_SB(0, 1), b2 + hstep, voffB); PG8_STAGE(PG8_SA(0, 0), a2, voffA);
;             PG8_WAIT_V(8); PG8_WAIT_L(0); PG8_BAR; PG8_MMA(1, 0, At, B0); PG8_MMA(1, 1, At, B1); PG8_BAR; PG8_SCHED;
;             PG8_LDB(B0, 1, 0); PG8_LDB(B1, 1, 1); PG8_SCHED; PG8_LDA(At, 1, 0); PG8_STAGE(PG8_SA(0, 1), a2 + hstep, voffA);
;             PG8_WAIT_V(8); PG8_WAIT_L(0); PG8_BAR; PG8_MMA(0, 0, At, B0); PG8_MMA(0, 1, At, B1); PG8_BAR; PG8_SCHED;
	v_mfma_f32_16x16x32_bf16 v[62:65], v[136:139], v[192:195], v[62:65]
	v_mfma_f32_16x16x32_bf16 v[62:65], v[140:143], v[196:199], v[62:65]
	v_mfma_f32_16x16x32_bf16 v[58:61], v[144:147], v[192:195], v[58:61]
	v_mfma_f32_16x16x32_bf16 v[58:61], v[148:151], v[196:199], v[58:61]
	v_mfma_f32_16x16x32_bf16 v[46:49], v[136:139], v[200:203], v[46:49]
	v_mfma_f32_16x16x32_bf16 v[46:49], v[140:143], v[224:227], v[46:49]
	v_mfma_f32_16x16x32_bf16 v[42:45], v[144:147], v[200:203], v[42:45]
	v_mfma_f32_16x16x32_bf16 v[42:45], v[148:151], v[224:227], v[42:45]
	v_mfma_f32_16x16x32_bf16 v[30:33], v[136:139], v[228:231], v[30:33]
	v_mfma_f32_16x16x32_bf16 v[30:33], v[140:143], v[232:235], v[30:33]
	v_mfma_f32_16x16x32_bf16 v[26:29], v[144:147], v[228:231], v[26:29]
	v_mfma_f32_16x16x32_bf16 v[26:29], v[148:151], v[232:235], v[26:29]
	v_mfma_f32_16x16x32_bf16 v[14:17], v[136:139], v[236:239], v[14:17]
	v_mfma_f32_16x16x32_bf16 v[14:17], v[140:143], v[240:243], v[14:17]
	v_mfma_f32_16x16x32_bf16 v[10:13], v[144:147], v[236:239], v[10:13]
	v_mfma_f32_16x16x32_bf16 v[10:13], v[148:151], v[240:243], v[10:13]
	s_setprio 0
	s_setprio 1
	v_mfma_f32_16x16x32_bf16 v[54:57], v[152:155], v[192:195], v[54:57]
	v_mfma_f32_16x16x32_bf16 v[54:57], v[156:159], v[196:199], v[54:57]
	v_mfma_f32_16x16x32_bf16 v[50:53], v[160:163], v[192:195], v[50:53]
	v_mfma_f32_16x16x32_bf16 v[50:53], v[164:167], v[196:199], v[50:53]
	v_mfma_f32_16x16x32_bf16 v[38:41], v[152:155], v[200:203], v[38:41]
	v_mfma_f32_16x16x32_bf16 v[38:41], v[156:159], v[224:227], v[38:41]
	v_mfma_f32_16x16x32_bf16 v[34:37], v[160:163], v[200:203], v[34:37]
	v_mfma_f32_16x16x32_bf16 v[34:37], v[164:167], v[224:227], v[34:37]
	v_mfma_f32_16x16x32_bf16 v[22:25], v[152:155], v[228:231], v[22:25]
	v_mfma_f32_16x16x32_bf16 v[22:25], v[156:159], v[232:235], v[22:25]
	v_mfma_f32_16x16x32_bf16 v[18:21], v[160:163], v[228:231], v[18:21]
	v_mfma_f32_16x16x32_bf16 v[18:21], v[164:167], v[232:235], v[18:21]
	v_mfma_f32_16x16x32_bf16 v[6:9], v[152:155], v[236:239], v[6:9]
	v_mfma_f32_16x16x32_bf16 v[6:9], v[156:159], v[240:243], v[6:9]
	s_setprio 2
	s_barrier
	v_mfma_f32_16x16x32_bf16 v[2:5], v[160:163], v[236:239], v[2:5]
	v_mfma_f32_16x16x32_bf16 v[2:5], v[164:167], v[240:243], v[2:5]
	s_setprio 0
	v_add_u32_e32 v148, s1, v221
	v_add_u32_e32 v164, s47, v221
	ds_read_b128 v[136:139], v148
	ds_read_b128 v[140:143], v148 offset:1024
	ds_read_b128 v[144:147], v148 offset:2048
	ds_read_b128 v[148:151], v148 offset:3072
	ds_read_b128 v[152:155], v164
	ds_read_b128 v[156:159], v164 offset:1024
	ds_read_b128 v[160:163], v164 offset:2048
	ds_read_b128 v[164:167], v164 offset:3072
	s_mov_b32 m0, s33
	v_lshl_add_u64 v[168:169], s[56:57], 0, v[186:187]
	ds_read_b128 v[192:195], v222 offset:32768
	ds_read_b128 v[196:199], v222 offset:33792
	ds_read_b128 v[200:203], v222 offset:34816
	ds_read_b128 v[224:227], v222 offset:35840
	ds_read_b128 v[228:231], v222 offset:36864
	ds_read_b128 v[232:235], v222 offset:37888
	ds_read_b128 v[236:239], v222 offset:38912
	ds_read_b128 v[240:243], v222 offset:39936
	global_load_lds_dwordx4 v[168:169], off
	v_lshl_add_u64 v[168:169], s[56:57], 0, v[182:183]
	s_mov_b32 m0, s30
	s_nop 0
	global_load_lds_dwordx4 v[168:169], off
	s_waitcnt vmcnt(8)
	s_waitcnt lgkmcnt(0)
	s_setprio 1
	s_barrier
	v_mfma_f32_16x16x32_bf16 v[128:131], v[136:139], v[192:195], v[128:131]
	v_mfma_f32_16x16x32_bf16 v[128:131], v[140:143], v[196:199], v[128:131]
	v_mfma_f32_16x16x32_bf16 v[124:127], v[144:147], v[192:195], v[124:127]
	v_mfma_f32_16x16x32_bf16 v[124:127], v[148:151], v[196:199], v[124:127]
	v_mfma_f32_16x16x32_bf16 v[112:115], v[136:139], v[200:203], v[112:115]
	v_mfma_f32_16x16x32_bf16 v[112:115], v[140:143], v[224:227], v[112:115]
	v_mfma_f32_16x16x32_bf16 v[108:111], v[144:147], v[200:203], v[108:111]
	v_mfma_f32_16x16x32_bf16 v[108:111], v[148:151], v[224:227], v[108:111]
	v_mfma_f32_16x16x32_bf16 v[94:97], v[136:139], v[228:231], v[94:97]
	v_mfma_f32_16x16x32_bf16 v[94:97], v[140:143], v[232:235], v[94:97]
	v_mfma_f32_16x16x32_bf16 v[90:93], v[144:147], v[228:231], v[90:93]
	v_mfma_f32_16x16x32_bf16 v[90:93], v[148:151], v[232:235], v[90:93]
	v_mfma_f32_16x16x32_bf16 v[78:81], v[136:139], v[236:239], v[78:81]
	v_mfma_f32_16x16x32_bf16 v[78:81], v[140:143], v[240:243], v[78:81]
	v_mfma_f32_16x16x32_bf16 v[74:77], v[144:147], v[236:239], v[74:77]
	v_mfma_f32_16x16x32_bf16 v[74:77], v[148:151], v[240:243], v[74:77]
	s_setprio 0
	s_setprio 1
	v_mfma_f32_16x16x32_bf16 v[120:123], v[152:155], v[192:195], v[120:123]
	v_mfma_f32_16x16x32_bf16 v[120:123], v[156:159], v[196:199], v[120:123]
	v_mfma_f32_16x16x32_bf16 v[116:119], v[160:163], v[192:195], v[116:119]
	v_mfma_f32_16x16x32_bf16 v[116:119], v[164:167], v[196:199], v[116:119]
	v_mfma_f32_16x16x32_bf16 v[104:107], v[152:155], v[200:203], v[104:107]
	v_mfma_f32_16x16x32_bf16 v[104:107], v[156:159], v[224:227], v[104:107]
	v_mfma_f32_16x16x32_bf16 v[100:103], v[160:163], v[200:203], v[100:103]
	v_mfma_f32_16x16x32_bf16 v[100:103], v[164:167], v[224:227], v[100:103]
	v_mfma_f32_16x16x32_bf16 v[86:89], v[152:155], v[228:231], v[86:89]
	v_mfma_f32_16x16x32_bf16 v[86:89], v[156:159], v[232:235], v[86:89]
	v_mfma_f32_16x16x32_bf16 v[82:85], v[160:163], v[228:231], v[82:85]
	v_mfma_f32_16x16x32_bf16 v[82:85], v[164:167], v[232:235], v[82:85]
	v_mfma_f32_16x16x32_bf16 v[70:73], v[152:155], v[236:239], v[70:73]
	v_mfma_f32_16x16x32_bf16 v[70:73], v[156:159], v[240:243], v[70:73]
	s_setprio 2
	s_barrier
; #define PG8_STAGE(bufoff, gbase, voff) do { _Pragma("unroll") for (int _i = 0; _i < 2; ++_i) \
;         __builtin_amdgcn_global_load_lds((const unsigned*)((const char*)(gbase) + (voff)[_i]), (PG8_LAS unsigned*)(lds + (bufoff) + ldsw + _i * 8192), 16, 0, AUX_A); } while (0)
; #define PG8_STAGEB(bufoff, gbase, voff) do { _Pragma("unroll") for (int _i = 0; _i < 2; ++_i) \
;         __builtin_amdgcn_global_load_lds((const unsigned*)((const char*)(gbase) + (voff)[_i]), (PG8_LAS unsigned*)(lds + (bufoff) + ldsw + _i * 8192), 16, 0, AUX_B); } while (0)
; #define PG8_LDA(dst, b, h) do { _Pragma("unroll") for (int m = 0; m < 4; ++m) _Pragma("unroll") for (int k = 0; k < 2; ++k) dst[m][k] = *(const PG8_LAS bf16x8*)(lds + PG8_SA(b, h) + aoff + m * 2048 + k * 1024); } while (0)
; #define PG8_MMA(ai, bj, At, Bt) do { __builtin_amdgcn_s_setprio(1); _Pragma("unroll") for (int m = 0; m < 4; ++m) _Pragma("unroll") for (int n = 0; n < 2; ++n) _Pragma("unroll") for (int k = 0; k < 2; ++k) \
;         acc[ai][bj][m][n] = __builtin_amdgcn_mfma_f32_16x16x32_bf16(Bt[n][k], At[m][k], acc[ai][bj][m][n], 0, 0, 0); __builtin_amdgcn_s_setprio(0); } while (0)
; #define PG8_WAIT_V(n) asm volatile("s_waitcnt vmcnt(" #n ")" ::: "memory")
; #define PG8_WAIT_L(n) asm volatile("s_waitcnt lgkmcnt(" #n ")" ::: "memory")
; #define PG8_BAR __builtin_amdgcn_s_barrier()
; #define PG8_SCHED __builtin_amdgcn_sched_barrier(0)
; template <class Epi, class Sched, bool ALIGN_EPI = false, bool SP2 = false>
; __device__ __forceinline__ void gemm_phase(PG8_LAS unsigned char* lds, const Gemm g, const Sched& S, const Epi& E) {
;     ...
;             PG8_WAIT_V(8); PG8_WAIT_L(0); PG8_BAR; PG8_MMA(0, 0, At, B0); PG8_MMA(0, 1, At, B1); PG8_BAR; PG8_SCHED;
;             PG8_LDA(At, 1, 1); PG8_STAGEB(PG8_SB(1, 0), b3, voffB); PG8_STAGEB(PG8_SB(1, 1), b3 + hstep, voffB); PG8_STAGE(PG8_SA(1, 0), a3, voffA);
;             PG8_WAIT_V(8); PG8_WAIT_L(0); PG8_BAR; PG8_MMA(1, 0, At, B0); PG8_MMA(1, 1, At, B1); PG8_BAR; PG8_SCHED;
	v_mfma_f32_16x16x32_bf16 v[66:69], v[160:163], v[236:239], v[66:69]
	v_mfma_f32_16x16x32_bf16 v[66:69], v[164:167], v[240:243], v[66:69]
	s_setprio 0
	s_mov_b32 m0, s0
	v_lshl_add_u64 v[168:169], v[244:245], 0, s[76:77]
	ds_read_b128 v[192:195], v222 offset:49152
	ds_read_b128 v[196:199], v222 offset:50176
	ds_read_b128 v[200:203], v222 offset:51200
	ds_read_b128 v[224:227], v222 offset:52224
	ds_read_b128 v[228:231], v222 offset:53248
	ds_read_b128 v[232:235], v222 offset:54272
	ds_read_b128 v[236:239], v222 offset:55296
	ds_read_b128 v[240:243], v222 offset:56320
	global_load_lds_dwordx4 v[168:169], off
	v_lshl_add_u64 v[168:169], v[246:247], 0, s[76:77]
	s_mov_b32 m0, s89
	s_nop 0
	global_load_lds_dwordx4 v[168:169], off
	v_lshl_add_u64 v[168:169], s[42:43], 0, v[184:185]
	s_mov_b32 m0, s46
	s_nop 0
	global_load_lds_dwordx4 v[168:169], off
	v_lshl_add_u64 v[168:169], s[42:43], 0, v[180:181]
	s_mov_b32 m0, s92
	s_nop 0
	global_load_lds_dwordx4 v[168:169], off
	v_lshl_add_u64 v[168:169], v[212:213], 0, s[76:77]
	s_mov_b32 m0, s90
	s_nop 0
	global_load_lds_dwordx4 v[168:169], off
	v_lshl_add_u64 v[168:169], v[172:173], 0, s[76:77]
	s_mov_b32 m0, s91
	s_nop 0
	global_load_lds_dwordx4 v[168:169], off
	s_waitcnt vmcnt(8)
	s_waitcnt lgkmcnt(0)
	s_setprio 1
	s_barrier
	v_mfma_f32_16x16x32_bf16 v[62:65], v[136:139], v[192:195], v[62:65]
	v_mfma_f32_16x16x32_bf16 v[62:65], v[140:143], v[196:199], v[62:65]
	v_mfma_f32_16x16x32_bf16 v[58:61], v[144:147], v[192:195], v[58:61]
	v_mfma_f32_16x16x32_bf16 v[58:61], v[148:151], v[196:199], v[58:61]
	v_mfma_f32_16x16x32_bf16 v[46:49], v[136:139], v[200:203], v[46:49]
	v_mfma_f32_16x16x32_bf16 v[46:49], v[140:143], v[224:227], v[46:49]
	v_mfma_f32_16x16x32_bf16 v[42:45], v[144:147], v[200:203], v[42:45]
	v_mfma_f32_16x16x32_bf16 v[42:45], v[148:151], v[224:227], v[42:45]
	v_mfma_f32_16x16x32_bf16 v[30:33], v[136:139], v[228:231], v[30:33]
	v_mfma_f32_16x16x32_bf16 v[30:33], v[140:143], v[232:235], v[30:33]
	v_mfma_f32_16x16x32_bf16 v[26:29], v[144:147], v[228:231], v[26:29]
	v_mfma_f32_16x16x32_bf16 v[26:29], v[148:151], v[232:235], v[26:29]
	v_mfma_f32_16x16x32_bf16 v[14:17], v[136:139], v[236:239], v[14:17]
	v_mfma_f32_16x16x32_bf16 v[14:17], v[140:143], v[240:243], v[14:17]
	v_mfma_f32_16x16x32_bf16 v[10:13], v[144:147], v[236:239], v[10:13]
	v_mfma_f32_16x16x32_bf16 v[10:13], v[148:151], v[240:243], v[10:13]
	s_setprio 0
	s_setprio 1
	v_mfma_f32_16x16x32_bf16 v[54:57], v[152:155], v[192:195], v[54:57]
	v_mfma_f32_16x16x32_bf16 v[54:57], v[156:159], v[196:199], v[54:57]
	v_mfma_f32_16x16x32_bf16 v[50:53], v[160:163], v[192:195], v[50:53]
	v_mfma_f32_16x16x32_bf16 v[50:53], v[164:167], v[196:199], v[50:53]
	v_mfma_f32_16x16x32_bf16 v[38:41], v[152:155], v[200:203], v[38:41]
	v_mfma_f32_16x16x32_bf16 v[38:41], v[156:159], v[224:227], v[38:41]
	v_mfma_f32_16x16x32_bf16 v[34:37], v[160:163], v[200:203], v[34:37]
	v_mfma_f32_16x16x32_bf16 v[34:37], v[164:167], v[224:227], v[34:37]
	v_mfma_f32_16x16x32_bf16 v[22:25], v[152:155], v[228:231], v[22:25]
	v_mfma_f32_16x16x32_bf16 v[22:25], v[156:159], v[232:235], v[22:25]
	v_mfma_f32_16x16x32_bf16 v[18:21], v[160:163], v[228:231], v[18:21]
	v_mfma_f32_16x16x32_bf16 v[18:21], v[164:167], v[232:235], v[18:21]
	v_mfma_f32_16x16x32_bf16 v[6:9], v[152:155], v[236:239], v[6:9]
	v_mfma_f32_16x16x32_bf16 v[6:9], v[156:159], v[240:243], v[6:9]
	s_setprio 2
	s_cbranch_scc0 .Lq4b_270l
	v_cmp_ne_u32_e64 vcc, s10, 0
	s_cbranch_vccz .Lq4s_270l

; #define PG8_BAR __builtin_amdgcn_s_barrier()
;     __device__ __forceinline__ void operator()(const f32x4 (&acc)[2][2][4][2], const Unit& u, int wr, int wc, int fr_in, int fq_in) const {
;     ...
;         const int row0 = u.pm * BM + wr * 64 + fr;
;         if (u.pn >= 4 && u.pn <= 8) {
;             const bool isk = u.pn == 8;
;             const float* g = isk ? kg : qg;
;             f32x4 gv[2][2];
; #pragma unroll
;             for (int bj = 0; bj < 2; ++bj)
; #pragma unroll
;                 for (int n = 0; n < 2; ++n) gv[bj][n] = *(const f32x4*)(g + 32 * bj + 8 * fq + 4 * n);
; #pragma unroll
;             for (int ai = 0; ai < 2; ++ai)
; #pragma unroll
;                 for (int m = 0; m < 4; ++m) {
; template <class Epi, class Sched, bool ALIGN_EPI = false, bool SP2 = false>
; __device__ __forceinline__ void gemm_phase(PG8_LAS unsigned char* lds, const Gemm g, const Sched& S, const Epi& E) {
;     ...
;             PG8_WAIT_V(8); PG8_WAIT_L(0); PG8_BAR; PG8_MMA(1, 0, At, B0); PG8_MMA(1, 1, At, B1); PG8_BAR; PG8_SCHED;
;             } else {
;             PG8_LDB(B0, 0, 0); PG8_SCHED; PG8_LDA(At, 0, 0); PG8_STAGE(PG8_SA(1, 1), a1 + hstep, voffA);
;             PG8_WAIT_L(8); PG8_BAR; PG8_WAIT_L(0); PG8_MMA(0, 0, At, B0); PG8_BAR; PG8_SCHED;
;             PG8_LDB(B1, 0, 1); PG8_STAGEB(PG8_SB(0, 0), b2, voffB);
;             PG8_BAR; PG8_WAIT_L(0); PG8_MMA(0, 1, At, B1); PG8_BAR;
;             PG8_LDA(At, 0, 1); PG8_STAGE(PG8_SA(0, 0), a2, voffA);
;             PG8_BAR; PG8_WAIT_L(0); PG8_MMA(1, 0, At, B0); PG8_BAR; PG8_SCHED;
;             PG8_STAGEB(PG8_SB(0, 1), b2 + hstep, voffB);
;             PG8_WAIT_V(6); PG8_BAR; PG8_MMA(1, 1, At, B1); PG8_BAR;
;             PG8_LDB(B0, 1, 0); PG8_SCHED; PG8_LDA(At, 1, 0); PG8_STAGE(PG8_SA(0, 1), a2 + hstep, voffA);
;             PG8_WAIT_L(8); PG8_BAR; PG8_WAIT_L(0); PG8_MMA(0, 0, At, B0); PG8_BAR; PG8_SCHED;
;             PG8_LDB(B1, 1, 1); PG8_STAGEB(PG8_SB(1, 0), b3, voffB);
;             PG8_BAR; PG8_WAIT_L(0); PG8_MMA(0, 1, At, B1); PG8_BAR;
;             PG8_LDA(At, 1, 1); PG8_STAGE(PG8_SA(1, 0), a3, voffA);
;             PG8_BAR; PG8_WAIT_L(0); PG8_MMA(1, 0, At, B0); PG8_BAR; PG8_SCHED;
;             PG8_STAGEB(PG8_SB(1, 1), b3 + hstep, voffB);
;             PG8_WAIT_V(6); PG8_BAR; PG8_MMA(1, 1, At, B1); PG8_BAR;
;             }
;         }
;         if constexpr (ALIGN_EPI) { if (wr == 0) PG8_BAR; }
.Lq4s_270l:
	v_mfma_f32_16x16x32_bf16 v[2:5], v[160:163], v[236:239], v[2:5]
	v_mfma_f32_16x16x32_bf16 v[2:5], v[164:167], v[240:243], v[2:5]
	s_setprio 0
	v_lshl_add_u64 v[132:133], v[132:133], 0, s[86:87]
	v_lshl_add_u64 v[134:135], v[134:135], 0, s[86:87]
	s_mov_b32 s29, s81
	s_cbranch_scc0 .LBB0_270
.Lpx_270:
	s_and_b64 vcc, exec, s[10:11]
	s_cbranch_vccz .LBB0_273
.LBB0_273:
	s_lshl_b32 s0, s78, 8
	v_mov_b32_e32 v223, v99
	v_mov_b32_e32 v224, v1
	s_add_i32 s0, s0, s6
	v_readlane_b32 s60, v251, 14
	v_add_u32_e32 v192, s0, v224
	s_add_i32 s0, s95, -4
	s_cmp_gt_u32 s0, 4
	s_mov_b64 s[38:39], -1
	v_readlane_b32 s61, v251, 15
	v_readlane_b32 s62, v251, 16
	v_readlane_b32 s63, v251, 17
	v_readlane_b32 s64, v251, 18
	v_readlane_b32 s65, v251, 19
	v_readlane_b32 s66, v251, 20
	v_readlane_b32 s67, v251, 21
	s_cbranch_scc0 .LBB0_443
	s_lshl_b32 s0, s95, 8
	v_readlane_b32 s1, v255, 0
	s_or_b32 s0, s0, s1
	s_cmp_gt_i32 s95, 9
	v_lshl_add_u32 v152, v223, 3, s0
	s_cselect_b64 s[42:43], -1, 0
	s_cmp_lt_i32 s95, 10
	v_readlane_b32 s0, v254, 60
	s_cselect_b64 s[40:41], -1, 0
	v_ashrrev_i32_e32 v153, 31, v152
	v_readlane_b32 s1, v254, 61
	v_mov_b32_e32 v140, 0
	s_and_b64 vcc, exec, s[40:41]
	v_lshl_add_u64 v[148:149], v[152:153], 2, s[0:1]
	v_mov_b32_e32 v144, 0
	v_mov_b32_e32 v145, 0
	v_mov_b32_e32 v146, 0
	v_mov_b32_e32 v147, 0
	s_cbranch_vccnz .LBB0_276
	v_add_co_u32_e32 v132, vcc, 0xffffe000, v148
	s_nop 1
	v_addc_co_u32_e32 v133, vcc, -1, v149, vcc
	global_load_dwordx4 v[144:147], v[132:133], off offset:-2048

; #define PG8_STAGE(bufoff, gbase, voff) do { _Pragma("unroll") for (int _i = 0; _i < 2; ++_i) \
;         __builtin_amdgcn_global_load_lds((const unsigned*)((const char*)(gbase) + (voff)[_i]), (PG8_LAS unsigned*)(lds + (bufoff) + ldsw + _i * 8192), 16, 0, AUX_A); } while (0)
; #define PG8_STAGEB(bufoff, gbase, voff) do { _Pragma("unroll") for (int _i = 0; _i < 2; ++_i) \
;         __builtin_amdgcn_global_load_lds((const unsigned*)((const char*)(gbase) + (voff)[_i]), (PG8_LAS unsigned*)(lds + (bufoff) + ldsw + _i * 8192), 16, 0, AUX_B); } while (0)
; #define PG8_LDA(dst, b, h) do { _Pragma("unroll") for (int m = 0; m < 4; ++m) _Pragma("unroll") for (int k = 0; k < 2; ++k) dst[m][k] = *(const PG8_LAS bf16x8*)(lds + PG8_SA(b, h) + aoff + m * 2048 + k * 1024); } while (0)
; #define PG8_LDB(dst, b, h) do { _Pragma("unroll") for (int n = 0; n < 2; ++n) _Pragma("unroll") for (int k = 0; k < 2; ++k) dst[n][k] = *(const PG8_LAS bf16x8*)(lds + PG8_SB(b, h) + boff + n * 2048 + k * 1024); } while (0)
; #define PG8_WAIT_V(n) asm volatile("s_waitcnt vmcnt(" #n ")" ::: "memory")
; #define PG8_WAIT_L(n) asm volatile("s_waitcnt lgkmcnt(" #n ")" ::: "memory")
; #define PG8_BAR __builtin_amdgcn_s_barrier()
; template <class Epi, class Sched, bool ALIGN_EPI = false, bool SP2 = false>
; __device__ __forceinline__ void gemm_phase(PG8_LAS unsigned char* lds, const Gemm g, const Sched& S, const Epi& E) {
;     ...
;         for (int t = 0; t < nt; t += 2) {
;             const bool last = (t == nt - 2);
;             const char* a1 = PG8_KP(cA, t + 1, rot, nt);
;             const char* a2 = last ? nAr : PG8_KP(cA, t + 2, rot, nt); const char* b2 = last ? nBr : PG8_KP(cB, t + 2, rot, nt);
;             const char* a3 = a2 + kstep; const char* b3 = b2 + kstep;
;             if (last && has_next) S.a_ready(nxt);
;             if constexpr (SP2) {
;             PG8_LDB(B0, 0, 0); PG8_LDB(B1, 0, 1); PG8_SCHED; PG8_LDA(At, 0, 0); PG8_STAGE(PG8_SA(1, 1), a1 + hstep, voffA);
;             PG8_WAIT_V(8); PG8_WAIT_L(0); PG8_BAR; PG8_MMA(0, 0, At, B0); PG8_MMA(0, 1, At, B1); PG8_BAR; PG8_SCHED;
;             PG8_LDA(At, 0, 1); PG8_STAGEB(PG8_SB(0, 0), b2, voffB); PG8_STAGEB(PG8_SB(0, 1), b2 + hstep, voffB); PG8_STAGE(PG8_SA(0, 0), a2, voffA);
;             PG8_WAIT_V(8); PG8_WAIT_L(0); PG8_BAR; PG8_MMA(1, 0, At, B0); PG8_MMA(1, 1, At, B1); PG8_BAR; PG8_SCHED;
.Lpk_936:
	s_add_i32 s81, s29, 2
	s_cmp_lt_u32 s29, 14
	s_cselect_b32 s0, 0, -16
	s_add_i32 s0, s81, s0
	s_ashr_i32 s1, s0, 31
	s_lshl_b64 s[0:1], s[0:1], 7
	s_add_u32 s2, s64, s0
	s_addc_u32 s46, s65, s1
	s_add_u32 s0, s26, s0
	s_addc_u32 s1, s27, s1
	s_cmp_eq_u32 s29, 14
	s_cselect_b32 s57, s15, s46
	s_cselect_b32 s56, s17, s2
	s_cselect_b32 s59, s43, s1
	s_cselect_b32 s58, s78, s0
	s_add_i32 s2, 0, 0x10000
	s_add_i32 s83, s2, s33
	s_add_i32 s46, 0, 0x14000
	s_add_i32 m0, s25, 0xc000
	s_add_i32 s82, s25, 0xe000
	s_add_i32 s84, s83, 0x2000
	s_add_u32 s60, s58, 0x40000
	s_addc_u32 s61, s59, 0
	s_add_i32 s88, s46, s33
	v_add_u32_e32 v160, s2, v99
	v_add_u32_e32 v166, s46, v99
	s_add_i32 s89, s88, 0x2000
	s_add_i32 s90, 0, 0x18000
	s_add_i32 s91, 0, 0x1c000
	ds_read_b128 v[22:25], v160
	ds_read_b128 v[34:37], v160 offset:1024
	ds_read_b128 v[38:41], v160 offset:2048
	ds_read_b128 v[160:163], v160 offset:3072
	ds_read_b128 v[180:183], v166
	ds_read_b128 v[184:187], v166 offset:1024
	ds_read_b128 v[188:191], v166 offset:2048
	ds_read_b128 v[192:195], v166 offset:3072
	s_add_u32 s54, s56, 0x40000
	s_addc_u32 s55, s57, 0
	s_add_i32 s1, s90, s33
	s_add_i32 s0, s1, 0x2000
	s_add_u32 s52, s58, 0x40080
	s_addc_u32 s53, s59, 0
	s_add_i32 s47, s91, s33
	s_add_i32 s46, s47, 0x2000
	s_cmp_gt_u32 s29, 13
	ds_read_b128 v[196:199], v165
	ds_read_b128 v[200:203], v165 offset:1024
	ds_read_b128 v[222:225], v165 offset:2048
	ds_read_b128 v[226:229], v165 offset:3072
	ds_read_b128 v[230:233], v165 offset:4096
	ds_read_b128 v[234:237], v165 offset:5120
	ds_read_b128 v[238:241], v165 offset:6144
	ds_read_b128 v[242:245], v165 offset:7168
	global_load_lds_dwordx4 v[16:17], off
	s_mov_b32 m0, s82
	s_nop 0
	global_load_lds_dwordx4 v[14:15], off
	s_waitcnt vmcnt(8)
	s_waitcnt lgkmcnt(0)
	s_setprio 1
	s_barrier
	v_mfma_f32_16x16x32_bf16 v[144:147], v[22:25], v[196:199], 0
	v_mfma_f32_16x16x32_bf16 v[144:147], v[34:37], v[200:203], v[144:147]
	v_mfma_f32_16x16x32_bf16 v[140:143], v[38:41], v[196:199], 0
	v_mfma_f32_16x16x32_bf16 v[140:143], v[160:163], v[200:203], v[140:143]
	v_mfma_f32_16x16x32_bf16 v[128:131], v[22:25], v[222:225], 0
	v_mfma_f32_16x16x32_bf16 v[128:131], v[34:37], v[226:229], v[128:131]
	v_mfma_f32_16x16x32_bf16 v[124:127], v[38:41], v[222:225], 0
	v_mfma_f32_16x16x32_bf16 v[124:127], v[160:163], v[226:229], v[124:127]
	v_mfma_f32_16x16x32_bf16 v[112:115], v[22:25], v[230:233], 0
	v_mfma_f32_16x16x32_bf16 v[112:115], v[34:37], v[234:237], v[112:115]
	v_mfma_f32_16x16x32_bf16 v[108:111], v[38:41], v[230:233], 0
	v_mfma_f32_16x16x32_bf16 v[108:111], v[160:163], v[234:237], v[108:111]
	v_mfma_f32_16x16x32_bf16 v[94:97], v[22:25], v[238:241], 0
	v_mfma_f32_16x16x32_bf16 v[94:97], v[34:37], v[242:245], v[94:97]
	v_mfma_f32_16x16x32_bf16 v[90:93], v[38:41], v[238:241], 0
	v_mfma_f32_16x16x32_bf16 v[90:93], v[160:163], v[242:245], v[90:93]
	s_setprio 0
	s_setprio 1
	v_mfma_f32_16x16x32_bf16 v[136:139], v[180:183], v[196:199], 0
	v_mfma_f32_16x16x32_bf16 v[136:139], v[184:187], v[200:203], v[136:139]
	v_mfma_f32_16x16x32_bf16 v[132:135], v[188:191], v[196:199], 0
	v_mfma_f32_16x16x32_bf16 v[132:135], v[192:195], v[200:203], v[132:135]
	v_mfma_f32_16x16x32_bf16 v[120:123], v[180:183], v[222:225], 0
	v_mfma_f32_16x16x32_bf16 v[120:123], v[184:187], v[226:229], v[120:123]
	v_mfma_f32_16x16x32_bf16 v[116:119], v[188:191], v[222:225], 0
	v_mfma_f32_16x16x32_bf16 v[116:119], v[192:195], v[226:229], v[116:119]
	v_mfma_f32_16x16x32_bf16 v[104:107], v[180:183], v[230:233], 0
	v_mfma_f32_16x16x32_bf16 v[104:107], v[184:187], v[234:237], v[104:107]
	v_mfma_f32_16x16x32_bf16 v[100:103], v[188:191], v[230:233], 0
	v_mfma_f32_16x16x32_bf16 v[100:103], v[192:195], v[234:237], v[100:103]
	v_mfma_f32_16x16x32_bf16 v[86:89], v[180:183], v[238:241], 0
	v_mfma_f32_16x16x32_bf16 v[86:89], v[184:187], v[242:245], v[86:89]
	s_setprio 2
	s_barrier
	v_mfma_f32_16x16x32_bf16 v[82:85], v[188:191], v[238:241], 0
	v_mfma_f32_16x16x32_bf16 v[82:85], v[192:195], v[242:245], v[82:85]
	s_setprio 0
	s_mov_b32 m0, s83
	v_lshl_add_u64 v[166:167], s[58:59], 0, v[150:151]
	ds_read_b128 v[196:199], v165 offset:16384
	ds_read_b128 v[200:203], v165 offset:17408
	ds_read_b128 v[222:225], v165 offset:18432
	ds_read_b128 v[226:229], v165 offset:19456
	ds_read_b128 v[230:233], v165 offset:20480
	ds_read_b128 v[234:237], v165 offset:21504
	ds_read_b128 v[238:241], v165 offset:22528
	ds_read_b128 v[242:245], v165 offset:23552
	global_load_lds_dwordx4 v[166:167], off
	v_lshl_add_u64 v[168:169], s[58:59], 0, v[154:155]
	s_mov_b32 m0, s84
	v_lshl_add_u64 v[172:173], s[60:61], 0, v[150:151]
	global_load_lds_dwordx4 v[168:169], off
	s_mov_b32 m0, s88
	v_lshl_add_u64 v[212:213], s[56:57], 0, v[152:153]
	global_load_lds_dwordx4 v[172:173], off
	v_lshl_add_u64 v[172:173], s[60:61], 0, v[154:155]
	s_mov_b32 m0, s89
	s_nop 0
	global_load_lds_dwordx4 v[172:173], off
	v_lshl_add_u64 v[172:173], s[56:57], 0, v[148:149]
	s_mov_b32 m0, s25
	s_nop 0
	global_load_lds_dwordx4 v[172:173], off
	s_mov_b32 m0, s62
	s_nop 0
	global_load_lds_dwordx4 v[212:213], off
	s_waitcnt vmcnt(8)
	s_waitcnt lgkmcnt(0)
	s_setprio 1
	s_barrier
; #define PG8_STAGE(bufoff, gbase, voff) do { _Pragma("unroll") for (int _i = 0; _i < 2; ++_i) \
;         __builtin_amdgcn_global_load_lds((const unsigned*)((const char*)(gbase) + (voff)[_i]), (PG8_LAS unsigned*)(lds + (bufoff) + ldsw + _i * 8192), 16, 0, AUX_A); } while (0)
; #define PG8_STAGEB(bufoff, gbase, voff) do { _Pragma("unroll") for (int _i = 0; _i < 2; ++_i) \
;         __builtin_amdgcn_global_load_lds((const unsigned*)((const char*)(gbase) + (voff)[_i]), (PG8_LAS unsigned*)(lds + (bufoff) + ldsw + _i * 8192), 16, 0, AUX_B); } while (0)
; #define PG8_LDA(dst, b, h) do { _Pragma("unroll") for (int m = 0; m < 4; ++m) _Pragma("unroll") for (int k = 0; k < 2; ++k) dst[m][k] = *(const PG8_LAS bf16x8*)(lds + PG8_SA(b, h) + aoff + m * 2048 + k * 1024); } while (0)
; #define PG8_LDB(dst, b, h) do { _Pragma("unroll") for (int n = 0; n < 2; ++n) _Pragma("unroll") for (int k = 0; k < 2; ++k) dst[n][k] = *(const PG8_LAS bf16x8*)(lds + PG8_SB(b, h) + boff + n * 2048 + k * 1024); } while (0)
; #define PG8_MMA(ai, bj, At, Bt) do { __builtin_amdgcn_s_setprio(1); _Pragma("unroll") for (int m = 0; m < 4; ++m) _Pragma("unroll") for (int n = 0; n < 2; ++n) _Pragma("unroll") for (int k = 0; k < 2; ++k) \
;         acc[ai][bj][m][n] = __builtin_amdgcn_mfma_f32_16x16x32_bf16(Bt[n][k], At[m][k], acc[ai][bj][m][n], 0, 0, 0); __builtin_amdgcn_s_setprio(0); } while (0)
; #define PG8_WAIT_V(n) asm volatile("s_waitcnt vmcnt(" #n ")" ::: "memory")
; #define PG8_WAIT_L(n) asm volatile("s_waitcnt lgkmcnt(" #n ")" ::: "memory")
; template <class Epi, class Sched, bool ALIGN_EPI = false, bool SP2 = false>
; __device__ __forceinline__ void gemm_phase(PG8_LAS unsigned char* lds, const Gemm g, const Sched& S, const Epi& E) {
;     ...
;             PG8_WAIT_V(8); PG8_WAIT_L(0); PG8_BAR; PG8_MMA(0, 0, At, B0); PG8_MMA(0, 1, At, B1); PG8_BAR; PG8_SCHED;
;             PG8_LDA(At, 0, 1); PG8_STAGEB(PG8_SB(0, 0), b2, voffB); PG8_STAGEB(PG8_SB(0, 1), b2 + hstep, voffB); PG8_STAGE(PG8_SA(0, 0), a2, voffA);
;             PG8_WAIT_V(8); PG8_WAIT_L(0); PG8_BAR; PG8_MMA(1, 0, At, B0); PG8_MMA(1, 1, At, B1); PG8_BAR; PG8_SCHED;
;             PG8_LDB(B0, 1, 0); PG8_LDB(B1, 1, 1); PG8_SCHED; PG8_LDA(At, 1, 0); PG8_STAGE(PG8_SA(0, 1), a2 + hstep, voffA);
;             PG8_WAIT_V(8); PG8_WAIT_L(0); PG8_BAR; PG8_MMA(0, 0, At, B0); PG8_MMA(0, 1, At, B1); PG8_BAR; PG8_SCHED;
	v_mfma_f32_16x16x32_bf16 v[78:81], v[22:25], v[196:199], 0
	v_mfma_f32_16x16x32_bf16 v[78:81], v[34:37], v[200:203], v[78:81]
	v_mfma_f32_16x16x32_bf16 v[74:77], v[38:41], v[196:199], 0
	v_mfma_f32_16x16x32_bf16 v[74:77], v[160:163], v[200:203], v[74:77]
	v_mfma_f32_16x16x32_bf16 v[62:65], v[22:25], v[222:225], 0
	v_mfma_f32_16x16x32_bf16 v[62:65], v[34:37], v[226:229], v[62:65]
	v_mfma_f32_16x16x32_bf16 v[58:61], v[38:41], v[222:225], 0
	v_mfma_f32_16x16x32_bf16 v[58:61], v[160:163], v[226:229], v[58:61]
	v_mfma_f32_16x16x32_bf16 v[46:49], v[22:25], v[230:233], 0
	v_mfma_f32_16x16x32_bf16 v[46:49], v[34:37], v[234:237], v[46:49]
	v_mfma_f32_16x16x32_bf16 v[42:45], v[38:41], v[230:233], 0
	v_mfma_f32_16x16x32_bf16 v[42:45], v[160:163], v[234:237], v[42:45]
	v_mfma_f32_16x16x32_bf16 v[18:21], v[22:25], v[238:241], 0
	v_mfma_f32_16x16x32_bf16 v[18:21], v[34:37], v[242:245], v[18:21]
	v_mfma_f32_16x16x32_bf16 v[10:13], v[38:41], v[238:241], 0
	v_mfma_f32_16x16x32_bf16 v[10:13], v[160:163], v[242:245], v[10:13]
	s_setprio 0
	s_setprio 1
	v_mfma_f32_16x16x32_bf16 v[50:53], v[188:191], v[222:225], 0
	v_mfma_f32_16x16x32_bf16 v[30:33], v[180:183], v[230:233], 0
	v_mfma_f32_16x16x32_bf16 v[26:29], v[188:191], v[230:233], 0
	v_mfma_f32_16x16x32_bf16 v[6:9], v[180:183], v[238:241], 0
	v_mfma_f32_16x16x32_bf16 v[2:5], v[188:191], v[238:241], 0
	v_mfma_f32_16x16x32_bf16 v[22:25], v[180:183], v[196:199], 0
	v_mfma_f32_16x16x32_bf16 v[34:37], v[188:191], v[196:199], 0
	v_mfma_f32_16x16x32_bf16 v[38:41], v[180:183], v[222:225], 0
	v_mfma_f32_16x16x32_bf16 v[50:53], v[192:195], v[226:229], v[50:53]
	v_mfma_f32_16x16x32_bf16 v[30:33], v[184:187], v[234:237], v[30:33]
	v_mfma_f32_16x16x32_bf16 v[26:29], v[192:195], v[234:237], v[26:29]
	v_mfma_f32_16x16x32_bf16 v[6:9], v[184:187], v[242:245], v[6:9]
	v_mfma_f32_16x16x32_bf16 v[2:5], v[192:195], v[242:245], v[2:5]
	v_mfma_f32_16x16x32_bf16 v[22:25], v[184:187], v[200:203], v[22:25]
	s_setprio 2
	s_barrier
	v_mfma_f32_16x16x32_bf16 v[34:37], v[192:195], v[200:203], v[34:37]
	v_mfma_f32_16x16x32_bf16 v[38:41], v[184:187], v[226:229], v[38:41]
	s_setprio 0
	v_add_u32_e32 v160, s90, v99
	v_add_u32_e32 v192, s91, v99
	ds_read_b128 v[54:57], v160
	ds_read_b128 v[66:69], v160 offset:1024
	ds_read_b128 v[70:73], v160 offset:2048
	ds_read_b128 v[160:163], v160 offset:3072
	ds_read_b128 v[180:183], v192
	ds_read_b128 v[184:187], v192 offset:1024
	ds_read_b128 v[188:191], v192 offset:2048
	ds_read_b128 v[192:195], v192 offset:3072
	s_mov_b32 m0, s63
	v_lshl_add_u64 v[246:247], s[54:55], 0, v[148:149]
	ds_read_b128 v[196:199], v165 offset:32768
	ds_read_b128 v[200:203], v165 offset:33792
	ds_read_b128 v[222:225], v165 offset:34816
	ds_read_b128 v[226:229], v165 offset:35840
	ds_read_b128 v[230:233], v165 offset:36864
	ds_read_b128 v[234:237], v165 offset:37888
	ds_read_b128 v[238:241], v165 offset:38912
	ds_read_b128 v[242:245], v165 offset:39936
	global_load_lds_dwordx4 v[246:247], off
	v_lshl_add_u64 v[246:247], s[54:55], 0, v[152:153]
	s_mov_b32 m0, s69
	s_nop 0
	global_load_lds_dwordx4 v[246:247], off
	s_waitcnt vmcnt(8)
	s_waitcnt lgkmcnt(0)
	s_setprio 1
	s_barrier
	v_mfma_f32_16x16x32_bf16 v[144:147], v[54:57], v[196:199], v[144:147]
	v_mfma_f32_16x16x32_bf16 v[144:147], v[66:69], v[200:203], v[144:147]
	v_mfma_f32_16x16x32_bf16 v[140:143], v[70:73], v[196:199], v[140:143]
	v_mfma_f32_16x16x32_bf16 v[140:143], v[160:163], v[200:203], v[140:143]
	v_mfma_f32_16x16x32_bf16 v[128:131], v[54:57], v[222:225], v[128:131]
	v_mfma_f32_16x16x32_bf16 v[128:131], v[66:69], v[226:229], v[128:131]
	v_mfma_f32_16x16x32_bf16 v[124:127], v[70:73], v[222:225], v[124:127]
	v_mfma_f32_16x16x32_bf16 v[124:127], v[160:163], v[226:229], v[124:127]
	v_mfma_f32_16x16x32_bf16 v[112:115], v[54:57], v[230:233], v[112:115]
	v_mfma_f32_16x16x32_bf16 v[112:115], v[66:69], v[234:237], v[112:115]
	v_mfma_f32_16x16x32_bf16 v[108:111], v[70:73], v[230:233], v[108:111]
	v_mfma_f32_16x16x32_bf16 v[108:111], v[160:163], v[234:237], v[108:111]
	v_mfma_f32_16x16x32_bf16 v[94:97], v[54:57], v[238:241], v[94:97]
	v_mfma_f32_16x16x32_bf16 v[94:97], v[66:69], v[242:245], v[94:97]
	v_mfma_f32_16x16x32_bf16 v[90:93], v[70:73], v[238:241], v[90:93]
	v_mfma_f32_16x16x32_bf16 v[90:93], v[160:163], v[242:245], v[90:93]
	s_setprio 0
	s_setprio 1
	v_mfma_f32_16x16x32_bf16 v[136:139], v[180:183], v[196:199], v[136:139]
	v_mfma_f32_16x16x32_bf16 v[136:139], v[184:187], v[200:203], v[136:139]
	v_mfma_f32_16x16x32_bf16 v[132:135], v[188:191], v[196:199], v[132:135]
	v_mfma_f32_16x16x32_bf16 v[132:135], v[192:195], v[200:203], v[132:135]
	v_mfma_f32_16x16x32_bf16 v[120:123], v[180:183], v[222:225], v[120:123]
	v_mfma_f32_16x16x32_bf16 v[120:123], v[184:187], v[226:229], v[120:123]
	v_mfma_f32_16x16x32_bf16 v[116:119], v[188:191], v[222:225], v[116:119]
	v_mfma_f32_16x16x32_bf16 v[116:119], v[192:195], v[226:229], v[116:119]
	v_mfma_f32_16x16x32_bf16 v[104:107], v[180:183], v[230:233], v[104:107]
	v_mfma_f32_16x16x32_bf16 v[104:107], v[184:187], v[234:237], v[104:107]
	v_mfma_f32_16x16x32_bf16 v[100:103], v[188:191], v[230:233], v[100:103]
	v_mfma_f32_16x16x32_bf16 v[100:103], v[192:195], v[234:237], v[100:103]
	v_mfma_f32_16x16x32_bf16 v[86:89], v[180:183], v[238:241], v[86:89]
	v_mfma_f32_16x16x32_bf16 v[86:89], v[184:187], v[242:245], v[86:89]
	s_setprio 2
	s_barrier
; #define PG8_STAGE(bufoff, gbase, voff) do { _Pragma("unroll") for (int _i = 0; _i < 2; ++_i) \
;         __builtin_amdgcn_global_load_lds((const unsigned*)((const char*)(gbase) + (voff)[_i]), (PG8_LAS unsigned*)(lds + (bufoff) + ldsw + _i * 8192), 16, 0, AUX_A); } while (0)
; #define PG8_STAGEB(bufoff, gbase, voff) do { _Pragma("unroll") for (int _i = 0; _i < 2; ++_i) \
;         __builtin_amdgcn_global_load_lds((const unsigned*)((const char*)(gbase) + (voff)[_i]), (PG8_LAS unsigned*)(lds + (bufoff) + ldsw + _i * 8192), 16, 0, AUX_B); } while (0)
; #define PG8_LDA(dst, b, h) do { _Pragma("unroll") for (int m = 0; m < 4; ++m) _Pragma("unroll") for (int k = 0; k < 2; ++k) dst[m][k] = *(const PG8_LAS bf16x8*)(lds + PG8_SA(b, h) + aoff + m * 2048 + k * 1024); } while (0)
; #define PG8_MMA(ai, bj, At, Bt) do { __builtin_amdgcn_s_setprio(1); _Pragma("unroll") for (int m = 0; m < 4; ++m) _Pragma("unroll") for (int n = 0; n < 2; ++n) _Pragma("unroll") for (int k = 0; k < 2; ++k) \
;         acc[ai][bj][m][n] = __builtin_amdgcn_mfma_f32_16x16x32_bf16(Bt[n][k], At[m][k], acc[ai][bj][m][n], 0, 0, 0); __builtin_amdgcn_s_setprio(0); } while (0)
; #define PG8_WAIT_V(n) asm volatile("s_waitcnt vmcnt(" #n ")" ::: "memory")
; #define PG8_WAIT_L(n) asm volatile("s_waitcnt lgkmcnt(" #n ")" ::: "memory")
; #define PG8_BAR __builtin_amdgcn_s_barrier()
; #define PG8_SCHED __builtin_amdgcn_sched_barrier(0)
; template <class Epi, class Sched, bool ALIGN_EPI = false, bool SP2 = false>
; __device__ __forceinline__ void gemm_phase(PG8_LAS unsigned char* lds, const Gemm g, const Sched& S, const Epi& E) {
;     ...
;             const bool last = (t == nt - 2);
;     ...
;             PG8_LDA(At, 1, 1); PG8_STAGEB(PG8_SB(1, 0), b3, voffB); PG8_STAGEB(PG8_SB(1, 1), b3 + hstep, voffB); PG8_STAGE(PG8_SA(1, 0), a3, voffA);
;             PG8_WAIT_V(8); PG8_WAIT_L(0); PG8_BAR; PG8_MMA(1, 0, At, B0); PG8_MMA(1, 1, At, B1); PG8_BAR; PG8_SCHED;
	v_mfma_f32_16x16x32_bf16 v[82:85], v[188:191], v[238:241], v[82:85]
	v_mfma_f32_16x16x32_bf16 v[82:85], v[192:195], v[242:245], v[82:85]
	s_setprio 0
	s_mov_b32 m0, s1
	v_lshl_add_u64 v[166:167], v[166:167], 0, s[76:77]
	ds_read_b128 v[196:199], v165 offset:49152
	ds_read_b128 v[200:203], v165 offset:50176
	ds_read_b128 v[222:225], v165 offset:51200
	ds_read_b128 v[226:229], v165 offset:52224
	ds_read_b128 v[230:233], v165 offset:53248
	ds_read_b128 v[234:237], v165 offset:54272
	ds_read_b128 v[238:241], v165 offset:55296
	ds_read_b128 v[242:245], v165 offset:56320
	global_load_lds_dwordx4 v[166:167], off
	v_lshl_add_u64 v[166:167], v[168:169], 0, s[76:77]
	s_mov_b32 m0, s0
	s_nop 0
	global_load_lds_dwordx4 v[166:167], off
	v_lshl_add_u64 v[166:167], s[52:53], 0, v[150:151]
	s_mov_b32 m0, s47
	s_nop 0
	global_load_lds_dwordx4 v[166:167], off
	v_lshl_add_u64 v[166:167], s[52:53], 0, v[154:155]
	s_mov_b32 m0, s46
	s_nop 0
	global_load_lds_dwordx4 v[166:167], off
	v_lshl_add_u64 v[166:167], v[172:173], 0, s[76:77]
	s_mov_b32 m0, s70
	s_nop 0
	global_load_lds_dwordx4 v[166:167], off
	v_lshl_add_u64 v[166:167], v[212:213], 0, s[76:77]
	s_mov_b32 m0, s71
	s_nop 0
	global_load_lds_dwordx4 v[166:167], off
	s_waitcnt vmcnt(8)
	s_waitcnt lgkmcnt(0)
	s_setprio 1
	s_barrier
	v_mfma_f32_16x16x32_bf16 v[78:81], v[54:57], v[196:199], v[78:81]
	v_mfma_f32_16x16x32_bf16 v[78:81], v[66:69], v[200:203], v[78:81]
	v_mfma_f32_16x16x32_bf16 v[74:77], v[70:73], v[196:199], v[74:77]
	v_mfma_f32_16x16x32_bf16 v[74:77], v[160:163], v[200:203], v[74:77]
	v_mfma_f32_16x16x32_bf16 v[62:65], v[54:57], v[222:225], v[62:65]
	v_mfma_f32_16x16x32_bf16 v[62:65], v[66:69], v[226:229], v[62:65]
	v_mfma_f32_16x16x32_bf16 v[58:61], v[70:73], v[222:225], v[58:61]
	v_mfma_f32_16x16x32_bf16 v[58:61], v[160:163], v[226:229], v[58:61]
	v_mfma_f32_16x16x32_bf16 v[46:49], v[54:57], v[230:233], v[46:49]
	v_mfma_f32_16x16x32_bf16 v[46:49], v[66:69], v[234:237], v[46:49]
	v_mfma_f32_16x16x32_bf16 v[42:45], v[70:73], v[230:233], v[42:45]
	v_mfma_f32_16x16x32_bf16 v[42:45], v[160:163], v[234:237], v[42:45]
	v_mfma_f32_16x16x32_bf16 v[18:21], v[54:57], v[238:241], v[18:21]
	v_mfma_f32_16x16x32_bf16 v[18:21], v[66:69], v[242:245], v[18:21]
	v_mfma_f32_16x16x32_bf16 v[10:13], v[70:73], v[238:241], v[10:13]
	v_mfma_f32_16x16x32_bf16 v[10:13], v[160:163], v[242:245], v[10:13]
	s_setprio 0
	s_setprio 1
	v_mfma_f32_16x16x32_bf16 v[22:25], v[180:183], v[196:199], v[22:25]
	v_mfma_f32_16x16x32_bf16 v[70:73], v[184:187], v[200:203], v[22:25]
	v_mfma_f32_16x16x32_bf16 v[22:25], v[188:191], v[196:199], v[34:37]
	v_mfma_f32_16x16x32_bf16 v[66:69], v[192:195], v[200:203], v[22:25]
	v_mfma_f32_16x16x32_bf16 v[22:25], v[180:183], v[222:225], v[38:41]
	v_mfma_f32_16x16x32_bf16 v[54:57], v[184:187], v[226:229], v[22:25]
	v_mfma_f32_16x16x32_bf16 v[22:25], v[188:191], v[222:225], v[50:53]
	v_mfma_f32_16x16x32_bf16 v[50:53], v[192:195], v[226:229], v[22:25]
	v_mfma_f32_16x16x32_bf16 v[22:25], v[180:183], v[230:233], v[30:33]
	v_mfma_f32_16x16x32_bf16 v[30:33], v[184:187], v[234:237], v[22:25]
	v_mfma_f32_16x16x32_bf16 v[22:25], v[188:191], v[230:233], v[26:29]
	v_mfma_f32_16x16x32_bf16 v[6:9], v[180:183], v[238:241], v[6:9]
	v_mfma_f32_16x16x32_bf16 v[2:5], v[188:191], v[238:241], v[2:5]
	v_mfma_f32_16x16x32_bf16 v[26:29], v[192:195], v[234:237], v[22:25]
	s_setprio 2
	s_cbranch_scc0 .Lq4b_936p
	v_cmp_ne_u32_e64 vcc, s12, 0
	s_cbranch_vccz .Lq4s_936p

; #define PG8_STAGE(bufoff, gbase, voff) do { _Pragma("unroll") for (int _i = 0; _i < 2; ++_i) \
;         __builtin_amdgcn_global_load_lds((const unsigned*)((const char*)(gbase) + (voff)[_i]), (PG8_LAS unsigned*)(lds + (bufoff) + ldsw + _i * 8192), 16, 0, AUX_A); } while (0)
; #define PG8_STAGEB(bufoff, gbase, voff) do { _Pragma("unroll") for (int _i = 0; _i < 2; ++_i) \
;         __builtin_amdgcn_global_load_lds((const unsigned*)((const char*)(gbase) + (voff)[_i]), (PG8_LAS unsigned*)(lds + (bufoff) + ldsw + _i * 8192), 16, 0, AUX_B); } while (0)
; #define PG8_LDA(dst, b, h) do { _Pragma("unroll") for (int m = 0; m < 4; ++m) _Pragma("unroll") for (int k = 0; k < 2; ++k) dst[m][k] = *(const PG8_LAS bf16x8*)(lds + PG8_SA(b, h) + aoff + m * 2048 + k * 1024); } while (0)
; #define PG8_WAIT_V(n) asm volatile("s_waitcnt vmcnt(" #n ")" ::: "memory")
; #define PG8_WAIT_L(n) asm volatile("s_waitcnt lgkmcnt(" #n ")" ::: "memory")
; #define PG8_BAR __builtin_amdgcn_s_barrier()
; template <class Epi, class Sched, bool ALIGN_EPI = false, bool SP2 = false>
; __device__ __forceinline__ void gemm_phase(PG8_LAS unsigned char* lds, const Gemm g, const Sched& S, const Epi& E) {
;     ...
;         for (int t = 0; t < nt; t += 2) {
;             const bool last = (t == nt - 2);
;             const char* a1 = PG8_KP(cA, t + 1, rot, nt);
;             const char* a2 = last ? nAr : PG8_KP(cA, t + 2, rot, nt); const char* b2 = last ? nBr : PG8_KP(cB, t + 2, rot, nt);
;             const char* a3 = a2 + kstep; const char* b3 = b2 + kstep;
;             if (last && has_next) S.a_ready(nxt);
;             if constexpr (SP2) {
;             PG8_LDB(B0, 0, 0); PG8_LDB(B1, 0, 1); PG8_SCHED; PG8_LDA(At, 0, 0); PG8_STAGE(PG8_SA(1, 1), a1 + hstep, voffA);
;             PG8_WAIT_V(8); PG8_WAIT_L(0); PG8_BAR; PG8_MMA(0, 0, At, B0); PG8_MMA(0, 1, At, B1); PG8_BAR; PG8_SCHED;
;             PG8_LDA(At, 0, 1); PG8_STAGEB(PG8_SB(0, 0), b2, voffB); PG8_STAGEB(PG8_SB(0, 1), b2 + hstep, voffB); PG8_STAGE(PG8_SA(0, 0), a2, voffA);
;             PG8_WAIT_V(8); PG8_WAIT_L(0); PG8_BAR; PG8_MMA(1, 0, At, B0); PG8_MMA(1, 1, At, B1); PG8_BAR; PG8_SCHED;
;             PG8_LDB(B0, 1, 0); PG8_LDB(B1, 1, 1); PG8_SCHED; PG8_LDA(At, 1, 0); PG8_STAGE(PG8_SA(0, 1), a2 + hstep, voffA);
;             PG8_WAIT_V(8); PG8_WAIT_L(0); PG8_BAR; PG8_MMA(0, 0, At, B0); PG8_MMA(0, 1, At, B1); PG8_BAR; PG8_SCHED;
.Lq4s_936p:
	v_mfma_f32_16x16x32_bf16 v[6:9], v[184:187], v[242:245], v[6:9]
	v_mfma_f32_16x16x32_bf16 v[2:5], v[192:195], v[242:245], v[2:5]
	s_setprio 0
	v_lshl_add_u64 v[14:15], v[14:15], 0, s[86:87]
	v_lshl_add_u64 v[16:17], v[16:17], 0, s[86:87]
	s_mov_b32 s29, s81
	s_cbranch_scc1 .Lpx_936
.LBB0_936:
	s_add_i32 s81, s29, 2
	s_cmp_lt_u32 s29, 14
	s_cselect_b32 s0, 0, -16
	s_add_i32 s0, s81, s0
	s_ashr_i32 s1, s0, 31
	s_lshl_b64 s[0:1], s[0:1], 7
	s_add_u32 s2, s64, s0
	s_addc_u32 s46, s65, s1
	s_add_u32 s0, s26, s0
	s_addc_u32 s1, s27, s1
	s_cmp_eq_u32 s29, 14
	s_cselect_b32 s57, s15, s46
	s_cselect_b32 s56, s17, s2
	s_cselect_b32 s59, s43, s1
	s_cselect_b32 s58, s78, s0
	s_add_i32 s2, 0, 0x10000
	s_add_i32 s83, s2, s33
	s_add_i32 s46, 0, 0x14000
	s_add_i32 m0, s25, 0xc000
	s_add_i32 s82, s25, 0xe000
	s_add_i32 s84, s83, 0x2000
	s_add_u32 s60, s58, 0x40000
	s_addc_u32 s61, s59, 0
	s_add_i32 s88, s46, s33
	v_add_u32_e32 v160, s2, v99
	v_add_u32_e32 v166, s46, v99
	s_add_i32 s89, s88, 0x2000
	s_add_i32 s90, 0, 0x18000
	s_add_i32 s91, 0, 0x1c000
	ds_read_b128 v[22:25], v160
	ds_read_b128 v[34:37], v160 offset:1024
	ds_read_b128 v[38:41], v160 offset:2048
	ds_read_b128 v[160:163], v160 offset:3072
	ds_read_b128 v[180:183], v166
	ds_read_b128 v[184:187], v166 offset:1024
	ds_read_b128 v[188:191], v166 offset:2048
	ds_read_b128 v[192:195], v166 offset:3072
	s_add_u32 s54, s56, 0x40000
	s_addc_u32 s55, s57, 0
	s_add_i32 s1, s90, s33
	s_add_i32 s0, s1, 0x2000
	s_add_u32 s52, s58, 0x40080
	s_addc_u32 s53, s59, 0
	s_add_i32 s47, s91, s33
	s_add_i32 s46, s47, 0x2000
	s_cmp_gt_u32 s29, 13
	ds_read_b128 v[196:199], v165
	ds_read_b128 v[200:203], v165 offset:1024
	ds_read_b128 v[222:225], v165 offset:2048
	ds_read_b128 v[226:229], v165 offset:3072
	ds_read_b128 v[230:233], v165 offset:4096
	ds_read_b128 v[234:237], v165 offset:5120
	ds_read_b128 v[238:241], v165 offset:6144
	ds_read_b128 v[242:245], v165 offset:7168
	global_load_lds_dwordx4 v[16:17], off
	s_mov_b32 m0, s82
	s_nop 0
	global_load_lds_dwordx4 v[14:15], off
	s_waitcnt vmcnt(8)
	s_waitcnt lgkmcnt(0)
	s_setprio 1
	s_barrier
	v_mfma_f32_16x16x32_bf16 v[144:147], v[22:25], v[196:199], v[144:147]
	v_mfma_f32_16x16x32_bf16 v[144:147], v[34:37], v[200:203], v[144:147]
	v_mfma_f32_16x16x32_bf16 v[140:143], v[38:41], v[196:199], v[140:143]
	v_mfma_f32_16x16x32_bf16 v[140:143], v[160:163], v[200:203], v[140:143]
	v_mfma_f32_16x16x32_bf16 v[128:131], v[22:25], v[222:225], v[128:131]
	v_mfma_f32_16x16x32_bf16 v[128:131], v[34:37], v[226:229], v[128:131]
	v_mfma_f32_16x16x32_bf16 v[124:127], v[38:41], v[222:225], v[124:127]
	v_mfma_f32_16x16x32_bf16 v[124:127], v[160:163], v[226:229], v[124:127]
	v_mfma_f32_16x16x32_bf16 v[112:115], v[22:25], v[230:233], v[112:115]
	v_mfma_f32_16x16x32_bf16 v[112:115], v[34:37], v[234:237], v[112:115]
	v_mfma_f32_16x16x32_bf16 v[108:111], v[38:41], v[230:233], v[108:111]
	v_mfma_f32_16x16x32_bf16 v[108:111], v[160:163], v[234:237], v[108:111]
	v_mfma_f32_16x16x32_bf16 v[94:97], v[22:25], v[238:241], v[94:97]
	v_mfma_f32_16x16x32_bf16 v[94:97], v[34:37], v[242:245], v[94:97]
	v_mfma_f32_16x16x32_bf16 v[90:93], v[38:41], v[238:241], v[90:93]
	v_mfma_f32_16x16x32_bf16 v[90:93], v[160:163], v[242:245], v[90:93]
	s_setprio 0
	s_setprio 1
	v_mfma_f32_16x16x32_bf16 v[136:139], v[180:183], v[196:199], v[136:139]
	v_mfma_f32_16x16x32_bf16 v[136:139], v[184:187], v[200:203], v[136:139]
	v_mfma_f32_16x16x32_bf16 v[132:135], v[188:191], v[196:199], v[132:135]
	v_mfma_f32_16x16x32_bf16 v[132:135], v[192:195], v[200:203], v[132:135]
	v_mfma_f32_16x16x32_bf16 v[120:123], v[180:183], v[222:225], v[120:123]
	v_mfma_f32_16x16x32_bf16 v[120:123], v[184:187], v[226:229], v[120:123]
	v_mfma_f32_16x16x32_bf16 v[116:119], v[188:191], v[222:225], v[116:119]
	v_mfma_f32_16x16x32_bf16 v[116:119], v[192:195], v[226:229], v[116:119]
	v_mfma_f32_16x16x32_bf16 v[104:107], v[180:183], v[230:233], v[104:107]
	v_mfma_f32_16x16x32_bf16 v[104:107], v[184:187], v[234:237], v[104:107]
	v_mfma_f32_16x16x32_bf16 v[100:103], v[188:191], v[230:233], v[100:103]
	v_mfma_f32_16x16x32_bf16 v[100:103], v[192:195], v[234:237], v[100:103]
	v_mfma_f32_16x16x32_bf16 v[86:89], v[180:183], v[238:241], v[86:89]
	v_mfma_f32_16x16x32_bf16 v[86:89], v[184:187], v[242:245], v[86:89]
	s_setprio 2
	s_barrier
	v_mfma_f32_16x16x32_bf16 v[82:85], v[188:191], v[238:241], v[82:85]
	v_mfma_f32_16x16x32_bf16 v[82:85], v[192:195], v[242:245], v[82:85]
	s_setprio 0
	s_mov_b32 m0, s83
	v_lshl_add_u64 v[166:167], s[58:59], 0, v[150:151]
	ds_read_b128 v[196:199], v165 offset:16384
	ds_read_b128 v[200:203], v165 offset:17408
	ds_read_b128 v[222:225], v165 offset:18432
	ds_read_b128 v[226:229], v165 offset:19456
	ds_read_b128 v[230:233], v165 offset:20480
	ds_read_b128 v[234:237], v165 offset:21504
	ds_read_b128 v[238:241], v165 offset:22528
	ds_read_b128 v[242:245], v165 offset:23552
	global_load_lds_dwordx4 v[166:167], off
	v_lshl_add_u64 v[168:169], s[58:59], 0, v[154:155]
	s_mov_b32 m0, s84
	v_lshl_add_u64 v[172:173], s[60:61], 0, v[150:151]
	global_load_lds_dwordx4 v[168:169], off
	s_mov_b32 m0, s88
	v_lshl_add_u64 v[212:213], s[56:57], 0, v[152:153]
	global_load_lds_dwordx4 v[172:173], off
	v_lshl_add_u64 v[172:173], s[60:61], 0, v[154:155]
	s_mov_b32 m0, s89
	s_nop 0
	global_load_lds_dwordx4 v[172:173], off
	v_lshl_add_u64 v[172:173], s[56:57], 0, v[148:149]
	s_mov_b32 m0, s25
	s_nop 0
	global_load_lds_dwordx4 v[172:173], off
	s_mov_b32 m0, s62
	s_nop 0
	global_load_lds_dwordx4 v[212:213], off
	s_waitcnt vmcnt(8)
	s_waitcnt lgkmcnt(0)
	s_setprio 1
	s_barrier
; #define PG8_STAGE(bufoff, gbase, voff) do { _Pragma("unroll") for (int _i = 0; _i < 2; ++_i) \
;         __builtin_amdgcn_global_load_lds((const unsigned*)((const char*)(gbase) + (voff)[_i]), (PG8_LAS unsigned*)(lds + (bufoff) + ldsw + _i * 8192), 16, 0, AUX_A); } while (0)
; #define PG8_STAGEB(bufoff, gbase, voff) do { _Pragma("unroll") for (int _i = 0; _i < 2; ++_i) \
;         __builtin_amdgcn_global_load_lds((const unsigned*)((const char*)(gbase) + (voff)[_i]), (PG8_LAS unsigned*)(lds + (bufoff) + ldsw + _i * 8192), 16, 0, AUX_B); } while (0)
; #define PG8_LDA(dst, b, h) do { _Pragma("unroll") for (int m = 0; m < 4; ++m) _Pragma("unroll") for (int k = 0; k < 2; ++k) dst[m][k] = *(const PG8_LAS bf16x8*)(lds + PG8_SA(b, h) + aoff + m * 2048 + k * 1024); } while (0)
; #define PG8_LDB(dst, b, h) do { _Pragma("unroll") for (int n = 0; n < 2; ++n) _Pragma("unroll") for (int k = 0; k < 2; ++k) dst[n][k] = *(const PG8_LAS bf16x8*)(lds + PG8_SB(b, h) + boff + n * 2048 + k * 1024); } while (0)
; #define PG8_MMA(ai, bj, At, Bt) do { __builtin_amdgcn_s_setprio(1); _Pragma("unroll") for (int m = 0; m < 4; ++m) _Pragma("unroll") for (int n = 0; n < 2; ++n) _Pragma("unroll") for (int k = 0; k < 2; ++k) \
;         acc[ai][bj][m][n] = __builtin_amdgcn_mfma_f32_16x16x32_bf16(Bt[n][k], At[m][k], acc[ai][bj][m][n], 0, 0, 0); __builtin_amdgcn_s_setprio(0); } while (0)
; #define PG8_WAIT_V(n) asm volatile("s_waitcnt vmcnt(" #n ")" ::: "memory")
; #define PG8_WAIT_L(n) asm volatile("s_waitcnt lgkmcnt(" #n ")" ::: "memory")
; #define PG8_BAR __builtin_amdgcn_s_barrier()
; #define PG8_SCHED __builtin_amdgcn_sched_barrier(0)
; template <class Epi, class Sched, bool ALIGN_EPI = false, bool SP2 = false>
; __device__ __forceinline__ void gemm_phase(PG8_LAS unsigned char* lds, const Gemm g, const Sched& S, const Epi& E) {
;     ...
;             PG8_LDA(At, 0, 1); PG8_STAGEB(PG8_SB(0, 0), b2, voffB); PG8_STAGEB(PG8_SB(0, 1), b2 + hstep, voffB); PG8_STAGE(PG8_SA(0, 0), a2, voffA);
;             PG8_WAIT_V(8); PG8_WAIT_L(0); PG8_BAR; PG8_MMA(1, 0, At, B0); PG8_MMA(1, 1, At, B1); PG8_BAR; PG8_SCHED;
;             PG8_LDB(B0, 1, 0); PG8_LDB(B1, 1, 1); PG8_SCHED; PG8_LDA(At, 1, 0); PG8_STAGE(PG8_SA(0, 1), a2 + hstep, voffA);
;             PG8_WAIT_V(8); PG8_WAIT_L(0); PG8_BAR; PG8_MMA(0, 0, At, B0); PG8_MMA(0, 1, At, B1); PG8_BAR; PG8_SCHED;
	v_mfma_f32_16x16x32_bf16 v[78:81], v[22:25], v[196:199], v[78:81]
	v_mfma_f32_16x16x32_bf16 v[78:81], v[34:37], v[200:203], v[78:81]
	v_mfma_f32_16x16x32_bf16 v[74:77], v[38:41], v[196:199], v[74:77]
	v_mfma_f32_16x16x32_bf16 v[74:77], v[160:163], v[200:203], v[74:77]
	v_mfma_f32_16x16x32_bf16 v[62:65], v[22:25], v[222:225], v[62:65]
	v_mfma_f32_16x16x32_bf16 v[62:65], v[34:37], v[226:229], v[62:65]
	v_mfma_f32_16x16x32_bf16 v[58:61], v[38:41], v[222:225], v[58:61]
	v_mfma_f32_16x16x32_bf16 v[58:61], v[160:163], v[226:229], v[58:61]
	v_mfma_f32_16x16x32_bf16 v[46:49], v[22:25], v[230:233], v[46:49]
	v_mfma_f32_16x16x32_bf16 v[46:49], v[34:37], v[234:237], v[46:49]
	v_mfma_f32_16x16x32_bf16 v[42:45], v[38:41], v[230:233], v[42:45]
	v_mfma_f32_16x16x32_bf16 v[42:45], v[160:163], v[234:237], v[42:45]
	v_mfma_f32_16x16x32_bf16 v[18:21], v[22:25], v[238:241], v[18:21]
	v_mfma_f32_16x16x32_bf16 v[18:21], v[34:37], v[242:245], v[18:21]
	v_mfma_f32_16x16x32_bf16 v[10:13], v[38:41], v[238:241], v[10:13]
	v_mfma_f32_16x16x32_bf16 v[10:13], v[160:163], v[242:245], v[10:13]
	s_setprio 0
	s_setprio 1
	v_mfma_f32_16x16x32_bf16 v[50:53], v[188:191], v[222:225], v[50:53]
	v_mfma_f32_16x16x32_bf16 v[30:33], v[180:183], v[230:233], v[30:33]
	v_mfma_f32_16x16x32_bf16 v[26:29], v[188:191], v[230:233], v[26:29]
	v_mfma_f32_16x16x32_bf16 v[6:9], v[180:183], v[238:241], v[6:9]
	v_mfma_f32_16x16x32_bf16 v[2:5], v[188:191], v[238:241], v[2:5]
	v_mfma_f32_16x16x32_bf16 v[22:25], v[180:183], v[196:199], v[70:73]
	v_mfma_f32_16x16x32_bf16 v[34:37], v[188:191], v[196:199], v[66:69]
	v_mfma_f32_16x16x32_bf16 v[38:41], v[180:183], v[222:225], v[54:57]
	v_mfma_f32_16x16x32_bf16 v[50:53], v[192:195], v[226:229], v[50:53]
	v_mfma_f32_16x16x32_bf16 v[30:33], v[184:187], v[234:237], v[30:33]
	v_mfma_f32_16x16x32_bf16 v[26:29], v[192:195], v[234:237], v[26:29]
	v_mfma_f32_16x16x32_bf16 v[6:9], v[184:187], v[242:245], v[6:9]
	v_mfma_f32_16x16x32_bf16 v[2:5], v[192:195], v[242:245], v[2:5]
	v_mfma_f32_16x16x32_bf16 v[22:25], v[184:187], v[200:203], v[22:25]
	s_setprio 2
	s_barrier
	v_mfma_f32_16x16x32_bf16 v[34:37], v[192:195], v[200:203], v[34:37]
	v_mfma_f32_16x16x32_bf16 v[38:41], v[184:187], v[226:229], v[38:41]
	s_setprio 0
	v_add_u32_e32 v160, s90, v99
	v_add_u32_e32 v192, s91, v99
	ds_read_b128 v[54:57], v160
	ds_read_b128 v[66:69], v160 offset:1024
	ds_read_b128 v[70:73], v160 offset:2048
	ds_read_b128 v[160:163], v160 offset:3072
	ds_read_b128 v[180:183], v192
	ds_read_b128 v[184:187], v192 offset:1024
	ds_read_b128 v[188:191], v192 offset:2048
	ds_read_b128 v[192:195], v192 offset:3072
	s_mov_b32 m0, s63
	v_lshl_add_u64 v[246:247], s[54:55], 0, v[148:149]
	ds_read_b128 v[196:199], v165 offset:32768
	ds_read_b128 v[200:203], v165 offset:33792
	ds_read_b128 v[222:225], v165 offset:34816
	ds_read_b128 v[226:229], v165 offset:35840
	ds_read_b128 v[230:233], v165 offset:36864
	ds_read_b128 v[234:237], v165 offset:37888
	ds_read_b128 v[238:241], v165 offset:38912
	ds_read_b128 v[242:245], v165 offset:39936
	global_load_lds_dwordx4 v[246:247], off
	v_lshl_add_u64 v[246:247], s[54:55], 0, v[152:153]
	s_mov_b32 m0, s69
	s_nop 0
	global_load_lds_dwordx4 v[246:247], off
	s_waitcnt vmcnt(8)
	s_waitcnt lgkmcnt(0)
	s_setprio 1
	s_barrier
	v_mfma_f32_16x16x32_bf16 v[144:147], v[54:57], v[196:199], v[144:147]
	v_mfma_f32_16x16x32_bf16 v[144:147], v[66:69], v[200:203], v[144:147]
	v_mfma_f32_16x16x32_bf16 v[140:143], v[70:73], v[196:199], v[140:143]
	v_mfma_f32_16x16x32_bf16 v[140:143], v[160:163], v[200:203], v[140:143]
	v_mfma_f32_16x16x32_bf16 v[128:131], v[54:57], v[222:225], v[128:131]
	v_mfma_f32_16x16x32_bf16 v[128:131], v[66:69], v[226:229], v[128:131]
	v_mfma_f32_16x16x32_bf16 v[124:127], v[70:73], v[222:225], v[124:127]
	v_mfma_f32_16x16x32_bf16 v[124:127], v[160:163], v[226:229], v[124:127]
	v_mfma_f32_16x16x32_bf16 v[112:115], v[54:57], v[230:233], v[112:115]
	v_mfma_f32_16x16x32_bf16 v[112:115], v[66:69], v[234:237], v[112:115]
	v_mfma_f32_16x16x32_bf16 v[108:111], v[70:73], v[230:233], v[108:111]
	v_mfma_f32_16x16x32_bf16 v[108:111], v[160:163], v[234:237], v[108:111]
	v_mfma_f32_16x16x32_bf16 v[94:97], v[54:57], v[238:241], v[94:97]
	v_mfma_f32_16x16x32_bf16 v[94:97], v[66:69], v[242:245], v[94:97]
	v_mfma_f32_16x16x32_bf16 v[90:93], v[70:73], v[238:241], v[90:93]
	v_mfma_f32_16x16x32_bf16 v[90:93], v[160:163], v[242:245], v[90:93]
	s_setprio 0
	s_setprio 1
	v_mfma_f32_16x16x32_bf16 v[136:139], v[180:183], v[196:199], v[136:139]
	v_mfma_f32_16x16x32_bf16 v[136:139], v[184:187], v[200:203], v[136:139]
	v_mfma_f32_16x16x32_bf16 v[132:135], v[188:191], v[196:199], v[132:135]
	v_mfma_f32_16x16x32_bf16 v[132:135], v[192:195], v[200:203], v[132:135]
	v_mfma_f32_16x16x32_bf16 v[120:123], v[180:183], v[222:225], v[120:123]
	v_mfma_f32_16x16x32_bf16 v[120:123], v[184:187], v[226:229], v[120:123]
	v_mfma_f32_16x16x32_bf16 v[116:119], v[188:191], v[222:225], v[116:119]
	v_mfma_f32_16x16x32_bf16 v[116:119], v[192:195], v[226:229], v[116:119]
	v_mfma_f32_16x16x32_bf16 v[104:107], v[180:183], v[230:233], v[104:107]
	v_mfma_f32_16x16x32_bf16 v[104:107], v[184:187], v[234:237], v[104:107]
	v_mfma_f32_16x16x32_bf16 v[100:103], v[188:191], v[230:233], v[100:103]
	v_mfma_f32_16x16x32_bf16 v[100:103], v[192:195], v[234:237], v[100:103]
	v_mfma_f32_16x16x32_bf16 v[86:89], v[180:183], v[238:241], v[86:89]
	v_mfma_f32_16x16x32_bf16 v[86:89], v[184:187], v[242:245], v[86:89]
	s_setprio 2
	s_barrier
; #define PG8_STAGE(bufoff, gbase, voff) do { _Pragma("unroll") for (int _i = 0; _i < 2; ++_i) \
;         __builtin_amdgcn_global_load_lds((const unsigned*)((const char*)(gbase) + (voff)[_i]), (PG8_LAS unsigned*)(lds + (bufoff) + ldsw + _i * 8192), 16, 0, AUX_A); } while (0)
; #define PG8_STAGEB(bufoff, gbase, voff) do { _Pragma("unroll") for (int _i = 0; _i < 2; ++_i) \
;         __builtin_amdgcn_global_load_lds((const unsigned*)((const char*)(gbase) + (voff)[_i]), (PG8_LAS unsigned*)(lds + (bufoff) + ldsw + _i * 8192), 16, 0, AUX_B); } while (0)
; #define PG8_LDA(dst, b, h) do { _Pragma("unroll") for (int m = 0; m < 4; ++m) _Pragma("unroll") for (int k = 0; k < 2; ++k) dst[m][k] = *(const PG8_LAS bf16x8*)(lds + PG8_SA(b, h) + aoff + m * 2048 + k * 1024); } while (0)
; #define PG8_MMA(ai, bj, At, Bt) do { __builtin_amdgcn_s_setprio(1); _Pragma("unroll") for (int m = 0; m < 4; ++m) _Pragma("unroll") for (int n = 0; n < 2; ++n) _Pragma("unroll") for (int k = 0; k < 2; ++k) \
;         acc[ai][bj][m][n] = __builtin_amdgcn_mfma_f32_16x16x32_bf16(Bt[n][k], At[m][k], acc[ai][bj][m][n], 0, 0, 0); __builtin_amdgcn_s_setprio(0); } while (0)
; #define PG8_WAIT_V(n) asm volatile("s_waitcnt vmcnt(" #n ")" ::: "memory")
; #define PG8_WAIT_L(n) asm volatile("s_waitcnt lgkmcnt(" #n ")" ::: "memory")
; #define PG8_BAR __builtin_amdgcn_s_barrier()
; #define PG8_SCHED __builtin_amdgcn_sched_barrier(0)
; template <class Epi, class Sched, bool ALIGN_EPI = false, bool SP2 = false>
; __device__ __forceinline__ void gemm_phase(PG8_LAS unsigned char* lds, const Gemm g, const Sched& S, const Epi& E) {
;     ...
;             PG8_LDA(At, 1, 1); PG8_STAGEB(PG8_SB(1, 0), b3, voffB); PG8_STAGEB(PG8_SB(1, 1), b3 + hstep, voffB); PG8_STAGE(PG8_SA(1, 0), a3, voffA);
;             PG8_WAIT_V(8); PG8_WAIT_L(0); PG8_BAR; PG8_MMA(1, 0, At, B0); PG8_MMA(1, 1, At, B1); PG8_BAR; PG8_SCHED;
	v_mfma_f32_16x16x32_bf16 v[82:85], v[188:191], v[238:241], v[82:85]
	v_mfma_f32_16x16x32_bf16 v[82:85], v[192:195], v[242:245], v[82:85]
	s_setprio 0
	s_mov_b32 m0, s1
	v_lshl_add_u64 v[166:167], v[166:167], 0, s[76:77]
	ds_read_b128 v[196:199], v165 offset:49152
	ds_read_b128 v[200:203], v165 offset:50176
	ds_read_b128 v[222:225], v165 offset:51200
	ds_read_b128 v[226:229], v165 offset:52224
	ds_read_b128 v[230:233], v165 offset:53248
	ds_read_b128 v[234:237], v165 offset:54272
	ds_read_b128 v[238:241], v165 offset:55296
	ds_read_b128 v[242:245], v165 offset:56320
	global_load_lds_dwordx4 v[166:167], off
	v_lshl_add_u64 v[166:167], v[168:169], 0, s[76:77]
	s_mov_b32 m0, s0
	s_nop 0
	global_load_lds_dwordx4 v[166:167], off
	v_lshl_add_u64 v[166:167], s[52:53], 0, v[150:151]
	s_mov_b32 m0, s47
	s_nop 0
	global_load_lds_dwordx4 v[166:167], off
	v_lshl_add_u64 v[166:167], s[52:53], 0, v[154:155]
	s_mov_b32 m0, s46
	s_nop 0
	global_load_lds_dwordx4 v[166:167], off
	v_lshl_add_u64 v[166:167], v[172:173], 0, s[76:77]
	s_mov_b32 m0, s70
	s_nop 0
	global_load_lds_dwordx4 v[166:167], off
	v_lshl_add_u64 v[166:167], v[212:213], 0, s[76:77]
	s_mov_b32 m0, s71
	s_nop 0
	global_load_lds_dwordx4 v[166:167], off
	s_waitcnt vmcnt(8)
	s_waitcnt lgkmcnt(0)
	s_setprio 1
	s_barrier
	v_mfma_f32_16x16x32_bf16 v[78:81], v[54:57], v[196:199], v[78:81]
	v_mfma_f32_16x16x32_bf16 v[78:81], v[66:69], v[200:203], v[78:81]
	v_mfma_f32_16x16x32_bf16 v[74:77], v[70:73], v[196:199], v[74:77]
	v_mfma_f32_16x16x32_bf16 v[74:77], v[160:163], v[200:203], v[74:77]
	v_mfma_f32_16x16x32_bf16 v[62:65], v[54:57], v[222:225], v[62:65]
	v_mfma_f32_16x16x32_bf16 v[62:65], v[66:69], v[226:229], v[62:65]
	v_mfma_f32_16x16x32_bf16 v[58:61], v[70:73], v[222:225], v[58:61]
	v_mfma_f32_16x16x32_bf16 v[58:61], v[160:163], v[226:229], v[58:61]
	v_mfma_f32_16x16x32_bf16 v[46:49], v[54:57], v[230:233], v[46:49]
	v_mfma_f32_16x16x32_bf16 v[46:49], v[66:69], v[234:237], v[46:49]
	v_mfma_f32_16x16x32_bf16 v[42:45], v[70:73], v[230:233], v[42:45]
	v_mfma_f32_16x16x32_bf16 v[42:45], v[160:163], v[234:237], v[42:45]
	v_mfma_f32_16x16x32_bf16 v[18:21], v[54:57], v[238:241], v[18:21]
	v_mfma_f32_16x16x32_bf16 v[18:21], v[66:69], v[242:245], v[18:21]
	v_mfma_f32_16x16x32_bf16 v[10:13], v[70:73], v[238:241], v[10:13]
	v_mfma_f32_16x16x32_bf16 v[10:13], v[160:163], v[242:245], v[10:13]
	s_setprio 0
	s_setprio 1
	v_mfma_f32_16x16x32_bf16 v[22:25], v[180:183], v[196:199], v[22:25]
	v_mfma_f32_16x16x32_bf16 v[70:73], v[184:187], v[200:203], v[22:25]
	v_mfma_f32_16x16x32_bf16 v[22:25], v[188:191], v[196:199], v[34:37]
	v_mfma_f32_16x16x32_bf16 v[66:69], v[192:195], v[200:203], v[22:25]
	v_mfma_f32_16x16x32_bf16 v[22:25], v[180:183], v[222:225], v[38:41]
	v_mfma_f32_16x16x32_bf16 v[54:57], v[184:187], v[226:229], v[22:25]
	v_mfma_f32_16x16x32_bf16 v[22:25], v[188:191], v[222:225], v[50:53]
	v_mfma_f32_16x16x32_bf16 v[50:53], v[192:195], v[226:229], v[22:25]
	v_mfma_f32_16x16x32_bf16 v[22:25], v[180:183], v[230:233], v[30:33]
	v_mfma_f32_16x16x32_bf16 v[30:33], v[184:187], v[234:237], v[22:25]
	v_mfma_f32_16x16x32_bf16 v[22:25], v[188:191], v[230:233], v[26:29]
	v_mfma_f32_16x16x32_bf16 v[6:9], v[180:183], v[238:241], v[6:9]
	v_mfma_f32_16x16x32_bf16 v[2:5], v[188:191], v[238:241], v[2:5]
	v_mfma_f32_16x16x32_bf16 v[26:29], v[192:195], v[234:237], v[22:25]
	s_setprio 2
	s_cbranch_scc0 .Lq4b_936l
	v_cmp_ne_u32_e64 vcc, s12, 0
	s_cbranch_vccz .Lq4s_936l

; #define GAS __attribute__((address_space(1)))
; __device__ __forceinline__ u32x4 pack8(f32x4 v0, f32x4 v1) { u32x4 w; w.x = cvt_pk_bf16(v0[0], v0[1]); w.y = cvt_pk_bf16(v0[2], v0[3]); w.z = cvt_pk_bf16(v1[0], v1[1]); w.w = cvt_pk_bf16(v1[2], v1[3]); return w; }
; __device__ __forceinline__ void unpack8(u32x4 w, f32x4& v0, f32x4& v1) { v0 = (f32x4){bflo(w.x), bfhi(w.x), bflo(w.y), bfhi(w.y)}; v1 = (f32x4){bflo(w.z), bfhi(w.z), bflo(w.w), bfhi(w.w)}; }
; #define PG8_BAR __builtin_amdgcn_s_barrier()
; #define GAS __attribute__((address_space(1)))
;     __device__ __forceinline__ void operator()(const f32x4 (&acc)[2][2][4][2], const Unit& u, int wr, int wc, int fr, int fq) const {
;         const int row0 = u.pm * BM + wr * 64 + fr, col0 = u.pn * BM + wc * 32 + 8 * fq;
;         f32x4 bv[2][2];
; #pragma unroll
;         for (int bj = 0; bj < 2; ++bj)
; #pragma unroll
;             for (int n = 0; n < 2; ++n) bv[bj][n] = *(const f32x4*)(bglu + col0 + bj * HALF + 4 * n);
;         const bf16_t* const zb = Z + (size_t)row0 * 1024 + col0; bf16_t* const sob = SO + (size_t)row0 * 1024 + col0;
; #pragma unroll
;         for (int ai = 0; ai < 2; ++ai)
; #pragma unroll
;             for (int m = 0; m < 4; ++m) { const size_t off = (size_t)(ai * HALF + m * 16) * 1024;
; #pragma unroll
;                 for (int bj = 0; bj < 2; ++bj) { f32x4 z0, z1; unpack8(*(const GAS u32x4*)(zb + off + bj * HALF), z0, z1);
;                     const f32x4 v0 = z0 * sigmoid4(acc[ai][bj][m][0] + bv[bj][0]), v1 = z1 * sigmoid4(acc[ai][bj][m][1] + bv[bj][1]);
;                     *(GAS u32x4*)(sob + off + bj * HALF) = pack8(v0, v1); } }
; template <class Epi, class Sched, bool ALIGN_EPI = false, bool SP2 = false>
; __device__ __forceinline__ void gemm_phase(PG8_LAS unsigned char* lds, const Gemm g, const Sched& S, const Epi& E) {
;     ...
;         if constexpr (ALIGN_EPI) { if (wr == 0) PG8_BAR; }
.Lq4s_936l:
	v_mfma_f32_16x16x32_bf16 v[6:9], v[184:187], v[242:245], v[6:9]
	v_mfma_f32_16x16x32_bf16 v[2:5], v[192:195], v[242:245], v[2:5]
	s_setprio 0
	v_lshl_add_u64 v[14:15], v[14:15], 0, s[86:87]
	v_lshl_add_u64 v[16:17], v[16:17], 0, s[86:87]
	s_mov_b32 s29, s81
	s_cbranch_scc0 .LBB0_936
.Lpx_936:
	s_and_b64 vcc, exec, s[12:13]
	s_cbranch_vccz .LBB0_939
.LBB0_939:
	v_lshl_or_b32 v160, s24, 8, v164
	v_ashrrev_i32_e32 v161, 31, v160
	v_lshl_add_u64 v[22:23], v[160:161], 2, s[8:9]
	global_load_dwordx4 v[34:37], v[22:23], off offset:16
	global_load_dwordx4 v[38:41], v[22:23], off
	global_load_dwordx4 v[14:17], v[22:23], off offset:528
	s_nop 0
	global_load_dwordx4 v[22:25], v[22:23], off offset:512
	v_lshl_add_u32 v162, s42, 8, v1
	v_ashrrev_i32_e32 v163, 31, v162
	v_lshlrev_b64 v[166:167], 11, v[162:163]
	v_lshl_add_u64 v[162:163], s[4:5], 0, v[166:167]
	v_lshlrev_b64 v[160:161], 1, v[160:161]
	v_lshl_add_u64 v[162:163], v[162:163], 0, v[160:161]
	global_load_dwordx4 v[180:183], v[162:163], off
	v_lshl_add_u64 v[166:167], s[10:11], 0, v[166:167]
	v_lshl_add_u64 v[160:161], v[166:167], 0, v[160:161]
	v_readlane_b32 s90, v254, 50
	s_mov_b64 s[42:43], -1
	v_readlane_b32 s91, v254, 51
	s_waitcnt vmcnt(0)
	v_pk_add_f32 v[142:143], v[142:143], v[36:37]
	v_pk_add_f32 v[146:147], v[146:147], v[40:41]
	v_pk_add_f32 v[144:145], v[144:145], v[38:39]
	v_pk_add_f32 v[140:141], v[140:141], v[34:35]
	v_pk_mul_f32 v[144:145], v[144:145], s[74:75] op_sel_hi:[1,0]
	v_pk_mul_f32 v[146:147], v[146:147], s[74:75] op_sel_hi:[1,0]
	v_pk_mul_f32 v[140:141], v[140:141], s[74:75] op_sel_hi:[1,0]
	v_pk_mul_f32 v[142:143], v[142:143], s[74:75] op_sel_hi:[1,0]
	v_exp_f32_e32 v144, v144
	v_exp_f32_e32 v145, v145
	v_exp_f32_e32 v146, v146
	v_exp_f32_e32 v147, v147
	v_exp_f32_e32 v140, v140
	v_exp_f32_e32 v141, v141
	v_exp_f32_e32 v142, v142
	v_exp_f32_e32 v143, v143
	v_pk_add_f32 v[144:145], v[144:145], 1.0 op_sel_hi:[1,0]
	v_pk_add_f32 v[146:147], v[146:147], 1.0 op_sel_hi:[1,0]
	v_pk_add_f32 v[140:141], v[140:141], 1.0 op_sel_hi:[1,0]
	v_pk_add_f32 v[142:143], v[142:143], 1.0 op_sel_hi:[1,0]
	v_rcp_f32_e32 v144, v144
	v_rcp_f32_e32 v145, v145
	v_rcp_f32_e32 v146, v146
	v_rcp_f32_e32 v147, v147
	v_rcp_f32_e32 v140, v140
	v_rcp_f32_e32 v141, v141
	v_rcp_f32_e32 v142, v142
	v_rcp_f32_e32 v143, v143
	v_lshlrev_b32_e32 v166, 16, v180
	v_and_b32_e32 v167, 0xffff0000, v180
	v_lshlrev_b32_e32 v168, 16, v181
	v_and_b32_e32 v169, 0xffff0000, v181
	v_lshlrev_b32_e32 v172, 16, v182
	v_and_b32_e32 v173, 0xffff0000, v182
	v_lshlrev_b32_e32 v180, 16, v183
	v_and_b32_e32 v181, 0xffff0000, v183
	v_pk_mul_f32 v[146:147], v[146:147], v[168:169]
	v_pk_mul_f32 v[144:145], v[144:145], v[166:167]
	v_pk_mul_f32 v[166:167], v[142:143], v[180:181]
	v_pk_mul_f32 v[142:143], v[140:141], v[172:173]
	v_cvt_pk_bf16_f32 v140, v144, v145
	v_cvt_pk_bf16_f32 v141, v146, v147
	v_cvt_pk_bf16_f32 v142, v142, v143
	v_cvt_pk_bf16_f32 v143, v166, v167
	global_store_dwordx4 v[160:161], v[140:143], off
	global_load_dwordx4 v[140:143], v[162:163], off offset:256
	v_pk_add_f32 v[138:139], v[138:139], v[24:25]
	v_pk_add_f32 v[136:137], v[136:137], v[22:23]
	v_pk_add_f32 v[134:135], v[134:135], v[16:17]
	v_pk_add_f32 v[132:133], v[132:133], v[14:15]
	v_pk_mul_f32 v[136:137], v[136:137], s[74:75] op_sel_hi:[1,0]
	v_pk_mul_f32 v[138:139], v[138:139], s[74:75] op_sel_hi:[1,0]
	v_pk_mul_f32 v[132:133], v[132:133], s[74:75] op_sel_hi:[1,0]
	v_pk_mul_f32 v[134:135], v[134:135], s[74:75] op_sel_hi:[1,0]
	v_exp_f32_e32 v136, v136
	v_exp_f32_e32 v137, v137
	v_exp_f32_e32 v138, v138
	v_exp_f32_e32 v139, v139
	v_exp_f32_e32 v132, v132
	v_exp_f32_e32 v133, v133
	v_exp_f32_e32 v134, v134
	v_exp_f32_e32 v135, v135
	v_pk_add_f32 v[136:137], v[136:137], 1.0 op_sel_hi:[1,0]
	v_pk_add_f32 v[138:139], v[138:139], 1.0 op_sel_hi:[1,0]
	v_pk_add_f32 v[132:133], v[132:133], 1.0 op_sel_hi:[1,0]
	v_pk_add_f32 v[134:135], v[134:135], 1.0 op_sel_hi:[1,0]
	v_rcp_f32_e32 v136, v136
	v_rcp_f32_e32 v137, v137
	v_rcp_f32_e32 v138, v138
	v_rcp_f32_e32 v139, v139
	v_rcp_f32_e32 v132, v132
	v_rcp_f32_e32 v133, v133
	v_rcp_f32_e32 v134, v134
	v_rcp_f32_e32 v135, v135
	v_pk_add_f32 v[128:129], v[128:129], v[38:39]
	v_pk_add_f32 v[124:125], v[124:125], v[34:35]
	v_pk_add_f32 v[130:131], v[130:131], v[40:41]
	v_pk_mul_f32 v[128:129], v[128:129], s[74:75] op_sel_hi:[1,0]
	v_pk_add_f32 v[126:127], v[126:127], v[36:37]
	v_pk_mul_f32 v[124:125], v[124:125], s[74:75] op_sel_hi:[1,0]
	v_pk_mul_f32 v[130:131], v[130:131], s[74:75] op_sel_hi:[1,0]
	v_exp_f32_e32 v128, v128
	v_exp_f32_e32 v129, v129
	v_pk_mul_f32 v[126:127], v[126:127], s[74:75] op_sel_hi:[1,0]
	v_exp_f32_e32 v124, v124
	v_exp_f32_e32 v125, v125
	v_exp_f32_e32 v130, v130
	v_exp_f32_e32 v131, v131
	v_exp_f32_e32 v126, v126
	v_exp_f32_e32 v127, v127
	v_pk_add_f32 v[128:129], v[128:129], 1.0 op_sel_hi:[1,0]
	v_pk_add_f32 v[124:125], v[124:125], 1.0 op_sel_hi:[1,0]
	v_pk_add_f32 v[130:131], v[130:131], 1.0 op_sel_hi:[1,0]
	v_rcp_f32_e32 v128, v128
	v_rcp_f32_e32 v129, v129
	v_pk_add_f32 v[126:127], v[126:127], 1.0 op_sel_hi:[1,0]
	v_rcp_f32_e32 v124, v124
	v_rcp_f32_e32 v125, v125
	v_rcp_f32_e32 v130, v130
	v_rcp_f32_e32 v131, v131
	v_rcp_f32_e32 v126, v126
	v_rcp_f32_e32 v127, v127
	v_pk_add_f32 v[122:123], v[122:123], v[24:25]
	v_pk_add_f32 v[120:121], v[120:121], v[22:23]
	v_pk_add_f32 v[118:119], v[118:119], v[16:17]
	v_pk_add_f32 v[116:117], v[116:117], v[14:15]
	v_pk_mul_f32 v[120:121], v[120:121], s[74:75] op_sel_hi:[1,0]
	v_pk_mul_f32 v[122:123], v[122:123], s[74:75] op_sel_hi:[1,0]
	v_pk_mul_f32 v[116:117], v[116:117], s[74:75] op_sel_hi:[1,0]
	v_pk_mul_f32 v[118:119], v[118:119], s[74:75] op_sel_hi:[1,0]
	v_exp_f32_e32 v120, v120
	v_exp_f32_e32 v121, v121
	v_exp_f32_e32 v122, v122
	v_exp_f32_e32 v123, v123
	v_exp_f32_e32 v116, v116
	v_exp_f32_e32 v117, v117
	v_exp_f32_e32 v118, v118
	v_exp_f32_e32 v119, v119
	v_pk_add_f32 v[120:121], v[120:121], 1.0 op_sel_hi:[1,0]
	v_pk_add_f32 v[122:123], v[122:123], 1.0 op_sel_hi:[1,0]
	v_pk_add_f32 v[116:117], v[116:117], 1.0 op_sel_hi:[1,0]
	v_pk_add_f32 v[118:119], v[118:119], 1.0 op_sel_hi:[1,0]
	v_rcp_f32_e32 v120, v120
	v_rcp_f32_e32 v121, v121
	v_rcp_f32_e32 v122, v122
	s_waitcnt vmcnt(0)
; #define GAS __attribute__((address_space(1)))
; __device__ __forceinline__ u32x4 pack8(f32x4 v0, f32x4 v1) { u32x4 w; w.x = cvt_pk_bf16(v0[0], v0[1]); w.y = cvt_pk_bf16(v0[2], v0[3]); w.z = cvt_pk_bf16(v1[0], v1[1]); w.w = cvt_pk_bf16(v1[2], v1[3]); return w; }
; __device__ __forceinline__ void unpack8(u32x4 w, f32x4& v0, f32x4& v1) { v0 = (f32x4){bflo(w.x), bfhi(w.x), bflo(w.y), bfhi(w.y)}; v1 = (f32x4){bflo(w.z), bfhi(w.z), bflo(w.w), bfhi(w.w)}; }
; #define GAS __attribute__((address_space(1)))
;     __device__ __forceinline__ void operator()(const f32x4 (&acc)[2][2][4][2], const Unit& u, int wr, int wc, int fr, int fq) const {
;     ...
;         for (int ai = 0; ai < 2; ++ai)
; #pragma unroll
;             for (int m = 0; m < 4; ++m) { const size_t off = (size_t)(ai * HALF + m * 16) * 1024;
; #pragma unroll
;                 for (int bj = 0; bj < 2; ++bj) { f32x4 z0, z1; unpack8(*(const GAS u32x4*)(zb + off + bj * HALF), z0, z1);
;                     const f32x4 v0 = z0 * sigmoid4(acc[ai][bj][m][0] + bv[bj][0]), v1 = z1 * sigmoid4(acc[ai][bj][m][1] + bv[bj][1]);
;                     *(GAS u32x4*)(sob + off + bj * HALF) = pack8(v0, v1); } }
	v_lshlrev_b32_e32 v144, 16, v140
	v_and_b32_e32 v145, 0xffff0000, v140
	v_lshlrev_b32_e32 v140, 16, v141
	v_and_b32_e32 v141, 0xffff0000, v141
	v_lshlrev_b32_e32 v146, 16, v142
	v_and_b32_e32 v147, 0xffff0000, v142
	v_lshlrev_b32_e32 v142, 16, v143
	v_and_b32_e32 v143, 0xffff0000, v143
	v_pk_mul_f32 v[138:139], v[138:139], v[140:141]
	v_pk_mul_f32 v[136:137], v[136:137], v[144:145]
	v_pk_mul_f32 v[140:141], v[134:135], v[142:143]
	v_pk_mul_f32 v[134:135], v[132:133], v[146:147]
	v_cvt_pk_bf16_f32 v132, v136, v137
	v_cvt_pk_bf16_f32 v133, v138, v139
	v_cvt_pk_bf16_f32 v134, v134, v135
	v_cvt_pk_bf16_f32 v135, v140, v141
	global_store_dwordx4 v[160:161], v[132:135], off offset:256
	v_rcp_f32_e32 v123, v123
	v_rcp_f32_e32 v116, v116
	v_add_co_u32_e32 v132, vcc, s94, v162
	v_rcp_f32_e32 v117, v117
	s_nop 0
	v_addc_co_u32_e32 v133, vcc, 0, v163, vcc
	global_load_dwordx4 v[134:137], v[132:133], off
	v_rcp_f32_e32 v118, v118
	v_rcp_f32_e32 v119, v119
	v_pk_add_f32 v[112:113], v[112:113], v[38:39]
	v_pk_add_f32 v[108:109], v[108:109], v[34:35]
	v_pk_add_f32 v[114:115], v[114:115], v[40:41]
	v_pk_mul_f32 v[112:113], v[112:113], s[74:75] op_sel_hi:[1,0]
	v_pk_add_f32 v[110:111], v[110:111], v[36:37]
	v_pk_mul_f32 v[108:109], v[108:109], s[74:75] op_sel_hi:[1,0]
	v_pk_mul_f32 v[114:115], v[114:115], s[74:75] op_sel_hi:[1,0]
	v_exp_f32_e32 v112, v112
	v_exp_f32_e32 v113, v113
	v_pk_mul_f32 v[110:111], v[110:111], s[74:75] op_sel_hi:[1,0]
	v_exp_f32_e32 v108, v108
	v_exp_f32_e32 v109, v109
	v_exp_f32_e32 v114, v114
	v_exp_f32_e32 v115, v115
	v_exp_f32_e32 v110, v110
	v_exp_f32_e32 v111, v111
	v_pk_add_f32 v[112:113], v[112:113], 1.0 op_sel_hi:[1,0]
	v_pk_add_f32 v[108:109], v[108:109], 1.0 op_sel_hi:[1,0]
	v_pk_add_f32 v[114:115], v[114:115], 1.0 op_sel_hi:[1,0]
	v_rcp_f32_e32 v112, v112
	v_rcp_f32_e32 v113, v113
	v_pk_add_f32 v[110:111], v[110:111], 1.0 op_sel_hi:[1,0]
	v_rcp_f32_e32 v108, v108
	v_rcp_f32_e32 v109, v109
	v_rcp_f32_e32 v114, v114
	v_rcp_f32_e32 v115, v115
	v_rcp_f32_e32 v110, v110
	v_rcp_f32_e32 v111, v111
	v_pk_add_f32 v[106:107], v[106:107], v[24:25]
	v_pk_add_f32 v[104:105], v[104:105], v[22:23]
	v_pk_add_f32 v[102:103], v[102:103], v[16:17]
	v_pk_add_f32 v[100:101], v[100:101], v[14:15]
	v_pk_mul_f32 v[104:105], v[104:105], s[74:75] op_sel_hi:[1,0]
	v_pk_mul_f32 v[106:107], v[106:107], s[74:75] op_sel_hi:[1,0]
	v_pk_mul_f32 v[100:101], v[100:101], s[74:75] op_sel_hi:[1,0]
	v_pk_mul_f32 v[102:103], v[102:103], s[74:75] op_sel_hi:[1,0]
	v_exp_f32_e32 v104, v104
	v_exp_f32_e32 v105, v105
	v_exp_f32_e32 v106, v106
	v_exp_f32_e32 v107, v107
	v_exp_f32_e32 v100, v100
	v_exp_f32_e32 v101, v101
	v_exp_f32_e32 v102, v102
	v_exp_f32_e32 v103, v103
	v_pk_add_f32 v[104:105], v[104:105], 1.0 op_sel_hi:[1,0]
	v_pk_add_f32 v[106:107], v[106:107], 1.0 op_sel_hi:[1,0]
	v_pk_add_f32 v[100:101], v[100:101], 1.0 op_sel_hi:[1,0]
	v_pk_add_f32 v[102:103], v[102:103], 1.0 op_sel_hi:[1,0]
	v_rcp_f32_e32 v104, v104
	v_rcp_f32_e32 v105, v105
	v_rcp_f32_e32 v106, v106
	v_rcp_f32_e32 v107, v107
	v_rcp_f32_e32 v100, v100
	v_rcp_f32_e32 v101, v101
	v_rcp_f32_e32 v102, v102
	v_rcp_f32_e32 v103, v103
	v_pk_add_f32 v[94:95], v[94:95], v[38:39]
	v_pk_add_f32 v[90:91], v[90:91], v[34:35]
	v_pk_add_f32 v[96:97], v[96:97], v[40:41]
	v_pk_mul_f32 v[94:95], v[94:95], s[74:75] op_sel_hi:[1,0]
	v_pk_add_f32 v[92:93], v[92:93], v[36:37]
	v_pk_mul_f32 v[90:91], v[90:91], s[74:75] op_sel_hi:[1,0]
	v_pk_mul_f32 v[96:97], v[96:97], s[74:75] op_sel_hi:[1,0]
	v_exp_f32_e32 v94, v94
	v_exp_f32_e32 v95, v95
	v_pk_mul_f32 v[92:93], v[92:93], s[74:75] op_sel_hi:[1,0]
	v_exp_f32_e32 v90, v90
	v_exp_f32_e32 v91, v91
	v_exp_f32_e32 v96, v96
	v_exp_f32_e32 v97, v97
	v_exp_f32_e32 v92, v92
	v_exp_f32_e32 v93, v93
	v_pk_add_f32 v[94:95], v[94:95], 1.0 op_sel_hi:[1,0]
	v_pk_add_f32 v[90:91], v[90:91], 1.0 op_sel_hi:[1,0]
	v_pk_add_f32 v[96:97], v[96:97], 1.0 op_sel_hi:[1,0]
	v_rcp_f32_e32 v94, v94
	v_rcp_f32_e32 v95, v95
	s_waitcnt vmcnt(0)
	v_lshlrev_b32_e32 v138, 16, v134
	v_and_b32_e32 v139, 0xffff0000, v134
	v_lshlrev_b32_e32 v140, 16, v136
	v_and_b32_e32 v141, 0xffff0000, v136
	v_lshlrev_b32_e32 v134, 16, v135
	v_and_b32_e32 v135, 0xffff0000, v135
	v_lshlrev_b32_e32 v136, 16, v137
	v_and_b32_e32 v137, 0xffff0000, v137
	v_pk_mul_f32 v[128:129], v[128:129], v[138:139]
	v_pk_mul_f32 v[124:125], v[124:125], v[140:141]
	v_pk_mul_f32 v[130:131], v[130:131], v[134:135]
	v_pk_mul_f32 v[134:135], v[126:127], v[136:137]
	v_cvt_pk_bf16_f32 v126, v128, v129
	v_cvt_pk_bf16_f32 v128, v124, v125
	v_add_co_u32_e32 v124, vcc, s94, v160
	v_cvt_pk_bf16_f32 v127, v130, v131
	v_cvt_pk_bf16_f32 v129, v134, v135
	v_addc_co_u32_e32 v125, vcc, 0, v161, vcc
	global_store_dwordx4 v[124:125], v[126:129], off
	global_load_dwordx4 v[126:129], v[132:133], off offset:256
	v_pk_add_f32 v[92:93], v[92:93], 1.0 op_sel_hi:[1,0]
	v_rcp_f32_e32 v90, v90
	v_rcp_f32_e32 v91, v91
	v_rcp_f32_e32 v96, v96
	v_rcp_f32_e32 v97, v97
	v_rcp_f32_e32 v92, v92
	v_rcp_f32_e32 v93, v93
	v_pk_add_f32 v[88:89], v[88:89], v[24:25]
	v_pk_add_f32 v[86:87], v[86:87], v[22:23]
	v_pk_add_f32 v[84:85], v[84:85], v[16:17]
	v_pk_add_f32 v[82:83], v[82:83], v[14:15]
	v_pk_mul_f32 v[86:87], v[86:87], s[74:75] op_sel_hi:[1,0]
	v_pk_mul_f32 v[88:89], v[88:89], s[74:75] op_sel_hi:[1,0]
	v_pk_mul_f32 v[82:83], v[82:83], s[74:75] op_sel_hi:[1,0]
	v_pk_mul_f32 v[84:85], v[84:85], s[74:75] op_sel_hi:[1,0]
	v_exp_f32_e32 v86, v86
	v_exp_f32_e32 v87, v87
	v_exp_f32_e32 v88, v88
	v_exp_f32_e32 v89, v89
	v_exp_f32_e32 v82, v82
	v_exp_f32_e32 v83, v83
	v_exp_f32_e32 v84, v84
	v_exp_f32_e32 v85, v85
	v_pk_add_f32 v[86:87], v[86:87], 1.0 op_sel_hi:[1,0]
; #define GAS __attribute__((address_space(1)))
; __device__ __forceinline__ u32x4 pack8(f32x4 v0, f32x4 v1) { u32x4 w; w.x = cvt_pk_bf16(v0[0], v0[1]); w.y = cvt_pk_bf16(v0[2], v0[3]); w.z = cvt_pk_bf16(v1[0], v1[1]); w.w = cvt_pk_bf16(v1[2], v1[3]); return w; }
; __device__ __forceinline__ void unpack8(u32x4 w, f32x4& v0, f32x4& v1) { v0 = (f32x4){bflo(w.x), bfhi(w.x), bflo(w.y), bfhi(w.y)}; v1 = (f32x4){bflo(w.z), bfhi(w.z), bflo(w.w), bfhi(w.w)}; }
; #define GAS __attribute__((address_space(1)))
;     __device__ __forceinline__ void operator()(const f32x4 (&acc)[2][2][4][2], const Unit& u, int wr, int wc, int fr, int fq) const {
;     ...
;         for (int ai = 0; ai < 2; ++ai)
; #pragma unroll
;             for (int m = 0; m < 4; ++m) { const size_t off = (size_t)(ai * HALF + m * 16) * 1024;
; #pragma unroll
;                 for (int bj = 0; bj < 2; ++bj) { f32x4 z0, z1; unpack8(*(const GAS u32x4*)(zb + off + bj * HALF), z0, z1);
;                     const f32x4 v0 = z0 * sigmoid4(acc[ai][bj][m][0] + bv[bj][0]), v1 = z1 * sigmoid4(acc[ai][bj][m][1] + bv[bj][1]);
;                     *(GAS u32x4*)(sob + off + bj * HALF) = pack8(v0, v1); } }
	v_pk_add_f32 v[88:89], v[88:89], 1.0 op_sel_hi:[1,0]
	v_pk_add_f32 v[82:83], v[82:83], 1.0 op_sel_hi:[1,0]
	v_pk_add_f32 v[84:85], v[84:85], 1.0 op_sel_hi:[1,0]
	v_rcp_f32_e32 v86, v86
	v_rcp_f32_e32 v87, v87
	v_rcp_f32_e32 v88, v88
	v_rcp_f32_e32 v89, v89
	v_rcp_f32_e32 v82, v82
	v_rcp_f32_e32 v83, v83
	v_rcp_f32_e32 v84, v84
	v_rcp_f32_e32 v85, v85
	v_pk_add_f32 v[78:79], v[78:79], v[38:39]
	v_pk_add_f32 v[74:75], v[74:75], v[34:35]
	v_pk_add_f32 v[80:81], v[80:81], v[40:41]
	v_pk_mul_f32 v[78:79], v[78:79], s[74:75] op_sel_hi:[1,0]
	v_pk_add_f32 v[76:77], v[76:77], v[36:37]
	v_pk_mul_f32 v[74:75], v[74:75], s[74:75] op_sel_hi:[1,0]
	v_pk_mul_f32 v[80:81], v[80:81], s[74:75] op_sel_hi:[1,0]
	v_exp_f32_e32 v78, v78
	v_exp_f32_e32 v79, v79
	v_pk_mul_f32 v[76:77], v[76:77], s[74:75] op_sel_hi:[1,0]
	v_exp_f32_e32 v74, v74
	v_exp_f32_e32 v75, v75
	v_exp_f32_e32 v80, v80
	v_exp_f32_e32 v81, v81
	v_exp_f32_e32 v76, v76
	v_exp_f32_e32 v77, v77
	v_pk_add_f32 v[78:79], v[78:79], 1.0 op_sel_hi:[1,0]
	v_pk_add_f32 v[74:75], v[74:75], 1.0 op_sel_hi:[1,0]
	v_pk_add_f32 v[80:81], v[80:81], 1.0 op_sel_hi:[1,0]
	v_rcp_f32_e32 v78, v78
	v_rcp_f32_e32 v79, v79
	v_pk_add_f32 v[76:77], v[76:77], 1.0 op_sel_hi:[1,0]
	v_rcp_f32_e32 v74, v74
	v_rcp_f32_e32 v75, v75
	v_rcp_f32_e32 v80, v80
	v_rcp_f32_e32 v81, v81
	v_rcp_f32_e32 v76, v76
	v_rcp_f32_e32 v77, v77
	v_pk_add_f32 v[72:73], v[72:73], v[24:25]
	v_pk_add_f32 v[70:71], v[70:71], v[22:23]
	v_pk_add_f32 v[68:69], v[68:69], v[16:17]
	v_pk_add_f32 v[66:67], v[66:67], v[14:15]
	v_pk_mul_f32 v[70:71], v[70:71], s[74:75] op_sel_hi:[1,0]
	v_pk_mul_f32 v[72:73], v[72:73], s[74:75] op_sel_hi:[1,0]
	v_pk_mul_f32 v[66:67], v[66:67], s[74:75] op_sel_hi:[1,0]
	v_pk_mul_f32 v[68:69], v[68:69], s[74:75] op_sel_hi:[1,0]
	v_exp_f32_e32 v70, v70
	v_exp_f32_e32 v71, v71
	v_exp_f32_e32 v72, v72
	v_exp_f32_e32 v73, v73
	v_exp_f32_e32 v66, v66
	v_exp_f32_e32 v67, v67
	v_exp_f32_e32 v68, v68
	v_exp_f32_e32 v69, v69
	s_waitcnt vmcnt(0)
	v_lshlrev_b32_e32 v130, 16, v126
	v_and_b32_e32 v131, 0xffff0000, v126
	v_lshlrev_b32_e32 v126, 16, v127
	v_and_b32_e32 v127, 0xffff0000, v127
	v_lshlrev_b32_e32 v132, 16, v128
	v_and_b32_e32 v133, 0xffff0000, v128
	v_lshlrev_b32_e32 v128, 16, v129
	v_and_b32_e32 v129, 0xffff0000, v129
	v_pk_mul_f32 v[122:123], v[122:123], v[126:127]
	v_pk_mul_f32 v[120:121], v[120:121], v[130:131]
	v_pk_mul_f32 v[126:127], v[118:119], v[128:129]
	v_pk_mul_f32 v[118:119], v[116:117], v[132:133]
	v_cvt_pk_bf16_f32 v116, v120, v121
	v_cvt_pk_bf16_f32 v117, v122, v123
	v_cvt_pk_bf16_f32 v118, v118, v119
	v_cvt_pk_bf16_f32 v119, v126, v127
	global_store_dwordx4 v[124:125], v[116:119], off offset:256
	v_pk_add_f32 v[70:71], v[70:71], 1.0 op_sel_hi:[1,0]
	v_pk_add_f32 v[72:73], v[72:73], 1.0 op_sel_hi:[1,0]
	v_add_co_u32_e32 v116, vcc, s73, v162
	v_pk_add_f32 v[66:67], v[66:67], 1.0 op_sel_hi:[1,0]
	s_nop 0
	v_addc_co_u32_e32 v117, vcc, 0, v163, vcc
	global_load_dwordx4 v[118:121], v[116:117], off
	v_pk_add_f32 v[68:69], v[68:69], 1.0 op_sel_hi:[1,0]
	v_rcp_f32_e32 v70, v70
	v_rcp_f32_e32 v71, v71
	v_rcp_f32_e32 v72, v72
	v_rcp_f32_e32 v73, v73
	v_rcp_f32_e32 v66, v66
	v_rcp_f32_e32 v67, v67
	v_rcp_f32_e32 v68, v68
	v_rcp_f32_e32 v69, v69
	v_pk_add_f32 v[62:63], v[62:63], v[38:39]
	v_pk_add_f32 v[58:59], v[58:59], v[34:35]
	v_pk_add_f32 v[64:65], v[64:65], v[40:41]
	v_pk_mul_f32 v[62:63], v[62:63], s[74:75] op_sel_hi:[1,0]
	v_pk_add_f32 v[60:61], v[60:61], v[36:37]
	v_pk_mul_f32 v[58:59], v[58:59], s[74:75] op_sel_hi:[1,0]
	v_pk_mul_f32 v[64:65], v[64:65], s[74:75] op_sel_hi:[1,0]
	v_exp_f32_e32 v62, v62
	v_exp_f32_e32 v63, v63
	v_pk_mul_f32 v[60:61], v[60:61], s[74:75] op_sel_hi:[1,0]
	v_exp_f32_e32 v58, v58
	v_exp_f32_e32 v59, v59
	v_exp_f32_e32 v64, v64
	v_exp_f32_e32 v65, v65
	v_exp_f32_e32 v60, v60
	v_exp_f32_e32 v61, v61
	v_pk_add_f32 v[62:63], v[62:63], 1.0 op_sel_hi:[1,0]
	v_pk_add_f32 v[58:59], v[58:59], 1.0 op_sel_hi:[1,0]
	v_pk_add_f32 v[64:65], v[64:65], 1.0 op_sel_hi:[1,0]
	v_rcp_f32_e32 v62, v62
	v_rcp_f32_e32 v63, v63
	v_pk_add_f32 v[60:61], v[60:61], 1.0 op_sel_hi:[1,0]
	v_rcp_f32_e32 v58, v58
	v_rcp_f32_e32 v59, v59
	v_rcp_f32_e32 v64, v64
	v_rcp_f32_e32 v65, v65
	v_rcp_f32_e32 v60, v60
	v_rcp_f32_e32 v61, v61
	v_pk_add_f32 v[56:57], v[56:57], v[24:25]
	v_pk_add_f32 v[54:55], v[54:55], v[22:23]
	v_pk_add_f32 v[52:53], v[52:53], v[16:17]
	v_pk_add_f32 v[50:51], v[50:51], v[14:15]
	v_pk_mul_f32 v[54:55], v[54:55], s[74:75] op_sel_hi:[1,0]
	v_pk_mul_f32 v[56:57], v[56:57], s[74:75] op_sel_hi:[1,0]
	v_pk_mul_f32 v[50:51], v[50:51], s[74:75] op_sel_hi:[1,0]
	v_pk_mul_f32 v[52:53], v[52:53], s[74:75] op_sel_hi:[1,0]
	v_exp_f32_e32 v54, v54
	v_exp_f32_e32 v55, v55
	v_exp_f32_e32 v56, v56
	v_exp_f32_e32 v57, v57
	v_exp_f32_e32 v50, v50
	v_exp_f32_e32 v51, v51
	v_exp_f32_e32 v52, v52
	v_exp_f32_e32 v53, v53
	v_pk_add_f32 v[54:55], v[54:55], 1.0 op_sel_hi:[1,0]
	v_pk_add_f32 v[56:57], v[56:57], 1.0 op_sel_hi:[1,0]
	v_pk_add_f32 v[50:51], v[50:51], 1.0 op_sel_hi:[1,0]
	v_pk_add_f32 v[52:53], v[52:53], 1.0 op_sel_hi:[1,0]
	v_rcp_f32_e32 v54, v54
	v_rcp_f32_e32 v55, v55
	v_rcp_f32_e32 v56, v56
	v_rcp_f32_e32 v57, v57
	v_rcp_f32_e32 v50, v50
	v_rcp_f32_e32 v51, v51
	v_rcp_f32_e32 v52, v52
	v_rcp_f32_e32 v53, v53
	v_pk_add_f32 v[46:47], v[46:47], v[38:39]
	v_pk_add_f32 v[42:43], v[42:43], v[34:35]
	v_pk_add_f32 v[48:49], v[48:49], v[40:41]
	v_pk_mul_f32 v[46:47], v[46:47], s[74:75] op_sel_hi:[1,0]
	v_pk_add_f32 v[44:45], v[44:45], v[36:37]
	v_pk_mul_f32 v[42:43], v[42:43], s[74:75] op_sel_hi:[1,0]
	v_pk_mul_f32 v[48:49], v[48:49], s[74:75] op_sel_hi:[1,0]
	v_exp_f32_e32 v46, v46
	v_exp_f32_e32 v47, v47
	v_pk_mul_f32 v[44:45], v[44:45], s[74:75] op_sel_hi:[1,0]
	v_exp_f32_e32 v42, v42
	v_exp_f32_e32 v43, v43
	v_exp_f32_e32 v48, v48
	v_exp_f32_e32 v49, v49
	s_waitcnt vmcnt(0)
; #define GAS __attribute__((address_space(1)))
; __device__ __forceinline__ u32x4 pack8(f32x4 v0, f32x4 v1) { u32x4 w; w.x = cvt_pk_bf16(v0[0], v0[1]); w.y = cvt_pk_bf16(v0[2], v0[3]); w.z = cvt_pk_bf16(v1[0], v1[1]); w.w = cvt_pk_bf16(v1[2], v1[3]); return w; }
; __device__ __forceinline__ void unpack8(u32x4 w, f32x4& v0, f32x4& v1) { v0 = (f32x4){bflo(w.x), bfhi(w.x), bflo(w.y), bfhi(w.y)}; v1 = (f32x4){bflo(w.z), bfhi(w.z), bflo(w.w), bfhi(w.w)}; }
; #define GAS __attribute__((address_space(1)))
;     __device__ __forceinline__ void operator()(const f32x4 (&acc)[2][2][4][2], const Unit& u, int wr, int wc, int fr, int fq) const {
;     ...
;         for (int ai = 0; ai < 2; ++ai)
; #pragma unroll
;             for (int m = 0; m < 4; ++m) { const size_t off = (size_t)(ai * HALF + m * 16) * 1024;
; #pragma unroll
;                 for (int bj = 0; bj < 2; ++bj) { f32x4 z0, z1; unpack8(*(const GAS u32x4*)(zb + off + bj * HALF), z0, z1);
;                     const f32x4 v0 = z0 * sigmoid4(acc[ai][bj][m][0] + bv[bj][0]), v1 = z1 * sigmoid4(acc[ai][bj][m][1] + bv[bj][1]);
;                     *(GAS u32x4*)(sob + off + bj * HALF) = pack8(v0, v1); } }
	v_lshlrev_b32_e32 v122, 16, v118
	v_and_b32_e32 v123, 0xffff0000, v118
	v_lshlrev_b32_e32 v124, 16, v120
	v_and_b32_e32 v125, 0xffff0000, v120
	v_lshlrev_b32_e32 v118, 16, v119
	v_and_b32_e32 v119, 0xffff0000, v119
	v_lshlrev_b32_e32 v120, 16, v121
	v_and_b32_e32 v121, 0xffff0000, v121
	v_pk_mul_f32 v[112:113], v[112:113], v[122:123]
	v_pk_mul_f32 v[108:109], v[108:109], v[124:125]
	v_pk_mul_f32 v[114:115], v[114:115], v[118:119]
	v_pk_mul_f32 v[118:119], v[110:111], v[120:121]
	v_cvt_pk_bf16_f32 v110, v112, v113
	v_cvt_pk_bf16_f32 v112, v108, v109
	v_add_co_u32_e32 v108, vcc, s73, v160
	v_cvt_pk_bf16_f32 v111, v114, v115
	v_cvt_pk_bf16_f32 v113, v118, v119
	v_addc_co_u32_e32 v109, vcc, 0, v161, vcc
	global_store_dwordx4 v[108:109], v[110:113], off
	global_load_dwordx4 v[110:113], v[116:117], off offset:256
	v_exp_f32_e32 v44, v44
	v_exp_f32_e32 v45, v45
	v_pk_add_f32 v[46:47], v[46:47], 1.0 op_sel_hi:[1,0]
	v_pk_add_f32 v[42:43], v[42:43], 1.0 op_sel_hi:[1,0]
	v_pk_add_f32 v[48:49], v[48:49], 1.0 op_sel_hi:[1,0]
	v_rcp_f32_e32 v46, v46
	v_rcp_f32_e32 v47, v47
	v_pk_add_f32 v[44:45], v[44:45], 1.0 op_sel_hi:[1,0]
	v_rcp_f32_e32 v42, v42
	v_rcp_f32_e32 v43, v43
	v_rcp_f32_e32 v48, v48
	v_rcp_f32_e32 v49, v49
	v_rcp_f32_e32 v44, v44
	v_rcp_f32_e32 v45, v45
	v_pk_add_f32 v[32:33], v[32:33], v[24:25]
	v_pk_add_f32 v[30:31], v[30:31], v[22:23]
	v_pk_add_f32 v[28:29], v[28:29], v[16:17]
	v_pk_add_f32 v[26:27], v[26:27], v[14:15]
	v_pk_mul_f32 v[30:31], v[30:31], s[74:75] op_sel_hi:[1,0]
	v_pk_mul_f32 v[32:33], v[32:33], s[74:75] op_sel_hi:[1,0]
	v_pk_mul_f32 v[26:27], v[26:27], s[74:75] op_sel_hi:[1,0]
	v_pk_mul_f32 v[28:29], v[28:29], s[74:75] op_sel_hi:[1,0]
	v_exp_f32_e32 v30, v30
	v_exp_f32_e32 v31, v31
	v_exp_f32_e32 v32, v32
	v_exp_f32_e32 v33, v33
	v_exp_f32_e32 v26, v26
	v_exp_f32_e32 v27, v27
	v_exp_f32_e32 v28, v28
	v_exp_f32_e32 v29, v29
	v_pk_add_f32 v[30:31], v[30:31], 1.0 op_sel_hi:[1,0]
	v_pk_add_f32 v[32:33], v[32:33], 1.0 op_sel_hi:[1,0]
	v_pk_add_f32 v[26:27], v[26:27], 1.0 op_sel_hi:[1,0]
	v_pk_add_f32 v[28:29], v[28:29], 1.0 op_sel_hi:[1,0]
	v_rcp_f32_e32 v30, v30
	v_rcp_f32_e32 v31, v31
	v_rcp_f32_e32 v32, v32
	v_rcp_f32_e32 v33, v33
	v_rcp_f32_e32 v26, v26
	v_rcp_f32_e32 v27, v27
	v_rcp_f32_e32 v28, v28
	v_rcp_f32_e32 v29, v29
	v_pk_add_f32 v[18:19], v[18:19], v[38:39]
	v_pk_add_f32 v[20:21], v[20:21], v[40:41]
	v_pk_mul_f32 v[18:19], v[18:19], s[74:75] op_sel_hi:[1,0]
	v_pk_add_f32 v[12:13], v[12:13], v[36:37]
	v_pk_add_f32 v[10:11], v[10:11], v[34:35]
	v_pk_mul_f32 v[20:21], v[20:21], s[74:75] op_sel_hi:[1,0]
	v_exp_f32_e32 v18, v18
	v_exp_f32_e32 v19, v19
	v_pk_mul_f32 v[10:11], v[10:11], s[74:75] op_sel_hi:[1,0]
	v_pk_mul_f32 v[12:13], v[12:13], s[74:75] op_sel_hi:[1,0]
	v_exp_f32_e32 v20, v20
	v_exp_f32_e32 v21, v21
	v_exp_f32_e32 v10, v10
	v_exp_f32_e32 v11, v11
	v_exp_f32_e32 v12, v12
	v_exp_f32_e32 v13, v13
	v_pk_add_f32 v[18:19], v[18:19], 1.0 op_sel_hi:[1,0]
	v_pk_add_f32 v[20:21], v[20:21], 1.0 op_sel_hi:[1,0]
	v_rcp_f32_e32 v18, v18
	v_rcp_f32_e32 v19, v19
	v_pk_add_f32 v[10:11], v[10:11], 1.0 op_sel_hi:[1,0]
	v_pk_add_f32 v[12:13], v[12:13], 1.0 op_sel_hi:[1,0]
	v_rcp_f32_e32 v20, v20
	v_rcp_f32_e32 v21, v21
	v_rcp_f32_e32 v10, v10
	v_rcp_f32_e32 v11, v11
	v_rcp_f32_e32 v12, v12
	v_rcp_f32_e32 v13, v13
	v_pk_add_f32 v[8:9], v[8:9], v[24:25]
	v_pk_add_f32 v[6:7], v[6:7], v[22:23]
	v_pk_add_f32 v[4:5], v[4:5], v[16:17]
	v_pk_add_f32 v[2:3], v[2:3], v[14:15]
	v_pk_mul_f32 v[6:7], v[6:7], s[74:75] op_sel_hi:[1,0]
	v_pk_mul_f32 v[8:9], v[8:9], s[74:75] op_sel_hi:[1,0]
	v_pk_mul_f32 v[2:3], v[2:3], s[74:75] op_sel_hi:[1,0]
	v_pk_mul_f32 v[4:5], v[4:5], s[74:75] op_sel_hi:[1,0]
	v_exp_f32_e32 v6, v6
	s_waitcnt vmcnt(0)
	v_lshlrev_b32_e32 v114, 16, v110
	v_and_b32_e32 v115, 0xffff0000, v110
	v_lshlrev_b32_e32 v110, 16, v111
	v_and_b32_e32 v111, 0xffff0000, v111
	v_lshlrev_b32_e32 v116, 16, v112
	v_and_b32_e32 v117, 0xffff0000, v112
	v_lshlrev_b32_e32 v112, 16, v113
	v_and_b32_e32 v113, 0xffff0000, v113
	v_pk_mul_f32 v[106:107], v[106:107], v[110:111]
	v_pk_mul_f32 v[104:105], v[104:105], v[114:115]
	v_pk_mul_f32 v[110:111], v[102:103], v[112:113]
	v_pk_mul_f32 v[102:103], v[100:101], v[116:117]
	v_cvt_pk_bf16_f32 v100, v104, v105
	v_cvt_pk_bf16_f32 v101, v106, v107
	v_cvt_pk_bf16_f32 v102, v102, v103
	v_cvt_pk_bf16_f32 v103, v110, v111
	global_store_dwordx4 v[108:109], v[100:103], off offset:256
	v_exp_f32_e32 v7, v7
	v_exp_f32_e32 v8, v8
	v_add_co_u32_e32 v100, vcc, s93, v162
	v_exp_f32_e32 v9, v9
	s_nop 0
	v_addc_co_u32_e32 v101, vcc, 0, v163, vcc
	global_load_dwordx4 v[102:105], v[100:101], off
	v_exp_f32_e32 v2, v2
	v_exp_f32_e32 v3, v3
	v_exp_f32_e32 v4, v4
	v_exp_f32_e32 v5, v5
	v_pk_add_f32 v[6:7], v[6:7], 1.0 op_sel_hi:[1,0]
	v_pk_add_f32 v[8:9], v[8:9], 1.0 op_sel_hi:[1,0]
	v_pk_add_f32 v[2:3], v[2:3], 1.0 op_sel_hi:[1,0]
	v_pk_add_f32 v[4:5], v[4:5], 1.0 op_sel_hi:[1,0]
	v_rcp_f32_e32 v6, v6
	v_rcp_f32_e32 v7, v7
	v_rcp_f32_e32 v8, v8
	v_rcp_f32_e32 v9, v9
	v_rcp_f32_e32 v2, v2
	v_rcp_f32_e32 v3, v3
	v_rcp_f32_e32 v4, v4
	v_rcp_f32_e32 v5, v5
	s_waitcnt vmcnt(0)
	v_lshlrev_b32_e32 v106, 16, v102
	v_and_b32_e32 v107, 0xffff0000, v102
	v_lshlrev_b32_e32 v108, 16, v104
	v_and_b32_e32 v109, 0xffff0000, v104
	v_lshlrev_b32_e32 v102, 16, v103
	v_and_b32_e32 v103, 0xffff0000, v103
	v_lshlrev_b32_e32 v104, 16, v105
	v_and_b32_e32 v105, 0xffff0000, v105
	v_pk_mul_f32 v[94:95], v[94:95], v[106:107]
	v_pk_mul_f32 v[90:91], v[90:91], v[108:109]
	v_pk_mul_f32 v[96:97], v[96:97], v[102:103]
	v_pk_mul_f32 v[102:103], v[92:93], v[104:105]
	v_cvt_pk_bf16_f32 v92, v94, v95
	v_cvt_pk_bf16_f32 v94, v90, v91
	v_add_co_u32_e32 v90, vcc, s93, v160
	v_cvt_pk_bf16_f32 v93, v96, v97
	v_cvt_pk_bf16_f32 v95, v102, v103
	v_addc_co_u32_e32 v91, vcc, 0, v161, vcc
	global_store_dwordx4 v[90:91], v[92:95], off
	global_load_dwordx4 v[92:95], v[100:101], off offset:256
	s_waitcnt vmcnt(0)
; #define GAS __attribute__((address_space(1)))
; __device__ __forceinline__ u32x4 pack8(f32x4 v0, f32x4 v1) { u32x4 w; w.x = cvt_pk_bf16(v0[0], v0[1]); w.y = cvt_pk_bf16(v0[2], v0[3]); w.z = cvt_pk_bf16(v1[0], v1[1]); w.w = cvt_pk_bf16(v1[2], v1[3]); return w; }
; __device__ __forceinline__ void unpack8(u32x4 w, f32x4& v0, f32x4& v1) { v0 = (f32x4){bflo(w.x), bfhi(w.x), bflo(w.y), bfhi(w.y)}; v1 = (f32x4){bflo(w.z), bfhi(w.z), bflo(w.w), bfhi(w.w)}; }
; #define GAS __attribute__((address_space(1)))
;     __device__ __forceinline__ void operator()(const f32x4 (&acc)[2][2][4][2], const Unit& u, int wr, int wc, int fr, int fq) const {
;     ...
;         for (int ai = 0; ai < 2; ++ai)
; #pragma unroll
;             for (int m = 0; m < 4; ++m) { const size_t off = (size_t)(ai * HALF + m * 16) * 1024;
; #pragma unroll
;                 for (int bj = 0; bj < 2; ++bj) { f32x4 z0, z1; unpack8(*(const GAS u32x4*)(zb + off + bj * HALF), z0, z1);
;                     const f32x4 v0 = z0 * sigmoid4(acc[ai][bj][m][0] + bv[bj][0]), v1 = z1 * sigmoid4(acc[ai][bj][m][1] + bv[bj][1]);
;                     *(GAS u32x4*)(sob + off + bj * HALF) = pack8(v0, v1); } }
	v_lshlrev_b32_e32 v96, 16, v92
	v_and_b32_e32 v97, 0xffff0000, v92
	v_lshlrev_b32_e32 v92, 16, v93
	v_and_b32_e32 v93, 0xffff0000, v93
	v_lshlrev_b32_e32 v100, 16, v94
	v_and_b32_e32 v101, 0xffff0000, v94
	v_lshlrev_b32_e32 v94, 16, v95
	v_and_b32_e32 v95, 0xffff0000, v95
	v_pk_mul_f32 v[88:89], v[88:89], v[92:93]
	v_pk_mul_f32 v[86:87], v[86:87], v[96:97]
	v_pk_mul_f32 v[92:93], v[84:85], v[94:95]
	v_pk_mul_f32 v[84:85], v[82:83], v[100:101]
	v_cvt_pk_bf16_f32 v82, v86, v87
	v_cvt_pk_bf16_f32 v83, v88, v89
	v_cvt_pk_bf16_f32 v84, v84, v85
	v_cvt_pk_bf16_f32 v85, v92, v93
	global_store_dwordx4 v[90:91], v[82:85], off offset:256
	s_nop 1
	v_add_co_u32_e32 v82, vcc, s49, v162
	s_nop 1
	v_addc_co_u32_e32 v83, vcc, 0, v163, vcc
	global_load_dwordx4 v[84:87], v[82:83], off
	s_waitcnt vmcnt(0)
	v_lshlrev_b32_e32 v88, 16, v84
	v_and_b32_e32 v89, 0xffff0000, v84
	v_lshlrev_b32_e32 v90, 16, v86
	v_and_b32_e32 v91, 0xffff0000, v86
	v_lshlrev_b32_e32 v84, 16, v85
	v_and_b32_e32 v85, 0xffff0000, v85
	v_lshlrev_b32_e32 v86, 16, v87
	v_and_b32_e32 v87, 0xffff0000, v87
	v_pk_mul_f32 v[78:79], v[78:79], v[88:89]
	v_pk_mul_f32 v[74:75], v[74:75], v[90:91]
	v_pk_mul_f32 v[80:81], v[80:81], v[84:85]
	v_pk_mul_f32 v[84:85], v[76:77], v[86:87]
	v_cvt_pk_bf16_f32 v76, v78, v79
	v_cvt_pk_bf16_f32 v78, v74, v75
	v_add_co_u32_e32 v74, vcc, s49, v160
	v_cvt_pk_bf16_f32 v77, v80, v81
	v_cvt_pk_bf16_f32 v79, v84, v85
	v_addc_co_u32_e32 v75, vcc, 0, v161, vcc
	global_store_dwordx4 v[74:75], v[76:79], off
	global_load_dwordx4 v[76:79], v[82:83], off offset:256
	s_waitcnt vmcnt(0)
	v_lshlrev_b32_e32 v80, 16, v76
	v_and_b32_e32 v81, 0xffff0000, v76
	v_lshlrev_b32_e32 v76, 16, v77
	v_and_b32_e32 v77, 0xffff0000, v77
	v_lshlrev_b32_e32 v82, 16, v78
	v_and_b32_e32 v83, 0xffff0000, v78
	v_lshlrev_b32_e32 v78, 16, v79
	v_and_b32_e32 v79, 0xffff0000, v79
	v_pk_mul_f32 v[72:73], v[72:73], v[76:77]
	v_pk_mul_f32 v[70:71], v[70:71], v[80:81]
	v_pk_mul_f32 v[76:77], v[68:69], v[78:79]
	v_pk_mul_f32 v[68:69], v[66:67], v[82:83]
	v_cvt_pk_bf16_f32 v66, v70, v71
	v_cvt_pk_bf16_f32 v67, v72, v73
	v_cvt_pk_bf16_f32 v68, v68, v69
	v_cvt_pk_bf16_f32 v69, v76, v77
	global_store_dwordx4 v[74:75], v[66:69], off offset:256
	s_nop 1
	v_add_co_u32_e32 v66, vcc, s50, v162
	s_nop 1
	v_addc_co_u32_e32 v67, vcc, 0, v163, vcc
	global_load_dwordx4 v[68:71], v[66:67], off
	s_waitcnt vmcnt(0)
	v_lshlrev_b32_e32 v72, 16, v68
	v_and_b32_e32 v73, 0xffff0000, v68
	v_lshlrev_b32_e32 v74, 16, v70
	v_and_b32_e32 v75, 0xffff0000, v70
	v_lshlrev_b32_e32 v68, 16, v69
	v_and_b32_e32 v69, 0xffff0000, v69
	v_lshlrev_b32_e32 v70, 16, v71
	v_and_b32_e32 v71, 0xffff0000, v71
	v_pk_mul_f32 v[62:63], v[62:63], v[72:73]
	v_pk_mul_f32 v[58:59], v[58:59], v[74:75]
	v_pk_mul_f32 v[64:65], v[64:65], v[68:69]
	v_pk_mul_f32 v[68:69], v[60:61], v[70:71]
	v_cvt_pk_bf16_f32 v60, v62, v63
	v_cvt_pk_bf16_f32 v62, v58, v59
	v_add_co_u32_e32 v58, vcc, s50, v160
	v_cvt_pk_bf16_f32 v61, v64, v65
	v_cvt_pk_bf16_f32 v63, v68, v69
	v_addc_co_u32_e32 v59, vcc, 0, v161, vcc
	global_store_dwordx4 v[58:59], v[60:63], off
	global_load_dwordx4 v[60:63], v[66:67], off offset:256
	s_waitcnt vmcnt(0)
	v_lshlrev_b32_e32 v64, 16, v60
	v_and_b32_e32 v65, 0xffff0000, v60
	v_lshlrev_b32_e32 v60, 16, v61
	v_and_b32_e32 v61, 0xffff0000, v61
	v_lshlrev_b32_e32 v66, 16, v62
	v_and_b32_e32 v67, 0xffff0000, v62
	v_lshlrev_b32_e32 v62, 16, v63
	v_and_b32_e32 v63, 0xffff0000, v63
	v_pk_mul_f32 v[56:57], v[56:57], v[60:61]
	v_pk_mul_f32 v[54:55], v[54:55], v[64:65]
	v_pk_mul_f32 v[60:61], v[52:53], v[62:63]
	v_pk_mul_f32 v[52:53], v[50:51], v[66:67]
	v_cvt_pk_bf16_f32 v50, v54, v55
	v_cvt_pk_bf16_f32 v51, v56, v57
	v_cvt_pk_bf16_f32 v52, v52, v53
	v_cvt_pk_bf16_f32 v53, v60, v61
	global_store_dwordx4 v[58:59], v[50:53], off offset:256
	s_nop 1
	v_add_co_u32_e32 v50, vcc, s51, v162
	s_nop 1
	v_addc_co_u32_e32 v51, vcc, 0, v163, vcc
	global_load_dwordx4 v[52:55], v[50:51], off
	s_waitcnt vmcnt(0)
	v_lshlrev_b32_e32 v56, 16, v52
	v_and_b32_e32 v57, 0xffff0000, v52
	v_lshlrev_b32_e32 v58, 16, v54
	v_and_b32_e32 v59, 0xffff0000, v54
	v_lshlrev_b32_e32 v52, 16, v53
	v_and_b32_e32 v53, 0xffff0000, v53
	v_lshlrev_b32_e32 v54, 16, v55
	v_and_b32_e32 v55, 0xffff0000, v55
	v_pk_mul_f32 v[46:47], v[46:47], v[56:57]
	v_pk_mul_f32 v[42:43], v[42:43], v[58:59]
	v_pk_mul_f32 v[48:49], v[48:49], v[52:53]
	v_pk_mul_f32 v[52:53], v[44:45], v[54:55]
	v_cvt_pk_bf16_f32 v44, v46, v47
	v_cvt_pk_bf16_f32 v46, v42, v43
	v_add_co_u32_e32 v42, vcc, s51, v160
	v_cvt_pk_bf16_f32 v45, v48, v49
	v_cvt_pk_bf16_f32 v47, v52, v53
	v_addc_co_u32_e32 v43, vcc, 0, v161, vcc
	global_store_dwordx4 v[42:43], v[44:47], off
	global_load_dwordx4 v[44:47], v[50:51], off offset:256
	s_waitcnt vmcnt(0)
	v_lshlrev_b32_e32 v48, 16, v44
	v_and_b32_e32 v49, 0xffff0000, v44
	v_lshlrev_b32_e32 v44, 16, v45
	v_and_b32_e32 v45, 0xffff0000, v45
	v_lshlrev_b32_e32 v50, 16, v46
	v_and_b32_e32 v51, 0xffff0000, v46
	v_lshlrev_b32_e32 v46, 16, v47
	v_and_b32_e32 v47, 0xffff0000, v47
	v_pk_mul_f32 v[32:33], v[32:33], v[44:45]
	v_pk_mul_f32 v[30:31], v[30:31], v[48:49]
	v_pk_mul_f32 v[44:45], v[28:29], v[46:47]
	v_pk_mul_f32 v[28:29], v[26:27], v[50:51]
	v_cvt_pk_bf16_f32 v26, v30, v31
	v_cvt_pk_bf16_f32 v27, v32, v33
	v_cvt_pk_bf16_f32 v28, v28, v29
	v_cvt_pk_bf16_f32 v29, v44, v45
	global_store_dwordx4 v[42:43], v[26:29], off offset:256
	s_nop 1
	v_add_co_u32_e32 v26, vcc, s66, v162
	s_nop 1
	v_addc_co_u32_e32 v27, vcc, 0, v163, vcc
	global_load_dwordx4 v[28:31], v[26:27], off
	s_waitcnt vmcnt(0)
	v_lshlrev_b32_e32 v32, 16, v28
	v_and_b32_e32 v33, 0xffff0000, v28
	v_lshlrev_b32_e32 v28, 16, v29
	v_and_b32_e32 v29, 0xffff0000, v29
	v_lshlrev_b32_e32 v42, 16, v30
	v_and_b32_e32 v43, 0xffff0000, v30
	v_lshlrev_b32_e32 v30, 16, v31
	v_and_b32_e32 v31, 0xffff0000, v31
	v_pk_mul_f32 v[18:19], v[18:19], v[32:33]
	v_pk_mul_f32 v[20:21], v[20:21], v[28:29]
	v_pk_mul_f32 v[28:29], v[12:13], v[30:31]
	v_pk_mul_f32 v[12:13], v[10:11], v[42:43]
	v_cvt_pk_bf16_f32 v10, v18, v19
	v_add_co_u32_e32 v18, vcc, s66, v160
	v_cvt_pk_bf16_f32 v11, v20, v21
	v_cvt_pk_bf16_f32 v12, v12, v13
	v_cvt_pk_bf16_f32 v13, v28, v29
	v_addc_co_u32_e32 v19, vcc, 0, v161, vcc
	global_store_dwordx4 v[18:19], v[10:13], off
	global_load_dwordx4 v[10:13], v[26:27], off offset:256
	s_andn2_b64 vcc, exec, s[18:19]
	s_waitcnt vmcnt(0)
	v_lshlrev_b32_e32 v20, 16, v10
	v_and_b32_e32 v21, 0xffff0000, v10
	v_lshlrev_b32_e32 v10, 16, v11
	v_and_b32_e32 v11, 0xffff0000, v11
	v_lshlrev_b32_e32 v26, 16, v12
	v_and_b32_e32 v27, 0xffff0000, v12
	v_lshlrev_b32_e32 v12, 16, v13
	v_and_b32_e32 v13, 0xffff0000, v13
	v_pk_mul_f32 v[8:9], v[8:9], v[10:11]
	v_pk_mul_f32 v[6:7], v[6:7], v[20:21]
	v_pk_mul_f32 v[10:11], v[4:5], v[12:13]
	v_pk_mul_f32 v[4:5], v[2:3], v[26:27]
	v_cvt_pk_bf16_f32 v2, v6, v7
	v_cvt_pk_bf16_f32 v3, v8, v9
	v_cvt_pk_bf16_f32 v4, v4, v5
	v_cvt_pk_bf16_f32 v5, v10, v11
	global_store_dwordx4 v[18:19], v[2:5], off offset:256
	s_cbranch_vccnz .LBB0_923
; #define PG8_BAR __builtin_amdgcn_s_barrier()
; template <class Epi, class Sched, bool ALIGN_EPI = false, bool SP2 = false>
; __device__ __forceinline__ void gemm_phase(PG8_LAS unsigned char* lds, const Gemm g, const Sched& S, const Epi& E) {
;     ...
;         if (!has_next) break;
; #pragma unroll
;         for (int a = 0; a < 2; ++a)
; #pragma unroll
;             for (int b = 0; b < 2; ++b)
; #pragma unroll
;                 for (int m = 0; m < 4; ++m)
; #pragma unroll
;                     for (int n = 0; n < 2; ++n) acc[a][b][m][n] = (f32x4){0.f, 0.f, 0.f, 0.f};
;         cur = nxt; cA = nA; cB = nB; ++ui;
;         if constexpr (ALIGN_EPI) { if (wr == 1) PG8_BAR; }
;     }
	s_andn2_b64 vcc, exec, s[6:7]
	s_cbranch_vccnz .LBB0_922
	s_barrier
	s_branch .LBB0_922

; #define PG8_STAGE(bufoff, gbase, voff) do { _Pragma("unroll") for (int _i = 0; _i < 2; ++_i) \
;         __builtin_amdgcn_global_load_lds((const unsigned*)((const char*)(gbase) + (voff)[_i]), (PG8_LAS unsigned*)(lds + (bufoff) + ldsw + _i * 8192), 16, 0, AUX_A); } while (0)
; #define PG8_STAGEB(bufoff, gbase, voff) do { _Pragma("unroll") for (int _i = 0; _i < 2; ++_i) \
;         __builtin_amdgcn_global_load_lds((const unsigned*)((const char*)(gbase) + (voff)[_i]), (PG8_LAS unsigned*)(lds + (bufoff) + ldsw + _i * 8192), 16, 0, AUX_B); } while (0)
; #define PG8_LDA(dst, b, h) do { _Pragma("unroll") for (int m = 0; m < 4; ++m) _Pragma("unroll") for (int k = 0; k < 2; ++k) dst[m][k] = *(const PG8_LAS bf16x8*)(lds + PG8_SA(b, h) + aoff + m * 2048 + k * 1024); } while (0)
; #define PG8_LDB(dst, b, h) do { _Pragma("unroll") for (int n = 0; n < 2; ++n) _Pragma("unroll") for (int k = 0; k < 2; ++k) dst[n][k] = *(const PG8_LAS bf16x8*)(lds + PG8_SB(b, h) + boff + n * 2048 + k * 1024); } while (0)
; #define PG8_MMA(ai, bj, At, Bt) do { __builtin_amdgcn_s_setprio(1); _Pragma("unroll") for (int m = 0; m < 4; ++m) _Pragma("unroll") for (int n = 0; n < 2; ++n) _Pragma("unroll") for (int k = 0; k < 2; ++k) \
;         acc[ai][bj][m][n] = __builtin_amdgcn_mfma_f32_16x16x32_bf16(Bt[n][k], At[m][k], acc[ai][bj][m][n], 0, 0, 0); __builtin_amdgcn_s_setprio(0); } while (0)
; #define PG8_WAIT_V(n) asm volatile("s_waitcnt vmcnt(" #n ")" ::: "memory")
; #define PG8_WAIT_L(n) asm volatile("s_waitcnt lgkmcnt(" #n ")" ::: "memory")
; #define PG8_BAR __builtin_amdgcn_s_barrier()
; #define PG8_SCHED __builtin_amdgcn_sched_barrier(0)
; template <class Epi, class Sched, bool ALIGN_EPI = false, bool SP2 = false>
; __device__ __forceinline__ void gemm_phase(PG8_LAS unsigned char* lds, const Gemm g, const Sched& S, const Epi& E) {
;     ...
;             PG8_LDB(B0, 0, 0); PG8_LDB(B1, 0, 1); PG8_SCHED; PG8_LDA(At, 0, 0); PG8_STAGE(PG8_SA(1, 1), a1 + hstep, voffA);
;             PG8_WAIT_V(8); PG8_WAIT_L(0); PG8_BAR; PG8_MMA(0, 0, At, B0); PG8_MMA(0, 1, At, B1); PG8_BAR; PG8_SCHED;
;             PG8_LDA(At, 0, 1); PG8_STAGEB(PG8_SB(0, 0), b2, voffB); PG8_STAGEB(PG8_SB(0, 1), b2 + hstep, voffB); PG8_STAGE(PG8_SA(0, 0), a2, voffA);
;             PG8_WAIT_V(8); PG8_WAIT_L(0); PG8_BAR; PG8_MMA(1, 0, At, B0); PG8_MMA(1, 1, At, B1); PG8_BAR; PG8_SCHED;
.Lpk_1067:
	s_add_i32 s81, s29, 2
	s_cmp_lt_u32 s29, 14
	s_cselect_b32 s0, 0, -16
	s_add_i32 s0, s81, s0
	s_ashr_i32 s1, s0, 31
	s_lshl_b64 s[0:1], s[0:1], 7
	s_add_u32 s2, s52, s0
	s_addc_u32 s46, s53, s1
	s_add_u32 s0, s42, s0
	s_addc_u32 s1, s43, s1
	s_cmp_eq_u32 s29, 14
	s_cselect_b32 s59, s15, s46
	s_cselect_b32 s58, s17, s2
	s_cselect_b32 s61, s92, s1
	s_cselect_b32 s60, s93, s0
	s_add_i32 s2, 0, 0x10000
	s_add_i32 s94, s2, s70
	s_add_i32 s46, 0, 0x14000
	s_add_i32 m0, s71, 0xc000
	s_add_i32 s84, s71, 0xe000
	s_add_i32 s95, s94, 0x2000
	s_add_u32 s62, s60, 0x40000
	v_add_u32_e32 v148, s2, v99
	s_addc_u32 s63, s61, 0
	s_add_i32 s96, s46, s70
	ds_read_b128 v[152:155], v148
	ds_read_b128 v[156:159], v148 offset:1024
	ds_read_b128 v[160:163], v148 offset:2048
	ds_read_b128 v[164:167], v148 offset:3072
	v_add_u32_e32 v148, s46, v99
	s_add_i32 s97, s96, 0x2000
	s_add_i32 vcc_lo, 0, 0x18000
	s_add_i32 vcc_hi, 0, 0x1c000
	ds_read_b128 v[180:183], v148
	ds_read_b128 v[184:187], v148 offset:1024
	ds_read_b128 v[188:191], v148 offset:2048
	ds_read_b128 v[192:195], v148 offset:3072
	s_add_u32 s56, s58, 0x40000
	s_addc_u32 s57, s59, 0
	s_add_i32 s1, vcc_lo, s70
	s_add_i32 s0, s1, 0x2000
	s_add_u32 s54, s60, 0x40080
	s_addc_u32 s55, s61, 0
	s_add_i32 s47, vcc_hi, s70
	s_add_i32 s46, s47, 0x2000
	s_cmp_gt_u32 s29, 13
	ds_read_b128 v[196:199], v151
	ds_read_b128 v[200:203], v151 offset:1024
	ds_read_b128 v[222:225], v151 offset:2048
	ds_read_b128 v[226:229], v151 offset:3072
	ds_read_b128 v[230:233], v151 offset:4096
	ds_read_b128 v[234:237], v151 offset:5120
	ds_read_b128 v[238:241], v151 offset:6144
	ds_read_b128 v[242:245], v151 offset:7168
	global_load_lds_dwordx4 v[146:147], off
	s_mov_b32 m0, s84
	s_nop 0
	global_load_lds_dwordx4 v[144:145], off
	s_waitcnt vmcnt(8)
	s_waitcnt lgkmcnt(0)
	s_setprio 1
	s_barrier
	v_mfma_f32_16x16x32_bf16 v[128:131], v[152:155], v[196:199], 0
	v_mfma_f32_16x16x32_bf16 v[128:131], v[156:159], v[200:203], v[128:131]
	v_mfma_f32_16x16x32_bf16 v[124:127], v[160:163], v[196:199], 0
	v_mfma_f32_16x16x32_bf16 v[124:127], v[164:167], v[200:203], v[124:127]
	v_mfma_f32_16x16x32_bf16 v[112:115], v[152:155], v[222:225], 0
	v_mfma_f32_16x16x32_bf16 v[112:115], v[156:159], v[226:229], v[112:115]
	v_mfma_f32_16x16x32_bf16 v[108:111], v[160:163], v[222:225], 0
	v_mfma_f32_16x16x32_bf16 v[108:111], v[164:167], v[226:229], v[108:111]
	v_mfma_f32_16x16x32_bf16 v[94:97], v[152:155], v[230:233], 0
	v_mfma_f32_16x16x32_bf16 v[94:97], v[156:159], v[234:237], v[94:97]
	v_mfma_f32_16x16x32_bf16 v[90:93], v[160:163], v[230:233], 0
	v_mfma_f32_16x16x32_bf16 v[90:93], v[164:167], v[234:237], v[90:93]
	v_mfma_f32_16x16x32_bf16 v[78:81], v[152:155], v[238:241], 0
	v_mfma_f32_16x16x32_bf16 v[78:81], v[156:159], v[242:245], v[78:81]
	v_mfma_f32_16x16x32_bf16 v[74:77], v[160:163], v[238:241], 0
	v_mfma_f32_16x16x32_bf16 v[74:77], v[164:167], v[242:245], v[74:77]
	s_setprio 0
	s_setprio 1
	v_mfma_f32_16x16x32_bf16 v[120:123], v[180:183], v[196:199], 0
	v_mfma_f32_16x16x32_bf16 v[120:123], v[184:187], v[200:203], v[120:123]
	v_mfma_f32_16x16x32_bf16 v[116:119], v[188:191], v[196:199], 0
	v_mfma_f32_16x16x32_bf16 v[116:119], v[192:195], v[200:203], v[116:119]
	v_mfma_f32_16x16x32_bf16 v[104:107], v[180:183], v[222:225], 0
	v_mfma_f32_16x16x32_bf16 v[104:107], v[184:187], v[226:229], v[104:107]
	v_mfma_f32_16x16x32_bf16 v[100:103], v[188:191], v[222:225], 0
	v_mfma_f32_16x16x32_bf16 v[100:103], v[192:195], v[226:229], v[100:103]
	v_mfma_f32_16x16x32_bf16 v[86:89], v[180:183], v[230:233], 0
	v_mfma_f32_16x16x32_bf16 v[86:89], v[184:187], v[234:237], v[86:89]
	v_mfma_f32_16x16x32_bf16 v[82:85], v[188:191], v[230:233], 0
	v_mfma_f32_16x16x32_bf16 v[82:85], v[192:195], v[234:237], v[82:85]
	v_mfma_f32_16x16x32_bf16 v[70:73], v[180:183], v[238:241], 0
	v_mfma_f32_16x16x32_bf16 v[70:73], v[184:187], v[242:245], v[70:73]
	s_setprio 2
	s_barrier
	v_mfma_f32_16x16x32_bf16 v[66:69], v[188:191], v[238:241], 0
	v_mfma_f32_16x16x32_bf16 v[66:69], v[192:195], v[242:245], v[66:69]
	s_setprio 0
	s_mov_b32 m0, s94
	v_lshl_add_u64 v[148:149], s[60:61], 0, v[136:137]
	ds_read_b128 v[196:199], v151 offset:16384
	ds_read_b128 v[200:203], v151 offset:17408
	ds_read_b128 v[222:225], v151 offset:18432
	ds_read_b128 v[226:229], v151 offset:19456
	ds_read_b128 v[230:233], v151 offset:20480
	ds_read_b128 v[234:237], v151 offset:21504
	ds_read_b128 v[238:241], v151 offset:22528
	ds_read_b128 v[242:245], v151 offset:23552
	global_load_lds_dwordx4 v[148:149], off
	v_lshl_add_u64 v[168:169], s[60:61], 0, v[132:133]
	s_mov_b32 m0, s95
	v_lshl_add_u64 v[172:173], s[62:63], 0, v[136:137]
	global_load_lds_dwordx4 v[168:169], off
	s_mov_b32 m0, s96
	v_lshl_add_u64 v[212:213], s[58:59], 0, v[134:135]
	global_load_lds_dwordx4 v[172:173], off
	v_lshl_add_u64 v[172:173], s[62:63], 0, v[132:133]
	s_mov_b32 m0, s97
	s_nop 0
	global_load_lds_dwordx4 v[172:173], off
	v_lshl_add_u64 v[172:173], s[58:59], 0, v[138:139]
	s_mov_b32 m0, s71
	s_nop 0
	global_load_lds_dwordx4 v[172:173], off
	s_mov_b32 m0, s75
	s_nop 0
	global_load_lds_dwordx4 v[212:213], off
	s_waitcnt vmcnt(8)
	s_waitcnt lgkmcnt(0)
	s_setprio 1
	s_barrier
; #define PG8_STAGE(bufoff, gbase, voff) do { _Pragma("unroll") for (int _i = 0; _i < 2; ++_i) \
;         __builtin_amdgcn_global_load_lds((const unsigned*)((const char*)(gbase) + (voff)[_i]), (PG8_LAS unsigned*)(lds + (bufoff) + ldsw + _i * 8192), 16, 0, AUX_A); } while (0)
; #define PG8_LDA(dst, b, h) do { _Pragma("unroll") for (int m = 0; m < 4; ++m) _Pragma("unroll") for (int k = 0; k < 2; ++k) dst[m][k] = *(const PG8_LAS bf16x8*)(lds + PG8_SA(b, h) + aoff + m * 2048 + k * 1024); } while (0)
; #define PG8_LDB(dst, b, h) do { _Pragma("unroll") for (int n = 0; n < 2; ++n) _Pragma("unroll") for (int k = 0; k < 2; ++k) dst[n][k] = *(const PG8_LAS bf16x8*)(lds + PG8_SB(b, h) + boff + n * 2048 + k * 1024); } while (0)
; #define PG8_MMA(ai, bj, At, Bt) do { __builtin_amdgcn_s_setprio(1); _Pragma("unroll") for (int m = 0; m < 4; ++m) _Pragma("unroll") for (int n = 0; n < 2; ++n) _Pragma("unroll") for (int k = 0; k < 2; ++k) \
;         acc[ai][bj][m][n] = __builtin_amdgcn_mfma_f32_16x16x32_bf16(Bt[n][k], At[m][k], acc[ai][bj][m][n], 0, 0, 0); __builtin_amdgcn_s_setprio(0); } while (0)
; #define PG8_WAIT_V(n) asm volatile("s_waitcnt vmcnt(" #n ")" ::: "memory")
; #define PG8_WAIT_L(n) asm volatile("s_waitcnt lgkmcnt(" #n ")" ::: "memory")
; #define PG8_BAR __builtin_amdgcn_s_barrier()
; #define PG8_SCHED __builtin_amdgcn_sched_barrier(0)
; template <class Epi, class Sched, bool ALIGN_EPI = false, bool SP2 = false>
; __device__ __forceinline__ void gemm_phase(PG8_LAS unsigned char* lds, const Gemm g, const Sched& S, const Epi& E) {
;     ...
;             PG8_WAIT_V(8); PG8_WAIT_L(0); PG8_BAR; PG8_MMA(1, 0, At, B0); PG8_MMA(1, 1, At, B1); PG8_BAR; PG8_SCHED;
;             PG8_LDB(B0, 1, 0); PG8_LDB(B1, 1, 1); PG8_SCHED; PG8_LDA(At, 1, 0); PG8_STAGE(PG8_SA(0, 1), a2 + hstep, voffA);
;             PG8_WAIT_V(8); PG8_WAIT_L(0); PG8_BAR; PG8_MMA(0, 0, At, B0); PG8_MMA(0, 1, At, B1); PG8_BAR; PG8_SCHED;
	v_mfma_f32_16x16x32_bf16 v[62:65], v[152:155], v[196:199], 0
	v_mfma_f32_16x16x32_bf16 v[62:65], v[156:159], v[200:203], v[62:65]
	v_mfma_f32_16x16x32_bf16 v[58:61], v[160:163], v[196:199], 0
	v_mfma_f32_16x16x32_bf16 v[58:61], v[164:167], v[200:203], v[58:61]
	v_mfma_f32_16x16x32_bf16 v[46:49], v[152:155], v[222:225], 0
	v_mfma_f32_16x16x32_bf16 v[46:49], v[156:159], v[226:229], v[46:49]
	v_mfma_f32_16x16x32_bf16 v[42:45], v[160:163], v[222:225], 0
	v_mfma_f32_16x16x32_bf16 v[42:45], v[164:167], v[226:229], v[42:45]
	v_mfma_f32_16x16x32_bf16 v[30:33], v[152:155], v[230:233], 0
	v_mfma_f32_16x16x32_bf16 v[30:33], v[156:159], v[234:237], v[30:33]
	v_mfma_f32_16x16x32_bf16 v[26:29], v[160:163], v[230:233], 0
	v_mfma_f32_16x16x32_bf16 v[26:29], v[164:167], v[234:237], v[26:29]
	v_mfma_f32_16x16x32_bf16 v[14:17], v[152:155], v[238:241], 0
	v_mfma_f32_16x16x32_bf16 v[14:17], v[156:159], v[242:245], v[14:17]
	v_mfma_f32_16x16x32_bf16 v[10:13], v[160:163], v[238:241], 0
	v_mfma_f32_16x16x32_bf16 v[10:13], v[164:167], v[242:245], v[10:13]
	s_setprio 0
	s_setprio 1
	v_mfma_f32_16x16x32_bf16 v[54:57], v[180:183], v[196:199], 0
	v_mfma_f32_16x16x32_bf16 v[54:57], v[184:187], v[200:203], v[54:57]
	v_mfma_f32_16x16x32_bf16 v[50:53], v[188:191], v[196:199], 0
	v_mfma_f32_16x16x32_bf16 v[50:53], v[192:195], v[200:203], v[50:53]
	v_mfma_f32_16x16x32_bf16 v[38:41], v[180:183], v[222:225], 0
	v_mfma_f32_16x16x32_bf16 v[38:41], v[184:187], v[226:229], v[38:41]
	v_mfma_f32_16x16x32_bf16 v[34:37], v[188:191], v[222:225], 0
	v_mfma_f32_16x16x32_bf16 v[34:37], v[192:195], v[226:229], v[34:37]
	v_mfma_f32_16x16x32_bf16 v[22:25], v[180:183], v[230:233], 0
	v_mfma_f32_16x16x32_bf16 v[22:25], v[184:187], v[234:237], v[22:25]
	v_mfma_f32_16x16x32_bf16 v[18:21], v[188:191], v[230:233], 0
	v_mfma_f32_16x16x32_bf16 v[18:21], v[192:195], v[234:237], v[18:21]
	v_mfma_f32_16x16x32_bf16 v[6:9], v[180:183], v[238:241], 0
	v_mfma_f32_16x16x32_bf16 v[6:9], v[184:187], v[242:245], v[6:9]
	s_setprio 2
	s_barrier
	v_mfma_f32_16x16x32_bf16 v[2:5], v[188:191], v[238:241], 0
	v_mfma_f32_16x16x32_bf16 v[2:5], v[192:195], v[242:245], v[2:5]
	s_setprio 0
	v_add_u32_e32 v164, vcc_lo, v99
	v_add_u32_e32 v192, vcc_hi, v99
	ds_read_b128 v[152:155], v164
	ds_read_b128 v[156:159], v164 offset:1024
	ds_read_b128 v[160:163], v164 offset:2048
	ds_read_b128 v[164:167], v164 offset:3072
	ds_read_b128 v[180:183], v192
	ds_read_b128 v[184:187], v192 offset:1024
	ds_read_b128 v[188:191], v192 offset:2048
	ds_read_b128 v[192:195], v192 offset:3072
	s_mov_b32 m0, s78
	v_lshl_add_u64 v[246:247], s[56:57], 0, v[138:139]
	ds_read_b128 v[196:199], v151 offset:32768
	ds_read_b128 v[200:203], v151 offset:33792
	ds_read_b128 v[222:225], v151 offset:34816
	ds_read_b128 v[226:229], v151 offset:35840
	ds_read_b128 v[230:233], v151 offset:36864
	ds_read_b128 v[234:237], v151 offset:37888
	ds_read_b128 v[238:241], v151 offset:38912
	ds_read_b128 v[242:245], v151 offset:39936
	global_load_lds_dwordx4 v[246:247], off
	v_lshl_add_u64 v[246:247], s[56:57], 0, v[134:135]
	s_mov_b32 m0, s82
	s_nop 0
	global_load_lds_dwordx4 v[246:247], off
	s_waitcnt vmcnt(8)
	s_waitcnt lgkmcnt(0)
	s_setprio 1
	s_barrier
	v_mfma_f32_16x16x32_bf16 v[128:131], v[152:155], v[196:199], v[128:131]
	v_mfma_f32_16x16x32_bf16 v[128:131], v[156:159], v[200:203], v[128:131]
	v_mfma_f32_16x16x32_bf16 v[124:127], v[160:163], v[196:199], v[124:127]
	v_mfma_f32_16x16x32_bf16 v[124:127], v[164:167], v[200:203], v[124:127]
	v_mfma_f32_16x16x32_bf16 v[112:115], v[152:155], v[222:225], v[112:115]
	v_mfma_f32_16x16x32_bf16 v[112:115], v[156:159], v[226:229], v[112:115]
	v_mfma_f32_16x16x32_bf16 v[108:111], v[160:163], v[222:225], v[108:111]
	v_mfma_f32_16x16x32_bf16 v[108:111], v[164:167], v[226:229], v[108:111]
	v_mfma_f32_16x16x32_bf16 v[94:97], v[152:155], v[230:233], v[94:97]
	v_mfma_f32_16x16x32_bf16 v[94:97], v[156:159], v[234:237], v[94:97]
	v_mfma_f32_16x16x32_bf16 v[90:93], v[160:163], v[230:233], v[90:93]
	v_mfma_f32_16x16x32_bf16 v[90:93], v[164:167], v[234:237], v[90:93]
	v_mfma_f32_16x16x32_bf16 v[78:81], v[152:155], v[238:241], v[78:81]
	v_mfma_f32_16x16x32_bf16 v[78:81], v[156:159], v[242:245], v[78:81]
	v_mfma_f32_16x16x32_bf16 v[74:77], v[160:163], v[238:241], v[74:77]
	v_mfma_f32_16x16x32_bf16 v[74:77], v[164:167], v[242:245], v[74:77]
	s_setprio 0
	s_setprio 1
	v_mfma_f32_16x16x32_bf16 v[120:123], v[180:183], v[196:199], v[120:123]
	v_mfma_f32_16x16x32_bf16 v[120:123], v[184:187], v[200:203], v[120:123]
	v_mfma_f32_16x16x32_bf16 v[116:119], v[188:191], v[196:199], v[116:119]
	v_mfma_f32_16x16x32_bf16 v[116:119], v[192:195], v[200:203], v[116:119]
	v_mfma_f32_16x16x32_bf16 v[104:107], v[180:183], v[222:225], v[104:107]
	v_mfma_f32_16x16x32_bf16 v[104:107], v[184:187], v[226:229], v[104:107]
	v_mfma_f32_16x16x32_bf16 v[100:103], v[188:191], v[222:225], v[100:103]
	v_mfma_f32_16x16x32_bf16 v[100:103], v[192:195], v[226:229], v[100:103]
	v_mfma_f32_16x16x32_bf16 v[86:89], v[180:183], v[230:233], v[86:89]
	v_mfma_f32_16x16x32_bf16 v[86:89], v[184:187], v[234:237], v[86:89]
	v_mfma_f32_16x16x32_bf16 v[82:85], v[188:191], v[230:233], v[82:85]
	v_mfma_f32_16x16x32_bf16 v[82:85], v[192:195], v[234:237], v[82:85]
	v_mfma_f32_16x16x32_bf16 v[70:73], v[180:183], v[238:241], v[70:73]
	v_mfma_f32_16x16x32_bf16 v[70:73], v[184:187], v[242:245], v[70:73]
	s_setprio 2
	s_barrier
; #define PG8_STAGE(bufoff, gbase, voff) do { _Pragma("unroll") for (int _i = 0; _i < 2; ++_i) \
;         __builtin_amdgcn_global_load_lds((const unsigned*)((const char*)(gbase) + (voff)[_i]), (PG8_LAS unsigned*)(lds + (bufoff) + ldsw + _i * 8192), 16, 0, AUX_A); } while (0)
; #define PG8_STAGEB(bufoff, gbase, voff) do { _Pragma("unroll") for (int _i = 0; _i < 2; ++_i) \
;         __builtin_amdgcn_global_load_lds((const unsigned*)((const char*)(gbase) + (voff)[_i]), (PG8_LAS unsigned*)(lds + (bufoff) + ldsw + _i * 8192), 16, 0, AUX_B); } while (0)
; #define PG8_LDA(dst, b, h) do { _Pragma("unroll") for (int m = 0; m < 4; ++m) _Pragma("unroll") for (int k = 0; k < 2; ++k) dst[m][k] = *(const PG8_LAS bf16x8*)(lds + PG8_SA(b, h) + aoff + m * 2048 + k * 1024); } while (0)
; #define PG8_MMA(ai, bj, At, Bt) do { __builtin_amdgcn_s_setprio(1); _Pragma("unroll") for (int m = 0; m < 4; ++m) _Pragma("unroll") for (int n = 0; n < 2; ++n) _Pragma("unroll") for (int k = 0; k < 2; ++k) \
;         acc[ai][bj][m][n] = __builtin_amdgcn_mfma_f32_16x16x32_bf16(Bt[n][k], At[m][k], acc[ai][bj][m][n], 0, 0, 0); __builtin_amdgcn_s_setprio(0); } while (0)
; #define PG8_WAIT_V(n) asm volatile("s_waitcnt vmcnt(" #n ")" ::: "memory")
; #define PG8_WAIT_L(n) asm volatile("s_waitcnt lgkmcnt(" #n ")" ::: "memory")
; #define PG8_BAR __builtin_amdgcn_s_barrier()
; #define PG8_SCHED __builtin_amdgcn_sched_barrier(0)
; template <class Epi, class Sched, bool ALIGN_EPI = false, bool SP2 = false>
; __device__ __forceinline__ void gemm_phase(PG8_LAS unsigned char* lds, const Gemm g, const Sched& S, const Epi& E) {
;     ...
;             PG8_LDA(At, 1, 1); PG8_STAGEB(PG8_SB(1, 0), b3, voffB); PG8_STAGEB(PG8_SB(1, 1), b3 + hstep, voffB); PG8_STAGE(PG8_SA(1, 0), a3, voffA);
;             PG8_WAIT_V(8); PG8_WAIT_L(0); PG8_BAR; PG8_MMA(1, 0, At, B0); PG8_MMA(1, 1, At, B1); PG8_BAR; PG8_SCHED;
	v_mfma_f32_16x16x32_bf16 v[66:69], v[188:191], v[238:241], v[66:69]
	v_mfma_f32_16x16x32_bf16 v[66:69], v[192:195], v[242:245], v[66:69]
	s_setprio 0
	s_mov_b32 m0, s1
	v_lshl_add_u64 v[148:149], v[148:149], 0, s[76:77]
	ds_read_b128 v[196:199], v151 offset:49152
	ds_read_b128 v[200:203], v151 offset:50176
	ds_read_b128 v[222:225], v151 offset:51200
	ds_read_b128 v[226:229], v151 offset:52224
	ds_read_b128 v[230:233], v151 offset:53248
	ds_read_b128 v[234:237], v151 offset:54272
	ds_read_b128 v[238:241], v151 offset:55296
	ds_read_b128 v[242:245], v151 offset:56320
	global_load_lds_dwordx4 v[148:149], off
	v_lshl_add_u64 v[148:149], v[168:169], 0, s[76:77]
	s_mov_b32 m0, s0
	s_nop 0
	global_load_lds_dwordx4 v[148:149], off
	v_lshl_add_u64 v[148:149], s[54:55], 0, v[136:137]
	s_mov_b32 m0, s47
	s_nop 0
	global_load_lds_dwordx4 v[148:149], off
	v_lshl_add_u64 v[148:149], s[54:55], 0, v[132:133]
	s_mov_b32 m0, s46
	s_nop 0
	global_load_lds_dwordx4 v[148:149], off
	v_lshl_add_u64 v[148:149], v[172:173], 0, s[76:77]
	s_mov_b32 m0, s83
	s_nop 0
	global_load_lds_dwordx4 v[148:149], off
	v_lshl_add_u64 v[148:149], v[212:213], 0, s[76:77]
	s_mov_b32 m0, s88
	s_nop 0
	global_load_lds_dwordx4 v[148:149], off
	s_waitcnt vmcnt(8)
	s_waitcnt lgkmcnt(0)
	s_setprio 1
	s_barrier
	v_mfma_f32_16x16x32_bf16 v[62:65], v[152:155], v[196:199], v[62:65]
	v_mfma_f32_16x16x32_bf16 v[62:65], v[156:159], v[200:203], v[62:65]
	v_mfma_f32_16x16x32_bf16 v[58:61], v[160:163], v[196:199], v[58:61]
	v_mfma_f32_16x16x32_bf16 v[58:61], v[164:167], v[200:203], v[58:61]
	v_mfma_f32_16x16x32_bf16 v[46:49], v[152:155], v[222:225], v[46:49]
	v_mfma_f32_16x16x32_bf16 v[46:49], v[156:159], v[226:229], v[46:49]
	v_mfma_f32_16x16x32_bf16 v[42:45], v[160:163], v[222:225], v[42:45]
	v_mfma_f32_16x16x32_bf16 v[42:45], v[164:167], v[226:229], v[42:45]
	v_mfma_f32_16x16x32_bf16 v[30:33], v[152:155], v[230:233], v[30:33]
	v_mfma_f32_16x16x32_bf16 v[30:33], v[156:159], v[234:237], v[30:33]
	v_mfma_f32_16x16x32_bf16 v[26:29], v[160:163], v[230:233], v[26:29]
	v_mfma_f32_16x16x32_bf16 v[26:29], v[164:167], v[234:237], v[26:29]
	v_mfma_f32_16x16x32_bf16 v[14:17], v[152:155], v[238:241], v[14:17]
	v_mfma_f32_16x16x32_bf16 v[14:17], v[156:159], v[242:245], v[14:17]
	v_mfma_f32_16x16x32_bf16 v[10:13], v[160:163], v[238:241], v[10:13]
	v_mfma_f32_16x16x32_bf16 v[10:13], v[164:167], v[242:245], v[10:13]
	s_setprio 0
	s_setprio 1
	v_mfma_f32_16x16x32_bf16 v[54:57], v[180:183], v[196:199], v[54:57]
	v_mfma_f32_16x16x32_bf16 v[54:57], v[184:187], v[200:203], v[54:57]
	v_mfma_f32_16x16x32_bf16 v[50:53], v[188:191], v[196:199], v[50:53]
	v_mfma_f32_16x16x32_bf16 v[50:53], v[192:195], v[200:203], v[50:53]
	v_mfma_f32_16x16x32_bf16 v[38:41], v[180:183], v[222:225], v[38:41]
	v_mfma_f32_16x16x32_bf16 v[38:41], v[184:187], v[226:229], v[38:41]
	v_mfma_f32_16x16x32_bf16 v[34:37], v[188:191], v[222:225], v[34:37]
	v_mfma_f32_16x16x32_bf16 v[34:37], v[192:195], v[226:229], v[34:37]
	v_mfma_f32_16x16x32_bf16 v[22:25], v[180:183], v[230:233], v[22:25]
	v_mfma_f32_16x16x32_bf16 v[22:25], v[184:187], v[234:237], v[22:25]
	v_mfma_f32_16x16x32_bf16 v[18:21], v[188:191], v[230:233], v[18:21]
	v_mfma_f32_16x16x32_bf16 v[18:21], v[192:195], v[234:237], v[18:21]
	v_mfma_f32_16x16x32_bf16 v[6:9], v[180:183], v[238:241], v[6:9]
	v_mfma_f32_16x16x32_bf16 v[6:9], v[184:187], v[242:245], v[6:9]
	s_setprio 2
	s_cbranch_scc0 .Lq4b_1067p
	v_cmp_ne_u32_e64 vcc, s12, 0
	s_cbranch_vccz .Lq4s_1067p

; #define PG8_STAGE(bufoff, gbase, voff) do { _Pragma("unroll") for (int _i = 0; _i < 2; ++_i) \
;         __builtin_amdgcn_global_load_lds((const unsigned*)((const char*)(gbase) + (voff)[_i]), (PG8_LAS unsigned*)(lds + (bufoff) + ldsw + _i * 8192), 16, 0, AUX_A); } while (0)
; #define PG8_STAGEB(bufoff, gbase, voff) do { _Pragma("unroll") for (int _i = 0; _i < 2; ++_i) \
;         __builtin_amdgcn_global_load_lds((const unsigned*)((const char*)(gbase) + (voff)[_i]), (PG8_LAS unsigned*)(lds + (bufoff) + ldsw + _i * 8192), 16, 0, AUX_B); } while (0)
; #define PG8_LDA(dst, b, h) do { _Pragma("unroll") for (int m = 0; m < 4; ++m) _Pragma("unroll") for (int k = 0; k < 2; ++k) dst[m][k] = *(const PG8_LAS bf16x8*)(lds + PG8_SA(b, h) + aoff + m * 2048 + k * 1024); } while (0)
; #define PG8_WAIT_V(n) asm volatile("s_waitcnt vmcnt(" #n ")" ::: "memory")
; #define PG8_WAIT_L(n) asm volatile("s_waitcnt lgkmcnt(" #n ")" ::: "memory")
; #define PG8_BAR __builtin_amdgcn_s_barrier()
; template <class Epi, class Sched, bool ALIGN_EPI = false, bool SP2 = false>
; __device__ __forceinline__ void gemm_phase(PG8_LAS unsigned char* lds, const Gemm g, const Sched& S, const Epi& E) {
;     ...
;         for (int t = 0; t < nt; t += 2) {
;             const bool last = (t == nt - 2);
;             const char* a1 = PG8_KP(cA, t + 1, rot, nt);
;             const char* a2 = last ? nAr : PG8_KP(cA, t + 2, rot, nt); const char* b2 = last ? nBr : PG8_KP(cB, t + 2, rot, nt);
;             const char* a3 = a2 + kstep; const char* b3 = b2 + kstep;
;             if (last && has_next) S.a_ready(nxt);
;             if constexpr (SP2) {
;             PG8_LDB(B0, 0, 0); PG8_LDB(B1, 0, 1); PG8_SCHED; PG8_LDA(At, 0, 0); PG8_STAGE(PG8_SA(1, 1), a1 + hstep, voffA);
;             PG8_WAIT_V(8); PG8_WAIT_L(0); PG8_BAR; PG8_MMA(0, 0, At, B0); PG8_MMA(0, 1, At, B1); PG8_BAR; PG8_SCHED;
;             PG8_LDA(At, 0, 1); PG8_STAGEB(PG8_SB(0, 0), b2, voffB); PG8_STAGEB(PG8_SB(0, 1), b2 + hstep, voffB); PG8_STAGE(PG8_SA(0, 0), a2, voffA);
;             PG8_WAIT_V(8); PG8_WAIT_L(0); PG8_BAR; PG8_MMA(1, 0, At, B0); PG8_MMA(1, 1, At, B1); PG8_BAR; PG8_SCHED;
;             PG8_LDB(B0, 1, 0); PG8_LDB(B1, 1, 1); PG8_SCHED; PG8_LDA(At, 1, 0); PG8_STAGE(PG8_SA(0, 1), a2 + hstep, voffA);
;             PG8_WAIT_V(8); PG8_WAIT_L(0); PG8_BAR; PG8_MMA(0, 0, At, B0); PG8_MMA(0, 1, At, B1); PG8_BAR; PG8_SCHED;
.Lq4s_1067p:
	v_mfma_f32_16x16x32_bf16 v[2:5], v[188:191], v[238:241], v[2:5]
	v_mfma_f32_16x16x32_bf16 v[2:5], v[192:195], v[242:245], v[2:5]
	s_setprio 0
	v_lshl_add_u64 v[144:145], v[144:145], 0, s[86:87]
	v_lshl_add_u64 v[146:147], v[146:147], 0, s[86:87]
	s_mov_b32 s29, s81
	s_cbranch_scc1 .Lpx_1067
.LBB0_1067:
	s_add_i32 s81, s29, 2
	s_cmp_lt_u32 s29, 14
	s_cselect_b32 s0, 0, -16
	s_add_i32 s0, s81, s0
	s_ashr_i32 s1, s0, 31
	s_lshl_b64 s[0:1], s[0:1], 7
	s_add_u32 s2, s52, s0
	s_addc_u32 s46, s53, s1
	s_add_u32 s0, s42, s0
	s_addc_u32 s1, s43, s1
	s_cmp_eq_u32 s29, 14
	s_cselect_b32 s59, s15, s46
	s_cselect_b32 s58, s17, s2
	s_cselect_b32 s61, s92, s1
	s_cselect_b32 s60, s93, s0
	s_add_i32 s2, 0, 0x10000
	s_add_i32 s94, s2, s70
	s_add_i32 s46, 0, 0x14000
	s_add_i32 m0, s71, 0xc000
	s_add_i32 s84, s71, 0xe000
	s_add_i32 s95, s94, 0x2000
	s_add_u32 s62, s60, 0x40000
	v_add_u32_e32 v148, s2, v99
	s_addc_u32 s63, s61, 0
	s_add_i32 s96, s46, s70
	ds_read_b128 v[152:155], v148
	ds_read_b128 v[156:159], v148 offset:1024
	ds_read_b128 v[160:163], v148 offset:2048
	ds_read_b128 v[164:167], v148 offset:3072
	v_add_u32_e32 v148, s46, v99
	s_add_i32 s97, s96, 0x2000
	s_add_i32 vcc_lo, 0, 0x18000
	s_add_i32 vcc_hi, 0, 0x1c000
	ds_read_b128 v[180:183], v148
	ds_read_b128 v[184:187], v148 offset:1024
	ds_read_b128 v[188:191], v148 offset:2048
	ds_read_b128 v[192:195], v148 offset:3072
	s_add_u32 s56, s58, 0x40000
	s_addc_u32 s57, s59, 0
	s_add_i32 s1, vcc_lo, s70
	s_add_i32 s0, s1, 0x2000
	s_add_u32 s54, s60, 0x40080
	s_addc_u32 s55, s61, 0
	s_add_i32 s47, vcc_hi, s70
	s_add_i32 s46, s47, 0x2000
	s_cmp_gt_u32 s29, 13
	ds_read_b128 v[196:199], v151
	ds_read_b128 v[200:203], v151 offset:1024
	ds_read_b128 v[222:225], v151 offset:2048
	ds_read_b128 v[226:229], v151 offset:3072
	ds_read_b128 v[230:233], v151 offset:4096
	ds_read_b128 v[234:237], v151 offset:5120
	ds_read_b128 v[238:241], v151 offset:6144
	ds_read_b128 v[242:245], v151 offset:7168
	global_load_lds_dwordx4 v[146:147], off
	s_mov_b32 m0, s84
	s_nop 0
	global_load_lds_dwordx4 v[144:145], off
	s_waitcnt vmcnt(8)
	s_waitcnt lgkmcnt(0)
	s_setprio 1
	s_barrier
	v_mfma_f32_16x16x32_bf16 v[128:131], v[152:155], v[196:199], v[128:131]
	v_mfma_f32_16x16x32_bf16 v[128:131], v[156:159], v[200:203], v[128:131]
	v_mfma_f32_16x16x32_bf16 v[124:127], v[160:163], v[196:199], v[124:127]
	v_mfma_f32_16x16x32_bf16 v[124:127], v[164:167], v[200:203], v[124:127]
	v_mfma_f32_16x16x32_bf16 v[112:115], v[152:155], v[222:225], v[112:115]
	v_mfma_f32_16x16x32_bf16 v[112:115], v[156:159], v[226:229], v[112:115]
	v_mfma_f32_16x16x32_bf16 v[108:111], v[160:163], v[222:225], v[108:111]
	v_mfma_f32_16x16x32_bf16 v[108:111], v[164:167], v[226:229], v[108:111]
	v_mfma_f32_16x16x32_bf16 v[94:97], v[152:155], v[230:233], v[94:97]
	v_mfma_f32_16x16x32_bf16 v[94:97], v[156:159], v[234:237], v[94:97]
	v_mfma_f32_16x16x32_bf16 v[90:93], v[160:163], v[230:233], v[90:93]
	v_mfma_f32_16x16x32_bf16 v[90:93], v[164:167], v[234:237], v[90:93]
	v_mfma_f32_16x16x32_bf16 v[78:81], v[152:155], v[238:241], v[78:81]
	v_mfma_f32_16x16x32_bf16 v[78:81], v[156:159], v[242:245], v[78:81]
	v_mfma_f32_16x16x32_bf16 v[74:77], v[160:163], v[238:241], v[74:77]
	v_mfma_f32_16x16x32_bf16 v[74:77], v[164:167], v[242:245], v[74:77]
	s_setprio 0
	s_setprio 1
	v_mfma_f32_16x16x32_bf16 v[120:123], v[180:183], v[196:199], v[120:123]
	v_mfma_f32_16x16x32_bf16 v[120:123], v[184:187], v[200:203], v[120:123]
	v_mfma_f32_16x16x32_bf16 v[116:119], v[188:191], v[196:199], v[116:119]
	v_mfma_f32_16x16x32_bf16 v[116:119], v[192:195], v[200:203], v[116:119]
	v_mfma_f32_16x16x32_bf16 v[104:107], v[180:183], v[222:225], v[104:107]
	v_mfma_f32_16x16x32_bf16 v[104:107], v[184:187], v[226:229], v[104:107]
	v_mfma_f32_16x16x32_bf16 v[100:103], v[188:191], v[222:225], v[100:103]
	v_mfma_f32_16x16x32_bf16 v[100:103], v[192:195], v[226:229], v[100:103]
	v_mfma_f32_16x16x32_bf16 v[86:89], v[180:183], v[230:233], v[86:89]
	v_mfma_f32_16x16x32_bf16 v[86:89], v[184:187], v[234:237], v[86:89]
	v_mfma_f32_16x16x32_bf16 v[82:85], v[188:191], v[230:233], v[82:85]
	v_mfma_f32_16x16x32_bf16 v[82:85], v[192:195], v[234:237], v[82:85]
	v_mfma_f32_16x16x32_bf16 v[70:73], v[180:183], v[238:241], v[70:73]
	v_mfma_f32_16x16x32_bf16 v[70:73], v[184:187], v[242:245], v[70:73]
	s_setprio 2
	s_barrier
	v_mfma_f32_16x16x32_bf16 v[66:69], v[188:191], v[238:241], v[66:69]
	v_mfma_f32_16x16x32_bf16 v[66:69], v[192:195], v[242:245], v[66:69]
	s_setprio 0
	s_mov_b32 m0, s94
	v_lshl_add_u64 v[148:149], s[60:61], 0, v[136:137]
	ds_read_b128 v[196:199], v151 offset:16384
	ds_read_b128 v[200:203], v151 offset:17408
	ds_read_b128 v[222:225], v151 offset:18432
	ds_read_b128 v[226:229], v151 offset:19456
	ds_read_b128 v[230:233], v151 offset:20480
	ds_read_b128 v[234:237], v151 offset:21504
	ds_read_b128 v[238:241], v151 offset:22528
	ds_read_b128 v[242:245], v151 offset:23552
	global_load_lds_dwordx4 v[148:149], off
	v_lshl_add_u64 v[168:169], s[60:61], 0, v[132:133]
	s_mov_b32 m0, s95
	v_lshl_add_u64 v[172:173], s[62:63], 0, v[136:137]
	global_load_lds_dwordx4 v[168:169], off
	s_mov_b32 m0, s96
	v_lshl_add_u64 v[212:213], s[58:59], 0, v[134:135]
	global_load_lds_dwordx4 v[172:173], off
	v_lshl_add_u64 v[172:173], s[62:63], 0, v[132:133]
	s_mov_b32 m0, s97
	s_nop 0
	global_load_lds_dwordx4 v[172:173], off
	v_lshl_add_u64 v[172:173], s[58:59], 0, v[138:139]
	s_mov_b32 m0, s71
	s_nop 0
	global_load_lds_dwordx4 v[172:173], off
	s_mov_b32 m0, s75
	s_nop 0
	global_load_lds_dwordx4 v[212:213], off
	s_waitcnt vmcnt(8)
	s_waitcnt lgkmcnt(0)
	s_setprio 1
	s_barrier
; #define PG8_STAGE(bufoff, gbase, voff) do { _Pragma("unroll") for (int _i = 0; _i < 2; ++_i) \
;         __builtin_amdgcn_global_load_lds((const unsigned*)((const char*)(gbase) + (voff)[_i]), (PG8_LAS unsigned*)(lds + (bufoff) + ldsw + _i * 8192), 16, 0, AUX_A); } while (0)
; #define PG8_STAGEB(bufoff, gbase, voff) do { _Pragma("unroll") for (int _i = 0; _i < 2; ++_i) \
;         __builtin_amdgcn_global_load_lds((const unsigned*)((const char*)(gbase) + (voff)[_i]), (PG8_LAS unsigned*)(lds + (bufoff) + ldsw + _i * 8192), 16, 0, AUX_B); } while (0)
; #define PG8_LDA(dst, b, h) do { _Pragma("unroll") for (int m = 0; m < 4; ++m) _Pragma("unroll") for (int k = 0; k < 2; ++k) dst[m][k] = *(const PG8_LAS bf16x8*)(lds + PG8_SA(b, h) + aoff + m * 2048 + k * 1024); } while (0)
; #define PG8_LDB(dst, b, h) do { _Pragma("unroll") for (int n = 0; n < 2; ++n) _Pragma("unroll") for (int k = 0; k < 2; ++k) dst[n][k] = *(const PG8_LAS bf16x8*)(lds + PG8_SB(b, h) + boff + n * 2048 + k * 1024); } while (0)
; #define PG8_MMA(ai, bj, At, Bt) do { __builtin_amdgcn_s_setprio(1); _Pragma("unroll") for (int m = 0; m < 4; ++m) _Pragma("unroll") for (int n = 0; n < 2; ++n) _Pragma("unroll") for (int k = 0; k < 2; ++k) \
;         acc[ai][bj][m][n] = __builtin_amdgcn_mfma_f32_16x16x32_bf16(Bt[n][k], At[m][k], acc[ai][bj][m][n], 0, 0, 0); __builtin_amdgcn_s_setprio(0); } while (0)
; #define PG8_WAIT_V(n) asm volatile("s_waitcnt vmcnt(" #n ")" ::: "memory")
; #define PG8_WAIT_L(n) asm volatile("s_waitcnt lgkmcnt(" #n ")" ::: "memory")
; #define PG8_BAR __builtin_amdgcn_s_barrier()
; #define PG8_SCHED __builtin_amdgcn_sched_barrier(0)
; template <class Epi, class Sched, bool ALIGN_EPI = false, bool SP2 = false>
; __device__ __forceinline__ void gemm_phase(PG8_LAS unsigned char* lds, const Gemm g, const Sched& S, const Epi& E) {
;     ...
;             PG8_LDA(At, 0, 1); PG8_STAGEB(PG8_SB(0, 0), b2, voffB); PG8_STAGEB(PG8_SB(0, 1), b2 + hstep, voffB); PG8_STAGE(PG8_SA(0, 0), a2, voffA);
;             PG8_WAIT_V(8); PG8_WAIT_L(0); PG8_BAR; PG8_MMA(1, 0, At, B0); PG8_MMA(1, 1, At, B1); PG8_BAR; PG8_SCHED;
;             PG8_LDB(B0, 1, 0); PG8_LDB(B1, 1, 1); PG8_SCHED; PG8_LDA(At, 1, 0); PG8_STAGE(PG8_SA(0, 1), a2 + hstep, voffA);
;             PG8_WAIT_V(8); PG8_WAIT_L(0); PG8_BAR; PG8_MMA(0, 0, At, B0); PG8_MMA(0, 1, At, B1); PG8_BAR; PG8_SCHED;
	v_mfma_f32_16x16x32_bf16 v[62:65], v[152:155], v[196:199], v[62:65]
	v_mfma_f32_16x16x32_bf16 v[62:65], v[156:159], v[200:203], v[62:65]
	v_mfma_f32_16x16x32_bf16 v[58:61], v[160:163], v[196:199], v[58:61]
	v_mfma_f32_16x16x32_bf16 v[58:61], v[164:167], v[200:203], v[58:61]
	v_mfma_f32_16x16x32_bf16 v[46:49], v[152:155], v[222:225], v[46:49]
	v_mfma_f32_16x16x32_bf16 v[46:49], v[156:159], v[226:229], v[46:49]
	v_mfma_f32_16x16x32_bf16 v[42:45], v[160:163], v[222:225], v[42:45]
	v_mfma_f32_16x16x32_bf16 v[42:45], v[164:167], v[226:229], v[42:45]
	v_mfma_f32_16x16x32_bf16 v[30:33], v[152:155], v[230:233], v[30:33]
	v_mfma_f32_16x16x32_bf16 v[30:33], v[156:159], v[234:237], v[30:33]
	v_mfma_f32_16x16x32_bf16 v[26:29], v[160:163], v[230:233], v[26:29]
	v_mfma_f32_16x16x32_bf16 v[26:29], v[164:167], v[234:237], v[26:29]
	v_mfma_f32_16x16x32_bf16 v[14:17], v[152:155], v[238:241], v[14:17]
	v_mfma_f32_16x16x32_bf16 v[14:17], v[156:159], v[242:245], v[14:17]
	v_mfma_f32_16x16x32_bf16 v[10:13], v[160:163], v[238:241], v[10:13]
	v_mfma_f32_16x16x32_bf16 v[10:13], v[164:167], v[242:245], v[10:13]
	s_setprio 0
	s_setprio 1
	v_mfma_f32_16x16x32_bf16 v[54:57], v[180:183], v[196:199], v[54:57]
	v_mfma_f32_16x16x32_bf16 v[54:57], v[184:187], v[200:203], v[54:57]
	v_mfma_f32_16x16x32_bf16 v[50:53], v[188:191], v[196:199], v[50:53]
	v_mfma_f32_16x16x32_bf16 v[50:53], v[192:195], v[200:203], v[50:53]
	v_mfma_f32_16x16x32_bf16 v[38:41], v[180:183], v[222:225], v[38:41]
	v_mfma_f32_16x16x32_bf16 v[38:41], v[184:187], v[226:229], v[38:41]
	v_mfma_f32_16x16x32_bf16 v[34:37], v[188:191], v[222:225], v[34:37]
	v_mfma_f32_16x16x32_bf16 v[34:37], v[192:195], v[226:229], v[34:37]
	v_mfma_f32_16x16x32_bf16 v[22:25], v[180:183], v[230:233], v[22:25]
	v_mfma_f32_16x16x32_bf16 v[22:25], v[184:187], v[234:237], v[22:25]
	v_mfma_f32_16x16x32_bf16 v[18:21], v[188:191], v[230:233], v[18:21]
	v_mfma_f32_16x16x32_bf16 v[18:21], v[192:195], v[234:237], v[18:21]
	v_mfma_f32_16x16x32_bf16 v[6:9], v[180:183], v[238:241], v[6:9]
	v_mfma_f32_16x16x32_bf16 v[6:9], v[184:187], v[242:245], v[6:9]
	s_setprio 2
	s_barrier
	v_mfma_f32_16x16x32_bf16 v[2:5], v[188:191], v[238:241], v[2:5]
	v_mfma_f32_16x16x32_bf16 v[2:5], v[192:195], v[242:245], v[2:5]
	s_setprio 0
	v_add_u32_e32 v164, vcc_lo, v99
	v_add_u32_e32 v192, vcc_hi, v99
	ds_read_b128 v[152:155], v164
	ds_read_b128 v[156:159], v164 offset:1024
	ds_read_b128 v[160:163], v164 offset:2048
	ds_read_b128 v[164:167], v164 offset:3072
	ds_read_b128 v[180:183], v192
	ds_read_b128 v[184:187], v192 offset:1024
	ds_read_b128 v[188:191], v192 offset:2048
	ds_read_b128 v[192:195], v192 offset:3072
	s_mov_b32 m0, s78
	v_lshl_add_u64 v[246:247], s[56:57], 0, v[138:139]
	ds_read_b128 v[196:199], v151 offset:32768
	ds_read_b128 v[200:203], v151 offset:33792
	ds_read_b128 v[222:225], v151 offset:34816
	ds_read_b128 v[226:229], v151 offset:35840
	ds_read_b128 v[230:233], v151 offset:36864
	ds_read_b128 v[234:237], v151 offset:37888
	ds_read_b128 v[238:241], v151 offset:38912
	ds_read_b128 v[242:245], v151 offset:39936
	global_load_lds_dwordx4 v[246:247], off
	v_lshl_add_u64 v[246:247], s[56:57], 0, v[134:135]
	s_mov_b32 m0, s82
	s_nop 0
	global_load_lds_dwordx4 v[246:247], off
	s_waitcnt vmcnt(8)
	s_waitcnt lgkmcnt(0)
	s_setprio 1
	s_barrier
	v_mfma_f32_16x16x32_bf16 v[128:131], v[152:155], v[196:199], v[128:131]
	v_mfma_f32_16x16x32_bf16 v[128:131], v[156:159], v[200:203], v[128:131]
	v_mfma_f32_16x16x32_bf16 v[124:127], v[160:163], v[196:199], v[124:127]
	v_mfma_f32_16x16x32_bf16 v[124:127], v[164:167], v[200:203], v[124:127]
	v_mfma_f32_16x16x32_bf16 v[112:115], v[152:155], v[222:225], v[112:115]
	v_mfma_f32_16x16x32_bf16 v[112:115], v[156:159], v[226:229], v[112:115]
	v_mfma_f32_16x16x32_bf16 v[108:111], v[160:163], v[222:225], v[108:111]
	v_mfma_f32_16x16x32_bf16 v[108:111], v[164:167], v[226:229], v[108:111]
	v_mfma_f32_16x16x32_bf16 v[94:97], v[152:155], v[230:233], v[94:97]
	v_mfma_f32_16x16x32_bf16 v[94:97], v[156:159], v[234:237], v[94:97]
	v_mfma_f32_16x16x32_bf16 v[90:93], v[160:163], v[230:233], v[90:93]
	v_mfma_f32_16x16x32_bf16 v[90:93], v[164:167], v[234:237], v[90:93]
	v_mfma_f32_16x16x32_bf16 v[78:81], v[152:155], v[238:241], v[78:81]
	v_mfma_f32_16x16x32_bf16 v[78:81], v[156:159], v[242:245], v[78:81]
	v_mfma_f32_16x16x32_bf16 v[74:77], v[160:163], v[238:241], v[74:77]
	v_mfma_f32_16x16x32_bf16 v[74:77], v[164:167], v[242:245], v[74:77]
	s_setprio 0
	s_setprio 1
	v_mfma_f32_16x16x32_bf16 v[120:123], v[180:183], v[196:199], v[120:123]
	v_mfma_f32_16x16x32_bf16 v[120:123], v[184:187], v[200:203], v[120:123]
	v_mfma_f32_16x16x32_bf16 v[116:119], v[188:191], v[196:199], v[116:119]
	v_mfma_f32_16x16x32_bf16 v[116:119], v[192:195], v[200:203], v[116:119]
	v_mfma_f32_16x16x32_bf16 v[104:107], v[180:183], v[222:225], v[104:107]
	v_mfma_f32_16x16x32_bf16 v[104:107], v[184:187], v[226:229], v[104:107]
	v_mfma_f32_16x16x32_bf16 v[100:103], v[188:191], v[222:225], v[100:103]
	v_mfma_f32_16x16x32_bf16 v[100:103], v[192:195], v[226:229], v[100:103]
	v_mfma_f32_16x16x32_bf16 v[86:89], v[180:183], v[230:233], v[86:89]
	v_mfma_f32_16x16x32_bf16 v[86:89], v[184:187], v[234:237], v[86:89]
	v_mfma_f32_16x16x32_bf16 v[82:85], v[188:191], v[230:233], v[82:85]
	v_mfma_f32_16x16x32_bf16 v[82:85], v[192:195], v[234:237], v[82:85]
	v_mfma_f32_16x16x32_bf16 v[70:73], v[180:183], v[238:241], v[70:73]
	v_mfma_f32_16x16x32_bf16 v[70:73], v[184:187], v[242:245], v[70:73]
	s_setprio 2
	s_barrier
; #define PG8_STAGE(bufoff, gbase, voff) do { _Pragma("unroll") for (int _i = 0; _i < 2; ++_i) \
;         __builtin_amdgcn_global_load_lds((const unsigned*)((const char*)(gbase) + (voff)[_i]), (PG8_LAS unsigned*)(lds + (bufoff) + ldsw + _i * 8192), 16, 0, AUX_A); } while (0)
; #define PG8_STAGEB(bufoff, gbase, voff) do { _Pragma("unroll") for (int _i = 0; _i < 2; ++_i) \
;         __builtin_amdgcn_global_load_lds((const unsigned*)((const char*)(gbase) + (voff)[_i]), (PG8_LAS unsigned*)(lds + (bufoff) + ldsw + _i * 8192), 16, 0, AUX_B); } while (0)
; #define PG8_LDA(dst, b, h) do { _Pragma("unroll") for (int m = 0; m < 4; ++m) _Pragma("unroll") for (int k = 0; k < 2; ++k) dst[m][k] = *(const PG8_LAS bf16x8*)(lds + PG8_SA(b, h) + aoff + m * 2048 + k * 1024); } while (0)
; #define PG8_MMA(ai, bj, At, Bt) do { __builtin_amdgcn_s_setprio(1); _Pragma("unroll") for (int m = 0; m < 4; ++m) _Pragma("unroll") for (int n = 0; n < 2; ++n) _Pragma("unroll") for (int k = 0; k < 2; ++k) \
;         acc[ai][bj][m][n] = __builtin_amdgcn_mfma_f32_16x16x32_bf16(Bt[n][k], At[m][k], acc[ai][bj][m][n], 0, 0, 0); __builtin_amdgcn_s_setprio(0); } while (0)
; #define PG8_WAIT_V(n) asm volatile("s_waitcnt vmcnt(" #n ")" ::: "memory")
; #define PG8_WAIT_L(n) asm volatile("s_waitcnt lgkmcnt(" #n ")" ::: "memory")
; #define PG8_BAR __builtin_amdgcn_s_barrier()
; #define PG8_SCHED __builtin_amdgcn_sched_barrier(0)
; template <class Epi, class Sched, bool ALIGN_EPI = false, bool SP2 = false>
; __device__ __forceinline__ void gemm_phase(PG8_LAS unsigned char* lds, const Gemm g, const Sched& S, const Epi& E) {
;     ...
;             PG8_LDA(At, 1, 1); PG8_STAGEB(PG8_SB(1, 0), b3, voffB); PG8_STAGEB(PG8_SB(1, 1), b3 + hstep, voffB); PG8_STAGE(PG8_SA(1, 0), a3, voffA);
;             PG8_WAIT_V(8); PG8_WAIT_L(0); PG8_BAR; PG8_MMA(1, 0, At, B0); PG8_MMA(1, 1, At, B1); PG8_BAR; PG8_SCHED;
	v_mfma_f32_16x16x32_bf16 v[66:69], v[188:191], v[238:241], v[66:69]
	v_mfma_f32_16x16x32_bf16 v[66:69], v[192:195], v[242:245], v[66:69]
	s_setprio 0
	s_mov_b32 m0, s1
	v_lshl_add_u64 v[148:149], v[148:149], 0, s[76:77]
	ds_read_b128 v[196:199], v151 offset:49152
	ds_read_b128 v[200:203], v151 offset:50176
	ds_read_b128 v[222:225], v151 offset:51200
	ds_read_b128 v[226:229], v151 offset:52224
	ds_read_b128 v[230:233], v151 offset:53248
	ds_read_b128 v[234:237], v151 offset:54272
	ds_read_b128 v[238:241], v151 offset:55296
	ds_read_b128 v[242:245], v151 offset:56320
	global_load_lds_dwordx4 v[148:149], off
	v_lshl_add_u64 v[148:149], v[168:169], 0, s[76:77]
	s_mov_b32 m0, s0
	s_nop 0
	global_load_lds_dwordx4 v[148:149], off
	v_lshl_add_u64 v[148:149], s[54:55], 0, v[136:137]
	s_mov_b32 m0, s47
	s_nop 0
	global_load_lds_dwordx4 v[148:149], off
	v_lshl_add_u64 v[148:149], s[54:55], 0, v[132:133]
	s_mov_b32 m0, s46
	s_nop 0
	global_load_lds_dwordx4 v[148:149], off
	v_lshl_add_u64 v[148:149], v[172:173], 0, s[76:77]
	s_mov_b32 m0, s83
	s_nop 0
	global_load_lds_dwordx4 v[148:149], off
	v_lshl_add_u64 v[148:149], v[212:213], 0, s[76:77]
	s_mov_b32 m0, s88
	s_nop 0
	global_load_lds_dwordx4 v[148:149], off
	s_waitcnt vmcnt(8)
	s_waitcnt lgkmcnt(0)
	s_setprio 1
	s_barrier
	v_mfma_f32_16x16x32_bf16 v[62:65], v[152:155], v[196:199], v[62:65]
	v_mfma_f32_16x16x32_bf16 v[62:65], v[156:159], v[200:203], v[62:65]
	v_mfma_f32_16x16x32_bf16 v[58:61], v[160:163], v[196:199], v[58:61]
	v_mfma_f32_16x16x32_bf16 v[58:61], v[164:167], v[200:203], v[58:61]
	v_mfma_f32_16x16x32_bf16 v[46:49], v[152:155], v[222:225], v[46:49]
	v_mfma_f32_16x16x32_bf16 v[46:49], v[156:159], v[226:229], v[46:49]
	v_mfma_f32_16x16x32_bf16 v[42:45], v[160:163], v[222:225], v[42:45]
	v_mfma_f32_16x16x32_bf16 v[42:45], v[164:167], v[226:229], v[42:45]
	v_mfma_f32_16x16x32_bf16 v[30:33], v[152:155], v[230:233], v[30:33]
	v_mfma_f32_16x16x32_bf16 v[30:33], v[156:159], v[234:237], v[30:33]
	v_mfma_f32_16x16x32_bf16 v[26:29], v[160:163], v[230:233], v[26:29]
	v_mfma_f32_16x16x32_bf16 v[26:29], v[164:167], v[234:237], v[26:29]
	v_mfma_f32_16x16x32_bf16 v[14:17], v[152:155], v[238:241], v[14:17]
	v_mfma_f32_16x16x32_bf16 v[14:17], v[156:159], v[242:245], v[14:17]
	v_mfma_f32_16x16x32_bf16 v[10:13], v[160:163], v[238:241], v[10:13]
	v_mfma_f32_16x16x32_bf16 v[10:13], v[164:167], v[242:245], v[10:13]
	s_setprio 0
	s_setprio 1
	v_mfma_f32_16x16x32_bf16 v[54:57], v[180:183], v[196:199], v[54:57]
	v_mfma_f32_16x16x32_bf16 v[54:57], v[184:187], v[200:203], v[54:57]
	v_mfma_f32_16x16x32_bf16 v[50:53], v[188:191], v[196:199], v[50:53]
	v_mfma_f32_16x16x32_bf16 v[50:53], v[192:195], v[200:203], v[50:53]
	v_mfma_f32_16x16x32_bf16 v[38:41], v[180:183], v[222:225], v[38:41]
	v_mfma_f32_16x16x32_bf16 v[38:41], v[184:187], v[226:229], v[38:41]
	v_mfma_f32_16x16x32_bf16 v[34:37], v[188:191], v[222:225], v[34:37]
	v_mfma_f32_16x16x32_bf16 v[34:37], v[192:195], v[226:229], v[34:37]
	v_mfma_f32_16x16x32_bf16 v[22:25], v[180:183], v[230:233], v[22:25]
	v_mfma_f32_16x16x32_bf16 v[22:25], v[184:187], v[234:237], v[22:25]
	v_mfma_f32_16x16x32_bf16 v[18:21], v[188:191], v[230:233], v[18:21]
	v_mfma_f32_16x16x32_bf16 v[18:21], v[192:195], v[234:237], v[18:21]
	v_mfma_f32_16x16x32_bf16 v[6:9], v[180:183], v[238:241], v[6:9]
	v_mfma_f32_16x16x32_bf16 v[6:9], v[184:187], v[242:245], v[6:9]
	s_setprio 2
	s_cbranch_scc0 .Lq4b_1067l
	v_cmp_ne_u32_e64 vcc, s12, 0
	s_cbranch_vccz .Lq4s_1067l

; #define GAS __attribute__((address_space(1)))
; __device__ __forceinline__ u32x4 pack8(f32x4 v0, f32x4 v1) { u32x4 w; w.x = cvt_pk_bf16(v0[0], v0[1]); w.y = cvt_pk_bf16(v0[2], v0[3]); w.z = cvt_pk_bf16(v1[0], v1[1]); w.w = cvt_pk_bf16(v1[2], v1[3]); return w; }
; __device__ __forceinline__ void unpack8(u32x4 w, f32x4& v0, f32x4& v1) { v0 = (f32x4){bflo(w.x), bfhi(w.x), bflo(w.y), bfhi(w.y)}; v1 = (f32x4){bflo(w.z), bfhi(w.z), bflo(w.w), bfhi(w.w)}; }
; #define PG8_BAR __builtin_amdgcn_s_barrier()
;     __device__ __forceinline__ void operator()(const f32x4 (&acc)[2][2][4][2], const Unit& u, int wr, int wc, int fr, int fq) const {
;         const int row0 = u.pm * BM + wr * 64 + fr, col0 = u.pn * BM + wc * 32 + 8 * fq;
;         const bool samp = u.pm >= 32;
;         GAS unsigned* flag = (GAS unsigned*)(flags + 64 * (u.pn * 4 + (u.pm & 3)));
;         if (MODE == 1 && samp) {
;             unsigned spins = 0u;
;             while (__hip_atomic_load(flag, __ATOMIC_RELAXED, __HIP_MEMORY_SCOPE_AGENT) < 8u) { __builtin_amdgcn_s_sleep(2); if (++spins > (1u << 18)) break; }
;             __builtin_amdgcn_fence(__ATOMIC_ACQUIRE, "agent"); asm volatile("s_waitcnt vmcnt(0)" ::: "memory");
;         }
; #pragma unroll
;         for (int ai = 0; ai < 2; ++ai)
; #pragma unroll
;             for (int m = 0; m < 4; ++m) { const size_t r = (size_t)(row0 + ai * HALF + m * 16); const size_t off = r * 2048 + col0; const bf16_t* gp = P + r * NPJ + 2560 + MODE * 2048 + col0;
; #pragma unroll
;                 for (int bj = 0; bj < 2; ++bj) { f32x4 g0, g1; unpack8(*(const GAS u32x4*)(gp + bj * HALF), g0, g1);
;                     f32x4 v0 = g0 * acc[ai][bj][m][0], v1 = g1 * acc[ai][bj][m][1];
;                     if (MODE == 1) { f32x4 t0, t1; unpack8(*(const GAS u32x4*)(T1 + off + bj * HALF), t0, t1); v0 += t0; v1 += t1; }
;                     const u32x4 w = pack8(v0, v1);
;                     if (MODE == 0 && samp) asm volatile("global_store_dwordx4 %0, %1, off sc1\n\ts_nop 1" :: "v"(O + off + bj * HALF), "v"(w) : "memory");
;                     else *(GAS u32x4*)(O + off + bj * HALF) = w; } }
; template <class Epi, class Sched, bool ALIGN_EPI = false, bool SP2 = false>
; __device__ __forceinline__ void gemm_phase(PG8_LAS unsigned char* lds, const Gemm g, const Sched& S, const Epi& E) {
;     ...
;         if constexpr (ALIGN_EPI) { if (wr == 0) PG8_BAR; }
.Lq4s_1067l:
	v_mfma_f32_16x16x32_bf16 v[2:5], v[188:191], v[238:241], v[2:5]
	v_mfma_f32_16x16x32_bf16 v[2:5], v[192:195], v[242:245], v[2:5]
	s_setprio 0
	v_lshl_add_u64 v[144:145], v[144:145], 0, s[86:87]
	v_lshl_add_u64 v[146:147], v[146:147], 0, s[86:87]
	s_mov_b32 s29, s81
	s_cbranch_scc0 .LBB0_1067
.Lpx_1067:
	s_and_b64 vcc, exec, s[12:13]
	s_cbranch_vccz .LBB0_1070
.LBB0_1070:
	s_lshl_b32 s15, s91, 8
	v_or_b32_e32 v144, s15, v150
	v_lshl_add_u32 v146, s90, 8, v1
	v_ashrrev_i32_e32 v145, 31, v144
	v_mov_b64_e32 v[148:149], s[8:9]
	s_movk_i32 s95, 0x3400
	v_mad_i64_i32 v[148:149], s[0:1], v146, s95, v[148:149]
	v_lshlrev_b64 v[144:145], 1, v[144:145]
	v_lshl_add_u64 v[148:149], v[148:149], 0, v[144:145]
	s_movk_i32 s0, 0x1000
	v_add_co_u32_e32 v152, vcc, s0, v148
	s_cmp_gt_i32 s90, 31
	s_nop 0
	v_addc_co_u32_e32 v153, vcc, 0, v149, vcc
	global_load_dwordx4 v[222:225], v[152:153], off offset:1024
	global_load_dwordx4 v[226:229], v[152:153], off offset:1280
	v_add_co_u32_e32 v188, vcc, 0x34000, v152
	s_nop 1
	v_addc_co_u32_e32 v189, vcc, 0, v153, vcc
	global_load_dwordx4 v[230:233], v[188:189], off offset:1024
	global_load_dwordx4 v[234:237], v[188:189], off offset:1280
	v_add_co_u32_e32 v188, vcc, 0x68000, v152
	s_nop 1
	v_addc_co_u32_e32 v189, vcc, 0, v153, vcc
	global_load_dwordx4 v[238:241], v[188:189], off offset:1024
	global_load_dwordx4 v[242:245], v[188:189], off offset:1280
	v_add_co_u32_e32 v188, vcc, 0x9c000, v152
	s_nop 1
	v_addc_co_u32_e32 v189, vcc, 0, v153, vcc
	global_load_dwordx4 v[180:183], v[188:189], off offset:1024
	global_load_dwordx4 v[184:187], v[188:189], off offset:1280
	v_ashrrev_i32_e32 v147, 31, v146
	s_cselect_b64 s[52:53], -1, 0
	s_cmp_lt_i32 s90, 32
	s_cselect_b64 s[54:55], -1, 0
	s_mov_b64 s[42:43], -1
	s_and_b64 vcc, exec, s[54:55]
	v_readlane_b32 s92, v254, 49
	s_mov_b64 s[2:3], 0x1400
	s_mov_b32 s93, 0x18000
	s_waitcnt vmcnt(7)
	s_nop 1
	v_mov_b32_e32 v152, v222
	v_mov_b32_e32 v153, v223
	v_mov_b32_e32 v154, v224
	v_mov_b32_e32 v155, v225
	v_lshlrev_b32_e32 v156, 16, v152
	v_and_b32_e32 v157, 0xffff0000, v152
	v_lshlrev_b32_e32 v152, 16, v153
	v_and_b32_e32 v153, 0xffff0000, v153
	v_lshlrev_b32_e32 v158, 16, v154
	v_and_b32_e32 v159, 0xffff0000, v154
	v_lshlrev_b32_e32 v154, 16, v155
	v_and_b32_e32 v155, 0xffff0000, v155
	v_pk_mul_f32 v[128:129], v[128:129], v[156:157]
	v_pk_mul_f32 v[130:131], v[130:131], v[152:153]
	v_pk_mul_f32 v[152:153], v[126:127], v[154:155]
	v_pk_mul_f32 v[126:127], v[124:125], v[158:159]
	v_cvt_pk_bf16_f32 v124, v128, v129
	v_lshlrev_b64 v[128:129], 12, v[146:147]
	v_lshl_add_u64 v[128:129], s[10:11], 0, v[128:129]
	v_cvt_pk_bf16_f32 v125, v130, v131
	v_cvt_pk_bf16_f32 v126, v126, v127
	v_cvt_pk_bf16_f32 v127, v152, v153
	v_lshl_add_u64 v[128:129], v[128:129], 0, v[144:145]
	s_cbranch_vccz .LBB0_1072
	global_store_dwordx4 v[128:129], v[124:127], off
	s_mov_b64 s[42:43], 0

; #define PG8_STAGE(bufoff, gbase, voff) do { _Pragma("unroll") for (int _i = 0; _i < 2; ++_i) \
;         __builtin_amdgcn_global_load_lds((const unsigned*)((const char*)(gbase) + (voff)[_i]), (PG8_LAS unsigned*)(lds + (bufoff) + ldsw + _i * 8192), 16, 0, AUX_A); } while (0)
; #define PG8_STAGEB(bufoff, gbase, voff) do { _Pragma("unroll") for (int _i = 0; _i < 2; ++_i) \
;         __builtin_amdgcn_global_load_lds((const unsigned*)((const char*)(gbase) + (voff)[_i]), (PG8_LAS unsigned*)(lds + (bufoff) + ldsw + _i * 8192), 16, 0, AUX_B); } while (0)
; #define PG8_LDA(dst, b, h) do { _Pragma("unroll") for (int m = 0; m < 4; ++m) _Pragma("unroll") for (int k = 0; k < 2; ++k) dst[m][k] = *(const PG8_LAS bf16x8*)(lds + PG8_SA(b, h) + aoff + m * 2048 + k * 1024); } while (0)
; #define PG8_LDB(dst, b, h) do { _Pragma("unroll") for (int n = 0; n < 2; ++n) _Pragma("unroll") for (int k = 0; k < 2; ++k) dst[n][k] = *(const PG8_LAS bf16x8*)(lds + PG8_SB(b, h) + boff + n * 2048 + k * 1024); } while (0)
; #define PG8_MMA(ai, bj, At, Bt) do { __builtin_amdgcn_s_setprio(1); _Pragma("unroll") for (int m = 0; m < 4; ++m) _Pragma("unroll") for (int n = 0; n < 2; ++n) _Pragma("unroll") for (int k = 0; k < 2; ++k) \
;         acc[ai][bj][m][n] = __builtin_amdgcn_mfma_f32_16x16x32_bf16(Bt[n][k], At[m][k], acc[ai][bj][m][n], 0, 0, 0); __builtin_amdgcn_s_setprio(0); } while (0)
; #define PG8_WAIT_V(n) asm volatile("s_waitcnt vmcnt(" #n ")" ::: "memory")
; #define PG8_WAIT_L(n) asm volatile("s_waitcnt lgkmcnt(" #n ")" ::: "memory")
; #define PG8_BAR __builtin_amdgcn_s_barrier()
; #define PG8_SCHED __builtin_amdgcn_sched_barrier(0)
; template <class Epi, class Sched, bool ALIGN_EPI = false, bool SP2 = false>
; __device__ __forceinline__ void gemm_phase(PG8_LAS unsigned char* lds, const Gemm g, const Sched& S, const Epi& E) {
;     ...
;             PG8_LDB(B0, 0, 0); PG8_LDB(B1, 0, 1); PG8_SCHED; PG8_LDA(At, 0, 0); PG8_STAGE(PG8_SA(1, 1), a1 + hstep, voffA);
;             PG8_WAIT_V(8); PG8_WAIT_L(0); PG8_BAR; PG8_MMA(0, 0, At, B0); PG8_MMA(0, 1, At, B1); PG8_BAR; PG8_SCHED;
;             PG8_LDA(At, 0, 1); PG8_STAGEB(PG8_SB(0, 0), b2, voffB); PG8_STAGEB(PG8_SB(0, 1), b2 + hstep, voffB); PG8_STAGE(PG8_SA(0, 0), a2, voffA);
;             PG8_WAIT_V(8); PG8_WAIT_L(0); PG8_BAR; PG8_MMA(1, 0, At, B0); PG8_MMA(1, 1, At, B1); PG8_BAR; PG8_SCHED;
.Lpk_1157:
	s_add_i32 s81, s29, 2
	s_cmp_lt_u32 s29, 14
	s_cselect_b32 s0, 0, -16
	s_add_i32 s0, s81, s0
	s_ashr_i32 s1, s0, 31
	s_lshl_b64 s[0:1], s[0:1], 7
	s_add_u32 s2, s52, s0
	s_addc_u32 s46, s53, s1
	s_add_u32 s0, s50, s0
	s_addc_u32 s1, s51, s1
	s_cmp_eq_u32 s29, 14
	s_cselect_b32 s59, s19, s46
	s_cselect_b32 s58, s39, s2
	s_cselect_b32 s61, s92, s1
	s_cselect_b32 s60, s93, s0
	s_add_i32 s2, 0, 0x10000
	s_add_i32 s94, s2, s70
	s_add_i32 s46, 0, 0x14000
	s_add_i32 m0, s71, 0xc000
	s_add_i32 s84, s71, 0xe000
	s_add_i32 s95, s94, 0x2000
	s_add_u32 s62, s60, 0x40000
	s_addc_u32 s63, s61, 0
	s_add_i32 s96, s46, s70
	v_add_u32_e32 v162, s2, v99
	v_add_u32_e32 v166, s46, v99
	s_add_i32 s97, s96, 0x2000
	s_add_i32 vcc_lo, 0, 0x18000
	s_add_i32 vcc_hi, 0, 0x1c000
	ds_read_b128 v[148:151], v162
	ds_read_b128 v[154:157], v162 offset:1024
	ds_read_b128 v[158:161], v162 offset:2048
	ds_read_b128 v[162:165], v162 offset:3072
	ds_read_b128 v[180:183], v166
	ds_read_b128 v[184:187], v166 offset:1024
	ds_read_b128 v[188:191], v166 offset:2048
	ds_read_b128 v[192:195], v166 offset:3072
	s_add_u32 s56, s58, 0x40000
	s_addc_u32 s57, s59, 0
	s_add_i32 s1, vcc_lo, s70
	s_add_i32 s0, s1, 0x2000
	s_add_u32 s54, s60, 0x40080
	s_addc_u32 s55, s61, 0
	s_add_i32 s47, vcc_hi, s70
	s_add_i32 s46, s47, 0x2000
	s_cmp_gt_u32 s29, 13
	ds_read_b128 v[196:199], v153
	ds_read_b128 v[200:203], v153 offset:1024
	ds_read_b128 v[222:225], v153 offset:2048
	ds_read_b128 v[226:229], v153 offset:3072
	ds_read_b128 v[230:233], v153 offset:4096
	ds_read_b128 v[234:237], v153 offset:5120
	ds_read_b128 v[238:241], v153 offset:6144
	ds_read_b128 v[242:245], v153 offset:7168
	global_load_lds_dwordx4 v[146:147], off
	s_mov_b32 m0, s84
	s_nop 0
	global_load_lds_dwordx4 v[144:145], off
	s_waitcnt vmcnt(8)
	s_waitcnt lgkmcnt(0)
	s_setprio 1
	s_barrier
	v_mfma_f32_16x16x32_bf16 v[128:131], v[148:151], v[196:199], 0
	v_mfma_f32_16x16x32_bf16 v[128:131], v[154:157], v[200:203], v[128:131]
	v_mfma_f32_16x16x32_bf16 v[124:127], v[158:161], v[196:199], 0
	v_mfma_f32_16x16x32_bf16 v[124:127], v[162:165], v[200:203], v[124:127]
	v_mfma_f32_16x16x32_bf16 v[112:115], v[148:151], v[222:225], 0
	v_mfma_f32_16x16x32_bf16 v[112:115], v[154:157], v[226:229], v[112:115]
	v_mfma_f32_16x16x32_bf16 v[108:111], v[158:161], v[222:225], 0
	v_mfma_f32_16x16x32_bf16 v[108:111], v[162:165], v[226:229], v[108:111]
	v_mfma_f32_16x16x32_bf16 v[94:97], v[148:151], v[230:233], 0
	v_mfma_f32_16x16x32_bf16 v[94:97], v[154:157], v[234:237], v[94:97]
	v_mfma_f32_16x16x32_bf16 v[90:93], v[158:161], v[230:233], 0
	v_mfma_f32_16x16x32_bf16 v[90:93], v[162:165], v[234:237], v[90:93]
	v_mfma_f32_16x16x32_bf16 v[78:81], v[148:151], v[238:241], 0
	v_mfma_f32_16x16x32_bf16 v[78:81], v[154:157], v[242:245], v[78:81]
	v_mfma_f32_16x16x32_bf16 v[74:77], v[158:161], v[238:241], 0
	v_mfma_f32_16x16x32_bf16 v[74:77], v[162:165], v[242:245], v[74:77]
	s_setprio 0
	s_setprio 1
	v_mfma_f32_16x16x32_bf16 v[120:123], v[180:183], v[196:199], 0
	v_mfma_f32_16x16x32_bf16 v[120:123], v[184:187], v[200:203], v[120:123]
	v_mfma_f32_16x16x32_bf16 v[116:119], v[188:191], v[196:199], 0
	v_mfma_f32_16x16x32_bf16 v[116:119], v[192:195], v[200:203], v[116:119]
	v_mfma_f32_16x16x32_bf16 v[104:107], v[180:183], v[222:225], 0
	v_mfma_f32_16x16x32_bf16 v[104:107], v[184:187], v[226:229], v[104:107]
	v_mfma_f32_16x16x32_bf16 v[100:103], v[188:191], v[222:225], 0
	v_mfma_f32_16x16x32_bf16 v[100:103], v[192:195], v[226:229], v[100:103]
	v_mfma_f32_16x16x32_bf16 v[86:89], v[180:183], v[230:233], 0
	v_mfma_f32_16x16x32_bf16 v[86:89], v[184:187], v[234:237], v[86:89]
	v_mfma_f32_16x16x32_bf16 v[82:85], v[188:191], v[230:233], 0
	v_mfma_f32_16x16x32_bf16 v[82:85], v[192:195], v[234:237], v[82:85]
	v_mfma_f32_16x16x32_bf16 v[70:73], v[180:183], v[238:241], 0
	v_mfma_f32_16x16x32_bf16 v[70:73], v[184:187], v[242:245], v[70:73]
	s_setprio 2
	s_barrier
	v_mfma_f32_16x16x32_bf16 v[66:69], v[188:191], v[238:241], 0
	v_mfma_f32_16x16x32_bf16 v[66:69], v[192:195], v[242:245], v[66:69]
	s_setprio 0
	s_mov_b32 m0, s94
	v_lshl_add_u64 v[166:167], s[60:61], 0, v[136:137]
	ds_read_b128 v[196:199], v153 offset:16384
	ds_read_b128 v[200:203], v153 offset:17408
	ds_read_b128 v[222:225], v153 offset:18432
	ds_read_b128 v[226:229], v153 offset:19456
	ds_read_b128 v[230:233], v153 offset:20480
	ds_read_b128 v[234:237], v153 offset:21504
	ds_read_b128 v[238:241], v153 offset:22528
	ds_read_b128 v[242:245], v153 offset:23552
	global_load_lds_dwordx4 v[166:167], off
	v_lshl_add_u64 v[168:169], s[60:61], 0, v[132:133]
	s_mov_b32 m0, s95
	v_lshl_add_u64 v[172:173], s[62:63], 0, v[136:137]
	global_load_lds_dwordx4 v[168:169], off
	s_mov_b32 m0, s96
	v_lshl_add_u64 v[212:213], s[58:59], 0, v[134:135]
	global_load_lds_dwordx4 v[172:173], off
	v_lshl_add_u64 v[172:173], s[62:63], 0, v[132:133]
	s_mov_b32 m0, s97
	s_nop 0
	global_load_lds_dwordx4 v[172:173], off
	v_lshl_add_u64 v[172:173], s[58:59], 0, v[138:139]
	s_mov_b32 m0, s71
	s_nop 0
	global_load_lds_dwordx4 v[172:173], off
	s_mov_b32 m0, s75
	s_nop 0
	global_load_lds_dwordx4 v[212:213], off
	s_waitcnt vmcnt(8)
	s_waitcnt lgkmcnt(0)
	s_setprio 1
	s_barrier
; #define PG8_STAGE(bufoff, gbase, voff) do { _Pragma("unroll") for (int _i = 0; _i < 2; ++_i) \
;         __builtin_amdgcn_global_load_lds((const unsigned*)((const char*)(gbase) + (voff)[_i]), (PG8_LAS unsigned*)(lds + (bufoff) + ldsw + _i * 8192), 16, 0, AUX_A); } while (0)
; #define PG8_LDA(dst, b, h) do { _Pragma("unroll") for (int m = 0; m < 4; ++m) _Pragma("unroll") for (int k = 0; k < 2; ++k) dst[m][k] = *(const PG8_LAS bf16x8*)(lds + PG8_SA(b, h) + aoff + m * 2048 + k * 1024); } while (0)
; #define PG8_LDB(dst, b, h) do { _Pragma("unroll") for (int n = 0; n < 2; ++n) _Pragma("unroll") for (int k = 0; k < 2; ++k) dst[n][k] = *(const PG8_LAS bf16x8*)(lds + PG8_SB(b, h) + boff + n * 2048 + k * 1024); } while (0)
; #define PG8_MMA(ai, bj, At, Bt) do { __builtin_amdgcn_s_setprio(1); _Pragma("unroll") for (int m = 0; m < 4; ++m) _Pragma("unroll") for (int n = 0; n < 2; ++n) _Pragma("unroll") for (int k = 0; k < 2; ++k) \
;         acc[ai][bj][m][n] = __builtin_amdgcn_mfma_f32_16x16x32_bf16(Bt[n][k], At[m][k], acc[ai][bj][m][n], 0, 0, 0); __builtin_amdgcn_s_setprio(0); } while (0)
; #define PG8_WAIT_V(n) asm volatile("s_waitcnt vmcnt(" #n ")" ::: "memory")
; #define PG8_WAIT_L(n) asm volatile("s_waitcnt lgkmcnt(" #n ")" ::: "memory")
; #define PG8_BAR __builtin_amdgcn_s_barrier()
; #define PG8_SCHED __builtin_amdgcn_sched_barrier(0)
; template <class Epi, class Sched, bool ALIGN_EPI = false, bool SP2 = false>
; __device__ __forceinline__ void gemm_phase(PG8_LAS unsigned char* lds, const Gemm g, const Sched& S, const Epi& E) {
;     ...
;             PG8_WAIT_V(8); PG8_WAIT_L(0); PG8_BAR; PG8_MMA(1, 0, At, B0); PG8_MMA(1, 1, At, B1); PG8_BAR; PG8_SCHED;
;             PG8_LDB(B0, 1, 0); PG8_LDB(B1, 1, 1); PG8_SCHED; PG8_LDA(At, 1, 0); PG8_STAGE(PG8_SA(0, 1), a2 + hstep, voffA);
;             PG8_WAIT_V(8); PG8_WAIT_L(0); PG8_BAR; PG8_MMA(0, 0, At, B0); PG8_MMA(0, 1, At, B1); PG8_BAR; PG8_SCHED;
	v_mfma_f32_16x16x32_bf16 v[62:65], v[148:151], v[196:199], 0
	v_mfma_f32_16x16x32_bf16 v[62:65], v[154:157], v[200:203], v[62:65]
	v_mfma_f32_16x16x32_bf16 v[58:61], v[158:161], v[196:199], 0
	v_mfma_f32_16x16x32_bf16 v[58:61], v[162:165], v[200:203], v[58:61]
	v_mfma_f32_16x16x32_bf16 v[46:49], v[148:151], v[222:225], 0
	v_mfma_f32_16x16x32_bf16 v[46:49], v[154:157], v[226:229], v[46:49]
	v_mfma_f32_16x16x32_bf16 v[42:45], v[158:161], v[222:225], 0
	v_mfma_f32_16x16x32_bf16 v[42:45], v[162:165], v[226:229], v[42:45]
	v_mfma_f32_16x16x32_bf16 v[30:33], v[148:151], v[230:233], 0
	v_mfma_f32_16x16x32_bf16 v[30:33], v[154:157], v[234:237], v[30:33]
	v_mfma_f32_16x16x32_bf16 v[26:29], v[158:161], v[230:233], 0
	v_mfma_f32_16x16x32_bf16 v[26:29], v[162:165], v[234:237], v[26:29]
	v_mfma_f32_16x16x32_bf16 v[14:17], v[148:151], v[238:241], 0
	v_mfma_f32_16x16x32_bf16 v[14:17], v[154:157], v[242:245], v[14:17]
	v_mfma_f32_16x16x32_bf16 v[10:13], v[158:161], v[238:241], 0
	v_mfma_f32_16x16x32_bf16 v[10:13], v[162:165], v[242:245], v[10:13]
	s_setprio 0
	s_setprio 1
	v_mfma_f32_16x16x32_bf16 v[54:57], v[180:183], v[196:199], 0
	v_mfma_f32_16x16x32_bf16 v[54:57], v[184:187], v[200:203], v[54:57]
	v_mfma_f32_16x16x32_bf16 v[50:53], v[188:191], v[196:199], 0
	v_mfma_f32_16x16x32_bf16 v[50:53], v[192:195], v[200:203], v[50:53]
	v_mfma_f32_16x16x32_bf16 v[38:41], v[180:183], v[222:225], 0
	v_mfma_f32_16x16x32_bf16 v[38:41], v[184:187], v[226:229], v[38:41]
	v_mfma_f32_16x16x32_bf16 v[34:37], v[188:191], v[222:225], 0
	v_mfma_f32_16x16x32_bf16 v[34:37], v[192:195], v[226:229], v[34:37]
	v_mfma_f32_16x16x32_bf16 v[22:25], v[180:183], v[230:233], 0
	v_mfma_f32_16x16x32_bf16 v[22:25], v[184:187], v[234:237], v[22:25]
	v_mfma_f32_16x16x32_bf16 v[18:21], v[188:191], v[230:233], 0
	v_mfma_f32_16x16x32_bf16 v[18:21], v[192:195], v[234:237], v[18:21]
	v_mfma_f32_16x16x32_bf16 v[6:9], v[180:183], v[238:241], 0
	v_mfma_f32_16x16x32_bf16 v[6:9], v[184:187], v[242:245], v[6:9]
	s_setprio 2
	s_barrier
	v_mfma_f32_16x16x32_bf16 v[2:5], v[188:191], v[238:241], 0
	v_mfma_f32_16x16x32_bf16 v[2:5], v[192:195], v[242:245], v[2:5]
	s_setprio 0
	v_add_u32_e32 v162, vcc_lo, v99
	v_add_u32_e32 v192, vcc_hi, v99
	ds_read_b128 v[148:151], v162
	ds_read_b128 v[154:157], v162 offset:1024
	ds_read_b128 v[158:161], v162 offset:2048
	ds_read_b128 v[162:165], v162 offset:3072
	ds_read_b128 v[180:183], v192
	ds_read_b128 v[184:187], v192 offset:1024
	ds_read_b128 v[188:191], v192 offset:2048
	ds_read_b128 v[192:195], v192 offset:3072
	s_mov_b32 m0, s78
	v_lshl_add_u64 v[246:247], s[56:57], 0, v[138:139]
	ds_read_b128 v[196:199], v153 offset:32768
	ds_read_b128 v[200:203], v153 offset:33792
	ds_read_b128 v[222:225], v153 offset:34816
	ds_read_b128 v[226:229], v153 offset:35840
	ds_read_b128 v[230:233], v153 offset:36864
	ds_read_b128 v[234:237], v153 offset:37888
	ds_read_b128 v[238:241], v153 offset:38912
	ds_read_b128 v[242:245], v153 offset:39936
	global_load_lds_dwordx4 v[246:247], off
	v_lshl_add_u64 v[246:247], s[56:57], 0, v[134:135]
	s_mov_b32 m0, s82
	s_nop 0
	global_load_lds_dwordx4 v[246:247], off
	s_waitcnt vmcnt(8)
	s_waitcnt lgkmcnt(0)
	s_setprio 1
	s_barrier
	v_mfma_f32_16x16x32_bf16 v[128:131], v[148:151], v[196:199], v[128:131]
	v_mfma_f32_16x16x32_bf16 v[128:131], v[154:157], v[200:203], v[128:131]
	v_mfma_f32_16x16x32_bf16 v[124:127], v[158:161], v[196:199], v[124:127]
	v_mfma_f32_16x16x32_bf16 v[124:127], v[162:165], v[200:203], v[124:127]
	v_mfma_f32_16x16x32_bf16 v[112:115], v[148:151], v[222:225], v[112:115]
	v_mfma_f32_16x16x32_bf16 v[112:115], v[154:157], v[226:229], v[112:115]
	v_mfma_f32_16x16x32_bf16 v[108:111], v[158:161], v[222:225], v[108:111]
	v_mfma_f32_16x16x32_bf16 v[108:111], v[162:165], v[226:229], v[108:111]
	v_mfma_f32_16x16x32_bf16 v[94:97], v[148:151], v[230:233], v[94:97]
	v_mfma_f32_16x16x32_bf16 v[94:97], v[154:157], v[234:237], v[94:97]
	v_mfma_f32_16x16x32_bf16 v[90:93], v[158:161], v[230:233], v[90:93]
	v_mfma_f32_16x16x32_bf16 v[90:93], v[162:165], v[234:237], v[90:93]
	v_mfma_f32_16x16x32_bf16 v[78:81], v[148:151], v[238:241], v[78:81]
	v_mfma_f32_16x16x32_bf16 v[78:81], v[154:157], v[242:245], v[78:81]
	v_mfma_f32_16x16x32_bf16 v[74:77], v[158:161], v[238:241], v[74:77]
	v_mfma_f32_16x16x32_bf16 v[74:77], v[162:165], v[242:245], v[74:77]
	s_setprio 0
	s_setprio 1
	v_mfma_f32_16x16x32_bf16 v[120:123], v[180:183], v[196:199], v[120:123]
	v_mfma_f32_16x16x32_bf16 v[120:123], v[184:187], v[200:203], v[120:123]
	v_mfma_f32_16x16x32_bf16 v[116:119], v[188:191], v[196:199], v[116:119]
	v_mfma_f32_16x16x32_bf16 v[116:119], v[192:195], v[200:203], v[116:119]
	v_mfma_f32_16x16x32_bf16 v[104:107], v[180:183], v[222:225], v[104:107]
	v_mfma_f32_16x16x32_bf16 v[104:107], v[184:187], v[226:229], v[104:107]
	v_mfma_f32_16x16x32_bf16 v[100:103], v[188:191], v[222:225], v[100:103]
	v_mfma_f32_16x16x32_bf16 v[100:103], v[192:195], v[226:229], v[100:103]
	v_mfma_f32_16x16x32_bf16 v[86:89], v[180:183], v[230:233], v[86:89]
	v_mfma_f32_16x16x32_bf16 v[86:89], v[184:187], v[234:237], v[86:89]
	v_mfma_f32_16x16x32_bf16 v[82:85], v[188:191], v[230:233], v[82:85]
	v_mfma_f32_16x16x32_bf16 v[82:85], v[192:195], v[234:237], v[82:85]
	v_mfma_f32_16x16x32_bf16 v[70:73], v[180:183], v[238:241], v[70:73]
	v_mfma_f32_16x16x32_bf16 v[70:73], v[184:187], v[242:245], v[70:73]
	s_setprio 2
	s_barrier
; #define PG8_STAGE(bufoff, gbase, voff) do { _Pragma("unroll") for (int _i = 0; _i < 2; ++_i) \
;         __builtin_amdgcn_global_load_lds((const unsigned*)((const char*)(gbase) + (voff)[_i]), (PG8_LAS unsigned*)(lds + (bufoff) + ldsw + _i * 8192), 16, 0, AUX_A); } while (0)
; #define PG8_STAGEB(bufoff, gbase, voff) do { _Pragma("unroll") for (int _i = 0; _i < 2; ++_i) \
;         __builtin_amdgcn_global_load_lds((const unsigned*)((const char*)(gbase) + (voff)[_i]), (PG8_LAS unsigned*)(lds + (bufoff) + ldsw + _i * 8192), 16, 0, AUX_B); } while (0)
; #define PG8_LDA(dst, b, h) do { _Pragma("unroll") for (int m = 0; m < 4; ++m) _Pragma("unroll") for (int k = 0; k < 2; ++k) dst[m][k] = *(const PG8_LAS bf16x8*)(lds + PG8_SA(b, h) + aoff + m * 2048 + k * 1024); } while (0)
; #define PG8_MMA(ai, bj, At, Bt) do { __builtin_amdgcn_s_setprio(1); _Pragma("unroll") for (int m = 0; m < 4; ++m) _Pragma("unroll") for (int n = 0; n < 2; ++n) _Pragma("unroll") for (int k = 0; k < 2; ++k) \
;         acc[ai][bj][m][n] = __builtin_amdgcn_mfma_f32_16x16x32_bf16(Bt[n][k], At[m][k], acc[ai][bj][m][n], 0, 0, 0); __builtin_amdgcn_s_setprio(0); } while (0)
; #define PG8_WAIT_V(n) asm volatile("s_waitcnt vmcnt(" #n ")" ::: "memory")
; #define PG8_WAIT_L(n) asm volatile("s_waitcnt lgkmcnt(" #n ")" ::: "memory")
; #define PG8_BAR __builtin_amdgcn_s_barrier()
; #define PG8_SCHED __builtin_amdgcn_sched_barrier(0)
; template <class Epi, class Sched, bool ALIGN_EPI = false, bool SP2 = false>
; __device__ __forceinline__ void gemm_phase(PG8_LAS unsigned char* lds, const Gemm g, const Sched& S, const Epi& E) {
;     ...
;             PG8_LDA(At, 1, 1); PG8_STAGEB(PG8_SB(1, 0), b3, voffB); PG8_STAGEB(PG8_SB(1, 1), b3 + hstep, voffB); PG8_STAGE(PG8_SA(1, 0), a3, voffA);
;             PG8_WAIT_V(8); PG8_WAIT_L(0); PG8_BAR; PG8_MMA(1, 0, At, B0); PG8_MMA(1, 1, At, B1); PG8_BAR; PG8_SCHED;
	v_mfma_f32_16x16x32_bf16 v[66:69], v[188:191], v[238:241], v[66:69]
	v_mfma_f32_16x16x32_bf16 v[66:69], v[192:195], v[242:245], v[66:69]
	s_setprio 0
	s_mov_b32 m0, s1
	v_lshl_add_u64 v[166:167], v[166:167], 0, s[76:77]
	ds_read_b128 v[196:199], v153 offset:49152
	ds_read_b128 v[200:203], v153 offset:50176
	ds_read_b128 v[222:225], v153 offset:51200
	ds_read_b128 v[226:229], v153 offset:52224
	ds_read_b128 v[230:233], v153 offset:53248
	ds_read_b128 v[234:237], v153 offset:54272
	ds_read_b128 v[238:241], v153 offset:55296
	ds_read_b128 v[242:245], v153 offset:56320
	global_load_lds_dwordx4 v[166:167], off
	v_lshl_add_u64 v[166:167], v[168:169], 0, s[76:77]
	s_mov_b32 m0, s0
	s_nop 0
	global_load_lds_dwordx4 v[166:167], off
	v_lshl_add_u64 v[166:167], s[54:55], 0, v[136:137]
	s_mov_b32 m0, s47
	s_nop 0
	global_load_lds_dwordx4 v[166:167], off
	v_lshl_add_u64 v[166:167], s[54:55], 0, v[132:133]
	s_mov_b32 m0, s46
	s_nop 0
	global_load_lds_dwordx4 v[166:167], off
	v_lshl_add_u64 v[166:167], v[172:173], 0, s[76:77]
	s_mov_b32 m0, s83
	s_nop 0
	global_load_lds_dwordx4 v[166:167], off
	v_lshl_add_u64 v[166:167], v[212:213], 0, s[76:77]
	s_mov_b32 m0, s88
	s_nop 0
	global_load_lds_dwordx4 v[166:167], off
	s_waitcnt vmcnt(8)
	s_waitcnt lgkmcnt(0)
	s_setprio 1
	s_barrier
	v_mfma_f32_16x16x32_bf16 v[62:65], v[148:151], v[196:199], v[62:65]
	v_mfma_f32_16x16x32_bf16 v[62:65], v[154:157], v[200:203], v[62:65]
	v_mfma_f32_16x16x32_bf16 v[58:61], v[158:161], v[196:199], v[58:61]
	v_mfma_f32_16x16x32_bf16 v[58:61], v[162:165], v[200:203], v[58:61]
	v_mfma_f32_16x16x32_bf16 v[46:49], v[148:151], v[222:225], v[46:49]
	v_mfma_f32_16x16x32_bf16 v[46:49], v[154:157], v[226:229], v[46:49]
	v_mfma_f32_16x16x32_bf16 v[42:45], v[158:161], v[222:225], v[42:45]
	v_mfma_f32_16x16x32_bf16 v[42:45], v[162:165], v[226:229], v[42:45]
	v_mfma_f32_16x16x32_bf16 v[30:33], v[148:151], v[230:233], v[30:33]
	v_mfma_f32_16x16x32_bf16 v[30:33], v[154:157], v[234:237], v[30:33]
	v_mfma_f32_16x16x32_bf16 v[26:29], v[158:161], v[230:233], v[26:29]
	v_mfma_f32_16x16x32_bf16 v[26:29], v[162:165], v[234:237], v[26:29]
	v_mfma_f32_16x16x32_bf16 v[14:17], v[148:151], v[238:241], v[14:17]
	v_mfma_f32_16x16x32_bf16 v[14:17], v[154:157], v[242:245], v[14:17]
	v_mfma_f32_16x16x32_bf16 v[10:13], v[158:161], v[238:241], v[10:13]
	v_mfma_f32_16x16x32_bf16 v[10:13], v[162:165], v[242:245], v[10:13]
	s_setprio 0
	s_setprio 1
	v_mfma_f32_16x16x32_bf16 v[54:57], v[180:183], v[196:199], v[54:57]
	v_mfma_f32_16x16x32_bf16 v[54:57], v[184:187], v[200:203], v[54:57]
	v_mfma_f32_16x16x32_bf16 v[50:53], v[188:191], v[196:199], v[50:53]
	v_mfma_f32_16x16x32_bf16 v[50:53], v[192:195], v[200:203], v[50:53]
	v_mfma_f32_16x16x32_bf16 v[38:41], v[180:183], v[222:225], v[38:41]
	v_mfma_f32_16x16x32_bf16 v[38:41], v[184:187], v[226:229], v[38:41]
	v_mfma_f32_16x16x32_bf16 v[34:37], v[188:191], v[222:225], v[34:37]
	v_mfma_f32_16x16x32_bf16 v[34:37], v[192:195], v[226:229], v[34:37]
	v_mfma_f32_16x16x32_bf16 v[22:25], v[180:183], v[230:233], v[22:25]
	v_mfma_f32_16x16x32_bf16 v[22:25], v[184:187], v[234:237], v[22:25]
	v_mfma_f32_16x16x32_bf16 v[18:21], v[188:191], v[230:233], v[18:21]
	v_mfma_f32_16x16x32_bf16 v[18:21], v[192:195], v[234:237], v[18:21]
	v_mfma_f32_16x16x32_bf16 v[6:9], v[180:183], v[238:241], v[6:9]
	v_mfma_f32_16x16x32_bf16 v[6:9], v[184:187], v[242:245], v[6:9]
	s_setprio 2
	s_cbranch_scc0 .Lq4b_1157p
	v_cmp_ne_u32_e64 vcc, s16, 0
	s_cbranch_vccz .Lq4s_1157p

; #define PG8_STAGE(bufoff, gbase, voff) do { _Pragma("unroll") for (int _i = 0; _i < 2; ++_i) \
;         __builtin_amdgcn_global_load_lds((const unsigned*)((const char*)(gbase) + (voff)[_i]), (PG8_LAS unsigned*)(lds + (bufoff) + ldsw + _i * 8192), 16, 0, AUX_A); } while (0)
; #define PG8_STAGEB(bufoff, gbase, voff) do { _Pragma("unroll") for (int _i = 0; _i < 2; ++_i) \
;         __builtin_amdgcn_global_load_lds((const unsigned*)((const char*)(gbase) + (voff)[_i]), (PG8_LAS unsigned*)(lds + (bufoff) + ldsw + _i * 8192), 16, 0, AUX_B); } while (0)
; #define PG8_LDA(dst, b, h) do { _Pragma("unroll") for (int m = 0; m < 4; ++m) _Pragma("unroll") for (int k = 0; k < 2; ++k) dst[m][k] = *(const PG8_LAS bf16x8*)(lds + PG8_SA(b, h) + aoff + m * 2048 + k * 1024); } while (0)
; #define PG8_LDB(dst, b, h) do { _Pragma("unroll") for (int n = 0; n < 2; ++n) _Pragma("unroll") for (int k = 0; k < 2; ++k) dst[n][k] = *(const PG8_LAS bf16x8*)(lds + PG8_SB(b, h) + boff + n * 2048 + k * 1024); } while (0)
; #define PG8_WAIT_V(n) asm volatile("s_waitcnt vmcnt(" #n ")" ::: "memory")
; #define PG8_WAIT_L(n) asm volatile("s_waitcnt lgkmcnt(" #n ")" ::: "memory")
; #define PG8_BAR __builtin_amdgcn_s_barrier()
; template <class Epi, class Sched, bool ALIGN_EPI = false, bool SP2 = false>
; __device__ __forceinline__ void gemm_phase(PG8_LAS unsigned char* lds, const Gemm g, const Sched& S, const Epi& E) {
;     ...
;         for (int t = 0; t < nt; t += 2) {
;             const bool last = (t == nt - 2);
;             const char* a1 = PG8_KP(cA, t + 1, rot, nt);
;             const char* a2 = last ? nAr : PG8_KP(cA, t + 2, rot, nt); const char* b2 = last ? nBr : PG8_KP(cB, t + 2, rot, nt);
;             const char* a3 = a2 + kstep; const char* b3 = b2 + kstep;
;             if (last && has_next) S.a_ready(nxt);
;             if constexpr (SP2) {
;             PG8_LDB(B0, 0, 0); PG8_LDB(B1, 0, 1); PG8_SCHED; PG8_LDA(At, 0, 0); PG8_STAGE(PG8_SA(1, 1), a1 + hstep, voffA);
;             PG8_WAIT_V(8); PG8_WAIT_L(0); PG8_BAR; PG8_MMA(0, 0, At, B0); PG8_MMA(0, 1, At, B1); PG8_BAR; PG8_SCHED;
;             PG8_LDA(At, 0, 1); PG8_STAGEB(PG8_SB(0, 0), b2, voffB); PG8_STAGEB(PG8_SB(0, 1), b2 + hstep, voffB); PG8_STAGE(PG8_SA(0, 0), a2, voffA);
;             PG8_WAIT_V(8); PG8_WAIT_L(0); PG8_BAR; PG8_MMA(1, 0, At, B0); PG8_MMA(1, 1, At, B1); PG8_BAR; PG8_SCHED;
.LBB0_1157:
	s_add_i32 s81, s29, 2
	s_cmp_lt_u32 s29, 14
	s_cselect_b32 s0, 0, -16
	s_add_i32 s0, s81, s0
	s_ashr_i32 s1, s0, 31
	s_lshl_b64 s[0:1], s[0:1], 7
	s_add_u32 s2, s52, s0
	s_addc_u32 s46, s53, s1
	s_add_u32 s0, s50, s0
	s_addc_u32 s1, s51, s1
	s_cmp_eq_u32 s29, 14
	s_cselect_b32 s59, s19, s46
	s_cselect_b32 s58, s39, s2
	s_cselect_b32 s61, s92, s1
	s_cselect_b32 s60, s93, s0
	s_add_i32 s2, 0, 0x10000
	s_add_i32 s94, s2, s70
	s_add_i32 s46, 0, 0x14000
	s_add_i32 m0, s71, 0xc000
	s_add_i32 s84, s71, 0xe000
	s_add_i32 s95, s94, 0x2000
	s_add_u32 s62, s60, 0x40000
	s_addc_u32 s63, s61, 0
	s_add_i32 s96, s46, s70
	v_add_u32_e32 v162, s2, v99
	v_add_u32_e32 v166, s46, v99
	s_add_i32 s97, s96, 0x2000
	s_add_i32 vcc_lo, 0, 0x18000
	s_add_i32 vcc_hi, 0, 0x1c000
	ds_read_b128 v[148:151], v162
	ds_read_b128 v[154:157], v162 offset:1024
	ds_read_b128 v[158:161], v162 offset:2048
	ds_read_b128 v[162:165], v162 offset:3072
	ds_read_b128 v[180:183], v166
	ds_read_b128 v[184:187], v166 offset:1024
	ds_read_b128 v[188:191], v166 offset:2048
	ds_read_b128 v[192:195], v166 offset:3072
	s_add_u32 s56, s58, 0x40000
	s_addc_u32 s57, s59, 0
	s_add_i32 s1, vcc_lo, s70
	s_add_i32 s0, s1, 0x2000
	s_add_u32 s54, s60, 0x40080
	s_addc_u32 s55, s61, 0
	s_add_i32 s47, vcc_hi, s70
	s_add_i32 s46, s47, 0x2000
	s_cmp_gt_u32 s29, 13
	ds_read_b128 v[196:199], v153
	ds_read_b128 v[200:203], v153 offset:1024
	ds_read_b128 v[222:225], v153 offset:2048
	ds_read_b128 v[226:229], v153 offset:3072
	ds_read_b128 v[230:233], v153 offset:4096
	ds_read_b128 v[234:237], v153 offset:5120
	ds_read_b128 v[238:241], v153 offset:6144
	ds_read_b128 v[242:245], v153 offset:7168
	global_load_lds_dwordx4 v[146:147], off
	s_mov_b32 m0, s84
	s_nop 0
	global_load_lds_dwordx4 v[144:145], off
	s_waitcnt vmcnt(8)
	s_waitcnt lgkmcnt(0)
	s_setprio 1
	s_barrier
	v_mfma_f32_16x16x32_bf16 v[128:131], v[148:151], v[196:199], v[128:131]
	v_mfma_f32_16x16x32_bf16 v[128:131], v[154:157], v[200:203], v[128:131]
	v_mfma_f32_16x16x32_bf16 v[124:127], v[158:161], v[196:199], v[124:127]
	v_mfma_f32_16x16x32_bf16 v[124:127], v[162:165], v[200:203], v[124:127]
	v_mfma_f32_16x16x32_bf16 v[112:115], v[148:151], v[222:225], v[112:115]
	v_mfma_f32_16x16x32_bf16 v[112:115], v[154:157], v[226:229], v[112:115]
	v_mfma_f32_16x16x32_bf16 v[108:111], v[158:161], v[222:225], v[108:111]
	v_mfma_f32_16x16x32_bf16 v[108:111], v[162:165], v[226:229], v[108:111]
	v_mfma_f32_16x16x32_bf16 v[94:97], v[148:151], v[230:233], v[94:97]
	v_mfma_f32_16x16x32_bf16 v[94:97], v[154:157], v[234:237], v[94:97]
	v_mfma_f32_16x16x32_bf16 v[90:93], v[158:161], v[230:233], v[90:93]
	v_mfma_f32_16x16x32_bf16 v[90:93], v[162:165], v[234:237], v[90:93]
	v_mfma_f32_16x16x32_bf16 v[78:81], v[148:151], v[238:241], v[78:81]
	v_mfma_f32_16x16x32_bf16 v[78:81], v[154:157], v[242:245], v[78:81]
	v_mfma_f32_16x16x32_bf16 v[74:77], v[158:161], v[238:241], v[74:77]
	v_mfma_f32_16x16x32_bf16 v[74:77], v[162:165], v[242:245], v[74:77]
	s_setprio 0
	s_setprio 1
	v_mfma_f32_16x16x32_bf16 v[120:123], v[180:183], v[196:199], v[120:123]
	v_mfma_f32_16x16x32_bf16 v[120:123], v[184:187], v[200:203], v[120:123]
	v_mfma_f32_16x16x32_bf16 v[116:119], v[188:191], v[196:199], v[116:119]
	v_mfma_f32_16x16x32_bf16 v[116:119], v[192:195], v[200:203], v[116:119]
	v_mfma_f32_16x16x32_bf16 v[104:107], v[180:183], v[222:225], v[104:107]
	v_mfma_f32_16x16x32_bf16 v[104:107], v[184:187], v[226:229], v[104:107]
	v_mfma_f32_16x16x32_bf16 v[100:103], v[188:191], v[222:225], v[100:103]
	v_mfma_f32_16x16x32_bf16 v[100:103], v[192:195], v[226:229], v[100:103]
	v_mfma_f32_16x16x32_bf16 v[86:89], v[180:183], v[230:233], v[86:89]
	v_mfma_f32_16x16x32_bf16 v[86:89], v[184:187], v[234:237], v[86:89]
	v_mfma_f32_16x16x32_bf16 v[82:85], v[188:191], v[230:233], v[82:85]
	v_mfma_f32_16x16x32_bf16 v[82:85], v[192:195], v[234:237], v[82:85]
	v_mfma_f32_16x16x32_bf16 v[70:73], v[180:183], v[238:241], v[70:73]
	v_mfma_f32_16x16x32_bf16 v[70:73], v[184:187], v[242:245], v[70:73]
	s_setprio 2
	s_barrier
	v_mfma_f32_16x16x32_bf16 v[66:69], v[188:191], v[238:241], v[66:69]
	v_mfma_f32_16x16x32_bf16 v[66:69], v[192:195], v[242:245], v[66:69]
	s_setprio 0
	s_mov_b32 m0, s94
	v_lshl_add_u64 v[166:167], s[60:61], 0, v[136:137]
	ds_read_b128 v[196:199], v153 offset:16384
	ds_read_b128 v[200:203], v153 offset:17408
	ds_read_b128 v[222:225], v153 offset:18432
	ds_read_b128 v[226:229], v153 offset:19456
	ds_read_b128 v[230:233], v153 offset:20480
	ds_read_b128 v[234:237], v153 offset:21504
	ds_read_b128 v[238:241], v153 offset:22528
	ds_read_b128 v[242:245], v153 offset:23552
	global_load_lds_dwordx4 v[166:167], off
	v_lshl_add_u64 v[168:169], s[60:61], 0, v[132:133]
	s_mov_b32 m0, s95
	v_lshl_add_u64 v[172:173], s[62:63], 0, v[136:137]
	global_load_lds_dwordx4 v[168:169], off
	s_mov_b32 m0, s96
	v_lshl_add_u64 v[212:213], s[58:59], 0, v[134:135]
	global_load_lds_dwordx4 v[172:173], off
	v_lshl_add_u64 v[172:173], s[62:63], 0, v[132:133]
	s_mov_b32 m0, s97
	s_nop 0
	global_load_lds_dwordx4 v[172:173], off
	v_lshl_add_u64 v[172:173], s[58:59], 0, v[138:139]
	s_mov_b32 m0, s71
	s_nop 0
	global_load_lds_dwordx4 v[172:173], off
	s_mov_b32 m0, s75
	s_nop 0
	global_load_lds_dwordx4 v[212:213], off
	s_waitcnt vmcnt(8)
	s_waitcnt lgkmcnt(0)
	s_setprio 1
	s_barrier
; #define PG8_STAGE(bufoff, gbase, voff) do { _Pragma("unroll") for (int _i = 0; _i < 2; ++_i) \
;         __builtin_amdgcn_global_load_lds((const unsigned*)((const char*)(gbase) + (voff)[_i]), (PG8_LAS unsigned*)(lds + (bufoff) + ldsw + _i * 8192), 16, 0, AUX_A); } while (0)
; #define PG8_LDA(dst, b, h) do { _Pragma("unroll") for (int m = 0; m < 4; ++m) _Pragma("unroll") for (int k = 0; k < 2; ++k) dst[m][k] = *(const PG8_LAS bf16x8*)(lds + PG8_SA(b, h) + aoff + m * 2048 + k * 1024); } while (0)
; #define PG8_LDB(dst, b, h) do { _Pragma("unroll") for (int n = 0; n < 2; ++n) _Pragma("unroll") for (int k = 0; k < 2; ++k) dst[n][k] = *(const PG8_LAS bf16x8*)(lds + PG8_SB(b, h) + boff + n * 2048 + k * 1024); } while (0)
; #define PG8_MMA(ai, bj, At, Bt) do { __builtin_amdgcn_s_setprio(1); _Pragma("unroll") for (int m = 0; m < 4; ++m) _Pragma("unroll") for (int n = 0; n < 2; ++n) _Pragma("unroll") for (int k = 0; k < 2; ++k) \
;         acc[ai][bj][m][n] = __builtin_amdgcn_mfma_f32_16x16x32_bf16(Bt[n][k], At[m][k], acc[ai][bj][m][n], 0, 0, 0); __builtin_amdgcn_s_setprio(0); } while (0)
; #define PG8_WAIT_V(n) asm volatile("s_waitcnt vmcnt(" #n ")" ::: "memory")
; #define PG8_WAIT_L(n) asm volatile("s_waitcnt lgkmcnt(" #n ")" ::: "memory")
; #define PG8_BAR __builtin_amdgcn_s_barrier()
; #define PG8_SCHED __builtin_amdgcn_sched_barrier(0)
; template <class Epi, class Sched, bool ALIGN_EPI = false, bool SP2 = false>
; __device__ __forceinline__ void gemm_phase(PG8_LAS unsigned char* lds, const Gemm g, const Sched& S, const Epi& E) {
;     ...
;             PG8_WAIT_V(8); PG8_WAIT_L(0); PG8_BAR; PG8_MMA(1, 0, At, B0); PG8_MMA(1, 1, At, B1); PG8_BAR; PG8_SCHED;
;             PG8_LDB(B0, 1, 0); PG8_LDB(B1, 1, 1); PG8_SCHED; PG8_LDA(At, 1, 0); PG8_STAGE(PG8_SA(0, 1), a2 + hstep, voffA);
;             PG8_WAIT_V(8); PG8_WAIT_L(0); PG8_BAR; PG8_MMA(0, 0, At, B0); PG8_MMA(0, 1, At, B1); PG8_BAR; PG8_SCHED;
	v_mfma_f32_16x16x32_bf16 v[62:65], v[148:151], v[196:199], v[62:65]
	v_mfma_f32_16x16x32_bf16 v[62:65], v[154:157], v[200:203], v[62:65]
	v_mfma_f32_16x16x32_bf16 v[58:61], v[158:161], v[196:199], v[58:61]
	v_mfma_f32_16x16x32_bf16 v[58:61], v[162:165], v[200:203], v[58:61]
	v_mfma_f32_16x16x32_bf16 v[46:49], v[148:151], v[222:225], v[46:49]
	v_mfma_f32_16x16x32_bf16 v[46:49], v[154:157], v[226:229], v[46:49]
	v_mfma_f32_16x16x32_bf16 v[42:45], v[158:161], v[222:225], v[42:45]
	v_mfma_f32_16x16x32_bf16 v[42:45], v[162:165], v[226:229], v[42:45]
	v_mfma_f32_16x16x32_bf16 v[30:33], v[148:151], v[230:233], v[30:33]
	v_mfma_f32_16x16x32_bf16 v[30:33], v[154:157], v[234:237], v[30:33]
	v_mfma_f32_16x16x32_bf16 v[26:29], v[158:161], v[230:233], v[26:29]
	v_mfma_f32_16x16x32_bf16 v[26:29], v[162:165], v[234:237], v[26:29]
	v_mfma_f32_16x16x32_bf16 v[14:17], v[148:151], v[238:241], v[14:17]
	v_mfma_f32_16x16x32_bf16 v[14:17], v[154:157], v[242:245], v[14:17]
	v_mfma_f32_16x16x32_bf16 v[10:13], v[158:161], v[238:241], v[10:13]
	v_mfma_f32_16x16x32_bf16 v[10:13], v[162:165], v[242:245], v[10:13]
	s_setprio 0
	s_setprio 1
	v_mfma_f32_16x16x32_bf16 v[54:57], v[180:183], v[196:199], v[54:57]
	v_mfma_f32_16x16x32_bf16 v[54:57], v[184:187], v[200:203], v[54:57]
	v_mfma_f32_16x16x32_bf16 v[50:53], v[188:191], v[196:199], v[50:53]
	v_mfma_f32_16x16x32_bf16 v[50:53], v[192:195], v[200:203], v[50:53]
	v_mfma_f32_16x16x32_bf16 v[38:41], v[180:183], v[222:225], v[38:41]
	v_mfma_f32_16x16x32_bf16 v[38:41], v[184:187], v[226:229], v[38:41]
	v_mfma_f32_16x16x32_bf16 v[34:37], v[188:191], v[222:225], v[34:37]
	v_mfma_f32_16x16x32_bf16 v[34:37], v[192:195], v[226:229], v[34:37]
	v_mfma_f32_16x16x32_bf16 v[22:25], v[180:183], v[230:233], v[22:25]
	v_mfma_f32_16x16x32_bf16 v[22:25], v[184:187], v[234:237], v[22:25]
	v_mfma_f32_16x16x32_bf16 v[18:21], v[188:191], v[230:233], v[18:21]
	v_mfma_f32_16x16x32_bf16 v[18:21], v[192:195], v[234:237], v[18:21]
	v_mfma_f32_16x16x32_bf16 v[6:9], v[180:183], v[238:241], v[6:9]
	v_mfma_f32_16x16x32_bf16 v[6:9], v[184:187], v[242:245], v[6:9]
	s_setprio 2
	s_barrier
	v_mfma_f32_16x16x32_bf16 v[2:5], v[188:191], v[238:241], v[2:5]
	v_mfma_f32_16x16x32_bf16 v[2:5], v[192:195], v[242:245], v[2:5]
	s_setprio 0
	v_add_u32_e32 v162, vcc_lo, v99
	v_add_u32_e32 v192, vcc_hi, v99
	ds_read_b128 v[148:151], v162
	ds_read_b128 v[154:157], v162 offset:1024
	ds_read_b128 v[158:161], v162 offset:2048
	ds_read_b128 v[162:165], v162 offset:3072
	ds_read_b128 v[180:183], v192
	ds_read_b128 v[184:187], v192 offset:1024
	ds_read_b128 v[188:191], v192 offset:2048
	ds_read_b128 v[192:195], v192 offset:3072
	s_mov_b32 m0, s78
	v_lshl_add_u64 v[246:247], s[56:57], 0, v[138:139]
	ds_read_b128 v[196:199], v153 offset:32768
	ds_read_b128 v[200:203], v153 offset:33792
	ds_read_b128 v[222:225], v153 offset:34816
	ds_read_b128 v[226:229], v153 offset:35840
	ds_read_b128 v[230:233], v153 offset:36864
	ds_read_b128 v[234:237], v153 offset:37888
	ds_read_b128 v[238:241], v153 offset:38912
	ds_read_b128 v[242:245], v153 offset:39936
	global_load_lds_dwordx4 v[246:247], off
	v_lshl_add_u64 v[246:247], s[56:57], 0, v[134:135]
	s_mov_b32 m0, s82
	s_nop 0
	global_load_lds_dwordx4 v[246:247], off
	s_waitcnt vmcnt(8)
	s_waitcnt lgkmcnt(0)
	s_setprio 1
	s_barrier
	v_mfma_f32_16x16x32_bf16 v[128:131], v[148:151], v[196:199], v[128:131]
	v_mfma_f32_16x16x32_bf16 v[128:131], v[154:157], v[200:203], v[128:131]
	v_mfma_f32_16x16x32_bf16 v[124:127], v[158:161], v[196:199], v[124:127]
	v_mfma_f32_16x16x32_bf16 v[124:127], v[162:165], v[200:203], v[124:127]
	v_mfma_f32_16x16x32_bf16 v[112:115], v[148:151], v[222:225], v[112:115]
	v_mfma_f32_16x16x32_bf16 v[112:115], v[154:157], v[226:229], v[112:115]
	v_mfma_f32_16x16x32_bf16 v[108:111], v[158:161], v[222:225], v[108:111]
	v_mfma_f32_16x16x32_bf16 v[108:111], v[162:165], v[226:229], v[108:111]
	v_mfma_f32_16x16x32_bf16 v[94:97], v[148:151], v[230:233], v[94:97]
	v_mfma_f32_16x16x32_bf16 v[94:97], v[154:157], v[234:237], v[94:97]
	v_mfma_f32_16x16x32_bf16 v[90:93], v[158:161], v[230:233], v[90:93]
	v_mfma_f32_16x16x32_bf16 v[90:93], v[162:165], v[234:237], v[90:93]
	v_mfma_f32_16x16x32_bf16 v[78:81], v[148:151], v[238:241], v[78:81]
	v_mfma_f32_16x16x32_bf16 v[78:81], v[154:157], v[242:245], v[78:81]
	v_mfma_f32_16x16x32_bf16 v[74:77], v[158:161], v[238:241], v[74:77]
	v_mfma_f32_16x16x32_bf16 v[74:77], v[162:165], v[242:245], v[74:77]
	s_setprio 0
	s_setprio 1
	v_mfma_f32_16x16x32_bf16 v[120:123], v[180:183], v[196:199], v[120:123]
	v_mfma_f32_16x16x32_bf16 v[120:123], v[184:187], v[200:203], v[120:123]
	v_mfma_f32_16x16x32_bf16 v[116:119], v[188:191], v[196:199], v[116:119]
	v_mfma_f32_16x16x32_bf16 v[116:119], v[192:195], v[200:203], v[116:119]
	v_mfma_f32_16x16x32_bf16 v[104:107], v[180:183], v[222:225], v[104:107]
	v_mfma_f32_16x16x32_bf16 v[104:107], v[184:187], v[226:229], v[104:107]
	v_mfma_f32_16x16x32_bf16 v[100:103], v[188:191], v[222:225], v[100:103]
	v_mfma_f32_16x16x32_bf16 v[100:103], v[192:195], v[226:229], v[100:103]
	v_mfma_f32_16x16x32_bf16 v[86:89], v[180:183], v[230:233], v[86:89]
	v_mfma_f32_16x16x32_bf16 v[86:89], v[184:187], v[234:237], v[86:89]
	v_mfma_f32_16x16x32_bf16 v[82:85], v[188:191], v[230:233], v[82:85]
	v_mfma_f32_16x16x32_bf16 v[82:85], v[192:195], v[234:237], v[82:85]
	v_mfma_f32_16x16x32_bf16 v[70:73], v[180:183], v[238:241], v[70:73]
	v_mfma_f32_16x16x32_bf16 v[70:73], v[184:187], v[242:245], v[70:73]
	s_setprio 2
	s_barrier
; #define PG8_STAGE(bufoff, gbase, voff) do { _Pragma("unroll") for (int _i = 0; _i < 2; ++_i) \
;         __builtin_amdgcn_global_load_lds((const unsigned*)((const char*)(gbase) + (voff)[_i]), (PG8_LAS unsigned*)(lds + (bufoff) + ldsw + _i * 8192), 16, 0, AUX_A); } while (0)
; #define PG8_STAGEB(bufoff, gbase, voff) do { _Pragma("unroll") for (int _i = 0; _i < 2; ++_i) \
;         __builtin_amdgcn_global_load_lds((const unsigned*)((const char*)(gbase) + (voff)[_i]), (PG8_LAS unsigned*)(lds + (bufoff) + ldsw + _i * 8192), 16, 0, AUX_B); } while (0)
; #define PG8_LDA(dst, b, h) do { _Pragma("unroll") for (int m = 0; m < 4; ++m) _Pragma("unroll") for (int k = 0; k < 2; ++k) dst[m][k] = *(const PG8_LAS bf16x8*)(lds + PG8_SA(b, h) + aoff + m * 2048 + k * 1024); } while (0)
; #define PG8_MMA(ai, bj, At, Bt) do { __builtin_amdgcn_s_setprio(1); _Pragma("unroll") for (int m = 0; m < 4; ++m) _Pragma("unroll") for (int n = 0; n < 2; ++n) _Pragma("unroll") for (int k = 0; k < 2; ++k) \
;         acc[ai][bj][m][n] = __builtin_amdgcn_mfma_f32_16x16x32_bf16(Bt[n][k], At[m][k], acc[ai][bj][m][n], 0, 0, 0); __builtin_amdgcn_s_setprio(0); } while (0)
; #define PG8_WAIT_V(n) asm volatile("s_waitcnt vmcnt(" #n ")" ::: "memory")
; #define PG8_WAIT_L(n) asm volatile("s_waitcnt lgkmcnt(" #n ")" ::: "memory")
; #define PG8_BAR __builtin_amdgcn_s_barrier()
; #define PG8_SCHED __builtin_amdgcn_sched_barrier(0)
; template <class Epi, class Sched, bool ALIGN_EPI = false, bool SP2 = false>
; __device__ __forceinline__ void gemm_phase(PG8_LAS unsigned char* lds, const Gemm g, const Sched& S, const Epi& E) {
;     ...
;             PG8_LDA(At, 1, 1); PG8_STAGEB(PG8_SB(1, 0), b3, voffB); PG8_STAGEB(PG8_SB(1, 1), b3 + hstep, voffB); PG8_STAGE(PG8_SA(1, 0), a3, voffA);
;             PG8_WAIT_V(8); PG8_WAIT_L(0); PG8_BAR; PG8_MMA(1, 0, At, B0); PG8_MMA(1, 1, At, B1); PG8_BAR; PG8_SCHED;
	v_mfma_f32_16x16x32_bf16 v[66:69], v[188:191], v[238:241], v[66:69]
	v_mfma_f32_16x16x32_bf16 v[66:69], v[192:195], v[242:245], v[66:69]
	s_setprio 0
	s_mov_b32 m0, s1
	v_lshl_add_u64 v[166:167], v[166:167], 0, s[76:77]
	ds_read_b128 v[196:199], v153 offset:49152
	ds_read_b128 v[200:203], v153 offset:50176
	ds_read_b128 v[222:225], v153 offset:51200
	ds_read_b128 v[226:229], v153 offset:52224
	ds_read_b128 v[230:233], v153 offset:53248
	ds_read_b128 v[234:237], v153 offset:54272
	ds_read_b128 v[238:241], v153 offset:55296
	ds_read_b128 v[242:245], v153 offset:56320
	global_load_lds_dwordx4 v[166:167], off
	v_lshl_add_u64 v[166:167], v[168:169], 0, s[76:77]
	s_mov_b32 m0, s0
	s_nop 0
	global_load_lds_dwordx4 v[166:167], off
	v_lshl_add_u64 v[166:167], s[54:55], 0, v[136:137]
	s_mov_b32 m0, s47
	s_nop 0
	global_load_lds_dwordx4 v[166:167], off
	v_lshl_add_u64 v[166:167], s[54:55], 0, v[132:133]
	s_mov_b32 m0, s46
	s_nop 0
	global_load_lds_dwordx4 v[166:167], off
	v_lshl_add_u64 v[166:167], v[172:173], 0, s[76:77]
	s_mov_b32 m0, s83
	s_nop 0
	global_load_lds_dwordx4 v[166:167], off
	v_lshl_add_u64 v[166:167], v[212:213], 0, s[76:77]
	s_mov_b32 m0, s88
	s_nop 0
	global_load_lds_dwordx4 v[166:167], off
	s_waitcnt vmcnt(8)
	s_waitcnt lgkmcnt(0)
	s_setprio 1
	s_barrier
	v_mfma_f32_16x16x32_bf16 v[62:65], v[148:151], v[196:199], v[62:65]
	v_mfma_f32_16x16x32_bf16 v[62:65], v[154:157], v[200:203], v[62:65]
	v_mfma_f32_16x16x32_bf16 v[58:61], v[158:161], v[196:199], v[58:61]
	v_mfma_f32_16x16x32_bf16 v[58:61], v[162:165], v[200:203], v[58:61]
	v_mfma_f32_16x16x32_bf16 v[46:49], v[148:151], v[222:225], v[46:49]
	v_mfma_f32_16x16x32_bf16 v[46:49], v[154:157], v[226:229], v[46:49]
	v_mfma_f32_16x16x32_bf16 v[42:45], v[158:161], v[222:225], v[42:45]
	v_mfma_f32_16x16x32_bf16 v[42:45], v[162:165], v[226:229], v[42:45]
	v_mfma_f32_16x16x32_bf16 v[30:33], v[148:151], v[230:233], v[30:33]
	v_mfma_f32_16x16x32_bf16 v[30:33], v[154:157], v[234:237], v[30:33]
	v_mfma_f32_16x16x32_bf16 v[26:29], v[158:161], v[230:233], v[26:29]
	v_mfma_f32_16x16x32_bf16 v[26:29], v[162:165], v[234:237], v[26:29]
	v_mfma_f32_16x16x32_bf16 v[14:17], v[148:151], v[238:241], v[14:17]
	v_mfma_f32_16x16x32_bf16 v[14:17], v[154:157], v[242:245], v[14:17]
	v_mfma_f32_16x16x32_bf16 v[10:13], v[158:161], v[238:241], v[10:13]
	v_mfma_f32_16x16x32_bf16 v[10:13], v[162:165], v[242:245], v[10:13]
	s_setprio 0
	s_setprio 1
	v_mfma_f32_16x16x32_bf16 v[54:57], v[180:183], v[196:199], v[54:57]
	v_mfma_f32_16x16x32_bf16 v[54:57], v[184:187], v[200:203], v[54:57]
	v_mfma_f32_16x16x32_bf16 v[50:53], v[188:191], v[196:199], v[50:53]
	v_mfma_f32_16x16x32_bf16 v[50:53], v[192:195], v[200:203], v[50:53]
	v_mfma_f32_16x16x32_bf16 v[38:41], v[180:183], v[222:225], v[38:41]
	v_mfma_f32_16x16x32_bf16 v[38:41], v[184:187], v[226:229], v[38:41]
	v_mfma_f32_16x16x32_bf16 v[34:37], v[188:191], v[222:225], v[34:37]
	v_mfma_f32_16x16x32_bf16 v[34:37], v[192:195], v[226:229], v[34:37]
	v_mfma_f32_16x16x32_bf16 v[22:25], v[180:183], v[230:233], v[22:25]
	v_mfma_f32_16x16x32_bf16 v[22:25], v[184:187], v[234:237], v[22:25]
	v_mfma_f32_16x16x32_bf16 v[18:21], v[188:191], v[230:233], v[18:21]
	v_mfma_f32_16x16x32_bf16 v[18:21], v[192:195], v[234:237], v[18:21]
	v_mfma_f32_16x16x32_bf16 v[6:9], v[180:183], v[238:241], v[6:9]
	v_mfma_f32_16x16x32_bf16 v[6:9], v[184:187], v[242:245], v[6:9]
	s_setprio 2
	s_cbranch_scc0 .Lq4b_1157l
	v_cmp_ne_u32_e64 vcc, s16, 0
	s_cbranch_vccz .Lq4s_1157l

; #define GAS __attribute__((address_space(1)))
; #define PG8_BAR __builtin_amdgcn_s_barrier()
; #define GAS __attribute__((address_space(1)))
;     __device__ __forceinline__ void operator()(const f32x4 (&acc)[2][2][4][2], const Unit& u, int wr, int wc, int fr, int fq) const {
;         const int row0 = u.pm * BM + wr * 64 + fr, col0 = u.pn * BM + wc * 32 + 8 * fq;
;         const bool samp = u.pm >= 32;
;         GAS unsigned* flag = (GAS unsigned*)(flags + 64 * (u.pn * 4 + (u.pm & 3)));
;         if (MODE == 1 && samp) {
;             unsigned spins = 0u;
;             while (__hip_atomic_load(flag, __ATOMIC_RELAXED, __HIP_MEMORY_SCOPE_AGENT) < 8u) { __builtin_amdgcn_s_sleep(2); if (++spins > (1u << 18)) break; }
;             __builtin_amdgcn_fence(__ATOMIC_ACQUIRE, "agent"); asm volatile("s_waitcnt vmcnt(0)" ::: "memory");
; template <class Epi, class Sched, bool ALIGN_EPI = false, bool SP2 = false>
; __device__ __forceinline__ void gemm_phase(PG8_LAS unsigned char* lds, const Gemm g, const Sched& S, const Epi& E) {
;     ...
;         if constexpr (ALIGN_EPI) { if (wr == 0) PG8_BAR; }
.Lpx_1157:
	s_and_b64 vcc, exec, s[16:17]
	s_cbranch_vccz .LBB0_1160
.LBB0_1160:
	s_lshl_b32 s19, s91, 8
	v_readlane_b32 s60, v251, 14
	s_cmp_lt_i32 s90, 32
	v_readlane_b32 s92, v254, 49
	v_readlane_b32 s61, v251, 15
	v_readlane_b32 s62, v251, 16
	v_readlane_b32 s63, v251, 17
	v_readlane_b32 s64, v251, 18
	v_readlane_b32 s65, v251, 19
	v_readlane_b32 s66, v251, 20
	v_readlane_b32 s67, v251, 21
	s_mov_b32 s93, 0x18000
	s_mov_b32 s94, 0x8000
	s_movk_i32 s95, 0x3400
	s_cbranch_scc1 .LBB0_1178
	s_lshl_b32 s0, s90, 6
	s_and_b32 s0, s0, 0xc0
	s_or_b32 s0, s0, s19
	s_ashr_i32 s1, s0, 31
	s_lshl_b64 s[0:1], s[0:1], 2
	s_add_u32 s50, s30, s0
	s_addc_u32 s51, s31, s1
	s_mov_b32 s29, 0x40001
	s_branch .LBB0_1163

; #define PG8_STAGE(bufoff, gbase, voff) do { _Pragma("unroll") for (int _i = 0; _i < 2; ++_i) \
;         __builtin_amdgcn_global_load_lds((const unsigned*)((const char*)(gbase) + (voff)[_i]), (PG8_LAS unsigned*)(lds + (bufoff) + ldsw + _i * 8192), 16, 0, AUX_A); } while (0)
; #define PG8_STAGEB(bufoff, gbase, voff) do { _Pragma("unroll") for (int _i = 0; _i < 2; ++_i) \
;         __builtin_amdgcn_global_load_lds((const unsigned*)((const char*)(gbase) + (voff)[_i]), (PG8_LAS unsigned*)(lds + (bufoff) + ldsw + _i * 8192), 16, 0, AUX_B); } while (0)
; #define PG8_LDA(dst, b, h) do { _Pragma("unroll") for (int m = 0; m < 4; ++m) _Pragma("unroll") for (int k = 0; k < 2; ++k) dst[m][k] = *(const PG8_LAS bf16x8*)(lds + PG8_SA(b, h) + aoff + m * 2048 + k * 1024); } while (0)
; #define PG8_LDB(dst, b, h) do { _Pragma("unroll") for (int n = 0; n < 2; ++n) _Pragma("unroll") for (int k = 0; k < 2; ++k) dst[n][k] = *(const PG8_LAS bf16x8*)(lds + PG8_SB(b, h) + boff + n * 2048 + k * 1024); } while (0)
; #define PG8_WAIT_V(n) asm volatile("s_waitcnt vmcnt(" #n ")" ::: "memory")
; #define PG8_WAIT_L(n) asm volatile("s_waitcnt lgkmcnt(" #n ")" ::: "memory")
; #define PG8_BAR __builtin_amdgcn_s_barrier()
; #define PG8_SCHED __builtin_amdgcn_sched_barrier(0)
; template <class Epi, class Sched, bool ALIGN_EPI = false, bool SP2 = false>
; __device__ __forceinline__ void gemm_phase(PG8_LAS unsigned char* lds, const Gemm g, const Sched& S, const Epi& E) {
;     ...
;         for (int t = 0; t < nt; t += 2) {
;             const bool last = (t == nt - 2);
;             const char* a1 = PG8_KP(cA, t + 1, rot, nt);
;             const char* a2 = last ? nAr : PG8_KP(cA, t + 2, rot, nt); const char* b2 = last ? nBr : PG8_KP(cB, t + 2, rot, nt);
;             const char* a3 = a2 + kstep; const char* b3 = b2 + kstep;
;             if (last && has_next) S.a_ready(nxt);
;             if constexpr (SP2) {
;             PG8_LDB(B0, 0, 0); PG8_LDB(B1, 0, 1); PG8_SCHED; PG8_LDA(At, 0, 0); PG8_STAGE(PG8_SA(1, 1), a1 + hstep, voffA);
;             PG8_WAIT_V(8); PG8_WAIT_L(0); PG8_BAR; PG8_MMA(0, 0, At, B0); PG8_MMA(0, 1, At, B1); PG8_BAR; PG8_SCHED;
;             PG8_LDA(At, 0, 1); PG8_STAGEB(PG8_SB(0, 0), b2, voffB); PG8_STAGEB(PG8_SB(0, 1), b2 + hstep, voffB); PG8_STAGE(PG8_SA(0, 0), a2, voffA);
.Lpk_1308:
	s_or_b32 s0, s11, 1
	s_cmp_ge_i32 s0, s71
	s_cselect_b32 s2, s71, 0
	s_add_i32 s11, s11, 2
	s_cmp_ge_i32 s11, s71
	s_cselect_b32 s0, s71, 0
	s_sub_i32 s0, s13, s0
	s_ashr_i32 s1, s0, 31
	s_lshl_b64 s[0:1], s[0:1], 7
	s_add_u32 s15, s40, s0
	s_addc_u32 s29, s41, s1
	s_add_u32 s0, s34, s0
	s_addc_u32 s1, s35, s1
	s_cmp_eq_u32 s71, s13
	s_cselect_b32 s45, s43, s29
	s_cselect_b32 s44, s42, s15
	s_cselect_b32 s37, s19, s1
	s_cselect_b32 s36, s18, s0
	s_add_i32 s15, 0, 0x10000
	s_add_i32 s29, 0, 0x14000
	v_add_u32_e32 v148, s15, v99
	v_add_u32_e32 v168, s29, v99
	ds_read_b128 v[136:139], v148
	ds_read_b128 v[140:143], v148 offset:1024
	ds_read_b128 v[144:147], v148 offset:2048
	ds_read_b128 v[148:151], v148 offset:3072
	ds_read_b128 v[164:167], v168
	ds_read_b128 v[182:185], v168 offset:1024
	ds_read_b128 v[186:189], v168 offset:2048
	ds_read_b128 v[190:193], v168 offset:3072
	v_mad_i64_i32 v[168:169], s[0:1], s2, v220, v[134:135]
	s_add_i32 m0, s50, 0xc000
	ds_read_b128 v[194:197], v181
	ds_read_b128 v[198:201], v181 offset:1024
	ds_read_b128 v[222:225], v181 offset:2048
	ds_read_b128 v[226:229], v181 offset:3072
	ds_read_b128 v[230:233], v181 offset:4096
	ds_read_b128 v[234:237], v181 offset:5120
	ds_read_b128 v[238:241], v181 offset:6144
	ds_read_b128 v[242:245], v181 offset:7168
	global_load_lds_dwordx4 v[168:169], off
	v_mad_i64_i32 v[168:169], s[0:1], s2, v220, v[132:133]
	s_add_i32 m0, s50, 0xe000
	s_nop 0
	global_load_lds_dwordx4 v[168:169], off
	s_waitcnt vmcnt(8)
	s_waitcnt lgkmcnt(0)
	s_setprio 1
	s_barrier
	v_mfma_f32_16x16x32_bf16 v[128:131], v[136:139], v[194:197], 0
	v_mfma_f32_16x16x32_bf16 v[128:131], v[140:143], v[198:201], v[128:131]
	v_mfma_f32_16x16x32_bf16 v[124:127], v[144:147], v[194:197], 0
	v_mfma_f32_16x16x32_bf16 v[124:127], v[148:151], v[198:201], v[124:127]
	v_mfma_f32_16x16x32_bf16 v[120:123], v[136:139], v[222:225], 0
	v_mfma_f32_16x16x32_bf16 v[120:123], v[140:143], v[226:229], v[120:123]
	v_mfma_f32_16x16x32_bf16 v[112:115], v[144:147], v[222:225], 0
	v_mfma_f32_16x16x32_bf16 v[112:115], v[148:151], v[226:229], v[112:115]
	v_mfma_f32_16x16x32_bf16 v[104:107], v[136:139], v[230:233], 0
	v_mfma_f32_16x16x32_bf16 v[104:107], v[140:143], v[234:237], v[104:107]
	v_mfma_f32_16x16x32_bf16 v[94:97], v[144:147], v[230:233], 0
	v_mfma_f32_16x16x32_bf16 v[94:97], v[148:151], v[234:237], v[94:97]
	v_mfma_f32_16x16x32_bf16 v[86:89], v[136:139], v[238:241], 0
	v_mfma_f32_16x16x32_bf16 v[86:89], v[140:143], v[242:245], v[86:89]
	v_mfma_f32_16x16x32_bf16 v[78:81], v[144:147], v[238:241], 0
	v_mfma_f32_16x16x32_bf16 v[78:81], v[148:151], v[242:245], v[78:81]
	s_setprio 0
	s_setprio 1
	v_mfma_f32_16x16x32_bf16 v[116:119], v[164:167], v[194:197], 0
	v_mfma_f32_16x16x32_bf16 v[116:119], v[182:185], v[198:201], v[116:119]
	v_mfma_f32_16x16x32_bf16 v[108:111], v[186:189], v[194:197], 0
	v_mfma_f32_16x16x32_bf16 v[108:111], v[190:193], v[198:201], v[108:111]
	v_mfma_f32_16x16x32_bf16 v[100:103], v[164:167], v[222:225], 0
	v_mfma_f32_16x16x32_bf16 v[100:103], v[182:185], v[226:229], v[100:103]
	v_mfma_f32_16x16x32_bf16 v[90:93], v[186:189], v[222:225], 0
	v_mfma_f32_16x16x32_bf16 v[90:93], v[190:193], v[226:229], v[90:93]
	v_mfma_f32_16x16x32_bf16 v[82:85], v[164:167], v[230:233], 0
	v_mfma_f32_16x16x32_bf16 v[82:85], v[182:185], v[234:237], v[82:85]
	v_mfma_f32_16x16x32_bf16 v[74:77], v[186:189], v[230:233], 0
	v_mfma_f32_16x16x32_bf16 v[74:77], v[190:193], v[234:237], v[74:77]
	v_mfma_f32_16x16x32_bf16 v[70:73], v[164:167], v[238:241], 0
	v_mfma_f32_16x16x32_bf16 v[70:73], v[182:185], v[242:245], v[70:73]
	s_setprio 2
	s_barrier
	v_mfma_f32_16x16x32_bf16 v[66:69], v[186:189], v[238:241], 0
	v_mfma_f32_16x16x32_bf16 v[66:69], v[190:193], v[242:245], v[66:69]
	s_setprio 0
	s_add_i32 s0, s15, s49
	v_lshl_add_u64 v[168:169], s[36:37], 0, v[156:157]
	s_mov_b32 m0, s0
	ds_read_b128 v[194:197], v181 offset:16384
	ds_read_b128 v[198:201], v181 offset:17408
	ds_read_b128 v[222:225], v181 offset:18432
	ds_read_b128 v[226:229], v181 offset:19456
	ds_read_b128 v[230:233], v181 offset:20480
	ds_read_b128 v[234:237], v181 offset:21504
	ds_read_b128 v[238:241], v181 offset:22528
	ds_read_b128 v[242:245], v181 offset:23552
	global_load_lds_dwordx4 v[168:169], off
	s_add_i32 m0, s0, 0x2000
	s_add_u32 s0, s36, 0x80000
	v_lshl_add_u64 v[172:173], s[36:37], 0, v[152:153]
	s_addc_u32 s1, s37, 0
	s_add_i32 s2, s29, s49
	global_load_lds_dwordx4 v[172:173], off
	v_lshl_add_u64 v[202:203], s[0:1], 0, v[156:157]
	s_mov_b32 m0, s2
	v_lshl_add_u64 v[212:213], s[44:45], 0, v[154:155]
	global_load_lds_dwordx4 v[202:203], off
	v_lshl_add_u64 v[202:203], s[0:1], 0, v[152:153]
	s_add_i32 m0, s2, 0x2000
	s_nop 0
	global_load_lds_dwordx4 v[202:203], off
	v_lshl_add_u64 v[202:203], s[44:45], 0, v[158:159]
	s_mov_b32 m0, s50
	s_nop 0
	global_load_lds_dwordx4 v[202:203], off
	s_mov_b32 m0, s51
	s_nop 0
	global_load_lds_dwordx4 v[212:213], off
	s_waitcnt vmcnt(8)
	s_waitcnt lgkmcnt(0)
	s_setprio 1
	s_barrier
; #define PG8_STAGE(bufoff, gbase, voff) do { _Pragma("unroll") for (int _i = 0; _i < 2; ++_i) \
;         __builtin_amdgcn_global_load_lds((const unsigned*)((const char*)(gbase) + (voff)[_i]), (PG8_LAS unsigned*)(lds + (bufoff) + ldsw + _i * 8192), 16, 0, AUX_A); } while (0)
; #define PG8_LDA(dst, b, h) do { _Pragma("unroll") for (int m = 0; m < 4; ++m) _Pragma("unroll") for (int k = 0; k < 2; ++k) dst[m][k] = *(const PG8_LAS bf16x8*)(lds + PG8_SA(b, h) + aoff + m * 2048 + k * 1024); } while (0)
; #define PG8_LDB(dst, b, h) do { _Pragma("unroll") for (int n = 0; n < 2; ++n) _Pragma("unroll") for (int k = 0; k < 2; ++k) dst[n][k] = *(const PG8_LAS bf16x8*)(lds + PG8_SB(b, h) + boff + n * 2048 + k * 1024); } while (0)
; #define PG8_MMA(ai, bj, At, Bt) do { __builtin_amdgcn_s_setprio(1); _Pragma("unroll") for (int m = 0; m < 4; ++m) _Pragma("unroll") for (int n = 0; n < 2; ++n) _Pragma("unroll") for (int k = 0; k < 2; ++k) \
;         acc[ai][bj][m][n] = __builtin_amdgcn_mfma_f32_16x16x32_bf16(Bt[n][k], At[m][k], acc[ai][bj][m][n], 0, 0, 0); __builtin_amdgcn_s_setprio(0); } while (0)
; #define PG8_WAIT_V(n) asm volatile("s_waitcnt vmcnt(" #n ")" ::: "memory")
; #define PG8_WAIT_L(n) asm volatile("s_waitcnt lgkmcnt(" #n ")" ::: "memory")
; #define PG8_BAR __builtin_amdgcn_s_barrier()
; #define PG8_SCHED __builtin_amdgcn_sched_barrier(0)
; template <class Epi, class Sched, bool ALIGN_EPI = false, bool SP2 = false>
; __device__ __forceinline__ void gemm_phase(PG8_LAS unsigned char* lds, const Gemm g, const Sched& S, const Epi& E) {
;     ...
;             PG8_WAIT_V(8); PG8_WAIT_L(0); PG8_BAR; PG8_MMA(1, 0, At, B0); PG8_MMA(1, 1, At, B1); PG8_BAR; PG8_SCHED;
;             PG8_LDB(B0, 1, 0); PG8_LDB(B1, 1, 1); PG8_SCHED; PG8_LDA(At, 1, 0); PG8_STAGE(PG8_SA(0, 1), a2 + hstep, voffA);
;             PG8_WAIT_V(8); PG8_WAIT_L(0); PG8_BAR; PG8_MMA(0, 0, At, B0); PG8_MMA(0, 1, At, B1); PG8_BAR; PG8_SCHED;
	v_mfma_f32_16x16x32_bf16 v[62:65], v[136:139], v[194:197], 0
	v_mfma_f32_16x16x32_bf16 v[62:65], v[140:143], v[198:201], v[62:65]
	v_mfma_f32_16x16x32_bf16 v[58:61], v[144:147], v[194:197], 0
	v_mfma_f32_16x16x32_bf16 v[58:61], v[148:151], v[198:201], v[58:61]
	v_mfma_f32_16x16x32_bf16 v[54:57], v[136:139], v[222:225], 0
	v_mfma_f32_16x16x32_bf16 v[54:57], v[140:143], v[226:229], v[54:57]
	v_mfma_f32_16x16x32_bf16 v[46:49], v[144:147], v[222:225], 0
	v_mfma_f32_16x16x32_bf16 v[46:49], v[148:151], v[226:229], v[46:49]
	v_mfma_f32_16x16x32_bf16 v[38:41], v[136:139], v[230:233], 0
	v_mfma_f32_16x16x32_bf16 v[38:41], v[140:143], v[234:237], v[38:41]
	v_mfma_f32_16x16x32_bf16 v[30:33], v[144:147], v[230:233], 0
	v_mfma_f32_16x16x32_bf16 v[30:33], v[148:151], v[234:237], v[30:33]
	v_mfma_f32_16x16x32_bf16 v[22:25], v[136:139], v[238:241], 0
	v_mfma_f32_16x16x32_bf16 v[22:25], v[140:143], v[242:245], v[22:25]
	v_mfma_f32_16x16x32_bf16 v[14:17], v[144:147], v[238:241], 0
	v_mfma_f32_16x16x32_bf16 v[14:17], v[148:151], v[242:245], v[14:17]
	s_setprio 0
	s_setprio 1
	v_mfma_f32_16x16x32_bf16 v[50:53], v[164:167], v[194:197], 0
	v_mfma_f32_16x16x32_bf16 v[50:53], v[182:185], v[198:201], v[50:53]
	v_mfma_f32_16x16x32_bf16 v[42:45], v[186:189], v[194:197], 0
	v_mfma_f32_16x16x32_bf16 v[42:45], v[190:193], v[198:201], v[42:45]
	v_mfma_f32_16x16x32_bf16 v[34:37], v[164:167], v[222:225], 0
	v_mfma_f32_16x16x32_bf16 v[34:37], v[182:185], v[226:229], v[34:37]
	v_mfma_f32_16x16x32_bf16 v[26:29], v[186:189], v[222:225], 0
	v_mfma_f32_16x16x32_bf16 v[26:29], v[190:193], v[226:229], v[26:29]
	v_mfma_f32_16x16x32_bf16 v[18:21], v[164:167], v[230:233], 0
	v_mfma_f32_16x16x32_bf16 v[18:21], v[182:185], v[234:237], v[18:21]
	v_mfma_f32_16x16x32_bf16 v[10:13], v[186:189], v[230:233], 0
	v_mfma_f32_16x16x32_bf16 v[10:13], v[190:193], v[234:237], v[10:13]
	v_mfma_f32_16x16x32_bf16 v[6:9], v[164:167], v[238:241], 0
	v_mfma_f32_16x16x32_bf16 v[6:9], v[182:185], v[242:245], v[6:9]
	s_setprio 2
	s_barrier
	v_mfma_f32_16x16x32_bf16 v[2:5], v[186:189], v[238:241], 0
	v_mfma_f32_16x16x32_bf16 v[2:5], v[190:193], v[242:245], v[2:5]
	s_setprio 0
	s_add_i32 s2, 0, 0x18000
	s_add_i32 s15, 0, 0x1c000
	v_add_u32_e32 v148, s2, v99
	v_add_u32_e32 v190, s15, v99
	ds_read_b128 v[136:139], v148
	ds_read_b128 v[140:143], v148 offset:1024
	ds_read_b128 v[144:147], v148 offset:2048
	ds_read_b128 v[148:151], v148 offset:3072
	ds_read_b128 v[164:167], v190
	ds_read_b128 v[182:185], v190 offset:1024
	ds_read_b128 v[186:189], v190 offset:2048
	ds_read_b128 v[190:193], v190 offset:3072
	s_add_u32 s0, s44, 0x80000
	s_addc_u32 s1, s45, 0
	s_mov_b32 m0, s52
	v_lshl_add_u64 v[246:247], s[0:1], 0, v[158:159]
	ds_read_b128 v[194:197], v181 offset:32768
	ds_read_b128 v[198:201], v181 offset:33792
	ds_read_b128 v[222:225], v181 offset:34816
	ds_read_b128 v[226:229], v181 offset:35840
	ds_read_b128 v[230:233], v181 offset:36864
	ds_read_b128 v[234:237], v181 offset:37888
	ds_read_b128 v[238:241], v181 offset:38912
	ds_read_b128 v[242:245], v181 offset:39936
	global_load_lds_dwordx4 v[246:247], off
	v_lshl_add_u64 v[246:247], s[0:1], 0, v[154:155]
	s_mov_b32 m0, s53
	s_nop 0
	global_load_lds_dwordx4 v[246:247], off
	s_waitcnt vmcnt(8)
	s_waitcnt lgkmcnt(0)
	s_setprio 1
	s_barrier
	v_mfma_f32_16x16x32_bf16 v[128:131], v[136:139], v[194:197], v[128:131]
	v_mfma_f32_16x16x32_bf16 v[128:131], v[140:143], v[198:201], v[128:131]
	v_mfma_f32_16x16x32_bf16 v[124:127], v[144:147], v[194:197], v[124:127]
	v_mfma_f32_16x16x32_bf16 v[124:127], v[148:151], v[198:201], v[124:127]
	v_mfma_f32_16x16x32_bf16 v[120:123], v[136:139], v[222:225], v[120:123]
	v_mfma_f32_16x16x32_bf16 v[120:123], v[140:143], v[226:229], v[120:123]
	v_mfma_f32_16x16x32_bf16 v[112:115], v[144:147], v[222:225], v[112:115]
	v_mfma_f32_16x16x32_bf16 v[112:115], v[148:151], v[226:229], v[112:115]
	v_mfma_f32_16x16x32_bf16 v[104:107], v[136:139], v[230:233], v[104:107]
	v_mfma_f32_16x16x32_bf16 v[104:107], v[140:143], v[234:237], v[104:107]
	v_mfma_f32_16x16x32_bf16 v[94:97], v[144:147], v[230:233], v[94:97]
	v_mfma_f32_16x16x32_bf16 v[94:97], v[148:151], v[234:237], v[94:97]
	v_mfma_f32_16x16x32_bf16 v[86:89], v[136:139], v[238:241], v[86:89]
	v_mfma_f32_16x16x32_bf16 v[86:89], v[140:143], v[242:245], v[86:89]
	v_mfma_f32_16x16x32_bf16 v[78:81], v[144:147], v[238:241], v[78:81]
	v_mfma_f32_16x16x32_bf16 v[78:81], v[148:151], v[242:245], v[78:81]
	s_setprio 0
	s_setprio 1
	v_mfma_f32_16x16x32_bf16 v[116:119], v[164:167], v[194:197], v[116:119]
	v_mfma_f32_16x16x32_bf16 v[116:119], v[182:185], v[198:201], v[116:119]
	v_mfma_f32_16x16x32_bf16 v[108:111], v[186:189], v[194:197], v[108:111]
	v_mfma_f32_16x16x32_bf16 v[108:111], v[190:193], v[198:201], v[108:111]
	v_mfma_f32_16x16x32_bf16 v[100:103], v[164:167], v[222:225], v[100:103]
	v_mfma_f32_16x16x32_bf16 v[100:103], v[182:185], v[226:229], v[100:103]
	v_mfma_f32_16x16x32_bf16 v[90:93], v[186:189], v[222:225], v[90:93]
	v_mfma_f32_16x16x32_bf16 v[90:93], v[190:193], v[226:229], v[90:93]
	v_mfma_f32_16x16x32_bf16 v[82:85], v[164:167], v[230:233], v[82:85]
	v_mfma_f32_16x16x32_bf16 v[82:85], v[182:185], v[234:237], v[82:85]
	v_mfma_f32_16x16x32_bf16 v[74:77], v[186:189], v[230:233], v[74:77]
	v_mfma_f32_16x16x32_bf16 v[74:77], v[190:193], v[234:237], v[74:77]
	v_mfma_f32_16x16x32_bf16 v[70:73], v[164:167], v[238:241], v[70:73]
	v_mfma_f32_16x16x32_bf16 v[70:73], v[182:185], v[242:245], v[70:73]
	s_setprio 2
	s_barrier
; #define PG8_STAGE(bufoff, gbase, voff) do { _Pragma("unroll") for (int _i = 0; _i < 2; ++_i) \
;         __builtin_amdgcn_global_load_lds((const unsigned*)((const char*)(gbase) + (voff)[_i]), (PG8_LAS unsigned*)(lds + (bufoff) + ldsw + _i * 8192), 16, 0, AUX_A); } while (0)
; #define PG8_STAGEB(bufoff, gbase, voff) do { _Pragma("unroll") for (int _i = 0; _i < 2; ++_i) \
;         __builtin_amdgcn_global_load_lds((const unsigned*)((const char*)(gbase) + (voff)[_i]), (PG8_LAS unsigned*)(lds + (bufoff) + ldsw + _i * 8192), 16, 0, AUX_B); } while (0)
; #define PG8_LDA(dst, b, h) do { _Pragma("unroll") for (int m = 0; m < 4; ++m) _Pragma("unroll") for (int k = 0; k < 2; ++k) dst[m][k] = *(const PG8_LAS bf16x8*)(lds + PG8_SA(b, h) + aoff + m * 2048 + k * 1024); } while (0)
; #define PG8_MMA(ai, bj, At, Bt) do { __builtin_amdgcn_s_setprio(1); _Pragma("unroll") for (int m = 0; m < 4; ++m) _Pragma("unroll") for (int n = 0; n < 2; ++n) _Pragma("unroll") for (int k = 0; k < 2; ++k) \
;         acc[ai][bj][m][n] = __builtin_amdgcn_mfma_f32_16x16x32_bf16(Bt[n][k], At[m][k], acc[ai][bj][m][n], 0, 0, 0); __builtin_amdgcn_s_setprio(0); } while (0)
; #define PG8_WAIT_V(n) asm volatile("s_waitcnt vmcnt(" #n ")" ::: "memory")
; #define PG8_WAIT_L(n) asm volatile("s_waitcnt lgkmcnt(" #n ")" ::: "memory")
; #define PG8_BAR __builtin_amdgcn_s_barrier()
; #define PG8_SCHED __builtin_amdgcn_sched_barrier(0)
; template <class Epi, class Sched, bool ALIGN_EPI = false, bool SP2 = false>
; __device__ __forceinline__ void gemm_phase(PG8_LAS unsigned char* lds, const Gemm g, const Sched& S, const Epi& E) {
;     ...
;             const bool last = (t == nt - 2);
;     ...
;             PG8_LDA(At, 1, 1); PG8_STAGEB(PG8_SB(1, 0), b3, voffB); PG8_STAGEB(PG8_SB(1, 1), b3 + hstep, voffB); PG8_STAGE(PG8_SA(1, 0), a3, voffA);
;             PG8_WAIT_V(8); PG8_WAIT_L(0); PG8_BAR; PG8_MMA(1, 0, At, B0); PG8_MMA(1, 1, At, B1); PG8_BAR; PG8_SCHED;
	v_mfma_f32_16x16x32_bf16 v[66:69], v[186:189], v[238:241], v[66:69]
	v_mfma_f32_16x16x32_bf16 v[66:69], v[190:193], v[242:245], v[66:69]
	s_setprio 0
	s_add_i32 s0, s2, s49
	v_lshl_add_u64 v[168:169], v[168:169], 0, s[76:77]
	s_mov_b32 m0, s0
	ds_read_b128 v[194:197], v181 offset:49152
	ds_read_b128 v[198:201], v181 offset:50176
	ds_read_b128 v[222:225], v181 offset:51200
	ds_read_b128 v[226:229], v181 offset:52224
	ds_read_b128 v[230:233], v181 offset:53248
	ds_read_b128 v[234:237], v181 offset:54272
	ds_read_b128 v[238:241], v181 offset:55296
	ds_read_b128 v[242:245], v181 offset:56320
	global_load_lds_dwordx4 v[168:169], off
	s_add_i32 m0, s0, 0x2000
	s_add_u32 s0, s36, 0x80080
	v_lshl_add_u64 v[168:169], v[172:173], 0, s[76:77]
	s_addc_u32 s1, s37, 0
	s_add_i32 s2, s15, s49
	global_load_lds_dwordx4 v[168:169], off
	v_lshl_add_u64 v[168:169], s[0:1], 0, v[156:157]
	s_mov_b32 m0, s2
	s_nop 0
	global_load_lds_dwordx4 v[168:169], off
	v_lshl_add_u64 v[168:169], s[0:1], 0, v[152:153]
	s_add_i32 m0, s2, 0x2000
	s_nop 0
	global_load_lds_dwordx4 v[168:169], off
	v_lshl_add_u64 v[168:169], v[202:203], 0, s[76:77]
	s_mov_b32 m0, s59
	s_nop 0
	global_load_lds_dwordx4 v[168:169], off
	v_lshl_add_u64 v[168:169], v[212:213], 0, s[76:77]
	s_mov_b32 m0, s60
	s_nop 0
	global_load_lds_dwordx4 v[168:169], off
	s_waitcnt vmcnt(8)
	s_waitcnt lgkmcnt(0)
	s_setprio 1
	s_barrier
	v_mfma_f32_16x16x32_bf16 v[62:65], v[136:139], v[194:197], v[62:65]
	v_mfma_f32_16x16x32_bf16 v[62:65], v[140:143], v[198:201], v[62:65]
	v_mfma_f32_16x16x32_bf16 v[58:61], v[144:147], v[194:197], v[58:61]
	v_mfma_f32_16x16x32_bf16 v[58:61], v[148:151], v[198:201], v[58:61]
	v_mfma_f32_16x16x32_bf16 v[54:57], v[136:139], v[222:225], v[54:57]
	v_mfma_f32_16x16x32_bf16 v[54:57], v[140:143], v[226:229], v[54:57]
	v_mfma_f32_16x16x32_bf16 v[46:49], v[144:147], v[222:225], v[46:49]
	v_mfma_f32_16x16x32_bf16 v[46:49], v[148:151], v[226:229], v[46:49]
	v_mfma_f32_16x16x32_bf16 v[38:41], v[136:139], v[230:233], v[38:41]
	v_mfma_f32_16x16x32_bf16 v[38:41], v[140:143], v[234:237], v[38:41]
	v_mfma_f32_16x16x32_bf16 v[30:33], v[144:147], v[230:233], v[30:33]
	v_mfma_f32_16x16x32_bf16 v[30:33], v[148:151], v[234:237], v[30:33]
	v_mfma_f32_16x16x32_bf16 v[22:25], v[136:139], v[238:241], v[22:25]
	v_mfma_f32_16x16x32_bf16 v[22:25], v[140:143], v[242:245], v[22:25]
	v_mfma_f32_16x16x32_bf16 v[14:17], v[144:147], v[238:241], v[14:17]
	v_mfma_f32_16x16x32_bf16 v[14:17], v[148:151], v[242:245], v[14:17]
	s_setprio 0
	s_setprio 1
	v_mfma_f32_16x16x32_bf16 v[50:53], v[164:167], v[194:197], v[50:53]
	v_mfma_f32_16x16x32_bf16 v[50:53], v[182:185], v[198:201], v[50:53]
	v_mfma_f32_16x16x32_bf16 v[42:45], v[186:189], v[194:197], v[42:45]
	v_mfma_f32_16x16x32_bf16 v[42:45], v[190:193], v[198:201], v[42:45]
	v_mfma_f32_16x16x32_bf16 v[34:37], v[164:167], v[222:225], v[34:37]
	v_mfma_f32_16x16x32_bf16 v[34:37], v[182:185], v[226:229], v[34:37]
	v_mfma_f32_16x16x32_bf16 v[26:29], v[186:189], v[222:225], v[26:29]
	v_mfma_f32_16x16x32_bf16 v[26:29], v[190:193], v[226:229], v[26:29]
	v_mfma_f32_16x16x32_bf16 v[18:21], v[164:167], v[230:233], v[18:21]
	v_mfma_f32_16x16x32_bf16 v[18:21], v[182:185], v[234:237], v[18:21]
	v_mfma_f32_16x16x32_bf16 v[10:13], v[186:189], v[230:233], v[10:13]
	v_mfma_f32_16x16x32_bf16 v[10:13], v[190:193], v[234:237], v[10:13]
	v_mfma_f32_16x16x32_bf16 v[6:9], v[164:167], v[238:241], v[6:9]
	v_mfma_f32_16x16x32_bf16 v[6:9], v[182:185], v[242:245], v[6:9]
	s_setprio 2
	s_cmp_ge_i32 s13, s71
	s_cbranch_scc0 .Lq4b_1308p
	v_cmp_ne_u32_e64 vcc, s8, 0
	s_cbranch_vccz .Lq4s_1308p

; #define PG8_STAGE(bufoff, gbase, voff) do { _Pragma("unroll") for (int _i = 0; _i < 2; ++_i) \
;         __builtin_amdgcn_global_load_lds((const unsigned*)((const char*)(gbase) + (voff)[_i]), (PG8_LAS unsigned*)(lds + (bufoff) + ldsw + _i * 8192), 16, 0, AUX_A); } while (0)
; #define PG8_STAGEB(bufoff, gbase, voff) do { _Pragma("unroll") for (int _i = 0; _i < 2; ++_i) \
;         __builtin_amdgcn_global_load_lds((const unsigned*)((const char*)(gbase) + (voff)[_i]), (PG8_LAS unsigned*)(lds + (bufoff) + ldsw + _i * 8192), 16, 0, AUX_B); } while (0)
; #define PG8_WAIT_V(n) asm volatile("s_waitcnt vmcnt(" #n ")" ::: "memory")
; #define PG8_WAIT_L(n) asm volatile("s_waitcnt lgkmcnt(" #n ")" ::: "memory")
; template <class Epi, class Sched, bool ALIGN_EPI = false, bool SP2 = false>
; __device__ __forceinline__ void gemm_phase(PG8_LAS unsigned char* lds, const Gemm g, const Sched& S, const Epi& E) {
;     ...
;         for (int t = 0; t < nt; t += 2) {
;             const bool last = (t == nt - 2);
;             const char* a1 = PG8_KP(cA, t + 1, rot, nt);
;             const char* a2 = last ? nAr : PG8_KP(cA, t + 2, rot, nt); const char* b2 = last ? nBr : PG8_KP(cB, t + 2, rot, nt);
;             const char* a3 = a2 + kstep; const char* b3 = b2 + kstep;
;             if (last && has_next) S.a_ready(nxt);
;             if constexpr (SP2) {
;             PG8_LDB(B0, 0, 0); PG8_LDB(B1, 0, 1); PG8_SCHED; PG8_LDA(At, 0, 0); PG8_STAGE(PG8_SA(1, 1), a1 + hstep, voffA);
;             PG8_WAIT_V(8); PG8_WAIT_L(0); PG8_BAR; PG8_MMA(0, 0, At, B0); PG8_MMA(0, 1, At, B1); PG8_BAR; PG8_SCHED;
;             PG8_LDA(At, 0, 1); PG8_STAGEB(PG8_SB(0, 0), b2, voffB); PG8_STAGEB(PG8_SB(0, 1), b2 + hstep, voffB); PG8_STAGE(PG8_SA(0, 0), a2, voffA);
;             PG8_WAIT_V(8); PG8_WAIT_L(0); PG8_BAR; PG8_MMA(1, 0, At, B0); PG8_MMA(1, 1, At, B1); PG8_BAR; PG8_SCHED;
;             PG8_LDB(B0, 1, 0); PG8_LDB(B1, 1, 1); PG8_SCHED; PG8_LDA(At, 1, 0); PG8_STAGE(PG8_SA(0, 1), a2 + hstep, voffA);
;             PG8_WAIT_V(8); PG8_WAIT_L(0); PG8_BAR; PG8_MMA(0, 0, At, B0); PG8_MMA(0, 1, At, B1); PG8_BAR; PG8_SCHED;
;             PG8_LDA(At, 1, 1); PG8_STAGEB(PG8_SB(1, 0), b3, voffB); PG8_STAGEB(PG8_SB(1, 1), b3 + hstep, voffB); PG8_STAGE(PG8_SA(1, 0), a3, voffA);
;             PG8_WAIT_V(8); PG8_WAIT_L(0); PG8_BAR; PG8_MMA(1, 0, At, B0); PG8_MMA(1, 1, At, B1); PG8_BAR; PG8_SCHED;
.Lq4s_1308p:
	v_mfma_f32_16x16x32_bf16 v[2:5], v[186:189], v[238:241], v[2:5]
	v_mfma_f32_16x16x32_bf16 v[2:5], v[190:193], v[242:245], v[2:5]
	s_setprio 0
	s_add_i32 s0, s13, 2
	v_lshl_add_u64 v[132:133], v[132:133], 0, s[86:87]
	v_lshl_add_u64 v[134:135], v[134:135], 0, s[86:87]
	s_cmp_ge_i32 s13, s71
	s_mov_b32 s13, s0
	s_cbranch_scc1 .Lpx_1308
.LBB0_1308:
	s_or_b32 s0, s11, 1
	s_cmp_ge_i32 s0, s71
	s_cselect_b32 s2, s71, 0
	s_add_i32 s11, s11, 2
	s_cmp_ge_i32 s11, s71
	s_cselect_b32 s0, s71, 0
	s_sub_i32 s0, s13, s0
	s_ashr_i32 s1, s0, 31
	s_lshl_b64 s[0:1], s[0:1], 7
	s_add_u32 s15, s40, s0
	s_addc_u32 s29, s41, s1
	s_add_u32 s0, s34, s0
	s_addc_u32 s1, s35, s1
	s_cmp_eq_u32 s71, s13
	s_cselect_b32 s45, s43, s29
	s_cselect_b32 s44, s42, s15
	s_cselect_b32 s37, s19, s1
	s_cselect_b32 s36, s18, s0
	s_add_i32 s15, 0, 0x10000
	s_add_i32 s29, 0, 0x14000
	v_add_u32_e32 v148, s15, v99
	v_add_u32_e32 v168, s29, v99
	ds_read_b128 v[136:139], v148
	ds_read_b128 v[140:143], v148 offset:1024
	ds_read_b128 v[144:147], v148 offset:2048
	ds_read_b128 v[148:151], v148 offset:3072
	ds_read_b128 v[164:167], v168
	ds_read_b128 v[182:185], v168 offset:1024
	ds_read_b128 v[186:189], v168 offset:2048
	ds_read_b128 v[190:193], v168 offset:3072
	v_mad_i64_i32 v[168:169], s[0:1], s2, v220, v[134:135]
	s_add_i32 m0, s50, 0xc000
	ds_read_b128 v[194:197], v181
	ds_read_b128 v[198:201], v181 offset:1024
	ds_read_b128 v[222:225], v181 offset:2048
	ds_read_b128 v[226:229], v181 offset:3072
	ds_read_b128 v[230:233], v181 offset:4096
	ds_read_b128 v[234:237], v181 offset:5120
	ds_read_b128 v[238:241], v181 offset:6144
	ds_read_b128 v[242:245], v181 offset:7168
	global_load_lds_dwordx4 v[168:169], off
	v_mad_i64_i32 v[168:169], s[0:1], s2, v220, v[132:133]
	s_add_i32 m0, s50, 0xe000
	s_nop 0
	global_load_lds_dwordx4 v[168:169], off
	s_waitcnt vmcnt(8)
	s_waitcnt lgkmcnt(0)
	s_setprio 1
	s_barrier
	v_mfma_f32_16x16x32_bf16 v[128:131], v[136:139], v[194:197], v[128:131]
	v_mfma_f32_16x16x32_bf16 v[128:131], v[140:143], v[198:201], v[128:131]
	v_mfma_f32_16x16x32_bf16 v[124:127], v[144:147], v[194:197], v[124:127]
	v_mfma_f32_16x16x32_bf16 v[124:127], v[148:151], v[198:201], v[124:127]
	v_mfma_f32_16x16x32_bf16 v[120:123], v[136:139], v[222:225], v[120:123]
	v_mfma_f32_16x16x32_bf16 v[120:123], v[140:143], v[226:229], v[120:123]
	v_mfma_f32_16x16x32_bf16 v[112:115], v[144:147], v[222:225], v[112:115]
	v_mfma_f32_16x16x32_bf16 v[112:115], v[148:151], v[226:229], v[112:115]
	v_mfma_f32_16x16x32_bf16 v[104:107], v[136:139], v[230:233], v[104:107]
	v_mfma_f32_16x16x32_bf16 v[104:107], v[140:143], v[234:237], v[104:107]
	v_mfma_f32_16x16x32_bf16 v[94:97], v[144:147], v[230:233], v[94:97]
	v_mfma_f32_16x16x32_bf16 v[94:97], v[148:151], v[234:237], v[94:97]
	v_mfma_f32_16x16x32_bf16 v[86:89], v[136:139], v[238:241], v[86:89]
	v_mfma_f32_16x16x32_bf16 v[86:89], v[140:143], v[242:245], v[86:89]
	v_mfma_f32_16x16x32_bf16 v[78:81], v[144:147], v[238:241], v[78:81]
	v_mfma_f32_16x16x32_bf16 v[78:81], v[148:151], v[242:245], v[78:81]
	s_setprio 0
	s_setprio 1
	v_mfma_f32_16x16x32_bf16 v[116:119], v[164:167], v[194:197], v[116:119]
	v_mfma_f32_16x16x32_bf16 v[116:119], v[182:185], v[198:201], v[116:119]
	v_mfma_f32_16x16x32_bf16 v[108:111], v[186:189], v[194:197], v[108:111]
	v_mfma_f32_16x16x32_bf16 v[108:111], v[190:193], v[198:201], v[108:111]
	v_mfma_f32_16x16x32_bf16 v[100:103], v[164:167], v[222:225], v[100:103]
	v_mfma_f32_16x16x32_bf16 v[100:103], v[182:185], v[226:229], v[100:103]
	v_mfma_f32_16x16x32_bf16 v[90:93], v[186:189], v[222:225], v[90:93]
	v_mfma_f32_16x16x32_bf16 v[90:93], v[190:193], v[226:229], v[90:93]
	v_mfma_f32_16x16x32_bf16 v[82:85], v[164:167], v[230:233], v[82:85]
	v_mfma_f32_16x16x32_bf16 v[82:85], v[182:185], v[234:237], v[82:85]
	v_mfma_f32_16x16x32_bf16 v[74:77], v[186:189], v[230:233], v[74:77]
	v_mfma_f32_16x16x32_bf16 v[74:77], v[190:193], v[234:237], v[74:77]
	v_mfma_f32_16x16x32_bf16 v[70:73], v[164:167], v[238:241], v[70:73]
	v_mfma_f32_16x16x32_bf16 v[70:73], v[182:185], v[242:245], v[70:73]
	s_setprio 2
	s_barrier
	v_mfma_f32_16x16x32_bf16 v[66:69], v[186:189], v[238:241], v[66:69]
	v_mfma_f32_16x16x32_bf16 v[66:69], v[190:193], v[242:245], v[66:69]
	s_setprio 0
	s_add_i32 s0, s15, s49
	v_lshl_add_u64 v[168:169], s[36:37], 0, v[156:157]
	s_mov_b32 m0, s0
	ds_read_b128 v[194:197], v181 offset:16384
	ds_read_b128 v[198:201], v181 offset:17408
	ds_read_b128 v[222:225], v181 offset:18432
	ds_read_b128 v[226:229], v181 offset:19456
	ds_read_b128 v[230:233], v181 offset:20480
	ds_read_b128 v[234:237], v181 offset:21504
	ds_read_b128 v[238:241], v181 offset:22528
	ds_read_b128 v[242:245], v181 offset:23552
	global_load_lds_dwordx4 v[168:169], off
	s_add_i32 m0, s0, 0x2000
	s_add_u32 s0, s36, 0x80000
	v_lshl_add_u64 v[172:173], s[36:37], 0, v[152:153]
	s_addc_u32 s1, s37, 0
	s_add_i32 s2, s29, s49
	global_load_lds_dwordx4 v[172:173], off
	v_lshl_add_u64 v[202:203], s[0:1], 0, v[156:157]
	s_mov_b32 m0, s2
	v_lshl_add_u64 v[212:213], s[44:45], 0, v[154:155]
	global_load_lds_dwordx4 v[202:203], off
	v_lshl_add_u64 v[202:203], s[0:1], 0, v[152:153]
	s_add_i32 m0, s2, 0x2000
	s_nop 0
	global_load_lds_dwordx4 v[202:203], off
	v_lshl_add_u64 v[202:203], s[44:45], 0, v[158:159]
	s_mov_b32 m0, s50
	s_nop 0
	global_load_lds_dwordx4 v[202:203], off
	s_mov_b32 m0, s51
	s_nop 0
	global_load_lds_dwordx4 v[212:213], off
	s_waitcnt vmcnt(8)
	s_waitcnt lgkmcnt(0)
	s_setprio 1
	s_barrier
; #define PG8_STAGE(bufoff, gbase, voff) do { _Pragma("unroll") for (int _i = 0; _i < 2; ++_i) \
;         __builtin_amdgcn_global_load_lds((const unsigned*)((const char*)(gbase) + (voff)[_i]), (PG8_LAS unsigned*)(lds + (bufoff) + ldsw + _i * 8192), 16, 0, AUX_A); } while (0)
; #define PG8_LDA(dst, b, h) do { _Pragma("unroll") for (int m = 0; m < 4; ++m) _Pragma("unroll") for (int k = 0; k < 2; ++k) dst[m][k] = *(const PG8_LAS bf16x8*)(lds + PG8_SA(b, h) + aoff + m * 2048 + k * 1024); } while (0)
; #define PG8_LDB(dst, b, h) do { _Pragma("unroll") for (int n = 0; n < 2; ++n) _Pragma("unroll") for (int k = 0; k < 2; ++k) dst[n][k] = *(const PG8_LAS bf16x8*)(lds + PG8_SB(b, h) + boff + n * 2048 + k * 1024); } while (0)
; #define PG8_MMA(ai, bj, At, Bt) do { __builtin_amdgcn_s_setprio(1); _Pragma("unroll") for (int m = 0; m < 4; ++m) _Pragma("unroll") for (int n = 0; n < 2; ++n) _Pragma("unroll") for (int k = 0; k < 2; ++k) \
;         acc[ai][bj][m][n] = __builtin_amdgcn_mfma_f32_16x16x32_bf16(Bt[n][k], At[m][k], acc[ai][bj][m][n], 0, 0, 0); __builtin_amdgcn_s_setprio(0); } while (0)
; #define PG8_WAIT_V(n) asm volatile("s_waitcnt vmcnt(" #n ")" ::: "memory")
; #define PG8_WAIT_L(n) asm volatile("s_waitcnt lgkmcnt(" #n ")" ::: "memory")
; #define PG8_BAR __builtin_amdgcn_s_barrier()
; #define PG8_SCHED __builtin_amdgcn_sched_barrier(0)
; template <class Epi, class Sched, bool ALIGN_EPI = false, bool SP2 = false>
; __device__ __forceinline__ void gemm_phase(PG8_LAS unsigned char* lds, const Gemm g, const Sched& S, const Epi& E) {
;     ...
;             PG8_WAIT_V(8); PG8_WAIT_L(0); PG8_BAR; PG8_MMA(1, 0, At, B0); PG8_MMA(1, 1, At, B1); PG8_BAR; PG8_SCHED;
;             PG8_LDB(B0, 1, 0); PG8_LDB(B1, 1, 1); PG8_SCHED; PG8_LDA(At, 1, 0); PG8_STAGE(PG8_SA(0, 1), a2 + hstep, voffA);
;             PG8_WAIT_V(8); PG8_WAIT_L(0); PG8_BAR; PG8_MMA(0, 0, At, B0); PG8_MMA(0, 1, At, B1); PG8_BAR; PG8_SCHED;
	v_mfma_f32_16x16x32_bf16 v[62:65], v[136:139], v[194:197], v[62:65]
	v_mfma_f32_16x16x32_bf16 v[62:65], v[140:143], v[198:201], v[62:65]
	v_mfma_f32_16x16x32_bf16 v[58:61], v[144:147], v[194:197], v[58:61]
	v_mfma_f32_16x16x32_bf16 v[58:61], v[148:151], v[198:201], v[58:61]
	v_mfma_f32_16x16x32_bf16 v[54:57], v[136:139], v[222:225], v[54:57]
	v_mfma_f32_16x16x32_bf16 v[54:57], v[140:143], v[226:229], v[54:57]
	v_mfma_f32_16x16x32_bf16 v[46:49], v[144:147], v[222:225], v[46:49]
	v_mfma_f32_16x16x32_bf16 v[46:49], v[148:151], v[226:229], v[46:49]
	v_mfma_f32_16x16x32_bf16 v[38:41], v[136:139], v[230:233], v[38:41]
	v_mfma_f32_16x16x32_bf16 v[38:41], v[140:143], v[234:237], v[38:41]
	v_mfma_f32_16x16x32_bf16 v[30:33], v[144:147], v[230:233], v[30:33]
	v_mfma_f32_16x16x32_bf16 v[30:33], v[148:151], v[234:237], v[30:33]
	v_mfma_f32_16x16x32_bf16 v[22:25], v[136:139], v[238:241], v[22:25]
	v_mfma_f32_16x16x32_bf16 v[22:25], v[140:143], v[242:245], v[22:25]
	v_mfma_f32_16x16x32_bf16 v[14:17], v[144:147], v[238:241], v[14:17]
	v_mfma_f32_16x16x32_bf16 v[14:17], v[148:151], v[242:245], v[14:17]
	s_setprio 0
	s_setprio 1
	v_mfma_f32_16x16x32_bf16 v[50:53], v[164:167], v[194:197], v[50:53]
	v_mfma_f32_16x16x32_bf16 v[50:53], v[182:185], v[198:201], v[50:53]
	v_mfma_f32_16x16x32_bf16 v[42:45], v[186:189], v[194:197], v[42:45]
	v_mfma_f32_16x16x32_bf16 v[42:45], v[190:193], v[198:201], v[42:45]
	v_mfma_f32_16x16x32_bf16 v[34:37], v[164:167], v[222:225], v[34:37]
	v_mfma_f32_16x16x32_bf16 v[34:37], v[182:185], v[226:229], v[34:37]
	v_mfma_f32_16x16x32_bf16 v[26:29], v[186:189], v[222:225], v[26:29]
	v_mfma_f32_16x16x32_bf16 v[26:29], v[190:193], v[226:229], v[26:29]
	v_mfma_f32_16x16x32_bf16 v[18:21], v[164:167], v[230:233], v[18:21]
	v_mfma_f32_16x16x32_bf16 v[18:21], v[182:185], v[234:237], v[18:21]
	v_mfma_f32_16x16x32_bf16 v[10:13], v[186:189], v[230:233], v[10:13]
	v_mfma_f32_16x16x32_bf16 v[10:13], v[190:193], v[234:237], v[10:13]
	v_mfma_f32_16x16x32_bf16 v[6:9], v[164:167], v[238:241], v[6:9]
	v_mfma_f32_16x16x32_bf16 v[6:9], v[182:185], v[242:245], v[6:9]
	s_setprio 2
	s_barrier
	v_mfma_f32_16x16x32_bf16 v[2:5], v[186:189], v[238:241], v[2:5]
	v_mfma_f32_16x16x32_bf16 v[2:5], v[190:193], v[242:245], v[2:5]
	s_setprio 0
	s_add_i32 s2, 0, 0x18000
	s_add_i32 s15, 0, 0x1c000
	v_add_u32_e32 v148, s2, v99
	v_add_u32_e32 v190, s15, v99
	ds_read_b128 v[136:139], v148
	ds_read_b128 v[140:143], v148 offset:1024
	ds_read_b128 v[144:147], v148 offset:2048
	ds_read_b128 v[148:151], v148 offset:3072
	ds_read_b128 v[164:167], v190
	ds_read_b128 v[182:185], v190 offset:1024
	ds_read_b128 v[186:189], v190 offset:2048
	ds_read_b128 v[190:193], v190 offset:3072
	s_add_u32 s0, s44, 0x80000
	s_addc_u32 s1, s45, 0
	s_mov_b32 m0, s52
	v_lshl_add_u64 v[246:247], s[0:1], 0, v[158:159]
	ds_read_b128 v[194:197], v181 offset:32768
	ds_read_b128 v[198:201], v181 offset:33792
	ds_read_b128 v[222:225], v181 offset:34816
	ds_read_b128 v[226:229], v181 offset:35840
	ds_read_b128 v[230:233], v181 offset:36864
	ds_read_b128 v[234:237], v181 offset:37888
	ds_read_b128 v[238:241], v181 offset:38912
	ds_read_b128 v[242:245], v181 offset:39936
	global_load_lds_dwordx4 v[246:247], off
	v_lshl_add_u64 v[246:247], s[0:1], 0, v[154:155]
	s_mov_b32 m0, s53
	s_nop 0
	global_load_lds_dwordx4 v[246:247], off
	s_waitcnt vmcnt(8)
	s_waitcnt lgkmcnt(0)
	s_setprio 1
	s_barrier
	v_mfma_f32_16x16x32_bf16 v[128:131], v[136:139], v[194:197], v[128:131]
	v_mfma_f32_16x16x32_bf16 v[128:131], v[140:143], v[198:201], v[128:131]
	v_mfma_f32_16x16x32_bf16 v[124:127], v[144:147], v[194:197], v[124:127]
	v_mfma_f32_16x16x32_bf16 v[124:127], v[148:151], v[198:201], v[124:127]
	v_mfma_f32_16x16x32_bf16 v[120:123], v[136:139], v[222:225], v[120:123]
	v_mfma_f32_16x16x32_bf16 v[120:123], v[140:143], v[226:229], v[120:123]
	v_mfma_f32_16x16x32_bf16 v[112:115], v[144:147], v[222:225], v[112:115]
	v_mfma_f32_16x16x32_bf16 v[112:115], v[148:151], v[226:229], v[112:115]
	v_mfma_f32_16x16x32_bf16 v[104:107], v[136:139], v[230:233], v[104:107]
	v_mfma_f32_16x16x32_bf16 v[104:107], v[140:143], v[234:237], v[104:107]
	v_mfma_f32_16x16x32_bf16 v[94:97], v[144:147], v[230:233], v[94:97]
	v_mfma_f32_16x16x32_bf16 v[94:97], v[148:151], v[234:237], v[94:97]
	v_mfma_f32_16x16x32_bf16 v[86:89], v[136:139], v[238:241], v[86:89]
	v_mfma_f32_16x16x32_bf16 v[86:89], v[140:143], v[242:245], v[86:89]
	v_mfma_f32_16x16x32_bf16 v[78:81], v[144:147], v[238:241], v[78:81]
	v_mfma_f32_16x16x32_bf16 v[78:81], v[148:151], v[242:245], v[78:81]
	s_setprio 0
	s_setprio 1
	v_mfma_f32_16x16x32_bf16 v[116:119], v[164:167], v[194:197], v[116:119]
	v_mfma_f32_16x16x32_bf16 v[116:119], v[182:185], v[198:201], v[116:119]
	v_mfma_f32_16x16x32_bf16 v[108:111], v[186:189], v[194:197], v[108:111]
	v_mfma_f32_16x16x32_bf16 v[108:111], v[190:193], v[198:201], v[108:111]
	v_mfma_f32_16x16x32_bf16 v[100:103], v[164:167], v[222:225], v[100:103]
	v_mfma_f32_16x16x32_bf16 v[100:103], v[182:185], v[226:229], v[100:103]
	v_mfma_f32_16x16x32_bf16 v[90:93], v[186:189], v[222:225], v[90:93]
	v_mfma_f32_16x16x32_bf16 v[90:93], v[190:193], v[226:229], v[90:93]
	v_mfma_f32_16x16x32_bf16 v[82:85], v[164:167], v[230:233], v[82:85]
	v_mfma_f32_16x16x32_bf16 v[82:85], v[182:185], v[234:237], v[82:85]
	v_mfma_f32_16x16x32_bf16 v[74:77], v[186:189], v[230:233], v[74:77]
	v_mfma_f32_16x16x32_bf16 v[74:77], v[190:193], v[234:237], v[74:77]
	v_mfma_f32_16x16x32_bf16 v[70:73], v[164:167], v[238:241], v[70:73]
	v_mfma_f32_16x16x32_bf16 v[70:73], v[182:185], v[242:245], v[70:73]
	s_setprio 2
	s_barrier
; #define PG8_STAGE(bufoff, gbase, voff) do { _Pragma("unroll") for (int _i = 0; _i < 2; ++_i) \
;         __builtin_amdgcn_global_load_lds((const unsigned*)((const char*)(gbase) + (voff)[_i]), (PG8_LAS unsigned*)(lds + (bufoff) + ldsw + _i * 8192), 16, 0, AUX_A); } while (0)
; #define PG8_STAGEB(bufoff, gbase, voff) do { _Pragma("unroll") for (int _i = 0; _i < 2; ++_i) \
;         __builtin_amdgcn_global_load_lds((const unsigned*)((const char*)(gbase) + (voff)[_i]), (PG8_LAS unsigned*)(lds + (bufoff) + ldsw + _i * 8192), 16, 0, AUX_B); } while (0)
; #define PG8_LDA(dst, b, h) do { _Pragma("unroll") for (int m = 0; m < 4; ++m) _Pragma("unroll") for (int k = 0; k < 2; ++k) dst[m][k] = *(const PG8_LAS bf16x8*)(lds + PG8_SA(b, h) + aoff + m * 2048 + k * 1024); } while (0)
; #define PG8_MMA(ai, bj, At, Bt) do { __builtin_amdgcn_s_setprio(1); _Pragma("unroll") for (int m = 0; m < 4; ++m) _Pragma("unroll") for (int n = 0; n < 2; ++n) _Pragma("unroll") for (int k = 0; k < 2; ++k) \
;         acc[ai][bj][m][n] = __builtin_amdgcn_mfma_f32_16x16x32_bf16(Bt[n][k], At[m][k], acc[ai][bj][m][n], 0, 0, 0); __builtin_amdgcn_s_setprio(0); } while (0)
; #define PG8_WAIT_V(n) asm volatile("s_waitcnt vmcnt(" #n ")" ::: "memory")
; #define PG8_WAIT_L(n) asm volatile("s_waitcnt lgkmcnt(" #n ")" ::: "memory")
; #define PG8_BAR __builtin_amdgcn_s_barrier()
; #define PG8_SCHED __builtin_amdgcn_sched_barrier(0)
; template <class Epi, class Sched, bool ALIGN_EPI = false, bool SP2 = false>
; __device__ __forceinline__ void gemm_phase(PG8_LAS unsigned char* lds, const Gemm g, const Sched& S, const Epi& E) {
;     ...
;             PG8_WAIT_V(8); PG8_WAIT_L(0); PG8_BAR; PG8_MMA(0, 0, At, B0); PG8_MMA(0, 1, At, B1); PG8_BAR; PG8_SCHED;
;             PG8_LDA(At, 1, 1); PG8_STAGEB(PG8_SB(1, 0), b3, voffB); PG8_STAGEB(PG8_SB(1, 1), b3 + hstep, voffB); PG8_STAGE(PG8_SA(1, 0), a3, voffA);
;             PG8_WAIT_V(8); PG8_WAIT_L(0); PG8_BAR; PG8_MMA(1, 0, At, B0); PG8_MMA(1, 1, At, B1); PG8_BAR; PG8_SCHED;
	v_mfma_f32_16x16x32_bf16 v[66:69], v[186:189], v[238:241], v[66:69]
	v_mfma_f32_16x16x32_bf16 v[66:69], v[190:193], v[242:245], v[66:69]
	s_setprio 0
	s_add_i32 s0, s2, s49
	v_lshl_add_u64 v[168:169], v[168:169], 0, s[76:77]
	s_mov_b32 m0, s0
	ds_read_b128 v[194:197], v181 offset:49152
	ds_read_b128 v[198:201], v181 offset:50176
	ds_read_b128 v[222:225], v181 offset:51200
	ds_read_b128 v[226:229], v181 offset:52224
	ds_read_b128 v[230:233], v181 offset:53248
	ds_read_b128 v[234:237], v181 offset:54272
	ds_read_b128 v[238:241], v181 offset:55296
	ds_read_b128 v[242:245], v181 offset:56320
	global_load_lds_dwordx4 v[168:169], off
	s_add_i32 m0, s0, 0x2000
	s_add_u32 s0, s36, 0x80080
	v_lshl_add_u64 v[168:169], v[172:173], 0, s[76:77]
	s_addc_u32 s1, s37, 0
	s_add_i32 s2, s15, s49
	global_load_lds_dwordx4 v[168:169], off
	v_lshl_add_u64 v[168:169], s[0:1], 0, v[156:157]
	s_mov_b32 m0, s2
	s_nop 0
	global_load_lds_dwordx4 v[168:169], off
	v_lshl_add_u64 v[168:169], s[0:1], 0, v[152:153]
	s_add_i32 m0, s2, 0x2000
	s_nop 0
	global_load_lds_dwordx4 v[168:169], off
	v_lshl_add_u64 v[168:169], v[202:203], 0, s[76:77]
	s_mov_b32 m0, s59
	s_nop 0
	global_load_lds_dwordx4 v[168:169], off
	v_lshl_add_u64 v[168:169], v[212:213], 0, s[76:77]
	s_mov_b32 m0, s60
	s_nop 0
	global_load_lds_dwordx4 v[168:169], off
	s_waitcnt vmcnt(8)
	s_waitcnt lgkmcnt(0)
	s_setprio 1
	s_barrier
	v_mfma_f32_16x16x32_bf16 v[62:65], v[136:139], v[194:197], v[62:65]
	v_mfma_f32_16x16x32_bf16 v[62:65], v[140:143], v[198:201], v[62:65]
	v_mfma_f32_16x16x32_bf16 v[58:61], v[144:147], v[194:197], v[58:61]
	v_mfma_f32_16x16x32_bf16 v[58:61], v[148:151], v[198:201], v[58:61]
	v_mfma_f32_16x16x32_bf16 v[54:57], v[136:139], v[222:225], v[54:57]
	v_mfma_f32_16x16x32_bf16 v[54:57], v[140:143], v[226:229], v[54:57]
	v_mfma_f32_16x16x32_bf16 v[46:49], v[144:147], v[222:225], v[46:49]
	v_mfma_f32_16x16x32_bf16 v[46:49], v[148:151], v[226:229], v[46:49]
	v_mfma_f32_16x16x32_bf16 v[38:41], v[136:139], v[230:233], v[38:41]
	v_mfma_f32_16x16x32_bf16 v[38:41], v[140:143], v[234:237], v[38:41]
	v_mfma_f32_16x16x32_bf16 v[30:33], v[144:147], v[230:233], v[30:33]
	v_mfma_f32_16x16x32_bf16 v[30:33], v[148:151], v[234:237], v[30:33]
	v_mfma_f32_16x16x32_bf16 v[22:25], v[136:139], v[238:241], v[22:25]
	v_mfma_f32_16x16x32_bf16 v[22:25], v[140:143], v[242:245], v[22:25]
	v_mfma_f32_16x16x32_bf16 v[14:17], v[144:147], v[238:241], v[14:17]
	v_mfma_f32_16x16x32_bf16 v[14:17], v[148:151], v[242:245], v[14:17]
	s_setprio 0
	s_setprio 1
	v_mfma_f32_16x16x32_bf16 v[50:53], v[164:167], v[194:197], v[50:53]
	v_mfma_f32_16x16x32_bf16 v[50:53], v[182:185], v[198:201], v[50:53]
	v_mfma_f32_16x16x32_bf16 v[42:45], v[186:189], v[194:197], v[42:45]
	v_mfma_f32_16x16x32_bf16 v[42:45], v[190:193], v[198:201], v[42:45]
	v_mfma_f32_16x16x32_bf16 v[34:37], v[164:167], v[222:225], v[34:37]
	v_mfma_f32_16x16x32_bf16 v[34:37], v[182:185], v[226:229], v[34:37]
	v_mfma_f32_16x16x32_bf16 v[26:29], v[186:189], v[222:225], v[26:29]
	v_mfma_f32_16x16x32_bf16 v[26:29], v[190:193], v[226:229], v[26:29]
	v_mfma_f32_16x16x32_bf16 v[18:21], v[164:167], v[230:233], v[18:21]
	v_mfma_f32_16x16x32_bf16 v[18:21], v[182:185], v[234:237], v[18:21]
	v_mfma_f32_16x16x32_bf16 v[10:13], v[186:189], v[230:233], v[10:13]
	v_mfma_f32_16x16x32_bf16 v[10:13], v[190:193], v[234:237], v[10:13]
	v_mfma_f32_16x16x32_bf16 v[6:9], v[164:167], v[238:241], v[6:9]
	v_mfma_f32_16x16x32_bf16 v[6:9], v[182:185], v[242:245], v[6:9]
	s_setprio 2
	s_cmp_ge_i32 s13, s71
	s_cbranch_scc0 .Lq4b_1308l
	v_cmp_ne_u32_e64 vcc, s8, 0
	s_cbranch_vccz .Lq4s_1308l

;     __device__ __forceinline__ void operator()(const f32x4 (&acc)[2][2][4][2], const Unit& u, int wr, int wc, int fr, int fq) const {
;         const int col0 = u.pn * BM + wc * 32 + 8 * fq;
;         const bool part = u.slab >= 0;
; #pragma unroll
;         for (int ai = 0; ai < 2; ++ai) {
;             const int rb = u.pm * BM + ai * HALF + wr * 64;
;             const int cb = rb < 8192 ? (rb >> 11) : 4 + ((rb - 8192) >> 6);
;             const float* g = gmod + (size_t)cb * 12288 + col0;
;             f32x4 gv[2][2];
; #pragma unroll
;             for (int bj = 0; bj < 2; ++bj)
; #pragma unroll
;                 for (int n = 0; n < 2; ++n) gv[bj][n] = *(const GAS f32x4*)(g + bj * HALF + 4 * n);
; template <class Epi, class Sched, bool ALIGN_EPI = false, bool SP2 = false>
; __device__ __forceinline__ void gemm_phase(PG8_LAS unsigned char* lds, const Gemm g, const Sched& S, const Epi& E) {
;     ...
;             PG8_WAIT_V(8); PG8_WAIT_L(0); PG8_BAR; PG8_MMA(1, 0, At, B0); PG8_MMA(1, 1, At, B1); PG8_BAR; PG8_SCHED;
;             } else {
;             PG8_LDB(B0, 0, 0); PG8_SCHED; PG8_LDA(At, 0, 0); PG8_STAGE(PG8_SA(1, 1), a1 + hstep, voffA);
;             PG8_WAIT_L(8); PG8_BAR; PG8_WAIT_L(0); PG8_MMA(0, 0, At, B0); PG8_BAR; PG8_SCHED;
;             PG8_LDB(B1, 0, 1); PG8_STAGEB(PG8_SB(0, 0), b2, voffB);
;             PG8_BAR; PG8_WAIT_L(0); PG8_MMA(0, 1, At, B1); PG8_BAR;
;             PG8_LDA(At, 0, 1); PG8_STAGE(PG8_SA(0, 0), a2, voffA);
;             PG8_BAR; PG8_WAIT_L(0); PG8_MMA(1, 0, At, B0); PG8_BAR; PG8_SCHED;
;             PG8_STAGEB(PG8_SB(0, 1), b2 + hstep, voffB);
;             PG8_WAIT_V(6); PG8_BAR; PG8_MMA(1, 1, At, B1); PG8_BAR;
;             PG8_LDB(B0, 1, 0); PG8_SCHED; PG8_LDA(At, 1, 0); PG8_STAGE(PG8_SA(0, 1), a2 + hstep, voffA);
;             PG8_WAIT_L(8); PG8_BAR; PG8_WAIT_L(0); PG8_MMA(0, 0, At, B0); PG8_BAR; PG8_SCHED;
;             PG8_LDB(B1, 1, 1); PG8_STAGEB(PG8_SB(1, 0), b3, voffB);
;             PG8_BAR; PG8_WAIT_L(0); PG8_MMA(0, 1, At, B1); PG8_BAR;
;             PG8_LDA(At, 1, 1); PG8_STAGE(PG8_SA(1, 0), a3, voffA);
;             PG8_BAR; PG8_WAIT_L(0); PG8_MMA(1, 0, At, B0); PG8_BAR; PG8_SCHED;
;             PG8_STAGEB(PG8_SB(1, 1), b3 + hstep, voffB);
;             PG8_WAIT_V(6); PG8_BAR; PG8_MMA(1, 1, At, B1); PG8_BAR;
;             }
;         }
;         if constexpr (ALIGN_EPI) { if (wr == 0) PG8_BAR; }
.Lq4s_1308l:
	v_mfma_f32_16x16x32_bf16 v[2:5], v[186:189], v[238:241], v[2:5]
	v_mfma_f32_16x16x32_bf16 v[2:5], v[190:193], v[242:245], v[2:5]
	s_setprio 0
	s_add_i32 s0, s13, 2
	v_lshl_add_u64 v[132:133], v[132:133], 0, s[86:87]
	v_lshl_add_u64 v[134:135], v[134:135], 0, s[86:87]
	s_cmp_ge_i32 s13, s71
	s_mov_b32 s13, s0
	s_cbranch_scc0 .LBB0_1308
.Lpx_1308:
	s_and_b64 vcc, exec, s[8:9]
	s_cbranch_vccz .LBB0_1311
.LBB0_1311:
	s_cmp_lt_i32 s78, 0
	s_cselect_b64 s[34:35], -1, 0
	s_lshl_b32 s11, s69, 8
	s_add_i32 s11, s11, s58
	s_add_i32 s13, s11, 0xffffe000
	s_lshr_b32 s1, s13, 6
	s_ashr_i32 s0, s11, 11
	s_add_i32 s1, s1, 4
	s_cmpk_lt_i32 s11, 0x2000
	s_cselect_b32 s0, s0, s1
	s_mul_hi_i32 s1, s0, 0xc000
	s_mul_i32 s0, s0, 0xc000
	v_lshl_or_b32 v164, s70, 8, v180
	s_add_u32 s0, s54, s0
	v_ashrrev_i32_e32 v165, 31, v164
	s_addc_u32 s1, s55, s1
	v_lshl_add_u64 v[136:137], v[164:165], 2, s[0:1]
	global_load_dwordx4 v[140:143], v[136:137], off offset:16
	global_load_dwordx4 v[144:147], v[136:137], off
	global_load_dwordx4 v[132:135], v[136:137], off offset:528
	s_nop 0
	global_load_dwordx4 v[136:139], v[136:137], off offset:512
	s_mov_b64 s[36:37], -1
	s_and_b64 vcc, exec, s[34:35]
	s_cbranch_vccz .LBB0_1313
	v_or_b32_e32 v148, s11, v1
	v_ashrrev_i32_e32 v149, 31, v148
	v_lshlrev_b64 v[148:149], 12, v[148:149]
	v_lshl_add_u64 v[148:149], s[6:7], 0, v[148:149]
	v_lshl_add_u64 v[148:149], v[164:165], 1, v[148:149]
	global_load_dwordx4 v[222:225], v[148:149], off
	global_load_dwordx4 v[226:229], v[148:149], off offset:256
	v_add_co_u32_e32 v188, vcc, s73, v148
	s_nop 1
	v_addc_co_u32_e32 v189, vcc, 0, v149, vcc
	global_load_dwordx4 v[230:233], v[188:189], off
	global_load_dwordx4 v[234:237], v[188:189], off offset:256
	v_add_co_u32_e32 v188, vcc, s3, v148
	s_nop 1
	v_addc_co_u32_e32 v189, vcc, 0, v149, vcc
	global_load_dwordx4 v[238:241], v[188:189], off
	global_load_dwordx4 v[242:245], v[188:189], off offset:256
	v_add_co_u32_e32 v188, vcc, s46, v148
	s_nop 1
	v_addc_co_u32_e32 v189, vcc, 0, v149, vcc
	global_load_dwordx4 v[194:197], v[188:189], off
	global_load_dwordx4 v[198:201], v[188:189], off offset:256
	s_mov_b64 s[36:37], 0
	s_waitcnt vmcnt(7)
	s_nop 1
	v_mov_b32_e32 v182, v222
	v_mov_b32_e32 v183, v223
	v_mov_b32_e32 v184, v224
	v_mov_b32_e32 v185, v225
	v_lshlrev_b32_e32 v150, 16, v182
	v_and_b32_e32 v151, 0xffff0000, v182
	v_lshlrev_b32_e32 v166, 16, v183
	v_and_b32_e32 v167, 0xffff0000, v183
	v_lshlrev_b32_e32 v168, 16, v184
	v_and_b32_e32 v169, 0xffff0000, v184
	v_lshlrev_b32_e32 v172, 16, v185
	v_and_b32_e32 v173, 0xffff0000, v185
	v_pk_fma_f32 v[166:167], v[130:131], v[146:147], v[166:167]
	v_pk_fma_f32 v[150:151], v[128:129], v[144:145], v[150:151]
	v_pk_fma_f32 v[172:173], v[126:127], v[142:143], v[172:173]
	v_pk_fma_f32 v[168:169], v[124:125], v[140:141], v[168:169]
	v_cvt_pk_bf16_f32 v182, v150, v151
	v_cvt_pk_bf16_f32 v183, v166, v167
	v_cvt_pk_bf16_f32 v184, v168, v169
	v_cvt_pk_bf16_f32 v185, v172, v173
	global_store_dwordx4 v[148:149], v[182:185], off
	s_waitcnt vmcnt(7)
	s_nop 1
	v_mov_b32_e32 v182, v226
	v_mov_b32_e32 v183, v227
	v_mov_b32_e32 v184, v228
	v_mov_b32_e32 v185, v229
	v_lshlrev_b32_e32 v150, 16, v182
	v_and_b32_e32 v151, 0xffff0000, v182
	v_lshlrev_b32_e32 v166, 16, v183
	v_and_b32_e32 v167, 0xffff0000, v183
	v_lshlrev_b32_e32 v168, 16, v184
	v_and_b32_e32 v169, 0xffff0000, v184
	v_lshlrev_b32_e32 v172, 16, v185
	v_and_b32_e32 v173, 0xffff0000, v185
	v_pk_fma_f32 v[150:151], v[116:117], v[136:137], v[150:151]
	v_pk_fma_f32 v[166:167], v[118:119], v[138:139], v[166:167]
	v_pk_fma_f32 v[172:173], v[110:111], v[134:135], v[172:173]
	v_pk_fma_f32 v[168:169], v[108:109], v[132:133], v[168:169]
	v_cvt_pk_bf16_f32 v182, v150, v151
	v_add_co_u32_e32 v150, vcc, s73, v148
	v_cvt_pk_bf16_f32 v183, v166, v167
	v_cvt_pk_bf16_f32 v184, v168, v169
	v_cvt_pk_bf16_f32 v185, v172, v173
	v_addc_co_u32_e32 v151, vcc, 0, v149, vcc
	global_store_dwordx4 v[148:149], v[182:185], off offset:256
	s_waitcnt vmcnt(7)
	s_nop 1
	v_mov_b32_e32 v182, v230
	v_mov_b32_e32 v183, v231
	v_mov_b32_e32 v184, v232
	v_mov_b32_e32 v185, v233
	v_lshlrev_b32_e32 v166, 16, v182
	v_and_b32_e32 v167, 0xffff0000, v182
	v_lshlrev_b32_e32 v168, 16, v183
	v_and_b32_e32 v169, 0xffff0000, v183
	v_lshlrev_b32_e32 v172, 16, v184
	v_and_b32_e32 v173, 0xffff0000, v184
	v_lshlrev_b32_e32 v182, 16, v185
	v_and_b32_e32 v183, 0xffff0000, v185
	v_pk_fma_f32 v[168:169], v[122:123], v[146:147], v[168:169]
	v_pk_fma_f32 v[166:167], v[120:121], v[144:145], v[166:167]
	v_pk_fma_f32 v[186:187], v[114:115], v[142:143], v[182:183]
	v_pk_fma_f32 v[172:173], v[112:113], v[140:141], v[172:173]
	v_cvt_pk_bf16_f32 v182, v166, v167
	v_cvt_pk_bf16_f32 v183, v168, v169
	v_cvt_pk_bf16_f32 v184, v172, v173
	v_cvt_pk_bf16_f32 v185, v186, v187
	global_store_dwordx4 v[150:151], v[182:185], off
	s_waitcnt vmcnt(7)
; #define GAS __attribute__((address_space(1)))
; __device__ __forceinline__ u32x4 pack8(f32x4 v0, f32x4 v1) { u32x4 w; w.x = cvt_pk_bf16(v0[0], v0[1]); w.y = cvt_pk_bf16(v0[2], v0[3]); w.z = cvt_pk_bf16(v1[0], v1[1]); w.w = cvt_pk_bf16(v1[2], v1[3]); return w; }
; __device__ __forceinline__ void unpack8(u32x4 w, f32x4& v0, f32x4& v1) { v0 = (f32x4){bflo(w.x), bfhi(w.x), bflo(w.y), bfhi(w.y)}; v1 = (f32x4){bflo(w.z), bfhi(w.z), bflo(w.w), bfhi(w.w)}; }
; #define GAS __attribute__((address_space(1)))
;     __device__ __forceinline__ void operator()(const f32x4 (&acc)[2][2][4][2], const Unit& u, int wr, int wc, int fr, int fq) const {
;     ...
;             } else { const size_t o0 = (size_t)(rb + fr) * 2048 + col0;
; #pragma unroll
;                 for (int m = 0; m < 4; ++m)
; #pragma unroll
;                     for (int bj = 0; bj < 2; ++bj) { const size_t o = o0 + (size_t)(m * 16) * 2048 + bj * HALF; f32x4 x0, x1; unpack8(*(const GAS u32x4*)(XB + o), x0, x1);
;                         const f32x4 v0 = x0 + gv[bj][0] * acc[ai][bj][m][0], v1 = x1 + gv[bj][1] * acc[ai][bj][m][1];
;                         if (OUTF != nullptr) { *(GAS f32x4*)(OUTF + o) = v0; *(GAS f32x4*)(OUTF + o + 4) = v1; } else *(GAS u32x4*)(XB + o) = pack8(v0, v1); }
	s_nop 1
	v_mov_b32_e32 v182, v234
	v_mov_b32_e32 v183, v235
	v_mov_b32_e32 v184, v236
	v_mov_b32_e32 v185, v237
	v_lshlrev_b32_e32 v166, 16, v182
	v_and_b32_e32 v167, 0xffff0000, v182
	v_lshlrev_b32_e32 v168, 16, v183
	v_and_b32_e32 v169, 0xffff0000, v183
	v_lshlrev_b32_e32 v172, 16, v184
	v_and_b32_e32 v173, 0xffff0000, v184
	v_lshlrev_b32_e32 v182, 16, v185
	v_and_b32_e32 v183, 0xffff0000, v185
	v_pk_fma_f32 v[168:169], v[102:103], v[138:139], v[168:169]
	v_pk_fma_f32 v[166:167], v[100:101], v[136:137], v[166:167]
	v_pk_fma_f32 v[186:187], v[92:93], v[134:135], v[182:183]
	v_pk_fma_f32 v[172:173], v[90:91], v[132:133], v[172:173]
	v_cvt_pk_bf16_f32 v182, v166, v167
	v_cvt_pk_bf16_f32 v183, v168, v169
	v_cvt_pk_bf16_f32 v184, v172, v173
	v_cvt_pk_bf16_f32 v185, v186, v187
	global_store_dwordx4 v[150:151], v[182:185], off offset:256
	v_add_co_u32_e32 v150, vcc, s3, v148
	s_nop 1
	v_addc_co_u32_e32 v151, vcc, 0, v149, vcc
	s_waitcnt vmcnt(7)
	s_nop 1
	v_mov_b32_e32 v182, v238
	v_mov_b32_e32 v183, v239
	v_mov_b32_e32 v184, v240
	v_mov_b32_e32 v185, v241
	v_lshlrev_b32_e32 v166, 16, v182
	v_and_b32_e32 v167, 0xffff0000, v182
	v_lshlrev_b32_e32 v168, 16, v183
	v_and_b32_e32 v169, 0xffff0000, v183
	v_lshlrev_b32_e32 v172, 16, v184
	v_and_b32_e32 v173, 0xffff0000, v184
	v_lshlrev_b32_e32 v182, 16, v185
	v_and_b32_e32 v183, 0xffff0000, v185
	v_pk_fma_f32 v[168:169], v[106:107], v[146:147], v[168:169]
	v_pk_fma_f32 v[166:167], v[104:105], v[144:145], v[166:167]
	v_pk_fma_f32 v[186:187], v[96:97], v[142:143], v[182:183]
	v_pk_fma_f32 v[172:173], v[94:95], v[140:141], v[172:173]
	v_cvt_pk_bf16_f32 v182, v166, v167
	v_cvt_pk_bf16_f32 v183, v168, v169
	v_cvt_pk_bf16_f32 v184, v172, v173
	v_cvt_pk_bf16_f32 v185, v186, v187
	global_store_dwordx4 v[150:151], v[182:185], off
	s_waitcnt vmcnt(7)
	s_nop 1
	v_mov_b32_e32 v182, v242
	v_mov_b32_e32 v183, v243
	v_mov_b32_e32 v184, v244
	v_mov_b32_e32 v185, v245
	v_lshlrev_b32_e32 v166, 16, v182
	v_and_b32_e32 v167, 0xffff0000, v182
	v_lshlrev_b32_e32 v168, 16, v183
	v_and_b32_e32 v169, 0xffff0000, v183
	v_lshlrev_b32_e32 v172, 16, v184
	v_and_b32_e32 v173, 0xffff0000, v184
	v_lshlrev_b32_e32 v182, 16, v185
	v_and_b32_e32 v183, 0xffff0000, v185
	v_pk_fma_f32 v[166:167], v[82:83], v[136:137], v[166:167]
	v_pk_fma_f32 v[168:169], v[84:85], v[138:139], v[168:169]
	v_pk_fma_f32 v[186:187], v[76:77], v[134:135], v[182:183]
	v_pk_fma_f32 v[172:173], v[74:75], v[132:133], v[172:173]
	v_cvt_pk_bf16_f32 v182, v166, v167
	v_add_co_u32_e32 v166, vcc, s46, v148
	v_cvt_pk_bf16_f32 v183, v168, v169
	v_cvt_pk_bf16_f32 v184, v172, v173
	v_cvt_pk_bf16_f32 v185, v186, v187
	v_addc_co_u32_e32 v167, vcc, 0, v149, vcc
	global_store_dwordx4 v[150:151], v[182:185], off offset:256
	s_waitcnt vmcnt(7)
	s_nop 1
	v_mov_b32_e32 v148, v194
	v_mov_b32_e32 v149, v195
	v_mov_b32_e32 v150, v196
	v_mov_b32_e32 v151, v197
	v_lshlrev_b32_e32 v168, 16, v148
	v_and_b32_e32 v169, 0xffff0000, v148
	v_lshlrev_b32_e32 v148, 16, v149
	v_and_b32_e32 v149, 0xffff0000, v149
	v_lshlrev_b32_e32 v172, 16, v150
	v_and_b32_e32 v173, 0xffff0000, v150
	v_lshlrev_b32_e32 v150, 16, v151
	v_and_b32_e32 v151, 0xffff0000, v151
	v_pk_fma_f32 v[182:183], v[88:89], v[146:147], v[148:149]
	v_pk_fma_f32 v[148:149], v[86:87], v[144:145], v[168:169]
	v_pk_fma_f32 v[168:169], v[80:81], v[142:143], v[150:151]
	v_pk_fma_f32 v[150:151], v[78:79], v[140:141], v[172:173]
	v_cvt_pk_bf16_f32 v148, v148, v149
	v_cvt_pk_bf16_f32 v149, v182, v183
	v_cvt_pk_bf16_f32 v150, v150, v151
	v_cvt_pk_bf16_f32 v151, v168, v169
	global_store_dwordx4 v[166:167], v[148:151], off
	s_waitcnt vmcnt(7)
	s_nop 1
	v_mov_b32_e32 v148, v198
	v_mov_b32_e32 v149, v199
	v_mov_b32_e32 v150, v200
	v_mov_b32_e32 v151, v201
	v_lshlrev_b32_e32 v168, 16, v148
	v_and_b32_e32 v169, 0xffff0000, v148
	v_lshlrev_b32_e32 v148, 16, v149
	v_and_b32_e32 v149, 0xffff0000, v149
	v_lshlrev_b32_e32 v172, 16, v150
	v_and_b32_e32 v173, 0xffff0000, v150
	v_lshlrev_b32_e32 v150, 16, v151
	v_and_b32_e32 v151, 0xffff0000, v151
	v_pk_fma_f32 v[182:183], v[72:73], v[138:139], v[148:149]
	v_pk_fma_f32 v[148:149], v[70:71], v[136:137], v[168:169]
	v_pk_fma_f32 v[168:169], v[68:69], v[134:135], v[150:151]
	v_pk_fma_f32 v[150:151], v[66:67], v[132:133], v[172:173]
	v_cvt_pk_bf16_f32 v148, v148, v149
	v_cvt_pk_bf16_f32 v149, v182, v183
	v_cvt_pk_bf16_f32 v150, v150, v151
	v_cvt_pk_bf16_f32 v151, v168, v169
	global_store_dwordx4 v[166:167], v[148:151], off offset:256

; #define PG8_STAGE(bufoff, gbase, voff) do { _Pragma("unroll") for (int _i = 0; _i < 2; ++_i) \
;         __builtin_amdgcn_global_load_lds((const unsigned*)((const char*)(gbase) + (voff)[_i]), (PG8_LAS unsigned*)(lds + (bufoff) + ldsw + _i * 8192), 16, 0, AUX_A); } while (0)
; #define PG8_STAGEB(bufoff, gbase, voff) do { _Pragma("unroll") for (int _i = 0; _i < 2; ++_i) \
;         __builtin_amdgcn_global_load_lds((const unsigned*)((const char*)(gbase) + (voff)[_i]), (PG8_LAS unsigned*)(lds + (bufoff) + ldsw + _i * 8192), 16, 0, AUX_B); } while (0)
; #define PG8_LDA(dst, b, h) do { _Pragma("unroll") for (int m = 0; m < 4; ++m) _Pragma("unroll") for (int k = 0; k < 2; ++k) dst[m][k] = *(const PG8_LAS bf16x8*)(lds + PG8_SA(b, h) + aoff + m * 2048 + k * 1024); } while (0)
; #define PG8_WAIT_V(n) asm volatile("s_waitcnt vmcnt(" #n ")" ::: "memory")
; #define PG8_WAIT_L(n) asm volatile("s_waitcnt lgkmcnt(" #n ")" ::: "memory")
; #define PG8_BAR __builtin_amdgcn_s_barrier()
; template <class Epi, class Sched, bool ALIGN_EPI = false, bool SP2 = false>
; __device__ __forceinline__ void gemm_phase(PG8_LAS unsigned char* lds, const Gemm g, const Sched& S, const Epi& E) {
;     ...
;         for (int t = 0; t < nt; t += 2) {
;             const bool last = (t == nt - 2);
;             const char* a1 = PG8_KP(cA, t + 1, rot, nt);
;             const char* a2 = last ? nAr : PG8_KP(cA, t + 2, rot, nt); const char* b2 = last ? nBr : PG8_KP(cB, t + 2, rot, nt);
;             const char* a3 = a2 + kstep; const char* b3 = b2 + kstep;
;             if (last && has_next) S.a_ready(nxt);
;             if constexpr (SP2) {
;             PG8_LDB(B0, 0, 0); PG8_LDB(B1, 0, 1); PG8_SCHED; PG8_LDA(At, 0, 0); PG8_STAGE(PG8_SA(1, 1), a1 + hstep, voffA);
;             PG8_WAIT_V(8); PG8_WAIT_L(0); PG8_BAR; PG8_MMA(0, 0, At, B0); PG8_MMA(0, 1, At, B1); PG8_BAR; PG8_SCHED;
;             PG8_LDA(At, 0, 1); PG8_STAGEB(PG8_SB(0, 0), b2, voffB); PG8_STAGEB(PG8_SB(0, 1), b2 + hstep, voffB); PG8_STAGE(PG8_SA(0, 0), a2, voffA);
;             PG8_WAIT_V(8); PG8_WAIT_L(0); PG8_BAR; PG8_MMA(1, 0, At, B0); PG8_MMA(1, 1, At, B1); PG8_BAR; PG8_SCHED;
;             PG8_LDB(B0, 1, 0); PG8_LDB(B1, 1, 1); PG8_SCHED; PG8_LDA(At, 1, 0); PG8_STAGE(PG8_SA(0, 1), a2 + hstep, voffA);
;             PG8_WAIT_V(8); PG8_WAIT_L(0); PG8_BAR; PG8_MMA(0, 0, At, B0); PG8_MMA(0, 1, At, B1); PG8_BAR; PG8_SCHED;
.Lpk_1458:
	s_lshl_b32 s100, s29, 7
	s_add_u32 s100, s40, s100
	s_addc_u32 s101, s41, 0
	s_add_u32 s100, s100, 0x80
	s_addc_u32 s101, s101, 0
	s_add_i32 s30, s29, 2
	s_cmp_lt_u32 s29, 30
	s_cselect_b32 s0, 0, 0xffffffe0
	s_add_i32 s0, s30, s0
	s_ashr_i32 s1, s0, 31
	s_lshl_b64 s[0:1], s[0:1], 7
	s_add_u32 s2, s40, s0
	s_addc_u32 s31, s41, s1
	s_add_u32 s0, s34, s0
	s_addc_u32 s1, s35, s1
	s_cmp_eq_u32 s29, 30
	s_cselect_b32 s45, s13, s31
	s_cselect_b32 s44, s15, s2
	s_cselect_b32 s49, s71, s1
	s_cselect_b32 s48, s75, s0
	s_add_i32 s2, 0, 0x10000
	s_add_i32 s78, s2, s56
	s_add_i32 s31, 0, 0x14000
	s_add_i32 s47, s57, 0xe000
	s_add_i32 s81, s78, 0x2000
	s_add_u32 s50, s48, 0x80000
	s_addc_u32 s51, s49, 0
	s_add_i32 s82, s31, s56
	v_add_u32_e32 v162, s2, v99
	v_add_u32_e32 v166, s31, v99
	s_add_i32 s83, s82, 0x2000
	s_add_i32 s84, 0, 0x18000
	s_add_i32 s88, 0, 0x1c000
	ds_read_b128 v[150:153], v162
	ds_read_b128 v[154:157], v162 offset:1024
	ds_read_b128 v[158:161], v162 offset:2048
	ds_read_b128 v[162:165], v162 offset:3072
	ds_read_b128 v[180:183], v166
	ds_read_b128 v[184:187], v166 offset:1024
	ds_read_b128 v[188:191], v166 offset:2048
	ds_read_b128 v[192:195], v166 offset:3072
	s_add_u32 s42, s44, 0x80000
	s_addc_u32 s43, s45, 0
	s_add_i32 s1, s84, s56
	s_add_i32 s0, s1, 0x2000
	s_add_u32 s36, s48, 0x80080
	s_addc_u32 s37, s49, 0
	s_add_i32 s46, s88, s56
	s_add_i32 s31, s46, 0x2000
	ds_read_b128 v[196:199], v149
	ds_read_b128 v[200:203], v149 offset:1024
	ds_read_b128 v[222:225], v149 offset:2048
	ds_read_b128 v[226:229], v149 offset:3072
	ds_read_b128 v[230:233], v149 offset:4096
	ds_read_b128 v[234:237], v149 offset:5120
	ds_read_b128 v[238:241], v149 offset:6144
	ds_read_b128 v[242:245], v149 offset:7168
	v_lshl_add_u64 v[166:167], s[100:101], 0, v[138:139]
	s_mov_b32 m0, s61
	v_lshl_add_u64 v[168:169], s[100:101], 0, v[134:135]
	global_load_lds_dwordx4 v[166:167], off
	s_mov_b32 m0, s62
	s_nop 0
	global_load_lds_dwordx4 v[168:169], off
	s_add_i32 m0, s57, 0xc000
	s_nop 0
	global_load_lds_dwordx4 v[146:147], off
	s_mov_b32 m0, s47
	s_nop 0
	global_load_lds_dwordx4 v[144:145], off
	s_waitcnt vmcnt(8)
	s_waitcnt lgkmcnt(0)
	s_setprio 1
	s_barrier
	v_mfma_f32_16x16x32_bf16 v[128:131], v[150:153], v[196:199], 0
	v_mfma_f32_16x16x32_bf16 v[128:131], v[154:157], v[200:203], v[128:131]
	v_mfma_f32_16x16x32_bf16 v[120:123], v[158:161], v[196:199], 0
	v_mfma_f32_16x16x32_bf16 v[120:123], v[162:165], v[200:203], v[120:123]
	v_mfma_f32_16x16x32_bf16 v[112:115], v[150:153], v[222:225], 0
	v_mfma_f32_16x16x32_bf16 v[112:115], v[154:157], v[226:229], v[112:115]
	v_mfma_f32_16x16x32_bf16 v[104:107], v[158:161], v[222:225], 0
	v_mfma_f32_16x16x32_bf16 v[104:107], v[162:165], v[226:229], v[104:107]
	v_mfma_f32_16x16x32_bf16 v[94:97], v[150:153], v[230:233], 0
	v_mfma_f32_16x16x32_bf16 v[94:97], v[154:157], v[234:237], v[94:97]
	v_mfma_f32_16x16x32_bf16 v[86:89], v[158:161], v[230:233], 0
	v_mfma_f32_16x16x32_bf16 v[86:89], v[162:165], v[234:237], v[86:89]
	v_mfma_f32_16x16x32_bf16 v[78:81], v[150:153], v[238:241], 0
	v_mfma_f32_16x16x32_bf16 v[78:81], v[154:157], v[242:245], v[78:81]
	v_mfma_f32_16x16x32_bf16 v[70:73], v[158:161], v[238:241], 0
	v_mfma_f32_16x16x32_bf16 v[70:73], v[162:165], v[242:245], v[70:73]
	s_setprio 0
	s_setprio 1
	v_mfma_f32_16x16x32_bf16 v[124:127], v[180:183], v[196:199], 0
	v_mfma_f32_16x16x32_bf16 v[124:127], v[184:187], v[200:203], v[124:127]
	v_mfma_f32_16x16x32_bf16 v[116:119], v[188:191], v[196:199], 0
	v_mfma_f32_16x16x32_bf16 v[116:119], v[192:195], v[200:203], v[116:119]
	v_mfma_f32_16x16x32_bf16 v[108:111], v[180:183], v[222:225], 0
	v_mfma_f32_16x16x32_bf16 v[108:111], v[184:187], v[226:229], v[108:111]
	v_mfma_f32_16x16x32_bf16 v[100:103], v[188:191], v[222:225], 0
	v_mfma_f32_16x16x32_bf16 v[100:103], v[192:195], v[226:229], v[100:103]
	v_mfma_f32_16x16x32_bf16 v[90:93], v[180:183], v[230:233], 0
	v_mfma_f32_16x16x32_bf16 v[90:93], v[184:187], v[234:237], v[90:93]
	v_mfma_f32_16x16x32_bf16 v[82:85], v[188:191], v[230:233], 0
	v_mfma_f32_16x16x32_bf16 v[82:85], v[192:195], v[234:237], v[82:85]
	v_mfma_f32_16x16x32_bf16 v[74:77], v[180:183], v[238:241], 0
	v_mfma_f32_16x16x32_bf16 v[74:77], v[184:187], v[242:245], v[74:77]
	s_setprio 2
	s_barrier
	v_mfma_f32_16x16x32_bf16 v[66:69], v[188:191], v[238:241], 0
	v_mfma_f32_16x16x32_bf16 v[66:69], v[192:195], v[242:245], v[66:69]
	s_setprio 0
	s_mov_b32 m0, s78
	v_lshl_add_u64 v[166:167], s[48:49], 0, v[136:137]
	ds_read_b128 v[196:199], v149 offset:16384
	ds_read_b128 v[200:203], v149 offset:17408
	ds_read_b128 v[222:225], v149 offset:18432
	ds_read_b128 v[226:229], v149 offset:19456
	ds_read_b128 v[230:233], v149 offset:20480
	ds_read_b128 v[234:237], v149 offset:21504
	ds_read_b128 v[238:241], v149 offset:22528
	ds_read_b128 v[242:245], v149 offset:23552
	global_load_lds_dwordx4 v[166:167], off
	v_lshl_add_u64 v[168:169], s[48:49], 0, v[132:133]
	s_mov_b32 m0, s81
	v_lshl_add_u64 v[172:173], s[50:51], 0, v[136:137]
	global_load_lds_dwordx4 v[168:169], off
	s_mov_b32 m0, s82
	global_load_lds_dwordx4 v[172:173], off
	v_lshl_add_u64 v[172:173], s[50:51], 0, v[132:133]
	s_mov_b32 m0, s83
	s_nop 0
	global_load_lds_dwordx4 v[172:173], off
	s_waitcnt vmcnt(6)
	s_waitcnt lgkmcnt(0)
	s_setprio 1
	s_barrier
; #define PG8_STAGE(bufoff, gbase, voff) do { _Pragma("unroll") for (int _i = 0; _i < 2; ++_i) \
;         __builtin_amdgcn_global_load_lds((const unsigned*)((const char*)(gbase) + (voff)[_i]), (PG8_LAS unsigned*)(lds + (bufoff) + ldsw + _i * 8192), 16, 0, AUX_A); } while (0)
; #define PG8_LDA(dst, b, h) do { _Pragma("unroll") for (int m = 0; m < 4; ++m) _Pragma("unroll") for (int k = 0; k < 2; ++k) dst[m][k] = *(const PG8_LAS bf16x8*)(lds + PG8_SA(b, h) + aoff + m * 2048 + k * 1024); } while (0)
; #define PG8_LDB(dst, b, h) do { _Pragma("unroll") for (int n = 0; n < 2; ++n) _Pragma("unroll") for (int k = 0; k < 2; ++k) dst[n][k] = *(const PG8_LAS bf16x8*)(lds + PG8_SB(b, h) + boff + n * 2048 + k * 1024); } while (0)
; #define PG8_MMA(ai, bj, At, Bt) do { __builtin_amdgcn_s_setprio(1); _Pragma("unroll") for (int m = 0; m < 4; ++m) _Pragma("unroll") for (int n = 0; n < 2; ++n) _Pragma("unroll") for (int k = 0; k < 2; ++k) \
;         acc[ai][bj][m][n] = __builtin_amdgcn_mfma_f32_16x16x32_bf16(Bt[n][k], At[m][k], acc[ai][bj][m][n], 0, 0, 0); __builtin_amdgcn_s_setprio(0); } while (0)
; #define PG8_WAIT_V(n) asm volatile("s_waitcnt vmcnt(" #n ")" ::: "memory")
; #define PG8_WAIT_L(n) asm volatile("s_waitcnt lgkmcnt(" #n ")" ::: "memory")
; #define PG8_BAR __builtin_amdgcn_s_barrier()
; #define PG8_SCHED __builtin_amdgcn_sched_barrier(0)
; template <class Epi, class Sched, bool ALIGN_EPI = false, bool SP2 = false>
; __device__ __forceinline__ void gemm_phase(PG8_LAS unsigned char* lds, const Gemm g, const Sched& S, const Epi& E) {
;     ...
;             PG8_WAIT_V(8); PG8_WAIT_L(0); PG8_BAR; PG8_MMA(1, 0, At, B0); PG8_MMA(1, 1, At, B1); PG8_BAR; PG8_SCHED;
;             PG8_LDB(B0, 1, 0); PG8_LDB(B1, 1, 1); PG8_SCHED; PG8_LDA(At, 1, 0); PG8_STAGE(PG8_SA(0, 1), a2 + hstep, voffA);
;             PG8_WAIT_V(8); PG8_WAIT_L(0); PG8_BAR; PG8_MMA(0, 0, At, B0); PG8_MMA(0, 1, At, B1); PG8_BAR; PG8_SCHED;
	v_mfma_f32_16x16x32_bf16 v[62:65], v[150:153], v[196:199], 0
	v_mfma_f32_16x16x32_bf16 v[62:65], v[154:157], v[200:203], v[62:65]
	v_mfma_f32_16x16x32_bf16 v[54:57], v[158:161], v[196:199], 0
	v_mfma_f32_16x16x32_bf16 v[54:57], v[162:165], v[200:203], v[54:57]
	v_mfma_f32_16x16x32_bf16 v[46:49], v[150:153], v[222:225], 0
	v_mfma_f32_16x16x32_bf16 v[46:49], v[154:157], v[226:229], v[46:49]
	v_mfma_f32_16x16x32_bf16 v[38:41], v[158:161], v[222:225], 0
	v_mfma_f32_16x16x32_bf16 v[38:41], v[162:165], v[226:229], v[38:41]
	v_mfma_f32_16x16x32_bf16 v[30:33], v[150:153], v[230:233], 0
	v_mfma_f32_16x16x32_bf16 v[30:33], v[154:157], v[234:237], v[30:33]
	v_mfma_f32_16x16x32_bf16 v[22:25], v[158:161], v[230:233], 0
	v_mfma_f32_16x16x32_bf16 v[22:25], v[162:165], v[234:237], v[22:25]
	v_mfma_f32_16x16x32_bf16 v[14:17], v[150:153], v[238:241], 0
	v_mfma_f32_16x16x32_bf16 v[14:17], v[154:157], v[242:245], v[14:17]
	v_mfma_f32_16x16x32_bf16 v[6:9], v[158:161], v[238:241], 0
	v_mfma_f32_16x16x32_bf16 v[6:9], v[162:165], v[242:245], v[6:9]
	s_setprio 0
	s_setprio 1
	v_mfma_f32_16x16x32_bf16 v[58:61], v[180:183], v[196:199], 0
	v_mfma_f32_16x16x32_bf16 v[58:61], v[184:187], v[200:203], v[58:61]
	v_mfma_f32_16x16x32_bf16 v[50:53], v[188:191], v[196:199], 0
	v_mfma_f32_16x16x32_bf16 v[50:53], v[192:195], v[200:203], v[50:53]
	v_mfma_f32_16x16x32_bf16 v[42:45], v[180:183], v[222:225], 0
	v_mfma_f32_16x16x32_bf16 v[42:45], v[184:187], v[226:229], v[42:45]
	v_mfma_f32_16x16x32_bf16 v[34:37], v[188:191], v[222:225], 0
	v_mfma_f32_16x16x32_bf16 v[34:37], v[192:195], v[226:229], v[34:37]
	v_mfma_f32_16x16x32_bf16 v[26:29], v[180:183], v[230:233], 0
	v_mfma_f32_16x16x32_bf16 v[26:29], v[184:187], v[234:237], v[26:29]
	v_mfma_f32_16x16x32_bf16 v[18:21], v[188:191], v[230:233], 0
	v_mfma_f32_16x16x32_bf16 v[18:21], v[192:195], v[234:237], v[18:21]
	v_mfma_f32_16x16x32_bf16 v[10:13], v[180:183], v[238:241], 0
	v_mfma_f32_16x16x32_bf16 v[10:13], v[184:187], v[242:245], v[10:13]
	s_setprio 2
	s_barrier
	v_mfma_f32_16x16x32_bf16 v[2:5], v[188:191], v[238:241], 0
	v_mfma_f32_16x16x32_bf16 v[2:5], v[192:195], v[242:245], v[2:5]
	s_setprio 0
	v_add_u32_e32 v162, s84, v99
	v_add_u32_e32 v192, s88, v99
	ds_read_b128 v[150:153], v162
	ds_read_b128 v[154:157], v162 offset:1024
	ds_read_b128 v[158:161], v162 offset:2048
	ds_read_b128 v[162:165], v162 offset:3072
	ds_read_b128 v[180:183], v192
	ds_read_b128 v[184:187], v192 offset:1024
	ds_read_b128 v[188:191], v192 offset:2048
	ds_read_b128 v[192:195], v192 offset:3072
	s_mov_b32 m0, s59
	v_lshl_add_u64 v[246:247], s[42:43], 0, v[138:139]
	ds_read_b128 v[196:199], v149 offset:32768
	ds_read_b128 v[200:203], v149 offset:33792
	ds_read_b128 v[222:225], v149 offset:34816
	ds_read_b128 v[226:229], v149 offset:35840
	ds_read_b128 v[230:233], v149 offset:36864
	ds_read_b128 v[234:237], v149 offset:37888
	ds_read_b128 v[238:241], v149 offset:38912
	ds_read_b128 v[242:245], v149 offset:39936
	v_lshl_add_u64 v[172:173], s[44:45], 0, v[138:139]
	s_mov_b32 m0, s57
	v_lshl_add_u64 v[212:213], s[44:45], 0, v[134:135]
	global_load_lds_dwordx4 v[172:173], off
	s_mov_b32 m0, s58
	s_nop 0
	global_load_lds_dwordx4 v[212:213], off
	s_mov_b32 m0, s59
	s_nop 0
	global_load_lds_dwordx4 v[246:247], off
	v_lshl_add_u64 v[246:247], s[42:43], 0, v[134:135]
	s_mov_b32 m0, s60
	s_nop 0
	global_load_lds_dwordx4 v[246:247], off
	s_waitcnt vmcnt(8)
	s_waitcnt lgkmcnt(0)
	s_setprio 1
	s_barrier
; #define PG8_STAGE(bufoff, gbase, voff) do { _Pragma("unroll") for (int _i = 0; _i < 2; ++_i) \
;         __builtin_amdgcn_global_load_lds((const unsigned*)((const char*)(gbase) + (voff)[_i]), (PG8_LAS unsigned*)(lds + (bufoff) + ldsw + _i * 8192), 16, 0, AUX_A); } while (0)
; #define PG8_STAGEB(bufoff, gbase, voff) do { _Pragma("unroll") for (int _i = 0; _i < 2; ++_i) \
;         __builtin_amdgcn_global_load_lds((const unsigned*)((const char*)(gbase) + (voff)[_i]), (PG8_LAS unsigned*)(lds + (bufoff) + ldsw + _i * 8192), 16, 0, AUX_B); } while (0)
; #define PG8_LDA(dst, b, h) do { _Pragma("unroll") for (int m = 0; m < 4; ++m) _Pragma("unroll") for (int k = 0; k < 2; ++k) dst[m][k] = *(const PG8_LAS bf16x8*)(lds + PG8_SA(b, h) + aoff + m * 2048 + k * 1024); } while (0)
; #define PG8_MMA(ai, bj, At, Bt) do { __builtin_amdgcn_s_setprio(1); _Pragma("unroll") for (int m = 0; m < 4; ++m) _Pragma("unroll") for (int n = 0; n < 2; ++n) _Pragma("unroll") for (int k = 0; k < 2; ++k) \
;         acc[ai][bj][m][n] = __builtin_amdgcn_mfma_f32_16x16x32_bf16(Bt[n][k], At[m][k], acc[ai][bj][m][n], 0, 0, 0); __builtin_amdgcn_s_setprio(0); } while (0)
; #define PG8_WAIT_V(n) asm volatile("s_waitcnt vmcnt(" #n ")" ::: "memory")
; #define PG8_WAIT_L(n) asm volatile("s_waitcnt lgkmcnt(" #n ")" ::: "memory")
; #define PG8_BAR __builtin_amdgcn_s_barrier()
; #define PG8_SCHED __builtin_amdgcn_sched_barrier(0)
; template <class Epi, class Sched, bool ALIGN_EPI = false, bool SP2 = false>
; __device__ __forceinline__ void gemm_phase(PG8_LAS unsigned char* lds, const Gemm g, const Sched& S, const Epi& E) {
;     ...
;             PG8_WAIT_V(8); PG8_WAIT_L(0); PG8_BAR; PG8_MMA(0, 0, At, B0); PG8_MMA(0, 1, At, B1); PG8_BAR; PG8_SCHED;
;             PG8_LDA(At, 1, 1); PG8_STAGEB(PG8_SB(1, 0), b3, voffB); PG8_STAGEB(PG8_SB(1, 1), b3 + hstep, voffB); PG8_STAGE(PG8_SA(1, 0), a3, voffA);
;             PG8_WAIT_V(8); PG8_WAIT_L(0); PG8_BAR; PG8_MMA(1, 0, At, B0); PG8_MMA(1, 1, At, B1); PG8_BAR; PG8_SCHED;
	v_mfma_f32_16x16x32_bf16 v[128:131], v[150:153], v[196:199], v[128:131]
	v_mfma_f32_16x16x32_bf16 v[128:131], v[154:157], v[200:203], v[128:131]
	v_mfma_f32_16x16x32_bf16 v[120:123], v[158:161], v[196:199], v[120:123]
	v_mfma_f32_16x16x32_bf16 v[120:123], v[162:165], v[200:203], v[120:123]
	v_mfma_f32_16x16x32_bf16 v[112:115], v[150:153], v[222:225], v[112:115]
	v_mfma_f32_16x16x32_bf16 v[112:115], v[154:157], v[226:229], v[112:115]
	v_mfma_f32_16x16x32_bf16 v[104:107], v[158:161], v[222:225], v[104:107]
	v_mfma_f32_16x16x32_bf16 v[104:107], v[162:165], v[226:229], v[104:107]
	v_mfma_f32_16x16x32_bf16 v[94:97], v[150:153], v[230:233], v[94:97]
	v_mfma_f32_16x16x32_bf16 v[94:97], v[154:157], v[234:237], v[94:97]
	v_mfma_f32_16x16x32_bf16 v[86:89], v[158:161], v[230:233], v[86:89]
	v_mfma_f32_16x16x32_bf16 v[86:89], v[162:165], v[234:237], v[86:89]
	v_mfma_f32_16x16x32_bf16 v[78:81], v[150:153], v[238:241], v[78:81]
	v_mfma_f32_16x16x32_bf16 v[78:81], v[154:157], v[242:245], v[78:81]
	v_mfma_f32_16x16x32_bf16 v[70:73], v[158:161], v[238:241], v[70:73]
	v_mfma_f32_16x16x32_bf16 v[70:73], v[162:165], v[242:245], v[70:73]
	s_setprio 0
	s_setprio 1
	v_mfma_f32_16x16x32_bf16 v[124:127], v[180:183], v[196:199], v[124:127]
	v_mfma_f32_16x16x32_bf16 v[124:127], v[184:187], v[200:203], v[124:127]
	v_mfma_f32_16x16x32_bf16 v[116:119], v[188:191], v[196:199], v[116:119]
	v_mfma_f32_16x16x32_bf16 v[116:119], v[192:195], v[200:203], v[116:119]
	v_mfma_f32_16x16x32_bf16 v[108:111], v[180:183], v[222:225], v[108:111]
	v_mfma_f32_16x16x32_bf16 v[108:111], v[184:187], v[226:229], v[108:111]
	v_mfma_f32_16x16x32_bf16 v[100:103], v[188:191], v[222:225], v[100:103]
	v_mfma_f32_16x16x32_bf16 v[100:103], v[192:195], v[226:229], v[100:103]
	v_mfma_f32_16x16x32_bf16 v[90:93], v[180:183], v[230:233], v[90:93]
	v_mfma_f32_16x16x32_bf16 v[90:93], v[184:187], v[234:237], v[90:93]
	v_mfma_f32_16x16x32_bf16 v[82:85], v[188:191], v[230:233], v[82:85]
	v_mfma_f32_16x16x32_bf16 v[82:85], v[192:195], v[234:237], v[82:85]
	v_mfma_f32_16x16x32_bf16 v[74:77], v[180:183], v[238:241], v[74:77]
	v_mfma_f32_16x16x32_bf16 v[74:77], v[184:187], v[242:245], v[74:77]
	s_setprio 2
	s_barrier
	v_mfma_f32_16x16x32_bf16 v[66:69], v[188:191], v[238:241], v[66:69]
	v_mfma_f32_16x16x32_bf16 v[66:69], v[192:195], v[242:245], v[66:69]
	s_setprio 0
	s_mov_b32 m0, s1
	v_lshl_add_u64 v[166:167], v[166:167], 0, s[76:77]
	ds_read_b128 v[196:199], v149 offset:49152
	ds_read_b128 v[200:203], v149 offset:50176
	ds_read_b128 v[222:225], v149 offset:51200
	ds_read_b128 v[226:229], v149 offset:52224
	ds_read_b128 v[230:233], v149 offset:53248
	ds_read_b128 v[234:237], v149 offset:54272
	ds_read_b128 v[238:241], v149 offset:55296
	ds_read_b128 v[242:245], v149 offset:56320
	global_load_lds_dwordx4 v[166:167], off
	v_lshl_add_u64 v[166:167], v[168:169], 0, s[76:77]
	s_mov_b32 m0, s0
	s_nop 0
	global_load_lds_dwordx4 v[166:167], off
	v_lshl_add_u64 v[166:167], s[36:37], 0, v[136:137]
	s_mov_b32 m0, s46
	s_nop 0
	global_load_lds_dwordx4 v[166:167], off
	v_lshl_add_u64 v[166:167], s[36:37], 0, v[132:133]
	s_mov_b32 m0, s31
	s_nop 0
	global_load_lds_dwordx4 v[166:167], off
	s_waitcnt vmcnt(6)
	s_waitcnt lgkmcnt(0)
	s_setprio 1
	s_barrier
	v_mfma_f32_16x16x32_bf16 v[62:65], v[150:153], v[196:199], v[62:65]
	v_mfma_f32_16x16x32_bf16 v[62:65], v[154:157], v[200:203], v[62:65]
	v_mfma_f32_16x16x32_bf16 v[54:57], v[158:161], v[196:199], v[54:57]
	v_mfma_f32_16x16x32_bf16 v[54:57], v[162:165], v[200:203], v[54:57]
	v_mfma_f32_16x16x32_bf16 v[46:49], v[150:153], v[222:225], v[46:49]
	v_mfma_f32_16x16x32_bf16 v[46:49], v[154:157], v[226:229], v[46:49]
	v_mfma_f32_16x16x32_bf16 v[38:41], v[158:161], v[222:225], v[38:41]
	v_mfma_f32_16x16x32_bf16 v[38:41], v[162:165], v[226:229], v[38:41]
	v_mfma_f32_16x16x32_bf16 v[30:33], v[150:153], v[230:233], v[30:33]
	v_mfma_f32_16x16x32_bf16 v[30:33], v[154:157], v[234:237], v[30:33]
	v_mfma_f32_16x16x32_bf16 v[22:25], v[158:161], v[230:233], v[22:25]
	v_mfma_f32_16x16x32_bf16 v[22:25], v[162:165], v[234:237], v[22:25]
	v_mfma_f32_16x16x32_bf16 v[14:17], v[150:153], v[238:241], v[14:17]
	v_mfma_f32_16x16x32_bf16 v[14:17], v[154:157], v[242:245], v[14:17]
	v_mfma_f32_16x16x32_bf16 v[6:9], v[158:161], v[238:241], v[6:9]
	v_mfma_f32_16x16x32_bf16 v[6:9], v[162:165], v[242:245], v[6:9]
	s_setprio 0
	s_setprio 1
	v_mfma_f32_16x16x32_bf16 v[58:61], v[180:183], v[196:199], v[58:61]
	v_mfma_f32_16x16x32_bf16 v[58:61], v[184:187], v[200:203], v[58:61]
	v_mfma_f32_16x16x32_bf16 v[50:53], v[188:191], v[196:199], v[50:53]
	v_mfma_f32_16x16x32_bf16 v[50:53], v[192:195], v[200:203], v[50:53]
	v_mfma_f32_16x16x32_bf16 v[42:45], v[180:183], v[222:225], v[42:45]
	v_mfma_f32_16x16x32_bf16 v[42:45], v[184:187], v[226:229], v[42:45]
	v_mfma_f32_16x16x32_bf16 v[34:37], v[188:191], v[222:225], v[34:37]
	v_mfma_f32_16x16x32_bf16 v[34:37], v[192:195], v[226:229], v[34:37]
	v_mfma_f32_16x16x32_bf16 v[26:29], v[180:183], v[230:233], v[26:29]
	v_mfma_f32_16x16x32_bf16 v[26:29], v[184:187], v[234:237], v[26:29]
	v_mfma_f32_16x16x32_bf16 v[18:21], v[188:191], v[230:233], v[18:21]
	v_mfma_f32_16x16x32_bf16 v[18:21], v[192:195], v[234:237], v[18:21]
	v_mfma_f32_16x16x32_bf16 v[10:13], v[180:183], v[238:241], v[10:13]
	v_mfma_f32_16x16x32_bf16 v[10:13], v[184:187], v[242:245], v[10:13]
	s_setprio 2
	s_cmp_gt_u32 s30, 31
	s_cbranch_scc0 .Lq4b_1458p
	v_cmp_ne_u32_e64 vcc, s10, 0
	s_cbranch_vccz .Lq4s_1458p

; #define PG8_STAGE(bufoff, gbase, voff) do { _Pragma("unroll") for (int _i = 0; _i < 2; ++_i) \
;         __builtin_amdgcn_global_load_lds((const unsigned*)((const char*)(gbase) + (voff)[_i]), (PG8_LAS unsigned*)(lds + (bufoff) + ldsw + _i * 8192), 16, 0, AUX_A); } while (0)
; #define PG8_STAGEB(bufoff, gbase, voff) do { _Pragma("unroll") for (int _i = 0; _i < 2; ++_i) \
;         __builtin_amdgcn_global_load_lds((const unsigned*)((const char*)(gbase) + (voff)[_i]), (PG8_LAS unsigned*)(lds + (bufoff) + ldsw + _i * 8192), 16, 0, AUX_B); } while (0)
; #define PG8_LDA(dst, b, h) do { _Pragma("unroll") for (int m = 0; m < 4; ++m) _Pragma("unroll") for (int k = 0; k < 2; ++k) dst[m][k] = *(const PG8_LAS bf16x8*)(lds + PG8_SA(b, h) + aoff + m * 2048 + k * 1024); } while (0)
; #define PG8_WAIT_V(n) asm volatile("s_waitcnt vmcnt(" #n ")" ::: "memory")
; #define PG8_WAIT_L(n) asm volatile("s_waitcnt lgkmcnt(" #n ")" ::: "memory")
; #define PG8_BAR __builtin_amdgcn_s_barrier()
; template <class Epi, class Sched, bool ALIGN_EPI = false, bool SP2 = false>
; __device__ __forceinline__ void gemm_phase(PG8_LAS unsigned char* lds, const Gemm g, const Sched& S, const Epi& E) {
;     ...
;         for (int t = 0; t < nt; t += 2) {
;             const bool last = (t == nt - 2);
;             const char* a1 = PG8_KP(cA, t + 1, rot, nt);
;             const char* a2 = last ? nAr : PG8_KP(cA, t + 2, rot, nt); const char* b2 = last ? nBr : PG8_KP(cB, t + 2, rot, nt);
;             const char* a3 = a2 + kstep; const char* b3 = b2 + kstep;
;             if (last && has_next) S.a_ready(nxt);
;             if constexpr (SP2) {
;             PG8_LDB(B0, 0, 0); PG8_LDB(B1, 0, 1); PG8_SCHED; PG8_LDA(At, 0, 0); PG8_STAGE(PG8_SA(1, 1), a1 + hstep, voffA);
;             PG8_WAIT_V(8); PG8_WAIT_L(0); PG8_BAR; PG8_MMA(0, 0, At, B0); PG8_MMA(0, 1, At, B1); PG8_BAR; PG8_SCHED;
;             PG8_LDA(At, 0, 1); PG8_STAGEB(PG8_SB(0, 0), b2, voffB); PG8_STAGEB(PG8_SB(0, 1), b2 + hstep, voffB); PG8_STAGE(PG8_SA(0, 0), a2, voffA);
;             PG8_WAIT_V(8); PG8_WAIT_L(0); PG8_BAR; PG8_MMA(1, 0, At, B0); PG8_MMA(1, 1, At, B1); PG8_BAR; PG8_SCHED;
;             PG8_LDB(B0, 1, 0); PG8_LDB(B1, 1, 1); PG8_SCHED; PG8_LDA(At, 1, 0); PG8_STAGE(PG8_SA(0, 1), a2 + hstep, voffA);
;             PG8_WAIT_V(8); PG8_WAIT_L(0); PG8_BAR; PG8_MMA(0, 0, At, B0); PG8_MMA(0, 1, At, B1); PG8_BAR; PG8_SCHED;
.Lq4s_1458p:
	v_mfma_f32_16x16x32_bf16 v[2:5], v[188:191], v[238:241], v[2:5]
	v_mfma_f32_16x16x32_bf16 v[2:5], v[192:195], v[242:245], v[2:5]
	s_setprio 0
	v_lshl_add_u64 v[144:145], v[144:145], 0, s[86:87]
	v_lshl_add_u64 v[146:147], v[146:147], 0, s[86:87]
	s_cmp_gt_u32 s30, 31
	s_mov_b32 s29, s30
	s_cbranch_scc1 .Lpx_1458
.LBB0_1458:
	s_lshl_b32 s100, s29, 7
	s_add_u32 s100, s40, s100
	s_addc_u32 s101, s41, 0
	s_add_u32 s100, s100, 0x80
	s_addc_u32 s101, s101, 0
	s_add_i32 s30, s29, 2
	s_cmp_lt_u32 s29, 30
	s_cselect_b32 s0, 0, 0xffffffe0
	s_add_i32 s0, s30, s0
	s_ashr_i32 s1, s0, 31
	s_lshl_b64 s[0:1], s[0:1], 7
	s_add_u32 s2, s40, s0
	s_addc_u32 s31, s41, s1
	s_add_u32 s0, s34, s0
	s_addc_u32 s1, s35, s1
	s_cmp_eq_u32 s29, 30
	s_cselect_b32 s45, s13, s31
	s_cselect_b32 s44, s15, s2
	s_cselect_b32 s49, s71, s1
	s_cselect_b32 s48, s75, s0
	s_add_i32 s2, 0, 0x10000
	s_add_i32 s78, s2, s56
	s_add_i32 s31, 0, 0x14000
	s_add_i32 s47, s57, 0xe000
	s_add_i32 s81, s78, 0x2000
	s_add_u32 s50, s48, 0x80000
	s_addc_u32 s51, s49, 0
	s_add_i32 s82, s31, s56
	v_add_u32_e32 v162, s2, v99
	v_add_u32_e32 v166, s31, v99
	s_add_i32 s83, s82, 0x2000
	s_add_i32 s84, 0, 0x18000
	s_add_i32 s88, 0, 0x1c000
	ds_read_b128 v[150:153], v162
	ds_read_b128 v[154:157], v162 offset:1024
	ds_read_b128 v[158:161], v162 offset:2048
	ds_read_b128 v[162:165], v162 offset:3072
	ds_read_b128 v[180:183], v166
	ds_read_b128 v[184:187], v166 offset:1024
	ds_read_b128 v[188:191], v166 offset:2048
	ds_read_b128 v[192:195], v166 offset:3072
	s_add_u32 s42, s44, 0x80000
	s_addc_u32 s43, s45, 0
	s_add_i32 s1, s84, s56
	s_add_i32 s0, s1, 0x2000
	s_add_u32 s36, s48, 0x80080
	s_addc_u32 s37, s49, 0
	s_add_i32 s46, s88, s56
	s_add_i32 s31, s46, 0x2000
	ds_read_b128 v[196:199], v149
	ds_read_b128 v[200:203], v149 offset:1024
	ds_read_b128 v[222:225], v149 offset:2048
	ds_read_b128 v[226:229], v149 offset:3072
	ds_read_b128 v[230:233], v149 offset:4096
	ds_read_b128 v[234:237], v149 offset:5120
	ds_read_b128 v[238:241], v149 offset:6144
	ds_read_b128 v[242:245], v149 offset:7168
	v_lshl_add_u64 v[166:167], s[100:101], 0, v[138:139]
	s_mov_b32 m0, s61
	v_lshl_add_u64 v[168:169], s[100:101], 0, v[134:135]
	global_load_lds_dwordx4 v[166:167], off
	s_mov_b32 m0, s62
	s_nop 0
	global_load_lds_dwordx4 v[168:169], off
	s_add_i32 m0, s57, 0xc000
	s_nop 0
	global_load_lds_dwordx4 v[146:147], off
	s_mov_b32 m0, s47
	s_nop 0
	global_load_lds_dwordx4 v[144:145], off
	s_waitcnt vmcnt(8)
	s_waitcnt lgkmcnt(0)
	s_setprio 1
	s_barrier
	v_mfma_f32_16x16x32_bf16 v[128:131], v[150:153], v[196:199], v[128:131]
	v_mfma_f32_16x16x32_bf16 v[128:131], v[154:157], v[200:203], v[128:131]
	v_mfma_f32_16x16x32_bf16 v[120:123], v[158:161], v[196:199], v[120:123]
	v_mfma_f32_16x16x32_bf16 v[120:123], v[162:165], v[200:203], v[120:123]
	v_mfma_f32_16x16x32_bf16 v[112:115], v[150:153], v[222:225], v[112:115]
	v_mfma_f32_16x16x32_bf16 v[112:115], v[154:157], v[226:229], v[112:115]
	v_mfma_f32_16x16x32_bf16 v[104:107], v[158:161], v[222:225], v[104:107]
	v_mfma_f32_16x16x32_bf16 v[104:107], v[162:165], v[226:229], v[104:107]
	v_mfma_f32_16x16x32_bf16 v[94:97], v[150:153], v[230:233], v[94:97]
	v_mfma_f32_16x16x32_bf16 v[94:97], v[154:157], v[234:237], v[94:97]
	v_mfma_f32_16x16x32_bf16 v[86:89], v[158:161], v[230:233], v[86:89]
	v_mfma_f32_16x16x32_bf16 v[86:89], v[162:165], v[234:237], v[86:89]
	v_mfma_f32_16x16x32_bf16 v[78:81], v[150:153], v[238:241], v[78:81]
	v_mfma_f32_16x16x32_bf16 v[78:81], v[154:157], v[242:245], v[78:81]
	v_mfma_f32_16x16x32_bf16 v[70:73], v[158:161], v[238:241], v[70:73]
	v_mfma_f32_16x16x32_bf16 v[70:73], v[162:165], v[242:245], v[70:73]
	s_setprio 0
	s_setprio 1
	v_mfma_f32_16x16x32_bf16 v[124:127], v[180:183], v[196:199], v[124:127]
	v_mfma_f32_16x16x32_bf16 v[124:127], v[184:187], v[200:203], v[124:127]
	v_mfma_f32_16x16x32_bf16 v[116:119], v[188:191], v[196:199], v[116:119]
	v_mfma_f32_16x16x32_bf16 v[116:119], v[192:195], v[200:203], v[116:119]
	v_mfma_f32_16x16x32_bf16 v[108:111], v[180:183], v[222:225], v[108:111]
	v_mfma_f32_16x16x32_bf16 v[108:111], v[184:187], v[226:229], v[108:111]
	v_mfma_f32_16x16x32_bf16 v[100:103], v[188:191], v[222:225], v[100:103]
	v_mfma_f32_16x16x32_bf16 v[100:103], v[192:195], v[226:229], v[100:103]
	v_mfma_f32_16x16x32_bf16 v[90:93], v[180:183], v[230:233], v[90:93]
	v_mfma_f32_16x16x32_bf16 v[90:93], v[184:187], v[234:237], v[90:93]
	v_mfma_f32_16x16x32_bf16 v[82:85], v[188:191], v[230:233], v[82:85]
	v_mfma_f32_16x16x32_bf16 v[82:85], v[192:195], v[234:237], v[82:85]
	v_mfma_f32_16x16x32_bf16 v[74:77], v[180:183], v[238:241], v[74:77]
	v_mfma_f32_16x16x32_bf16 v[74:77], v[184:187], v[242:245], v[74:77]
	s_setprio 2
	s_barrier
	v_mfma_f32_16x16x32_bf16 v[66:69], v[188:191], v[238:241], v[66:69]
	v_mfma_f32_16x16x32_bf16 v[66:69], v[192:195], v[242:245], v[66:69]
	s_setprio 0
	s_mov_b32 m0, s78
	v_lshl_add_u64 v[166:167], s[48:49], 0, v[136:137]
	ds_read_b128 v[196:199], v149 offset:16384
	ds_read_b128 v[200:203], v149 offset:17408
	ds_read_b128 v[222:225], v149 offset:18432
	ds_read_b128 v[226:229], v149 offset:19456
	ds_read_b128 v[230:233], v149 offset:20480
	ds_read_b128 v[234:237], v149 offset:21504
	ds_read_b128 v[238:241], v149 offset:22528
	ds_read_b128 v[242:245], v149 offset:23552
	global_load_lds_dwordx4 v[166:167], off
	v_lshl_add_u64 v[168:169], s[48:49], 0, v[132:133]
	s_mov_b32 m0, s81
	v_lshl_add_u64 v[172:173], s[50:51], 0, v[136:137]
	global_load_lds_dwordx4 v[168:169], off
	s_mov_b32 m0, s82
	global_load_lds_dwordx4 v[172:173], off
	v_lshl_add_u64 v[172:173], s[50:51], 0, v[132:133]
	s_mov_b32 m0, s83
	s_nop 0
	global_load_lds_dwordx4 v[172:173], off
	s_waitcnt vmcnt(6)
	s_waitcnt lgkmcnt(0)
	s_setprio 1
	s_barrier
; #define PG8_STAGE(bufoff, gbase, voff) do { _Pragma("unroll") for (int _i = 0; _i < 2; ++_i) \
;         __builtin_amdgcn_global_load_lds((const unsigned*)((const char*)(gbase) + (voff)[_i]), (PG8_LAS unsigned*)(lds + (bufoff) + ldsw + _i * 8192), 16, 0, AUX_A); } while (0)
; #define PG8_LDA(dst, b, h) do { _Pragma("unroll") for (int m = 0; m < 4; ++m) _Pragma("unroll") for (int k = 0; k < 2; ++k) dst[m][k] = *(const PG8_LAS bf16x8*)(lds + PG8_SA(b, h) + aoff + m * 2048 + k * 1024); } while (0)
; #define PG8_LDB(dst, b, h) do { _Pragma("unroll") for (int n = 0; n < 2; ++n) _Pragma("unroll") for (int k = 0; k < 2; ++k) dst[n][k] = *(const PG8_LAS bf16x8*)(lds + PG8_SB(b, h) + boff + n * 2048 + k * 1024); } while (0)
; #define PG8_MMA(ai, bj, At, Bt) do { __builtin_amdgcn_s_setprio(1); _Pragma("unroll") for (int m = 0; m < 4; ++m) _Pragma("unroll") for (int n = 0; n < 2; ++n) _Pragma("unroll") for (int k = 0; k < 2; ++k) \
;         acc[ai][bj][m][n] = __builtin_amdgcn_mfma_f32_16x16x32_bf16(Bt[n][k], At[m][k], acc[ai][bj][m][n], 0, 0, 0); __builtin_amdgcn_s_setprio(0); } while (0)
; #define PG8_WAIT_V(n) asm volatile("s_waitcnt vmcnt(" #n ")" ::: "memory")
; #define PG8_WAIT_L(n) asm volatile("s_waitcnt lgkmcnt(" #n ")" ::: "memory")
; #define PG8_BAR __builtin_amdgcn_s_barrier()
; #define PG8_SCHED __builtin_amdgcn_sched_barrier(0)
; template <class Epi, class Sched, bool ALIGN_EPI = false, bool SP2 = false>
; __device__ __forceinline__ void gemm_phase(PG8_LAS unsigned char* lds, const Gemm g, const Sched& S, const Epi& E) {
;     ...
;             PG8_WAIT_V(8); PG8_WAIT_L(0); PG8_BAR; PG8_MMA(1, 0, At, B0); PG8_MMA(1, 1, At, B1); PG8_BAR; PG8_SCHED;
;             PG8_LDB(B0, 1, 0); PG8_LDB(B1, 1, 1); PG8_SCHED; PG8_LDA(At, 1, 0); PG8_STAGE(PG8_SA(0, 1), a2 + hstep, voffA);
;             PG8_WAIT_V(8); PG8_WAIT_L(0); PG8_BAR; PG8_MMA(0, 0, At, B0); PG8_MMA(0, 1, At, B1); PG8_BAR; PG8_SCHED;
	v_mfma_f32_16x16x32_bf16 v[62:65], v[150:153], v[196:199], v[62:65]
	v_mfma_f32_16x16x32_bf16 v[62:65], v[154:157], v[200:203], v[62:65]
	v_mfma_f32_16x16x32_bf16 v[54:57], v[158:161], v[196:199], v[54:57]
	v_mfma_f32_16x16x32_bf16 v[54:57], v[162:165], v[200:203], v[54:57]
	v_mfma_f32_16x16x32_bf16 v[46:49], v[150:153], v[222:225], v[46:49]
	v_mfma_f32_16x16x32_bf16 v[46:49], v[154:157], v[226:229], v[46:49]
	v_mfma_f32_16x16x32_bf16 v[38:41], v[158:161], v[222:225], v[38:41]
	v_mfma_f32_16x16x32_bf16 v[38:41], v[162:165], v[226:229], v[38:41]
	v_mfma_f32_16x16x32_bf16 v[30:33], v[150:153], v[230:233], v[30:33]
	v_mfma_f32_16x16x32_bf16 v[30:33], v[154:157], v[234:237], v[30:33]
	v_mfma_f32_16x16x32_bf16 v[22:25], v[158:161], v[230:233], v[22:25]
	v_mfma_f32_16x16x32_bf16 v[22:25], v[162:165], v[234:237], v[22:25]
	v_mfma_f32_16x16x32_bf16 v[14:17], v[150:153], v[238:241], v[14:17]
	v_mfma_f32_16x16x32_bf16 v[14:17], v[154:157], v[242:245], v[14:17]
	v_mfma_f32_16x16x32_bf16 v[6:9], v[158:161], v[238:241], v[6:9]
	v_mfma_f32_16x16x32_bf16 v[6:9], v[162:165], v[242:245], v[6:9]
	s_setprio 0
	s_setprio 1
	v_mfma_f32_16x16x32_bf16 v[58:61], v[180:183], v[196:199], v[58:61]
	v_mfma_f32_16x16x32_bf16 v[58:61], v[184:187], v[200:203], v[58:61]
	v_mfma_f32_16x16x32_bf16 v[50:53], v[188:191], v[196:199], v[50:53]
	v_mfma_f32_16x16x32_bf16 v[50:53], v[192:195], v[200:203], v[50:53]
	v_mfma_f32_16x16x32_bf16 v[42:45], v[180:183], v[222:225], v[42:45]
	v_mfma_f32_16x16x32_bf16 v[42:45], v[184:187], v[226:229], v[42:45]
	v_mfma_f32_16x16x32_bf16 v[34:37], v[188:191], v[222:225], v[34:37]
	v_mfma_f32_16x16x32_bf16 v[34:37], v[192:195], v[226:229], v[34:37]
	v_mfma_f32_16x16x32_bf16 v[26:29], v[180:183], v[230:233], v[26:29]
	v_mfma_f32_16x16x32_bf16 v[26:29], v[184:187], v[234:237], v[26:29]
	v_mfma_f32_16x16x32_bf16 v[18:21], v[188:191], v[230:233], v[18:21]
	v_mfma_f32_16x16x32_bf16 v[18:21], v[192:195], v[234:237], v[18:21]
	v_mfma_f32_16x16x32_bf16 v[10:13], v[180:183], v[238:241], v[10:13]
	v_mfma_f32_16x16x32_bf16 v[10:13], v[184:187], v[242:245], v[10:13]
	s_setprio 2
	s_barrier
	v_mfma_f32_16x16x32_bf16 v[2:5], v[188:191], v[238:241], v[2:5]
	v_mfma_f32_16x16x32_bf16 v[2:5], v[192:195], v[242:245], v[2:5]
	s_setprio 0
	v_add_u32_e32 v162, s84, v99
	v_add_u32_e32 v192, s88, v99
	ds_read_b128 v[150:153], v162
	ds_read_b128 v[154:157], v162 offset:1024
	ds_read_b128 v[158:161], v162 offset:2048
	ds_read_b128 v[162:165], v162 offset:3072
	ds_read_b128 v[180:183], v192
	ds_read_b128 v[184:187], v192 offset:1024
	ds_read_b128 v[188:191], v192 offset:2048
	ds_read_b128 v[192:195], v192 offset:3072
	s_mov_b32 m0, s59
	v_lshl_add_u64 v[246:247], s[42:43], 0, v[138:139]
	ds_read_b128 v[196:199], v149 offset:32768
	ds_read_b128 v[200:203], v149 offset:33792
	ds_read_b128 v[222:225], v149 offset:34816
	ds_read_b128 v[226:229], v149 offset:35840
	ds_read_b128 v[230:233], v149 offset:36864
	ds_read_b128 v[234:237], v149 offset:37888
	ds_read_b128 v[238:241], v149 offset:38912
	ds_read_b128 v[242:245], v149 offset:39936
	v_lshl_add_u64 v[172:173], s[44:45], 0, v[138:139]
	s_mov_b32 m0, s57
	v_lshl_add_u64 v[212:213], s[44:45], 0, v[134:135]
	global_load_lds_dwordx4 v[172:173], off
	s_mov_b32 m0, s58
	s_nop 0
	global_load_lds_dwordx4 v[212:213], off
	s_mov_b32 m0, s59
	s_nop 0
	global_load_lds_dwordx4 v[246:247], off
	v_lshl_add_u64 v[246:247], s[42:43], 0, v[134:135]
	s_mov_b32 m0, s60
	s_nop 0
	global_load_lds_dwordx4 v[246:247], off
	s_waitcnt vmcnt(8)
	s_waitcnt lgkmcnt(0)
	s_setprio 1
	s_barrier
; #define PG8_STAGE(bufoff, gbase, voff) do { _Pragma("unroll") for (int _i = 0; _i < 2; ++_i) \
;         __builtin_amdgcn_global_load_lds((const unsigned*)((const char*)(gbase) + (voff)[_i]), (PG8_LAS unsigned*)(lds + (bufoff) + ldsw + _i * 8192), 16, 0, AUX_A); } while (0)
; #define PG8_STAGEB(bufoff, gbase, voff) do { _Pragma("unroll") for (int _i = 0; _i < 2; ++_i) \
;         __builtin_amdgcn_global_load_lds((const unsigned*)((const char*)(gbase) + (voff)[_i]), (PG8_LAS unsigned*)(lds + (bufoff) + ldsw + _i * 8192), 16, 0, AUX_B); } while (0)
; #define PG8_LDA(dst, b, h) do { _Pragma("unroll") for (int m = 0; m < 4; ++m) _Pragma("unroll") for (int k = 0; k < 2; ++k) dst[m][k] = *(const PG8_LAS bf16x8*)(lds + PG8_SA(b, h) + aoff + m * 2048 + k * 1024); } while (0)
; #define PG8_MMA(ai, bj, At, Bt) do { __builtin_amdgcn_s_setprio(1); _Pragma("unroll") for (int m = 0; m < 4; ++m) _Pragma("unroll") for (int n = 0; n < 2; ++n) _Pragma("unroll") for (int k = 0; k < 2; ++k) \
;         acc[ai][bj][m][n] = __builtin_amdgcn_mfma_f32_16x16x32_bf16(Bt[n][k], At[m][k], acc[ai][bj][m][n], 0, 0, 0); __builtin_amdgcn_s_setprio(0); } while (0)
; #define PG8_WAIT_V(n) asm volatile("s_waitcnt vmcnt(" #n ")" ::: "memory")
; #define PG8_WAIT_L(n) asm volatile("s_waitcnt lgkmcnt(" #n ")" ::: "memory")
; #define PG8_BAR __builtin_amdgcn_s_barrier()
; #define PG8_SCHED __builtin_amdgcn_sched_barrier(0)
; template <class Epi, class Sched, bool ALIGN_EPI = false, bool SP2 = false>
; __device__ __forceinline__ void gemm_phase(PG8_LAS unsigned char* lds, const Gemm g, const Sched& S, const Epi& E) {
;     ...
;             PG8_WAIT_V(8); PG8_WAIT_L(0); PG8_BAR; PG8_MMA(0, 0, At, B0); PG8_MMA(0, 1, At, B1); PG8_BAR; PG8_SCHED;
;             PG8_LDA(At, 1, 1); PG8_STAGEB(PG8_SB(1, 0), b3, voffB); PG8_STAGEB(PG8_SB(1, 1), b3 + hstep, voffB); PG8_STAGE(PG8_SA(1, 0), a3, voffA);
;             PG8_WAIT_V(8); PG8_WAIT_L(0); PG8_BAR; PG8_MMA(1, 0, At, B0); PG8_MMA(1, 1, At, B1); PG8_BAR; PG8_SCHED;
	v_mfma_f32_16x16x32_bf16 v[128:131], v[150:153], v[196:199], v[128:131]
	v_mfma_f32_16x16x32_bf16 v[128:131], v[154:157], v[200:203], v[128:131]
	v_mfma_f32_16x16x32_bf16 v[120:123], v[158:161], v[196:199], v[120:123]
	v_mfma_f32_16x16x32_bf16 v[120:123], v[162:165], v[200:203], v[120:123]
	v_mfma_f32_16x16x32_bf16 v[112:115], v[150:153], v[222:225], v[112:115]
	v_mfma_f32_16x16x32_bf16 v[112:115], v[154:157], v[226:229], v[112:115]
	v_mfma_f32_16x16x32_bf16 v[104:107], v[158:161], v[222:225], v[104:107]
	v_mfma_f32_16x16x32_bf16 v[104:107], v[162:165], v[226:229], v[104:107]
	v_mfma_f32_16x16x32_bf16 v[94:97], v[150:153], v[230:233], v[94:97]
	v_mfma_f32_16x16x32_bf16 v[94:97], v[154:157], v[234:237], v[94:97]
	v_mfma_f32_16x16x32_bf16 v[86:89], v[158:161], v[230:233], v[86:89]
	v_mfma_f32_16x16x32_bf16 v[86:89], v[162:165], v[234:237], v[86:89]
	v_mfma_f32_16x16x32_bf16 v[78:81], v[150:153], v[238:241], v[78:81]
	v_mfma_f32_16x16x32_bf16 v[78:81], v[154:157], v[242:245], v[78:81]
	v_mfma_f32_16x16x32_bf16 v[70:73], v[158:161], v[238:241], v[70:73]
	v_mfma_f32_16x16x32_bf16 v[70:73], v[162:165], v[242:245], v[70:73]
	s_setprio 0
	s_setprio 1
	v_mfma_f32_16x16x32_bf16 v[124:127], v[180:183], v[196:199], v[124:127]
	v_mfma_f32_16x16x32_bf16 v[124:127], v[184:187], v[200:203], v[124:127]
	v_mfma_f32_16x16x32_bf16 v[116:119], v[188:191], v[196:199], v[116:119]
	v_mfma_f32_16x16x32_bf16 v[116:119], v[192:195], v[200:203], v[116:119]
	v_mfma_f32_16x16x32_bf16 v[108:111], v[180:183], v[222:225], v[108:111]
	v_mfma_f32_16x16x32_bf16 v[108:111], v[184:187], v[226:229], v[108:111]
	v_mfma_f32_16x16x32_bf16 v[100:103], v[188:191], v[222:225], v[100:103]
	v_mfma_f32_16x16x32_bf16 v[100:103], v[192:195], v[226:229], v[100:103]
	v_mfma_f32_16x16x32_bf16 v[90:93], v[180:183], v[230:233], v[90:93]
	v_mfma_f32_16x16x32_bf16 v[90:93], v[184:187], v[234:237], v[90:93]
	v_mfma_f32_16x16x32_bf16 v[82:85], v[188:191], v[230:233], v[82:85]
	v_mfma_f32_16x16x32_bf16 v[82:85], v[192:195], v[234:237], v[82:85]
	v_mfma_f32_16x16x32_bf16 v[74:77], v[180:183], v[238:241], v[74:77]
	v_mfma_f32_16x16x32_bf16 v[74:77], v[184:187], v[242:245], v[74:77]
	s_setprio 2
	s_barrier
	v_mfma_f32_16x16x32_bf16 v[66:69], v[188:191], v[238:241], v[66:69]
	v_mfma_f32_16x16x32_bf16 v[66:69], v[192:195], v[242:245], v[66:69]
	s_setprio 0
	s_mov_b32 m0, s1
	v_lshl_add_u64 v[166:167], v[166:167], 0, s[76:77]
	ds_read_b128 v[196:199], v149 offset:49152
	ds_read_b128 v[200:203], v149 offset:50176
	ds_read_b128 v[222:225], v149 offset:51200
	ds_read_b128 v[226:229], v149 offset:52224
	ds_read_b128 v[230:233], v149 offset:53248
	ds_read_b128 v[234:237], v149 offset:54272
	ds_read_b128 v[238:241], v149 offset:55296
	ds_read_b128 v[242:245], v149 offset:56320
	global_load_lds_dwordx4 v[166:167], off
	v_lshl_add_u64 v[166:167], v[168:169], 0, s[76:77]
	s_mov_b32 m0, s0
	s_nop 0
	global_load_lds_dwordx4 v[166:167], off
	v_lshl_add_u64 v[166:167], s[36:37], 0, v[136:137]
	s_mov_b32 m0, s46
	s_nop 0
	global_load_lds_dwordx4 v[166:167], off
	v_lshl_add_u64 v[166:167], s[36:37], 0, v[132:133]
	s_mov_b32 m0, s31
	s_nop 0
	global_load_lds_dwordx4 v[166:167], off
	s_waitcnt vmcnt(6)
	s_waitcnt lgkmcnt(0)
	s_setprio 1
	s_barrier
	v_mfma_f32_16x16x32_bf16 v[62:65], v[150:153], v[196:199], v[62:65]
	v_mfma_f32_16x16x32_bf16 v[62:65], v[154:157], v[200:203], v[62:65]
	v_mfma_f32_16x16x32_bf16 v[54:57], v[158:161], v[196:199], v[54:57]
	v_mfma_f32_16x16x32_bf16 v[54:57], v[162:165], v[200:203], v[54:57]
	v_mfma_f32_16x16x32_bf16 v[46:49], v[150:153], v[222:225], v[46:49]
	v_mfma_f32_16x16x32_bf16 v[46:49], v[154:157], v[226:229], v[46:49]
	v_mfma_f32_16x16x32_bf16 v[38:41], v[158:161], v[222:225], v[38:41]
	v_mfma_f32_16x16x32_bf16 v[38:41], v[162:165], v[226:229], v[38:41]
	v_mfma_f32_16x16x32_bf16 v[30:33], v[150:153], v[230:233], v[30:33]
	v_mfma_f32_16x16x32_bf16 v[30:33], v[154:157], v[234:237], v[30:33]
	v_mfma_f32_16x16x32_bf16 v[22:25], v[158:161], v[230:233], v[22:25]
	v_mfma_f32_16x16x32_bf16 v[22:25], v[162:165], v[234:237], v[22:25]
	v_mfma_f32_16x16x32_bf16 v[14:17], v[150:153], v[238:241], v[14:17]
	v_mfma_f32_16x16x32_bf16 v[14:17], v[154:157], v[242:245], v[14:17]
	v_mfma_f32_16x16x32_bf16 v[6:9], v[158:161], v[238:241], v[6:9]
	v_mfma_f32_16x16x32_bf16 v[6:9], v[162:165], v[242:245], v[6:9]
	s_setprio 0
	s_setprio 1
	v_mfma_f32_16x16x32_bf16 v[58:61], v[180:183], v[196:199], v[58:61]
	v_mfma_f32_16x16x32_bf16 v[58:61], v[184:187], v[200:203], v[58:61]
	v_mfma_f32_16x16x32_bf16 v[50:53], v[188:191], v[196:199], v[50:53]
	v_mfma_f32_16x16x32_bf16 v[50:53], v[192:195], v[200:203], v[50:53]
	v_mfma_f32_16x16x32_bf16 v[42:45], v[180:183], v[222:225], v[42:45]
	v_mfma_f32_16x16x32_bf16 v[42:45], v[184:187], v[226:229], v[42:45]
	v_mfma_f32_16x16x32_bf16 v[34:37], v[188:191], v[222:225], v[34:37]
	v_mfma_f32_16x16x32_bf16 v[34:37], v[192:195], v[226:229], v[34:37]
	v_mfma_f32_16x16x32_bf16 v[26:29], v[180:183], v[230:233], v[26:29]
	v_mfma_f32_16x16x32_bf16 v[26:29], v[184:187], v[234:237], v[26:29]
	v_mfma_f32_16x16x32_bf16 v[18:21], v[188:191], v[230:233], v[18:21]
	v_mfma_f32_16x16x32_bf16 v[18:21], v[192:195], v[234:237], v[18:21]
	v_mfma_f32_16x16x32_bf16 v[10:13], v[180:183], v[238:241], v[10:13]
	v_mfma_f32_16x16x32_bf16 v[10:13], v[184:187], v[242:245], v[10:13]
	s_setprio 2
	s_cmp_gt_u32 s30, 31
	s_cbranch_scc0 .Lq4b_1458l
	v_cmp_ne_u32_e64 vcc, s10, 0
	s_cbranch_vccz .Lq4s_1458l

;     __device__ __forceinline__ void operator()(const f32x4 (&acc)[2][2][4][2], const Unit& u, int wr, int wc, int fr, int fq) const {
;         const int row0 = u.pm * BM + wr * 64 + fr, col0 = u.pn * HALF + wc * 32 + 8 * fq;
;         bf16_t* const p0 = ACT + (size_t)row0 * 5632 + col0;
; #pragma unroll
;         for (int ai = 0; ai < 2; ++ai)
; #pragma unroll
;             for (int m = 0; m < 4; ++m) {
;                 const f32x4 g0 = acc[ai][0][m][0], g1 = acc[ai][0][m][1];
;                 const f32x4 v0 = g0 * sigmoid4(g0) * acc[ai][1][m][0], v1 = g1 * sigmoid4(g1) * acc[ai][1][m][1];
;                 store16_wt(p0 + (size_t)(ai * HALF + m * 16) * 5632, pack8(v0, v1)); }
; template <class Epi, class Sched, bool ALIGN_EPI = false, bool SP2 = false>
; __device__ __forceinline__ void gemm_phase(PG8_LAS unsigned char* lds, const Gemm g, const Sched& S, const Epi& E) {
;     ...
;             PG8_WAIT_V(8); PG8_WAIT_L(0); PG8_BAR; PG8_MMA(1, 0, At, B0); PG8_MMA(1, 1, At, B1); PG8_BAR; PG8_SCHED;
;             } else {
;             PG8_LDB(B0, 0, 0); PG8_SCHED; PG8_LDA(At, 0, 0); PG8_STAGE(PG8_SA(1, 1), a1 + hstep, voffA);
;             PG8_WAIT_L(8); PG8_BAR; PG8_WAIT_L(0); PG8_MMA(0, 0, At, B0); PG8_BAR; PG8_SCHED;
;             PG8_LDB(B1, 0, 1); PG8_STAGEB(PG8_SB(0, 0), b2, voffB);
;             PG8_BAR; PG8_WAIT_L(0); PG8_MMA(0, 1, At, B1); PG8_BAR;
;             PG8_LDA(At, 0, 1); PG8_STAGE(PG8_SA(0, 0), a2, voffA);
;             PG8_BAR; PG8_WAIT_L(0); PG8_MMA(1, 0, At, B0); PG8_BAR; PG8_SCHED;
;             PG8_STAGEB(PG8_SB(0, 1), b2 + hstep, voffB);
;             PG8_WAIT_V(6); PG8_BAR; PG8_MMA(1, 1, At, B1); PG8_BAR;
;             PG8_LDB(B0, 1, 0); PG8_SCHED; PG8_LDA(At, 1, 0); PG8_STAGE(PG8_SA(0, 1), a2 + hstep, voffA);
;             PG8_WAIT_L(8); PG8_BAR; PG8_WAIT_L(0); PG8_MMA(0, 0, At, B0); PG8_BAR; PG8_SCHED;
;             PG8_LDB(B1, 1, 1); PG8_STAGEB(PG8_SB(1, 0), b3, voffB);
;             PG8_BAR; PG8_WAIT_L(0); PG8_MMA(0, 1, At, B1); PG8_BAR;
;             PG8_LDA(At, 1, 1); PG8_STAGE(PG8_SA(1, 0), a3, voffA);
;             PG8_BAR; PG8_WAIT_L(0); PG8_MMA(1, 0, At, B0); PG8_BAR; PG8_SCHED;
;             PG8_STAGEB(PG8_SB(1, 1), b3 + hstep, voffB);
;             PG8_WAIT_V(6); PG8_BAR; PG8_MMA(1, 1, At, B1); PG8_BAR;
;             }
;         }
;         if constexpr (ALIGN_EPI) { if (wr == 0) PG8_BAR; }
.Lq4s_1458l:
	v_mfma_f32_16x16x32_bf16 v[2:5], v[188:191], v[238:241], v[2:5]
	v_mfma_f32_16x16x32_bf16 v[2:5], v[192:195], v[242:245], v[2:5]
	s_setprio 0
	v_lshl_add_u64 v[144:145], v[144:145], 0, s[86:87]
	v_lshl_add_u64 v[146:147], v[146:147], 0, s[86:87]
	s_cmp_gt_u32 s30, 31
	s_mov_b32 s29, s30
	s_cbranch_scc0 .LBB0_1458
.Lpx_1458:
	s_and_b64 vcc, exec, s[10:11]
	s_cbranch_vccz .LBB0_1461
.LBB0_1461:
	v_lshl_add_u32 v145, s70, 8, v1
	v_lshl_or_b32 v144, s69, 7, v148
	v_mov_b64_e32 v[146:147], s[8:9]
	s_movk_i32 s0, 0x2c00
	v_mad_i64_i32 v[146:147], s[0:1], v145, s0, v[146:147]
	v_ashrrev_i32_e32 v145, 31, v144
	v_lshl_add_u64 v[144:145], v[144:145], 1, v[146:147]
	v_pk_mul_f32 v[146:147], v[128:129], s[74:75] op_sel_hi:[1,0]
	v_pk_mul_f32 v[150:151], v[130:131], s[74:75] op_sel_hi:[1,0]
	v_exp_f32_e32 v146, v146
	v_exp_f32_e32 v147, v147
	v_exp_f32_e32 v150, v150
	v_exp_f32_e32 v151, v151
	s_mov_b32 s0, 0x160000
	v_pk_add_f32 v[146:147], v[146:147], 1.0 op_sel_hi:[1,0]
	s_mov_b64 s[34:35], -1
	v_pk_add_f32 v[150:151], v[150:151], 1.0 op_sel_hi:[1,0]
	v_rcp_f32_e32 v146, v146
	v_rcp_f32_e32 v147, v147
	v_rcp_f32_e32 v150, v150
	v_rcp_f32_e32 v151, v151
	v_pk_mul_f32 v[128:129], v[128:129], v[146:147]
	s_nop 0
	v_pk_mul_f32 v[124:125], v[124:125], v[128:129]
	v_pk_mul_f32 v[130:131], v[130:131], v[150:151]
	v_pk_mul_f32 v[128:129], v[120:121], s[74:75] op_sel_hi:[1,0]
	v_pk_mul_f32 v[126:127], v[126:127], v[130:131]
	v_pk_mul_f32 v[130:131], v[122:123], s[74:75] op_sel_hi:[1,0]
	v_exp_f32_e32 v128, v128
	v_exp_f32_e32 v129, v129
	v_exp_f32_e32 v130, v130
	v_exp_f32_e32 v131, v131
	v_pk_add_f32 v[128:129], v[128:129], 1.0 op_sel_hi:[1,0]
	s_nop 0
	v_rcp_f32_e32 v128, v128
	v_pk_add_f32 v[130:131], v[130:131], 1.0 op_sel_hi:[1,0]
	v_rcp_f32_e32 v129, v129
	v_rcp_f32_e32 v130, v130
	v_rcp_f32_e32 v131, v131
	v_pk_mul_f32 v[120:121], v[120:121], v[128:129]
	v_pk_mul_f32 v[122:123], v[122:123], v[130:131]
	s_nop 0
	v_pk_mul_f32 v[122:123], v[118:119], v[122:123]
	v_pk_mul_f32 v[118:119], v[116:117], v[120:121]
	v_cvt_pk_bf16_f32 v116, v124, v125
	v_cvt_pk_bf16_f32 v117, v126, v127
	v_cvt_pk_bf16_f32 v118, v118, v119
	v_cvt_pk_bf16_f32 v119, v122, v123
	global_store_dwordx4 v[144:145], v[116:119], off sc1
	s_nop 1
	v_pk_mul_f32 v[116:117], v[112:113], s[74:75] op_sel_hi:[1,0]
	v_pk_mul_f32 v[118:119], v[114:115], s[74:75] op_sel_hi:[1,0]
	v_exp_f32_e32 v116, v116
	v_exp_f32_e32 v117, v117
	v_exp_f32_e32 v118, v118
	v_exp_f32_e32 v119, v119
	v_pk_add_f32 v[116:117], v[116:117], 1.0 op_sel_hi:[1,0]
	s_nop 0
	v_rcp_f32_e32 v116, v116
	v_pk_add_f32 v[118:119], v[118:119], 1.0 op_sel_hi:[1,0]
	v_rcp_f32_e32 v117, v117
	v_rcp_f32_e32 v118, v118
	v_rcp_f32_e32 v119, v119
	v_pk_mul_f32 v[112:113], v[112:113], v[116:117]
	s_nop 0
	v_pk_mul_f32 v[108:109], v[108:109], v[112:113]
	v_pk_mul_f32 v[114:115], v[114:115], v[118:119]
	v_pk_mul_f32 v[112:113], v[104:105], s[74:75] op_sel_hi:[1,0]
	v_pk_mul_f32 v[110:111], v[110:111], v[114:115]
	v_pk_mul_f32 v[114:115], v[106:107], s[74:75] op_sel_hi:[1,0]
	v_exp_f32_e32 v112, v112
	v_exp_f32_e32 v113, v113
	v_exp_f32_e32 v114, v114
	v_exp_f32_e32 v115, v115
	v_pk_add_f32 v[112:113], v[112:113], 1.0 op_sel_hi:[1,0]
	s_nop 0
	v_rcp_f32_e32 v112, v112
	v_pk_add_f32 v[114:115], v[114:115], 1.0 op_sel_hi:[1,0]
	v_rcp_f32_e32 v113, v113
	v_rcp_f32_e32 v114, v114
	v_rcp_f32_e32 v115, v115
	v_pk_mul_f32 v[104:105], v[104:105], v[112:113]
	v_pk_mul_f32 v[106:107], v[106:107], v[114:115]
	s_nop 0
	v_pk_mul_f32 v[106:107], v[102:103], v[106:107]
	v_pk_mul_f32 v[102:103], v[100:101], v[104:105]
	v_add_co_u32_e32 v104, vcc, s65, v144
	v_cvt_pk_bf16_f32 v100, v108, v109
	v_cvt_pk_bf16_f32 v101, v110, v111
	v_cvt_pk_bf16_f32 v102, v102, v103
	v_cvt_pk_bf16_f32 v103, v106, v107
	v_addc_co_u32_e32 v105, vcc, 0, v145, vcc
	global_store_dwordx4 v[104:105], v[100:103], off sc1
	s_nop 1
	v_pk_mul_f32 v[100:101], v[94:95], s[74:75] op_sel_hi:[1,0]
	v_pk_mul_f32 v[102:103], v[96:97], s[74:75] op_sel_hi:[1,0]
	v_exp_f32_e32 v100, v100
	v_exp_f32_e32 v101, v101
	v_exp_f32_e32 v102, v102
	v_exp_f32_e32 v103, v103
	v_pk_add_f32 v[100:101], v[100:101], 1.0 op_sel_hi:[1,0]
	s_nop 0
	v_rcp_f32_e32 v100, v100
	v_pk_add_f32 v[102:103], v[102:103], 1.0 op_sel_hi:[1,0]
	v_rcp_f32_e32 v101, v101
	v_rcp_f32_e32 v102, v102
	v_rcp_f32_e32 v103, v103
	v_pk_mul_f32 v[94:95], v[94:95], v[100:101]
	s_nop 0
	v_pk_mul_f32 v[90:91], v[90:91], v[94:95]
	v_pk_mul_f32 v[96:97], v[96:97], v[102:103]
	v_pk_mul_f32 v[94:95], v[86:87], s[74:75] op_sel_hi:[1,0]
	v_pk_mul_f32 v[92:93], v[92:93], v[96:97]
	v_pk_mul_f32 v[96:97], v[88:89], s[74:75] op_sel_hi:[1,0]
	v_exp_f32_e32 v94, v94
	v_exp_f32_e32 v95, v95
	v_exp_f32_e32 v96, v96
	v_exp_f32_e32 v97, v97
	v_pk_add_f32 v[94:95], v[94:95], 1.0 op_sel_hi:[1,0]
	s_nop 0
	v_rcp_f32_e32 v94, v94
	v_pk_add_f32 v[96:97], v[96:97], 1.0 op_sel_hi:[1,0]
	v_rcp_f32_e32 v95, v95
	v_rcp_f32_e32 v96, v96
	v_rcp_f32_e32 v97, v97
	v_pk_mul_f32 v[86:87], v[86:87], v[94:95]
	v_pk_mul_f32 v[88:89], v[88:89], v[96:97]
	s_nop 0
	v_pk_mul_f32 v[88:89], v[84:85], v[88:89]
	v_pk_mul_f32 v[84:85], v[82:83], v[86:87]
	v_add_co_u32_e32 v86, vcc, s64, v144
	v_cvt_pk_bf16_f32 v82, v90, v91
	v_cvt_pk_bf16_f32 v83, v92, v93
	v_cvt_pk_bf16_f32 v84, v84, v85
	v_cvt_pk_bf16_f32 v85, v88, v89
	v_addc_co_u32_e32 v87, vcc, 0, v145, vcc
	global_store_dwordx4 v[86:87], v[82:85], off sc1
	s_nop 1
	v_pk_mul_f32 v[82:83], v[78:79], s[74:75] op_sel_hi:[1,0]
	v_pk_mul_f32 v[84:85], v[80:81], s[74:75] op_sel_hi:[1,0]
	v_exp_f32_e32 v82, v82
	v_exp_f32_e32 v83, v83
	v_exp_f32_e32 v84, v84
	v_exp_f32_e32 v85, v85
	v_pk_add_f32 v[82:83], v[82:83], 1.0 op_sel_hi:[1,0]
; __device__ __forceinline__ u32x4 pack8(f32x4 v0, f32x4 v1) { u32x4 w; w.x = cvt_pk_bf16(v0[0], v0[1]); w.y = cvt_pk_bf16(v0[2], v0[3]); w.z = cvt_pk_bf16(v1[0], v1[1]); w.w = cvt_pk_bf16(v1[2], v1[3]); return w; }
;     __device__ __forceinline__ void operator()(const f32x4 (&acc)[2][2][4][2], const Unit& u, int wr, int wc, int fr, int fq) const {
;     ...
;         for (int ai = 0; ai < 2; ++ai)
; #pragma unroll
;             for (int m = 0; m < 4; ++m) {
;                 const f32x4 g0 = acc[ai][0][m][0], g1 = acc[ai][0][m][1];
;                 const f32x4 v0 = g0 * sigmoid4(g0) * acc[ai][1][m][0], v1 = g1 * sigmoid4(g1) * acc[ai][1][m][1];
;                 store16_wt(p0 + (size_t)(ai * HALF + m * 16) * 5632, pack8(v0, v1)); }
	s_nop 0
	v_rcp_f32_e32 v82, v82
	v_pk_add_f32 v[84:85], v[84:85], 1.0 op_sel_hi:[1,0]
	v_rcp_f32_e32 v83, v83
	v_rcp_f32_e32 v84, v84
	v_rcp_f32_e32 v85, v85
	v_pk_mul_f32 v[78:79], v[78:79], v[82:83]
	s_nop 0
	v_pk_mul_f32 v[74:75], v[74:75], v[78:79]
	v_pk_mul_f32 v[80:81], v[80:81], v[84:85]
	v_pk_mul_f32 v[78:79], v[70:71], s[74:75] op_sel_hi:[1,0]
	v_pk_mul_f32 v[76:77], v[76:77], v[80:81]
	v_pk_mul_f32 v[80:81], v[72:73], s[74:75] op_sel_hi:[1,0]
	v_exp_f32_e32 v78, v78
	v_exp_f32_e32 v79, v79
	v_exp_f32_e32 v80, v80
	v_exp_f32_e32 v81, v81
	v_pk_add_f32 v[78:79], v[78:79], 1.0 op_sel_hi:[1,0]
	s_nop 0
	v_rcp_f32_e32 v78, v78
	v_pk_add_f32 v[80:81], v[80:81], 1.0 op_sel_hi:[1,0]
	v_rcp_f32_e32 v79, v79
	v_rcp_f32_e32 v80, v80
	v_rcp_f32_e32 v81, v81
	v_pk_mul_f32 v[70:71], v[70:71], v[78:79]
	v_pk_mul_f32 v[72:73], v[72:73], v[80:81]
	s_nop 0
	v_pk_mul_f32 v[72:73], v[68:69], v[72:73]
	v_pk_mul_f32 v[68:69], v[66:67], v[70:71]
	v_add_co_u32_e32 v70, vcc, s66, v144
	v_cvt_pk_bf16_f32 v66, v74, v75
	v_cvt_pk_bf16_f32 v67, v76, v77
	v_cvt_pk_bf16_f32 v68, v68, v69
	v_cvt_pk_bf16_f32 v69, v72, v73
	v_addc_co_u32_e32 v71, vcc, 0, v145, vcc
	global_store_dwordx4 v[70:71], v[66:69], off sc1
	s_nop 1
	v_pk_mul_f32 v[66:67], v[62:63], s[74:75] op_sel_hi:[1,0]
	v_pk_mul_f32 v[68:69], v[64:65], s[74:75] op_sel_hi:[1,0]
	v_exp_f32_e32 v66, v66
	v_exp_f32_e32 v67, v67
	v_exp_f32_e32 v68, v68
	v_exp_f32_e32 v69, v69
	v_pk_add_f32 v[66:67], v[66:67], 1.0 op_sel_hi:[1,0]
	s_nop 0
	v_rcp_f32_e32 v66, v66
	v_pk_add_f32 v[68:69], v[68:69], 1.0 op_sel_hi:[1,0]
	v_rcp_f32_e32 v67, v67
	v_rcp_f32_e32 v68, v68
	v_rcp_f32_e32 v69, v69
	v_pk_mul_f32 v[62:63], v[62:63], v[66:67]
	s_nop 0
	v_pk_mul_f32 v[58:59], v[58:59], v[62:63]
	v_pk_mul_f32 v[64:65], v[64:65], v[68:69]
	v_pk_mul_f32 v[62:63], v[54:55], s[74:75] op_sel_hi:[1,0]
	v_pk_mul_f32 v[60:61], v[60:61], v[64:65]
	v_pk_mul_f32 v[64:65], v[56:57], s[74:75] op_sel_hi:[1,0]
	v_exp_f32_e32 v62, v62
	v_exp_f32_e32 v63, v63
	v_exp_f32_e32 v64, v64
	v_exp_f32_e32 v65, v65
	v_pk_add_f32 v[62:63], v[62:63], 1.0 op_sel_hi:[1,0]
	s_nop 0
	v_rcp_f32_e32 v62, v62
	v_pk_add_f32 v[64:65], v[64:65], 1.0 op_sel_hi:[1,0]
	v_rcp_f32_e32 v63, v63
	v_rcp_f32_e32 v64, v64
	v_rcp_f32_e32 v65, v65
	v_pk_mul_f32 v[54:55], v[54:55], v[62:63]
	v_pk_mul_f32 v[56:57], v[56:57], v[64:65]
	s_nop 0
	v_pk_mul_f32 v[56:57], v[52:53], v[56:57]
	v_pk_mul_f32 v[52:53], v[50:51], v[54:55]
	v_add_co_u32_e32 v54, vcc, s0, v144
	v_cvt_pk_bf16_f32 v50, v58, v59
	v_cvt_pk_bf16_f32 v51, v60, v61
	v_cvt_pk_bf16_f32 v52, v52, v53
	v_cvt_pk_bf16_f32 v53, v56, v57
	v_addc_co_u32_e32 v55, vcc, 0, v145, vcc
	global_store_dwordx4 v[54:55], v[50:53], off sc1
	s_mov_b32 s0, 0x18c000
	s_nop 0
	v_pk_mul_f32 v[50:51], v[46:47], s[74:75] op_sel_hi:[1,0]
	v_pk_mul_f32 v[52:53], v[48:49], s[74:75] op_sel_hi:[1,0]
	v_exp_f32_e32 v50, v50
	v_exp_f32_e32 v51, v51
	v_exp_f32_e32 v52, v52
	v_exp_f32_e32 v53, v53
	v_pk_add_f32 v[50:51], v[50:51], 1.0 op_sel_hi:[1,0]
	s_nop 0
	v_rcp_f32_e32 v50, v50
	v_pk_add_f32 v[52:53], v[52:53], 1.0 op_sel_hi:[1,0]
	v_rcp_f32_e32 v51, v51
	v_rcp_f32_e32 v52, v52
	v_rcp_f32_e32 v53, v53
	v_pk_mul_f32 v[46:47], v[46:47], v[50:51]
	s_nop 0
	v_pk_mul_f32 v[42:43], v[42:43], v[46:47]
	v_pk_mul_f32 v[48:49], v[48:49], v[52:53]
	v_pk_mul_f32 v[46:47], v[38:39], s[74:75] op_sel_hi:[1,0]
	v_pk_mul_f32 v[44:45], v[44:45], v[48:49]
	v_pk_mul_f32 v[48:49], v[40:41], s[74:75] op_sel_hi:[1,0]
	v_exp_f32_e32 v46, v46
	v_exp_f32_e32 v47, v47
	v_exp_f32_e32 v48, v48
	v_exp_f32_e32 v49, v49
	v_pk_add_f32 v[46:47], v[46:47], 1.0 op_sel_hi:[1,0]
	s_nop 0
	v_rcp_f32_e32 v46, v46
; __device__ __forceinline__ u32x4 pack8(f32x4 v0, f32x4 v1) { u32x4 w; w.x = cvt_pk_bf16(v0[0], v0[1]); w.y = cvt_pk_bf16(v0[2], v0[3]); w.z = cvt_pk_bf16(v1[0], v1[1]); w.w = cvt_pk_bf16(v1[2], v1[3]); return w; }
; #define PG8_BAR __builtin_amdgcn_s_barrier()
;     __device__ __forceinline__ void operator()(const f32x4 (&acc)[2][2][4][2], const Unit& u, int wr, int wc, int fr, int fq) const {
;     ...
;         for (int ai = 0; ai < 2; ++ai)
; #pragma unroll
;             for (int m = 0; m < 4; ++m) {
;                 const f32x4 g0 = acc[ai][0][m][0], g1 = acc[ai][0][m][1];
;                 const f32x4 v0 = g0 * sigmoid4(g0) * acc[ai][1][m][0], v1 = g1 * sigmoid4(g1) * acc[ai][1][m][1];
;                 store16_wt(p0 + (size_t)(ai * HALF + m * 16) * 5632, pack8(v0, v1)); }
; template <class Epi, class Sched, bool ALIGN_EPI = false, bool SP2 = false>
; __device__ __forceinline__ void gemm_phase(PG8_LAS unsigned char* lds, const Gemm g, const Sched& S, const Epi& E) {
;     ...
;         if (!has_next) break;
; #pragma unroll
;         for (int a = 0; a < 2; ++a)
; #pragma unroll
;             for (int b = 0; b < 2; ++b)
; #pragma unroll
;                 for (int m = 0; m < 4; ++m)
; #pragma unroll
;                     for (int n = 0; n < 2; ++n) acc[a][b][m][n] = (f32x4){0.f, 0.f, 0.f, 0.f};
;         cur = nxt; cA = nA; cB = nB; ++ui;
;         if constexpr (ALIGN_EPI) { if (wr == 1) PG8_BAR; }
	v_pk_add_f32 v[48:49], v[48:49], 1.0 op_sel_hi:[1,0]
	v_rcp_f32_e32 v47, v47
	v_rcp_f32_e32 v48, v48
	v_rcp_f32_e32 v49, v49
	v_pk_mul_f32 v[38:39], v[38:39], v[46:47]
	v_pk_mul_f32 v[40:41], v[40:41], v[48:49]
	s_nop 0
	v_pk_mul_f32 v[40:41], v[36:37], v[40:41]
	v_pk_mul_f32 v[36:37], v[34:35], v[38:39]
	v_add_co_u32_e32 v38, vcc, s0, v144
	v_cvt_pk_bf16_f32 v34, v42, v43
	v_cvt_pk_bf16_f32 v35, v44, v45
	v_cvt_pk_bf16_f32 v36, v36, v37
	v_cvt_pk_bf16_f32 v37, v40, v41
	v_addc_co_u32_e32 v39, vcc, 0, v145, vcc
	global_store_dwordx4 v[38:39], v[34:37], off sc1
	s_mov_b32 s0, 0x1b8000
	s_nop 0
	v_pk_mul_f32 v[34:35], v[30:31], s[74:75] op_sel_hi:[1,0]
	v_pk_mul_f32 v[36:37], v[32:33], s[74:75] op_sel_hi:[1,0]
	v_exp_f32_e32 v34, v34
	v_exp_f32_e32 v35, v35
	v_exp_f32_e32 v36, v36
	v_exp_f32_e32 v37, v37
	v_pk_add_f32 v[34:35], v[34:35], 1.0 op_sel_hi:[1,0]
	s_nop 0
	v_rcp_f32_e32 v34, v34
	v_pk_add_f32 v[36:37], v[36:37], 1.0 op_sel_hi:[1,0]
	v_rcp_f32_e32 v35, v35
	v_rcp_f32_e32 v36, v36
	v_rcp_f32_e32 v37, v37
	v_pk_mul_f32 v[30:31], v[30:31], v[34:35]
	s_nop 0
	v_pk_mul_f32 v[26:27], v[26:27], v[30:31]
	v_pk_mul_f32 v[32:33], v[32:33], v[36:37]
	v_pk_mul_f32 v[30:31], v[22:23], s[74:75] op_sel_hi:[1,0]
	v_pk_mul_f32 v[28:29], v[28:29], v[32:33]
	v_pk_mul_f32 v[32:33], v[24:25], s[74:75] op_sel_hi:[1,0]
	v_exp_f32_e32 v30, v30
	v_exp_f32_e32 v31, v31
	v_exp_f32_e32 v32, v32
	v_exp_f32_e32 v33, v33
	v_pk_add_f32 v[30:31], v[30:31], 1.0 op_sel_hi:[1,0]
	s_nop 0
	v_rcp_f32_e32 v30, v30
	v_pk_add_f32 v[32:33], v[32:33], 1.0 op_sel_hi:[1,0]
	v_rcp_f32_e32 v31, v31
	v_rcp_f32_e32 v32, v32
	v_rcp_f32_e32 v33, v33
	v_pk_mul_f32 v[22:23], v[22:23], v[30:31]
	v_pk_mul_f32 v[24:25], v[24:25], v[32:33]
	s_nop 0
	v_pk_mul_f32 v[24:25], v[20:21], v[24:25]
	v_pk_mul_f32 v[20:21], v[18:19], v[22:23]
	v_add_co_u32_e32 v22, vcc, s0, v144
	v_cvt_pk_bf16_f32 v18, v26, v27
	v_cvt_pk_bf16_f32 v19, v28, v29
	v_cvt_pk_bf16_f32 v20, v20, v21
	v_cvt_pk_bf16_f32 v21, v24, v25
	v_addc_co_u32_e32 v23, vcc, 0, v145, vcc
	global_store_dwordx4 v[22:23], v[18:21], off sc1
	s_nop 1
	v_pk_mul_f32 v[18:19], v[14:15], s[74:75] op_sel_hi:[1,0]
	v_pk_mul_f32 v[20:21], v[16:17], s[74:75] op_sel_hi:[1,0]
	v_exp_f32_e32 v18, v18
	v_exp_f32_e32 v19, v19
	v_exp_f32_e32 v20, v20
	v_exp_f32_e32 v21, v21
	v_pk_add_f32 v[18:19], v[18:19], 1.0 op_sel_hi:[1,0]
	s_nop 0
	v_rcp_f32_e32 v18, v18
	v_pk_add_f32 v[20:21], v[20:21], 1.0 op_sel_hi:[1,0]
	v_rcp_f32_e32 v19, v19
	v_rcp_f32_e32 v20, v20
	v_rcp_f32_e32 v21, v21
	v_pk_mul_f32 v[14:15], v[14:15], v[18:19]
	s_nop 0
	v_pk_mul_f32 v[10:11], v[10:11], v[14:15]
	v_pk_mul_f32 v[16:17], v[16:17], v[20:21]
	v_pk_mul_f32 v[14:15], v[6:7], s[74:75] op_sel_hi:[1,0]
	v_pk_mul_f32 v[12:13], v[12:13], v[16:17]
	v_pk_mul_f32 v[16:17], v[8:9], s[74:75] op_sel_hi:[1,0]
	v_exp_f32_e32 v14, v14
	v_exp_f32_e32 v15, v15
	v_exp_f32_e32 v16, v16
	v_exp_f32_e32 v17, v17
	v_pk_add_f32 v[14:15], v[14:15], 1.0 op_sel_hi:[1,0]
	s_nop 0
	v_rcp_f32_e32 v14, v14
	v_pk_add_f32 v[16:17], v[16:17], 1.0 op_sel_hi:[1,0]
	v_rcp_f32_e32 v15, v15
	v_rcp_f32_e32 v16, v16
	v_rcp_f32_e32 v17, v17
	v_pk_mul_f32 v[6:7], v[6:7], v[14:15]
	v_pk_mul_f32 v[8:9], v[8:9], v[16:17]
	s_nop 0
	v_pk_mul_f32 v[8:9], v[4:5], v[8:9]
	v_pk_mul_f32 v[4:5], v[2:3], v[6:7]
	v_add_co_u32_e32 v6, vcc, 0x1e4000, v144
	v_cvt_pk_bf16_f32 v2, v10, v11
	s_nop 0
	v_addc_co_u32_e32 v7, vcc, 0, v145, vcc
	v_cvt_pk_bf16_f32 v3, v12, v13
	v_cvt_pk_bf16_f32 v4, v4, v5
	v_cvt_pk_bf16_f32 v5, v8, v9
	s_andn2_b64 vcc, exec, s[38:39]
	global_store_dwordx4 v[6:7], v[2:5], off sc1
	s_cbranch_vccnz .LBB0_1454
	s_andn2_b64 vcc, exec, s[6:7]
	s_cbranch_vccnz .LBB0_1453
	s_barrier
	s_branch .LBB0_1453

; #define PG8_STAGE(bufoff, gbase, voff) do { _Pragma("unroll") for (int _i = 0; _i < 2; ++_i) \
;         __builtin_amdgcn_global_load_lds((const unsigned*)((const char*)(gbase) + (voff)[_i]), (PG8_LAS unsigned*)(lds + (bufoff) + ldsw + _i * 8192), 16, 0, AUX_A); } while (0)
; #define PG8_STAGEB(bufoff, gbase, voff) do { _Pragma("unroll") for (int _i = 0; _i < 2; ++_i) \
;         __builtin_amdgcn_global_load_lds((const unsigned*)((const char*)(gbase) + (voff)[_i]), (PG8_LAS unsigned*)(lds + (bufoff) + ldsw + _i * 8192), 16, 0, AUX_B); } while (0)
; #define PG8_LDA(dst, b, h) do { _Pragma("unroll") for (int m = 0; m < 4; ++m) _Pragma("unroll") for (int k = 0; k < 2; ++k) dst[m][k] = *(const PG8_LAS bf16x8*)(lds + PG8_SA(b, h) + aoff + m * 2048 + k * 1024); } while (0)
; #define PG8_WAIT_V(n) asm volatile("s_waitcnt vmcnt(" #n ")" ::: "memory")
; #define PG8_WAIT_L(n) asm volatile("s_waitcnt lgkmcnt(" #n ")" ::: "memory")
; #define PG8_BAR __builtin_amdgcn_s_barrier()
; template <class Epi, class Sched, bool ALIGN_EPI = false, bool SP2 = false>
; __device__ __forceinline__ void gemm_phase(PG8_LAS unsigned char* lds, const Gemm g, const Sched& S, const Epi& E) {
;     ...
;         for (int t = 0; t < nt; t += 2) {
;             const bool last = (t == nt - 2);
;             const char* a1 = PG8_KP(cA, t + 1, rot, nt);
;             const char* a2 = last ? nAr : PG8_KP(cA, t + 2, rot, nt); const char* b2 = last ? nBr : PG8_KP(cB, t + 2, rot, nt);
;             const char* a3 = a2 + kstep; const char* b3 = b2 + kstep;
;             if (last && has_next) S.a_ready(nxt);
;             if constexpr (SP2) {
;             PG8_LDB(B0, 0, 0); PG8_LDB(B1, 0, 1); PG8_SCHED; PG8_LDA(At, 0, 0); PG8_STAGE(PG8_SA(1, 1), a1 + hstep, voffA);
;             PG8_WAIT_V(8); PG8_WAIT_L(0); PG8_BAR; PG8_MMA(0, 0, At, B0); PG8_MMA(0, 1, At, B1); PG8_BAR; PG8_SCHED;
;             PG8_LDA(At, 0, 1); PG8_STAGEB(PG8_SB(0, 0), b2, voffB); PG8_STAGEB(PG8_SB(0, 1), b2 + hstep, voffB); PG8_STAGE(PG8_SA(0, 0), a2, voffA);
;             PG8_WAIT_V(8); PG8_WAIT_L(0); PG8_BAR; PG8_MMA(1, 0, At, B0); PG8_MMA(1, 1, At, B1); PG8_BAR; PG8_SCHED;
;             PG8_LDB(B0, 1, 0); PG8_LDB(B1, 1, 1); PG8_SCHED; PG8_LDA(At, 1, 0); PG8_STAGE(PG8_SA(0, 1), a2 + hstep, voffA);
;             PG8_WAIT_V(8); PG8_WAIT_L(0); PG8_BAR; PG8_MMA(0, 0, At, B0); PG8_MMA(0, 1, At, B1); PG8_BAR; PG8_SCHED;
.Lpk_1654:
	s_or_b32 s0, s15, 1
	s_cmp_ge_i32 s0, s82
	s_cselect_b32 s2, s82, 0
	s_add_i32 s15, s15, 2
	s_cmp_ge_i32 s15, s82
	s_cselect_b32 s0, s82, 0
	s_sub_i32 s0, s83, s0
	s_ashr_i32 s1, s0, 31
	s_lshl_b64 s[0:1], s[0:1], 7
	s_add_u32 s29, s38, s0
	s_addc_u32 s42, s39, s1
	s_add_u32 s0, s34, s0
	s_addc_u32 s1, s35, s1
	s_cmp_eq_u32 s82, s83
	s_cselect_b32 s45, s41, s42
	s_cselect_b32 s44, s40, s29
	s_cselect_b32 s43, s19, s1
	s_cselect_b32 s42, s18, s0
	s_add_i32 s29, 0, 0x10000
	s_add_i32 s46, 0, 0x14000
	v_add_u32_e32 v148, s29, v99
	v_add_u32_e32 v168, s46, v99
	ds_read_b128 v[136:139], v148
	ds_read_b128 v[140:143], v148 offset:1024
	ds_read_b128 v[144:147], v148 offset:2048
	ds_read_b128 v[148:151], v148 offset:3072
	ds_read_b128 v[152:155], v168
	ds_read_b128 v[180:183], v168 offset:1024
	ds_read_b128 v[184:187], v168 offset:2048
	ds_read_b128 v[190:193], v168 offset:3072
	v_mad_i64_i32 v[168:169], s[0:1], s2, v220, v[134:135]
	s_add_i32 m0, s50, 0xc000
	ds_read_b128 v[194:197], v189
	ds_read_b128 v[198:201], v189 offset:1024
	ds_read_b128 v[222:225], v189 offset:2048
	ds_read_b128 v[226:229], v189 offset:3072
	ds_read_b128 v[230:233], v189 offset:4096
	ds_read_b128 v[234:237], v189 offset:5120
	ds_read_b128 v[238:241], v189 offset:6144
	ds_read_b128 v[242:245], v189 offset:7168
	global_load_lds_dwordx4 v[168:169], off
	v_mad_i64_i32 v[168:169], s[0:1], s2, v220, v[132:133]
	s_add_i32 m0, s50, 0xe000
	s_nop 0
	global_load_lds_dwordx4 v[168:169], off
	s_waitcnt vmcnt(8)
	s_waitcnt lgkmcnt(0)
	s_setprio 1
	s_barrier
	v_mfma_f32_16x16x32_bf16 v[128:131], v[136:139], v[194:197], 0
	v_mfma_f32_16x16x32_bf16 v[128:131], v[140:143], v[198:201], v[128:131]
	v_mfma_f32_16x16x32_bf16 v[124:127], v[144:147], v[194:197], 0
	v_mfma_f32_16x16x32_bf16 v[124:127], v[148:151], v[198:201], v[124:127]
	v_mfma_f32_16x16x32_bf16 v[120:123], v[136:139], v[222:225], 0
	v_mfma_f32_16x16x32_bf16 v[120:123], v[140:143], v[226:229], v[120:123]
	v_mfma_f32_16x16x32_bf16 v[112:115], v[144:147], v[222:225], 0
	v_mfma_f32_16x16x32_bf16 v[112:115], v[148:151], v[226:229], v[112:115]
	v_mfma_f32_16x16x32_bf16 v[104:107], v[136:139], v[230:233], 0
	v_mfma_f32_16x16x32_bf16 v[104:107], v[140:143], v[234:237], v[104:107]
	v_mfma_f32_16x16x32_bf16 v[94:97], v[144:147], v[230:233], 0
	v_mfma_f32_16x16x32_bf16 v[94:97], v[148:151], v[234:237], v[94:97]
	v_mfma_f32_16x16x32_bf16 v[86:89], v[136:139], v[238:241], 0
	v_mfma_f32_16x16x32_bf16 v[86:89], v[140:143], v[242:245], v[86:89]
	v_mfma_f32_16x16x32_bf16 v[78:81], v[144:147], v[238:241], 0
	v_mfma_f32_16x16x32_bf16 v[78:81], v[148:151], v[242:245], v[78:81]
	s_setprio 0
	s_setprio 1
	v_mfma_f32_16x16x32_bf16 v[116:119], v[152:155], v[194:197], 0
	v_mfma_f32_16x16x32_bf16 v[116:119], v[180:183], v[198:201], v[116:119]
	v_mfma_f32_16x16x32_bf16 v[108:111], v[184:187], v[194:197], 0
	v_mfma_f32_16x16x32_bf16 v[108:111], v[190:193], v[198:201], v[108:111]
	v_mfma_f32_16x16x32_bf16 v[100:103], v[152:155], v[222:225], 0
	v_mfma_f32_16x16x32_bf16 v[100:103], v[180:183], v[226:229], v[100:103]
	v_mfma_f32_16x16x32_bf16 v[90:93], v[184:187], v[222:225], 0
	v_mfma_f32_16x16x32_bf16 v[90:93], v[190:193], v[226:229], v[90:93]
	v_mfma_f32_16x16x32_bf16 v[82:85], v[152:155], v[230:233], 0
	v_mfma_f32_16x16x32_bf16 v[82:85], v[180:183], v[234:237], v[82:85]
	v_mfma_f32_16x16x32_bf16 v[74:77], v[184:187], v[230:233], 0
	v_mfma_f32_16x16x32_bf16 v[74:77], v[190:193], v[234:237], v[74:77]
	v_mfma_f32_16x16x32_bf16 v[70:73], v[152:155], v[238:241], 0
	v_mfma_f32_16x16x32_bf16 v[70:73], v[180:183], v[242:245], v[70:73]
	s_setprio 2
	s_barrier
	v_mfma_f32_16x16x32_bf16 v[66:69], v[184:187], v[238:241], 0
	v_mfma_f32_16x16x32_bf16 v[66:69], v[190:193], v[242:245], v[66:69]
	s_setprio 0
	s_add_i32 s0, s29, s49
	v_lshl_add_u64 v[168:169], s[42:43], 0, v[160:161]
	s_mov_b32 m0, s0
	ds_read_b128 v[194:197], v189 offset:16384
	ds_read_b128 v[198:201], v189 offset:17408
	ds_read_b128 v[222:225], v189 offset:18432
	ds_read_b128 v[226:229], v189 offset:19456
	ds_read_b128 v[230:233], v189 offset:20480
	ds_read_b128 v[234:237], v189 offset:21504
	ds_read_b128 v[238:241], v189 offset:22528
	ds_read_b128 v[242:245], v189 offset:23552
	global_load_lds_dwordx4 v[168:169], off
	s_add_i32 m0, s0, 0x2000
	s_add_u32 s0, s42, 0x160000
	v_lshl_add_u64 v[172:173], s[42:43], 0, v[156:157]
	s_addc_u32 s1, s43, 0
	s_add_i32 s2, s46, s49
	global_load_lds_dwordx4 v[172:173], off
	v_lshl_add_u64 v[202:203], s[0:1], 0, v[160:161]
	s_mov_b32 m0, s2
	v_lshl_add_u64 v[212:213], s[44:45], 0, v[158:159]
	global_load_lds_dwordx4 v[202:203], off
	v_lshl_add_u64 v[202:203], s[0:1], 0, v[156:157]
	s_add_i32 m0, s2, 0x2000
	s_nop 0
	global_load_lds_dwordx4 v[202:203], off
	v_lshl_add_u64 v[202:203], s[44:45], 0, v[162:163]
	s_mov_b32 m0, s50
	s_nop 0
	global_load_lds_dwordx4 v[202:203], off
	s_mov_b32 m0, s51
	s_nop 0
	global_load_lds_dwordx4 v[212:213], off
	s_waitcnt vmcnt(8)
	s_waitcnt lgkmcnt(0)
	s_setprio 1
	s_barrier
; #define PG8_STAGE(bufoff, gbase, voff) do { _Pragma("unroll") for (int _i = 0; _i < 2; ++_i) \
;         __builtin_amdgcn_global_load_lds((const unsigned*)((const char*)(gbase) + (voff)[_i]), (PG8_LAS unsigned*)(lds + (bufoff) + ldsw + _i * 8192), 16, 0, AUX_A); } while (0)
; #define PG8_LDA(dst, b, h) do { _Pragma("unroll") for (int m = 0; m < 4; ++m) _Pragma("unroll") for (int k = 0; k < 2; ++k) dst[m][k] = *(const PG8_LAS bf16x8*)(lds + PG8_SA(b, h) + aoff + m * 2048 + k * 1024); } while (0)
; #define PG8_LDB(dst, b, h) do { _Pragma("unroll") for (int n = 0; n < 2; ++n) _Pragma("unroll") for (int k = 0; k < 2; ++k) dst[n][k] = *(const PG8_LAS bf16x8*)(lds + PG8_SB(b, h) + boff + n * 2048 + k * 1024); } while (0)
; #define PG8_MMA(ai, bj, At, Bt) do { __builtin_amdgcn_s_setprio(1); _Pragma("unroll") for (int m = 0; m < 4; ++m) _Pragma("unroll") for (int n = 0; n < 2; ++n) _Pragma("unroll") for (int k = 0; k < 2; ++k) \
;         acc[ai][bj][m][n] = __builtin_amdgcn_mfma_f32_16x16x32_bf16(Bt[n][k], At[m][k], acc[ai][bj][m][n], 0, 0, 0); __builtin_amdgcn_s_setprio(0); } while (0)
; #define PG8_WAIT_V(n) asm volatile("s_waitcnt vmcnt(" #n ")" ::: "memory")
; #define PG8_WAIT_L(n) asm volatile("s_waitcnt lgkmcnt(" #n ")" ::: "memory")
; #define PG8_BAR __builtin_amdgcn_s_barrier()
; #define PG8_SCHED __builtin_amdgcn_sched_barrier(0)
; template <class Epi, class Sched, bool ALIGN_EPI = false, bool SP2 = false>
; __device__ __forceinline__ void gemm_phase(PG8_LAS unsigned char* lds, const Gemm g, const Sched& S, const Epi& E) {
;     ...
;             PG8_WAIT_V(8); PG8_WAIT_L(0); PG8_BAR; PG8_MMA(1, 0, At, B0); PG8_MMA(1, 1, At, B1); PG8_BAR; PG8_SCHED;
;             PG8_LDB(B0, 1, 0); PG8_LDB(B1, 1, 1); PG8_SCHED; PG8_LDA(At, 1, 0); PG8_STAGE(PG8_SA(0, 1), a2 + hstep, voffA);
;             PG8_WAIT_V(8); PG8_WAIT_L(0); PG8_BAR; PG8_MMA(0, 0, At, B0); PG8_MMA(0, 1, At, B1); PG8_BAR; PG8_SCHED;
	v_mfma_f32_16x16x32_bf16 v[62:65], v[136:139], v[194:197], 0
	v_mfma_f32_16x16x32_bf16 v[62:65], v[140:143], v[198:201], v[62:65]
	v_mfma_f32_16x16x32_bf16 v[58:61], v[144:147], v[194:197], 0
	v_mfma_f32_16x16x32_bf16 v[58:61], v[148:151], v[198:201], v[58:61]
	v_mfma_f32_16x16x32_bf16 v[54:57], v[136:139], v[222:225], 0
	v_mfma_f32_16x16x32_bf16 v[54:57], v[140:143], v[226:229], v[54:57]
	v_mfma_f32_16x16x32_bf16 v[46:49], v[144:147], v[222:225], 0
	v_mfma_f32_16x16x32_bf16 v[46:49], v[148:151], v[226:229], v[46:49]
	v_mfma_f32_16x16x32_bf16 v[38:41], v[136:139], v[230:233], 0
	v_mfma_f32_16x16x32_bf16 v[38:41], v[140:143], v[234:237], v[38:41]
	v_mfma_f32_16x16x32_bf16 v[30:33], v[144:147], v[230:233], 0
	v_mfma_f32_16x16x32_bf16 v[30:33], v[148:151], v[234:237], v[30:33]
	v_mfma_f32_16x16x32_bf16 v[22:25], v[136:139], v[238:241], 0
	v_mfma_f32_16x16x32_bf16 v[22:25], v[140:143], v[242:245], v[22:25]
	v_mfma_f32_16x16x32_bf16 v[14:17], v[144:147], v[238:241], 0
	v_mfma_f32_16x16x32_bf16 v[14:17], v[148:151], v[242:245], v[14:17]
	s_setprio 0
	s_setprio 1
	v_mfma_f32_16x16x32_bf16 v[50:53], v[152:155], v[194:197], 0
	v_mfma_f32_16x16x32_bf16 v[50:53], v[180:183], v[198:201], v[50:53]
	v_mfma_f32_16x16x32_bf16 v[42:45], v[184:187], v[194:197], 0
	v_mfma_f32_16x16x32_bf16 v[42:45], v[190:193], v[198:201], v[42:45]
	v_mfma_f32_16x16x32_bf16 v[34:37], v[152:155], v[222:225], 0
	v_mfma_f32_16x16x32_bf16 v[34:37], v[180:183], v[226:229], v[34:37]
	v_mfma_f32_16x16x32_bf16 v[26:29], v[184:187], v[222:225], 0
	v_mfma_f32_16x16x32_bf16 v[26:29], v[190:193], v[226:229], v[26:29]
	v_mfma_f32_16x16x32_bf16 v[18:21], v[152:155], v[230:233], 0
	v_mfma_f32_16x16x32_bf16 v[18:21], v[180:183], v[234:237], v[18:21]
	v_mfma_f32_16x16x32_bf16 v[10:13], v[184:187], v[230:233], 0
	v_mfma_f32_16x16x32_bf16 v[10:13], v[190:193], v[234:237], v[10:13]
	v_mfma_f32_16x16x32_bf16 v[6:9], v[152:155], v[238:241], 0
	v_mfma_f32_16x16x32_bf16 v[6:9], v[180:183], v[242:245], v[6:9]
	s_setprio 2
	s_barrier
	v_mfma_f32_16x16x32_bf16 v[2:5], v[184:187], v[238:241], 0
	v_mfma_f32_16x16x32_bf16 v[2:5], v[190:193], v[242:245], v[2:5]
	s_setprio 0
	s_add_i32 s2, 0, 0x18000
	s_add_i32 s29, 0, 0x1c000
	v_add_u32_e32 v148, s2, v99
	v_add_u32_e32 v190, s29, v99
	ds_read_b128 v[136:139], v148
	ds_read_b128 v[140:143], v148 offset:1024
	ds_read_b128 v[144:147], v148 offset:2048
	ds_read_b128 v[148:151], v148 offset:3072
	ds_read_b128 v[152:155], v190
	ds_read_b128 v[180:183], v190 offset:1024
	ds_read_b128 v[184:187], v190 offset:2048
	ds_read_b128 v[190:193], v190 offset:3072
	s_add_u32 s0, s44, 0x160000
	s_addc_u32 s1, s45, 0
	s_mov_b32 m0, s52
	v_lshl_add_u64 v[246:247], s[0:1], 0, v[162:163]
	ds_read_b128 v[194:197], v189 offset:32768
	ds_read_b128 v[198:201], v189 offset:33792
	ds_read_b128 v[222:225], v189 offset:34816
	ds_read_b128 v[226:229], v189 offset:35840
	ds_read_b128 v[230:233], v189 offset:36864
	ds_read_b128 v[234:237], v189 offset:37888
	ds_read_b128 v[238:241], v189 offset:38912
	ds_read_b128 v[242:245], v189 offset:39936
	global_load_lds_dwordx4 v[246:247], off
	v_lshl_add_u64 v[246:247], s[0:1], 0, v[158:159]
	s_mov_b32 m0, s53
	s_nop 0
	global_load_lds_dwordx4 v[246:247], off
	s_waitcnt vmcnt(8)
	s_waitcnt lgkmcnt(0)
	s_setprio 1
	s_barrier
	v_mfma_f32_16x16x32_bf16 v[128:131], v[136:139], v[194:197], v[128:131]
	v_mfma_f32_16x16x32_bf16 v[128:131], v[140:143], v[198:201], v[128:131]
	v_mfma_f32_16x16x32_bf16 v[124:127], v[144:147], v[194:197], v[124:127]
	v_mfma_f32_16x16x32_bf16 v[124:127], v[148:151], v[198:201], v[124:127]
	v_mfma_f32_16x16x32_bf16 v[120:123], v[136:139], v[222:225], v[120:123]
	v_mfma_f32_16x16x32_bf16 v[120:123], v[140:143], v[226:229], v[120:123]
	v_mfma_f32_16x16x32_bf16 v[112:115], v[144:147], v[222:225], v[112:115]
	v_mfma_f32_16x16x32_bf16 v[112:115], v[148:151], v[226:229], v[112:115]
	v_mfma_f32_16x16x32_bf16 v[104:107], v[136:139], v[230:233], v[104:107]
	v_mfma_f32_16x16x32_bf16 v[104:107], v[140:143], v[234:237], v[104:107]
	v_mfma_f32_16x16x32_bf16 v[94:97], v[144:147], v[230:233], v[94:97]
	v_mfma_f32_16x16x32_bf16 v[94:97], v[148:151], v[234:237], v[94:97]
	v_mfma_f32_16x16x32_bf16 v[86:89], v[136:139], v[238:241], v[86:89]
	v_mfma_f32_16x16x32_bf16 v[86:89], v[140:143], v[242:245], v[86:89]
	v_mfma_f32_16x16x32_bf16 v[78:81], v[144:147], v[238:241], v[78:81]
	v_mfma_f32_16x16x32_bf16 v[78:81], v[148:151], v[242:245], v[78:81]
	s_setprio 0
	s_setprio 1
	v_mfma_f32_16x16x32_bf16 v[116:119], v[152:155], v[194:197], v[116:119]
	v_mfma_f32_16x16x32_bf16 v[116:119], v[180:183], v[198:201], v[116:119]
	v_mfma_f32_16x16x32_bf16 v[108:111], v[184:187], v[194:197], v[108:111]
	v_mfma_f32_16x16x32_bf16 v[108:111], v[190:193], v[198:201], v[108:111]
	v_mfma_f32_16x16x32_bf16 v[100:103], v[152:155], v[222:225], v[100:103]
	v_mfma_f32_16x16x32_bf16 v[100:103], v[180:183], v[226:229], v[100:103]
	v_mfma_f32_16x16x32_bf16 v[90:93], v[184:187], v[222:225], v[90:93]
	v_mfma_f32_16x16x32_bf16 v[90:93], v[190:193], v[226:229], v[90:93]
	v_mfma_f32_16x16x32_bf16 v[82:85], v[152:155], v[230:233], v[82:85]
	v_mfma_f32_16x16x32_bf16 v[82:85], v[180:183], v[234:237], v[82:85]
	v_mfma_f32_16x16x32_bf16 v[74:77], v[184:187], v[230:233], v[74:77]
	v_mfma_f32_16x16x32_bf16 v[74:77], v[190:193], v[234:237], v[74:77]
	v_mfma_f32_16x16x32_bf16 v[70:73], v[152:155], v[238:241], v[70:73]
	v_mfma_f32_16x16x32_bf16 v[70:73], v[180:183], v[242:245], v[70:73]
	s_setprio 2
	s_barrier
; #define PG8_STAGE(bufoff, gbase, voff) do { _Pragma("unroll") for (int _i = 0; _i < 2; ++_i) \
;         __builtin_amdgcn_global_load_lds((const unsigned*)((const char*)(gbase) + (voff)[_i]), (PG8_LAS unsigned*)(lds + (bufoff) + ldsw + _i * 8192), 16, 0, AUX_A); } while (0)
; #define PG8_STAGEB(bufoff, gbase, voff) do { _Pragma("unroll") for (int _i = 0; _i < 2; ++_i) \
;         __builtin_amdgcn_global_load_lds((const unsigned*)((const char*)(gbase) + (voff)[_i]), (PG8_LAS unsigned*)(lds + (bufoff) + ldsw + _i * 8192), 16, 0, AUX_B); } while (0)
; #define PG8_LDA(dst, b, h) do { _Pragma("unroll") for (int m = 0; m < 4; ++m) _Pragma("unroll") for (int k = 0; k < 2; ++k) dst[m][k] = *(const PG8_LAS bf16x8*)(lds + PG8_SA(b, h) + aoff + m * 2048 + k * 1024); } while (0)
; #define PG8_MMA(ai, bj, At, Bt) do { __builtin_amdgcn_s_setprio(1); _Pragma("unroll") for (int m = 0; m < 4; ++m) _Pragma("unroll") for (int n = 0; n < 2; ++n) _Pragma("unroll") for (int k = 0; k < 2; ++k) \
;         acc[ai][bj][m][n] = __builtin_amdgcn_mfma_f32_16x16x32_bf16(Bt[n][k], At[m][k], acc[ai][bj][m][n], 0, 0, 0); __builtin_amdgcn_s_setprio(0); } while (0)
; #define PG8_WAIT_V(n) asm volatile("s_waitcnt vmcnt(" #n ")" ::: "memory")
; #define PG8_WAIT_L(n) asm volatile("s_waitcnt lgkmcnt(" #n ")" ::: "memory")
; #define PG8_BAR __builtin_amdgcn_s_barrier()
; #define PG8_SCHED __builtin_amdgcn_sched_barrier(0)
; template <class Epi, class Sched, bool ALIGN_EPI = false, bool SP2 = false>
; __device__ __forceinline__ void gemm_phase(PG8_LAS unsigned char* lds, const Gemm g, const Sched& S, const Epi& E) {
;     ...
;             PG8_WAIT_V(8); PG8_WAIT_L(0); PG8_BAR; PG8_MMA(0, 0, At, B0); PG8_MMA(0, 1, At, B1); PG8_BAR; PG8_SCHED;
;             PG8_LDA(At, 1, 1); PG8_STAGEB(PG8_SB(1, 0), b3, voffB); PG8_STAGEB(PG8_SB(1, 1), b3 + hstep, voffB); PG8_STAGE(PG8_SA(1, 0), a3, voffA);
;             PG8_WAIT_V(8); PG8_WAIT_L(0); PG8_BAR; PG8_MMA(1, 0, At, B0); PG8_MMA(1, 1, At, B1); PG8_BAR; PG8_SCHED;
	v_mfma_f32_16x16x32_bf16 v[66:69], v[184:187], v[238:241], v[66:69]
	v_mfma_f32_16x16x32_bf16 v[66:69], v[190:193], v[242:245], v[66:69]
	s_setprio 0
	s_add_i32 s0, s2, s49
	v_lshl_add_u64 v[168:169], v[168:169], 0, s[76:77]
	s_mov_b32 m0, s0
	ds_read_b128 v[194:197], v189 offset:49152
	ds_read_b128 v[198:201], v189 offset:50176
	ds_read_b128 v[222:225], v189 offset:51200
	ds_read_b128 v[226:229], v189 offset:52224
	ds_read_b128 v[230:233], v189 offset:53248
	ds_read_b128 v[234:237], v189 offset:54272
	ds_read_b128 v[238:241], v189 offset:55296
	ds_read_b128 v[242:245], v189 offset:56320
	global_load_lds_dwordx4 v[168:169], off
	s_add_i32 m0, s0, 0x2000
	s_add_u32 s0, s42, 0x160080
	v_lshl_add_u64 v[168:169], v[172:173], 0, s[76:77]
	s_addc_u32 s1, s43, 0
	s_add_i32 s2, s29, s49
	global_load_lds_dwordx4 v[168:169], off
	v_lshl_add_u64 v[168:169], s[0:1], 0, v[160:161]
	s_mov_b32 m0, s2
	s_nop 0
	global_load_lds_dwordx4 v[168:169], off
	v_lshl_add_u64 v[168:169], s[0:1], 0, v[156:157]
	s_add_i32 m0, s2, 0x2000
	s_nop 0
	global_load_lds_dwordx4 v[168:169], off
	v_lshl_add_u64 v[168:169], v[202:203], 0, s[76:77]
	s_mov_b32 m0, s60
	s_nop 0
	global_load_lds_dwordx4 v[168:169], off
	v_lshl_add_u64 v[168:169], v[212:213], 0, s[76:77]
	s_mov_b32 m0, s61
	s_nop 0
	global_load_lds_dwordx4 v[168:169], off
	s_waitcnt vmcnt(8)
	s_waitcnt lgkmcnt(0)
	s_setprio 1
	s_barrier
	v_mfma_f32_16x16x32_bf16 v[62:65], v[136:139], v[194:197], v[62:65]
	v_mfma_f32_16x16x32_bf16 v[62:65], v[140:143], v[198:201], v[62:65]
	v_mfma_f32_16x16x32_bf16 v[58:61], v[144:147], v[194:197], v[58:61]
	v_mfma_f32_16x16x32_bf16 v[58:61], v[148:151], v[198:201], v[58:61]
	v_mfma_f32_16x16x32_bf16 v[54:57], v[136:139], v[222:225], v[54:57]
	v_mfma_f32_16x16x32_bf16 v[54:57], v[140:143], v[226:229], v[54:57]
	v_mfma_f32_16x16x32_bf16 v[46:49], v[144:147], v[222:225], v[46:49]
	v_mfma_f32_16x16x32_bf16 v[46:49], v[148:151], v[226:229], v[46:49]
	v_mfma_f32_16x16x32_bf16 v[38:41], v[136:139], v[230:233], v[38:41]
	v_mfma_f32_16x16x32_bf16 v[38:41], v[140:143], v[234:237], v[38:41]
	v_mfma_f32_16x16x32_bf16 v[30:33], v[144:147], v[230:233], v[30:33]
	v_mfma_f32_16x16x32_bf16 v[30:33], v[148:151], v[234:237], v[30:33]
	v_mfma_f32_16x16x32_bf16 v[22:25], v[136:139], v[238:241], v[22:25]
	v_mfma_f32_16x16x32_bf16 v[22:25], v[140:143], v[242:245], v[22:25]
	v_mfma_f32_16x16x32_bf16 v[14:17], v[144:147], v[238:241], v[14:17]
	v_mfma_f32_16x16x32_bf16 v[14:17], v[148:151], v[242:245], v[14:17]
	s_setprio 0
	s_setprio 1
	v_mfma_f32_16x16x32_bf16 v[50:53], v[152:155], v[194:197], v[50:53]
	v_mfma_f32_16x16x32_bf16 v[50:53], v[180:183], v[198:201], v[50:53]
	v_mfma_f32_16x16x32_bf16 v[42:45], v[184:187], v[194:197], v[42:45]
	v_mfma_f32_16x16x32_bf16 v[42:45], v[190:193], v[198:201], v[42:45]
	v_mfma_f32_16x16x32_bf16 v[34:37], v[152:155], v[222:225], v[34:37]
	v_mfma_f32_16x16x32_bf16 v[34:37], v[180:183], v[226:229], v[34:37]
	v_mfma_f32_16x16x32_bf16 v[26:29], v[184:187], v[222:225], v[26:29]
	v_mfma_f32_16x16x32_bf16 v[26:29], v[190:193], v[226:229], v[26:29]
	v_mfma_f32_16x16x32_bf16 v[18:21], v[152:155], v[230:233], v[18:21]
	v_mfma_f32_16x16x32_bf16 v[18:21], v[180:183], v[234:237], v[18:21]
	v_mfma_f32_16x16x32_bf16 v[10:13], v[184:187], v[230:233], v[10:13]
	v_mfma_f32_16x16x32_bf16 v[10:13], v[190:193], v[234:237], v[10:13]
	v_mfma_f32_16x16x32_bf16 v[6:9], v[152:155], v[238:241], v[6:9]
	v_mfma_f32_16x16x32_bf16 v[6:9], v[180:183], v[242:245], v[6:9]
	s_setprio 2
	s_cmp_ge_i32 s83, s82
	s_cbranch_scc0 .Lq4b_1654p
	v_cmp_ne_u32_e64 vcc, s12, 0
	s_cbranch_vccz .Lq4s_1654p

; #define PG8_STAGE(bufoff, gbase, voff) do { _Pragma("unroll") for (int _i = 0; _i < 2; ++_i) \
;         __builtin_amdgcn_global_load_lds((const unsigned*)((const char*)(gbase) + (voff)[_i]), (PG8_LAS unsigned*)(lds + (bufoff) + ldsw + _i * 8192), 16, 0, AUX_A); } while (0)
; #define PG8_STAGEB(bufoff, gbase, voff) do { _Pragma("unroll") for (int _i = 0; _i < 2; ++_i) \
;         __builtin_amdgcn_global_load_lds((const unsigned*)((const char*)(gbase) + (voff)[_i]), (PG8_LAS unsigned*)(lds + (bufoff) + ldsw + _i * 8192), 16, 0, AUX_B); } while (0)
; #define PG8_LDA(dst, b, h) do { _Pragma("unroll") for (int m = 0; m < 4; ++m) _Pragma("unroll") for (int k = 0; k < 2; ++k) dst[m][k] = *(const PG8_LAS bf16x8*)(lds + PG8_SA(b, h) + aoff + m * 2048 + k * 1024); } while (0)
; #define PG8_WAIT_V(n) asm volatile("s_waitcnt vmcnt(" #n ")" ::: "memory")
; #define PG8_WAIT_L(n) asm volatile("s_waitcnt lgkmcnt(" #n ")" ::: "memory")
; #define PG8_BAR __builtin_amdgcn_s_barrier()
; template <class Epi, class Sched, bool ALIGN_EPI = false, bool SP2 = false>
; __device__ __forceinline__ void gemm_phase(PG8_LAS unsigned char* lds, const Gemm g, const Sched& S, const Epi& E) {
;     ...
;         for (int t = 0; t < nt; t += 2) {
;             const bool last = (t == nt - 2);
;             const char* a1 = PG8_KP(cA, t + 1, rot, nt);
;             const char* a2 = last ? nAr : PG8_KP(cA, t + 2, rot, nt); const char* b2 = last ? nBr : PG8_KP(cB, t + 2, rot, nt);
;             const char* a3 = a2 + kstep; const char* b3 = b2 + kstep;
;             if (last && has_next) S.a_ready(nxt);
;             if constexpr (SP2) {
;             PG8_LDB(B0, 0, 0); PG8_LDB(B1, 0, 1); PG8_SCHED; PG8_LDA(At, 0, 0); PG8_STAGE(PG8_SA(1, 1), a1 + hstep, voffA);
;             PG8_WAIT_V(8); PG8_WAIT_L(0); PG8_BAR; PG8_MMA(0, 0, At, B0); PG8_MMA(0, 1, At, B1); PG8_BAR; PG8_SCHED;
;             PG8_LDA(At, 0, 1); PG8_STAGEB(PG8_SB(0, 0), b2, voffB); PG8_STAGEB(PG8_SB(0, 1), b2 + hstep, voffB); PG8_STAGE(PG8_SA(0, 0), a2, voffA);
;             PG8_WAIT_V(8); PG8_WAIT_L(0); PG8_BAR; PG8_MMA(1, 0, At, B0); PG8_MMA(1, 1, At, B1); PG8_BAR; PG8_SCHED;
;             PG8_LDB(B0, 1, 0); PG8_LDB(B1, 1, 1); PG8_SCHED; PG8_LDA(At, 1, 0); PG8_STAGE(PG8_SA(0, 1), a2 + hstep, voffA);
;             PG8_WAIT_V(8); PG8_WAIT_L(0); PG8_BAR; PG8_MMA(0, 0, At, B0); PG8_MMA(0, 1, At, B1); PG8_BAR; PG8_SCHED;
.Lq4s_1654p:
	v_mfma_f32_16x16x32_bf16 v[2:5], v[184:187], v[238:241], v[2:5]
	v_mfma_f32_16x16x32_bf16 v[2:5], v[190:193], v[242:245], v[2:5]
	s_setprio 0
	s_add_i32 s0, s83, 2
	v_lshl_add_u64 v[132:133], v[132:133], 0, s[86:87]
	v_lshl_add_u64 v[134:135], v[134:135], 0, s[86:87]
	s_cmp_ge_i32 s83, s82
	s_mov_b32 s83, s0
	s_cbranch_scc1 .Lpx_1654
.LBB0_1654:
	s_or_b32 s0, s15, 1
	s_cmp_ge_i32 s0, s82
	s_cselect_b32 s2, s82, 0
	s_add_i32 s15, s15, 2
	s_cmp_ge_i32 s15, s82
	s_cselect_b32 s0, s82, 0
	s_sub_i32 s0, s83, s0
	s_ashr_i32 s1, s0, 31
	s_lshl_b64 s[0:1], s[0:1], 7
	s_add_u32 s29, s38, s0
	s_addc_u32 s42, s39, s1
	s_add_u32 s0, s34, s0
	s_addc_u32 s1, s35, s1
	s_cmp_eq_u32 s82, s83
	s_cselect_b32 s45, s41, s42
	s_cselect_b32 s44, s40, s29
	s_cselect_b32 s43, s19, s1
	s_cselect_b32 s42, s18, s0
	s_add_i32 s29, 0, 0x10000
	s_add_i32 s46, 0, 0x14000
	v_add_u32_e32 v148, s29, v99
	v_add_u32_e32 v168, s46, v99
	ds_read_b128 v[136:139], v148
	ds_read_b128 v[140:143], v148 offset:1024
	ds_read_b128 v[144:147], v148 offset:2048
	ds_read_b128 v[148:151], v148 offset:3072
	ds_read_b128 v[152:155], v168
	ds_read_b128 v[180:183], v168 offset:1024
	ds_read_b128 v[184:187], v168 offset:2048
	ds_read_b128 v[190:193], v168 offset:3072
	v_mad_i64_i32 v[168:169], s[0:1], s2, v220, v[134:135]
	s_add_i32 m0, s50, 0xc000
	ds_read_b128 v[194:197], v189
	ds_read_b128 v[198:201], v189 offset:1024
	ds_read_b128 v[222:225], v189 offset:2048
	ds_read_b128 v[226:229], v189 offset:3072
	ds_read_b128 v[230:233], v189 offset:4096
	ds_read_b128 v[234:237], v189 offset:5120
	ds_read_b128 v[238:241], v189 offset:6144
	ds_read_b128 v[242:245], v189 offset:7168
	global_load_lds_dwordx4 v[168:169], off
	v_mad_i64_i32 v[168:169], s[0:1], s2, v220, v[132:133]
	s_add_i32 m0, s50, 0xe000
	s_nop 0
	global_load_lds_dwordx4 v[168:169], off
	s_waitcnt vmcnt(8)
	s_waitcnt lgkmcnt(0)
	s_setprio 1
	s_barrier
	v_mfma_f32_16x16x32_bf16 v[128:131], v[136:139], v[194:197], v[128:131]
	v_mfma_f32_16x16x32_bf16 v[128:131], v[140:143], v[198:201], v[128:131]
	v_mfma_f32_16x16x32_bf16 v[124:127], v[144:147], v[194:197], v[124:127]
	v_mfma_f32_16x16x32_bf16 v[124:127], v[148:151], v[198:201], v[124:127]
	v_mfma_f32_16x16x32_bf16 v[120:123], v[136:139], v[222:225], v[120:123]
	v_mfma_f32_16x16x32_bf16 v[120:123], v[140:143], v[226:229], v[120:123]
	v_mfma_f32_16x16x32_bf16 v[112:115], v[144:147], v[222:225], v[112:115]
	v_mfma_f32_16x16x32_bf16 v[112:115], v[148:151], v[226:229], v[112:115]
	v_mfma_f32_16x16x32_bf16 v[104:107], v[136:139], v[230:233], v[104:107]
	v_mfma_f32_16x16x32_bf16 v[104:107], v[140:143], v[234:237], v[104:107]
	v_mfma_f32_16x16x32_bf16 v[94:97], v[144:147], v[230:233], v[94:97]
	v_mfma_f32_16x16x32_bf16 v[94:97], v[148:151], v[234:237], v[94:97]
	v_mfma_f32_16x16x32_bf16 v[86:89], v[136:139], v[238:241], v[86:89]
	v_mfma_f32_16x16x32_bf16 v[86:89], v[140:143], v[242:245], v[86:89]
	v_mfma_f32_16x16x32_bf16 v[78:81], v[144:147], v[238:241], v[78:81]
	v_mfma_f32_16x16x32_bf16 v[78:81], v[148:151], v[242:245], v[78:81]
	s_setprio 0
	s_setprio 1
	v_mfma_f32_16x16x32_bf16 v[116:119], v[152:155], v[194:197], v[116:119]
	v_mfma_f32_16x16x32_bf16 v[116:119], v[180:183], v[198:201], v[116:119]
	v_mfma_f32_16x16x32_bf16 v[108:111], v[184:187], v[194:197], v[108:111]
	v_mfma_f32_16x16x32_bf16 v[108:111], v[190:193], v[198:201], v[108:111]
	v_mfma_f32_16x16x32_bf16 v[100:103], v[152:155], v[222:225], v[100:103]
	v_mfma_f32_16x16x32_bf16 v[100:103], v[180:183], v[226:229], v[100:103]
	v_mfma_f32_16x16x32_bf16 v[90:93], v[184:187], v[222:225], v[90:93]
	v_mfma_f32_16x16x32_bf16 v[90:93], v[190:193], v[226:229], v[90:93]
	v_mfma_f32_16x16x32_bf16 v[82:85], v[152:155], v[230:233], v[82:85]
	v_mfma_f32_16x16x32_bf16 v[82:85], v[180:183], v[234:237], v[82:85]
	v_mfma_f32_16x16x32_bf16 v[74:77], v[184:187], v[230:233], v[74:77]
	v_mfma_f32_16x16x32_bf16 v[74:77], v[190:193], v[234:237], v[74:77]
	v_mfma_f32_16x16x32_bf16 v[70:73], v[152:155], v[238:241], v[70:73]
	v_mfma_f32_16x16x32_bf16 v[70:73], v[180:183], v[242:245], v[70:73]
	s_setprio 2
	s_barrier
	v_mfma_f32_16x16x32_bf16 v[66:69], v[184:187], v[238:241], v[66:69]
	v_mfma_f32_16x16x32_bf16 v[66:69], v[190:193], v[242:245], v[66:69]
	s_setprio 0
	s_add_i32 s0, s29, s49
	v_lshl_add_u64 v[168:169], s[42:43], 0, v[160:161]
	s_mov_b32 m0, s0
	ds_read_b128 v[194:197], v189 offset:16384
	ds_read_b128 v[198:201], v189 offset:17408
	ds_read_b128 v[222:225], v189 offset:18432
	ds_read_b128 v[226:229], v189 offset:19456
	ds_read_b128 v[230:233], v189 offset:20480
	ds_read_b128 v[234:237], v189 offset:21504
	ds_read_b128 v[238:241], v189 offset:22528
	ds_read_b128 v[242:245], v189 offset:23552
	global_load_lds_dwordx4 v[168:169], off
	s_add_i32 m0, s0, 0x2000
	s_add_u32 s0, s42, 0x160000
	v_lshl_add_u64 v[172:173], s[42:43], 0, v[156:157]
	s_addc_u32 s1, s43, 0
	s_add_i32 s2, s46, s49
	global_load_lds_dwordx4 v[172:173], off
	v_lshl_add_u64 v[202:203], s[0:1], 0, v[160:161]
	s_mov_b32 m0, s2
	v_lshl_add_u64 v[212:213], s[44:45], 0, v[158:159]
	global_load_lds_dwordx4 v[202:203], off
	v_lshl_add_u64 v[202:203], s[0:1], 0, v[156:157]
	s_add_i32 m0, s2, 0x2000
	s_nop 0
	global_load_lds_dwordx4 v[202:203], off
	v_lshl_add_u64 v[202:203], s[44:45], 0, v[162:163]
	s_mov_b32 m0, s50
	s_nop 0
	global_load_lds_dwordx4 v[202:203], off
	s_mov_b32 m0, s51
	s_nop 0
	global_load_lds_dwordx4 v[212:213], off
	s_waitcnt vmcnt(8)
	s_waitcnt lgkmcnt(0)
	s_setprio 1
	s_barrier
; #define PG8_STAGE(bufoff, gbase, voff) do { _Pragma("unroll") for (int _i = 0; _i < 2; ++_i) \
;         __builtin_amdgcn_global_load_lds((const unsigned*)((const char*)(gbase) + (voff)[_i]), (PG8_LAS unsigned*)(lds + (bufoff) + ldsw + _i * 8192), 16, 0, AUX_A); } while (0)
; #define PG8_LDA(dst, b, h) do { _Pragma("unroll") for (int m = 0; m < 4; ++m) _Pragma("unroll") for (int k = 0; k < 2; ++k) dst[m][k] = *(const PG8_LAS bf16x8*)(lds + PG8_SA(b, h) + aoff + m * 2048 + k * 1024); } while (0)
; #define PG8_LDB(dst, b, h) do { _Pragma("unroll") for (int n = 0; n < 2; ++n) _Pragma("unroll") for (int k = 0; k < 2; ++k) dst[n][k] = *(const PG8_LAS bf16x8*)(lds + PG8_SB(b, h) + boff + n * 2048 + k * 1024); } while (0)
; #define PG8_MMA(ai, bj, At, Bt) do { __builtin_amdgcn_s_setprio(1); _Pragma("unroll") for (int m = 0; m < 4; ++m) _Pragma("unroll") for (int n = 0; n < 2; ++n) _Pragma("unroll") for (int k = 0; k < 2; ++k) \
;         acc[ai][bj][m][n] = __builtin_amdgcn_mfma_f32_16x16x32_bf16(Bt[n][k], At[m][k], acc[ai][bj][m][n], 0, 0, 0); __builtin_amdgcn_s_setprio(0); } while (0)
; #define PG8_WAIT_V(n) asm volatile("s_waitcnt vmcnt(" #n ")" ::: "memory")
; #define PG8_WAIT_L(n) asm volatile("s_waitcnt lgkmcnt(" #n ")" ::: "memory")
; #define PG8_BAR __builtin_amdgcn_s_barrier()
; #define PG8_SCHED __builtin_amdgcn_sched_barrier(0)
; template <class Epi, class Sched, bool ALIGN_EPI = false, bool SP2 = false>
; __device__ __forceinline__ void gemm_phase(PG8_LAS unsigned char* lds, const Gemm g, const Sched& S, const Epi& E) {
;     ...
;             PG8_WAIT_V(8); PG8_WAIT_L(0); PG8_BAR; PG8_MMA(1, 0, At, B0); PG8_MMA(1, 1, At, B1); PG8_BAR; PG8_SCHED;
;             PG8_LDB(B0, 1, 0); PG8_LDB(B1, 1, 1); PG8_SCHED; PG8_LDA(At, 1, 0); PG8_STAGE(PG8_SA(0, 1), a2 + hstep, voffA);
;             PG8_WAIT_V(8); PG8_WAIT_L(0); PG8_BAR; PG8_MMA(0, 0, At, B0); PG8_MMA(0, 1, At, B1); PG8_BAR; PG8_SCHED;
	v_mfma_f32_16x16x32_bf16 v[62:65], v[136:139], v[194:197], v[62:65]
	v_mfma_f32_16x16x32_bf16 v[62:65], v[140:143], v[198:201], v[62:65]
	v_mfma_f32_16x16x32_bf16 v[58:61], v[144:147], v[194:197], v[58:61]
	v_mfma_f32_16x16x32_bf16 v[58:61], v[148:151], v[198:201], v[58:61]
	v_mfma_f32_16x16x32_bf16 v[54:57], v[136:139], v[222:225], v[54:57]
	v_mfma_f32_16x16x32_bf16 v[54:57], v[140:143], v[226:229], v[54:57]
	v_mfma_f32_16x16x32_bf16 v[46:49], v[144:147], v[222:225], v[46:49]
	v_mfma_f32_16x16x32_bf16 v[46:49], v[148:151], v[226:229], v[46:49]
	v_mfma_f32_16x16x32_bf16 v[38:41], v[136:139], v[230:233], v[38:41]
	v_mfma_f32_16x16x32_bf16 v[38:41], v[140:143], v[234:237], v[38:41]
	v_mfma_f32_16x16x32_bf16 v[30:33], v[144:147], v[230:233], v[30:33]
	v_mfma_f32_16x16x32_bf16 v[30:33], v[148:151], v[234:237], v[30:33]
	v_mfma_f32_16x16x32_bf16 v[22:25], v[136:139], v[238:241], v[22:25]
	v_mfma_f32_16x16x32_bf16 v[22:25], v[140:143], v[242:245], v[22:25]
	v_mfma_f32_16x16x32_bf16 v[14:17], v[144:147], v[238:241], v[14:17]
	v_mfma_f32_16x16x32_bf16 v[14:17], v[148:151], v[242:245], v[14:17]
	s_setprio 0
	s_setprio 1
	v_mfma_f32_16x16x32_bf16 v[50:53], v[152:155], v[194:197], v[50:53]
	v_mfma_f32_16x16x32_bf16 v[50:53], v[180:183], v[198:201], v[50:53]
	v_mfma_f32_16x16x32_bf16 v[42:45], v[184:187], v[194:197], v[42:45]
	v_mfma_f32_16x16x32_bf16 v[42:45], v[190:193], v[198:201], v[42:45]
	v_mfma_f32_16x16x32_bf16 v[34:37], v[152:155], v[222:225], v[34:37]
	v_mfma_f32_16x16x32_bf16 v[34:37], v[180:183], v[226:229], v[34:37]
	v_mfma_f32_16x16x32_bf16 v[26:29], v[184:187], v[222:225], v[26:29]
	v_mfma_f32_16x16x32_bf16 v[26:29], v[190:193], v[226:229], v[26:29]
	v_mfma_f32_16x16x32_bf16 v[18:21], v[152:155], v[230:233], v[18:21]
	v_mfma_f32_16x16x32_bf16 v[18:21], v[180:183], v[234:237], v[18:21]
	v_mfma_f32_16x16x32_bf16 v[10:13], v[184:187], v[230:233], v[10:13]
	v_mfma_f32_16x16x32_bf16 v[10:13], v[190:193], v[234:237], v[10:13]
	v_mfma_f32_16x16x32_bf16 v[6:9], v[152:155], v[238:241], v[6:9]
	v_mfma_f32_16x16x32_bf16 v[6:9], v[180:183], v[242:245], v[6:9]
	s_setprio 2
	s_barrier
	v_mfma_f32_16x16x32_bf16 v[2:5], v[184:187], v[238:241], v[2:5]
	v_mfma_f32_16x16x32_bf16 v[2:5], v[190:193], v[242:245], v[2:5]
	s_setprio 0
	s_add_i32 s2, 0, 0x18000
	s_add_i32 s29, 0, 0x1c000
	v_add_u32_e32 v148, s2, v99
	v_add_u32_e32 v190, s29, v99
	ds_read_b128 v[136:139], v148
	ds_read_b128 v[140:143], v148 offset:1024
	ds_read_b128 v[144:147], v148 offset:2048
	ds_read_b128 v[148:151], v148 offset:3072
	ds_read_b128 v[152:155], v190
	ds_read_b128 v[180:183], v190 offset:1024
	ds_read_b128 v[184:187], v190 offset:2048
	ds_read_b128 v[190:193], v190 offset:3072
	s_add_u32 s0, s44, 0x160000
	s_addc_u32 s1, s45, 0
	s_mov_b32 m0, s52
	v_lshl_add_u64 v[246:247], s[0:1], 0, v[162:163]
	ds_read_b128 v[194:197], v189 offset:32768
	ds_read_b128 v[198:201], v189 offset:33792
	ds_read_b128 v[222:225], v189 offset:34816
	ds_read_b128 v[226:229], v189 offset:35840
	ds_read_b128 v[230:233], v189 offset:36864
	ds_read_b128 v[234:237], v189 offset:37888
	ds_read_b128 v[238:241], v189 offset:38912
	ds_read_b128 v[242:245], v189 offset:39936
	global_load_lds_dwordx4 v[246:247], off
	v_lshl_add_u64 v[246:247], s[0:1], 0, v[158:159]
	s_mov_b32 m0, s53
	s_nop 0
	global_load_lds_dwordx4 v[246:247], off
	s_waitcnt vmcnt(8)
	s_waitcnt lgkmcnt(0)
	s_setprio 1
	s_barrier
	v_mfma_f32_16x16x32_bf16 v[128:131], v[136:139], v[194:197], v[128:131]
	v_mfma_f32_16x16x32_bf16 v[128:131], v[140:143], v[198:201], v[128:131]
	v_mfma_f32_16x16x32_bf16 v[124:127], v[144:147], v[194:197], v[124:127]
	v_mfma_f32_16x16x32_bf16 v[124:127], v[148:151], v[198:201], v[124:127]
	v_mfma_f32_16x16x32_bf16 v[120:123], v[136:139], v[222:225], v[120:123]
	v_mfma_f32_16x16x32_bf16 v[120:123], v[140:143], v[226:229], v[120:123]
	v_mfma_f32_16x16x32_bf16 v[112:115], v[144:147], v[222:225], v[112:115]
	v_mfma_f32_16x16x32_bf16 v[112:115], v[148:151], v[226:229], v[112:115]
	v_mfma_f32_16x16x32_bf16 v[104:107], v[136:139], v[230:233], v[104:107]
	v_mfma_f32_16x16x32_bf16 v[104:107], v[140:143], v[234:237], v[104:107]
	v_mfma_f32_16x16x32_bf16 v[94:97], v[144:147], v[230:233], v[94:97]
	v_mfma_f32_16x16x32_bf16 v[94:97], v[148:151], v[234:237], v[94:97]
	v_mfma_f32_16x16x32_bf16 v[86:89], v[136:139], v[238:241], v[86:89]
	v_mfma_f32_16x16x32_bf16 v[86:89], v[140:143], v[242:245], v[86:89]
	v_mfma_f32_16x16x32_bf16 v[78:81], v[144:147], v[238:241], v[78:81]
	v_mfma_f32_16x16x32_bf16 v[78:81], v[148:151], v[242:245], v[78:81]
	s_setprio 0
	s_setprio 1
	v_mfma_f32_16x16x32_bf16 v[116:119], v[152:155], v[194:197], v[116:119]
	v_mfma_f32_16x16x32_bf16 v[116:119], v[180:183], v[198:201], v[116:119]
	v_mfma_f32_16x16x32_bf16 v[108:111], v[184:187], v[194:197], v[108:111]
	v_mfma_f32_16x16x32_bf16 v[108:111], v[190:193], v[198:201], v[108:111]
	v_mfma_f32_16x16x32_bf16 v[100:103], v[152:155], v[222:225], v[100:103]
	v_mfma_f32_16x16x32_bf16 v[100:103], v[180:183], v[226:229], v[100:103]
	v_mfma_f32_16x16x32_bf16 v[90:93], v[184:187], v[222:225], v[90:93]
	v_mfma_f32_16x16x32_bf16 v[90:93], v[190:193], v[226:229], v[90:93]
	v_mfma_f32_16x16x32_bf16 v[82:85], v[152:155], v[230:233], v[82:85]
	v_mfma_f32_16x16x32_bf16 v[82:85], v[180:183], v[234:237], v[82:85]
	v_mfma_f32_16x16x32_bf16 v[74:77], v[184:187], v[230:233], v[74:77]
	v_mfma_f32_16x16x32_bf16 v[74:77], v[190:193], v[234:237], v[74:77]
	v_mfma_f32_16x16x32_bf16 v[70:73], v[152:155], v[238:241], v[70:73]
	v_mfma_f32_16x16x32_bf16 v[70:73], v[180:183], v[242:245], v[70:73]
	s_setprio 2
	s_barrier
; #define PG8_STAGE(bufoff, gbase, voff) do { _Pragma("unroll") for (int _i = 0; _i < 2; ++_i) \
;         __builtin_amdgcn_global_load_lds((const unsigned*)((const char*)(gbase) + (voff)[_i]), (PG8_LAS unsigned*)(lds + (bufoff) + ldsw + _i * 8192), 16, 0, AUX_A); } while (0)
; #define PG8_STAGEB(bufoff, gbase, voff) do { _Pragma("unroll") for (int _i = 0; _i < 2; ++_i) \
;         __builtin_amdgcn_global_load_lds((const unsigned*)((const char*)(gbase) + (voff)[_i]), (PG8_LAS unsigned*)(lds + (bufoff) + ldsw + _i * 8192), 16, 0, AUX_B); } while (0)
; #define PG8_LDA(dst, b, h) do { _Pragma("unroll") for (int m = 0; m < 4; ++m) _Pragma("unroll") for (int k = 0; k < 2; ++k) dst[m][k] = *(const PG8_LAS bf16x8*)(lds + PG8_SA(b, h) + aoff + m * 2048 + k * 1024); } while (0)
; #define PG8_MMA(ai, bj, At, Bt) do { __builtin_amdgcn_s_setprio(1); _Pragma("unroll") for (int m = 0; m < 4; ++m) _Pragma("unroll") for (int n = 0; n < 2; ++n) _Pragma("unroll") for (int k = 0; k < 2; ++k) \
;         acc[ai][bj][m][n] = __builtin_amdgcn_mfma_f32_16x16x32_bf16(Bt[n][k], At[m][k], acc[ai][bj][m][n], 0, 0, 0); __builtin_amdgcn_s_setprio(0); } while (0)
; #define PG8_WAIT_V(n) asm volatile("s_waitcnt vmcnt(" #n ")" ::: "memory")
; #define PG8_WAIT_L(n) asm volatile("s_waitcnt lgkmcnt(" #n ")" ::: "memory")
; #define PG8_BAR __builtin_amdgcn_s_barrier()
; #define PG8_SCHED __builtin_amdgcn_sched_barrier(0)
; template <class Epi, class Sched, bool ALIGN_EPI = false, bool SP2 = false>
; __device__ __forceinline__ void gemm_phase(PG8_LAS unsigned char* lds, const Gemm g, const Sched& S, const Epi& E) {
;     ...
;             PG8_WAIT_V(8); PG8_WAIT_L(0); PG8_BAR; PG8_MMA(0, 0, At, B0); PG8_MMA(0, 1, At, B1); PG8_BAR; PG8_SCHED;
;             PG8_LDA(At, 1, 1); PG8_STAGEB(PG8_SB(1, 0), b3, voffB); PG8_STAGEB(PG8_SB(1, 1), b3 + hstep, voffB); PG8_STAGE(PG8_SA(1, 0), a3, voffA);
;             PG8_WAIT_V(8); PG8_WAIT_L(0); PG8_BAR; PG8_MMA(1, 0, At, B0); PG8_MMA(1, 1, At, B1); PG8_BAR; PG8_SCHED;
	v_mfma_f32_16x16x32_bf16 v[66:69], v[184:187], v[238:241], v[66:69]
	v_mfma_f32_16x16x32_bf16 v[66:69], v[190:193], v[242:245], v[66:69]
	s_setprio 0
	s_add_i32 s0, s2, s49
	v_lshl_add_u64 v[168:169], v[168:169], 0, s[76:77]
	s_mov_b32 m0, s0
	ds_read_b128 v[194:197], v189 offset:49152
	ds_read_b128 v[198:201], v189 offset:50176
	ds_read_b128 v[222:225], v189 offset:51200
	ds_read_b128 v[226:229], v189 offset:52224
	ds_read_b128 v[230:233], v189 offset:53248
	ds_read_b128 v[234:237], v189 offset:54272
	ds_read_b128 v[238:241], v189 offset:55296
	ds_read_b128 v[242:245], v189 offset:56320
	global_load_lds_dwordx4 v[168:169], off
	s_add_i32 m0, s0, 0x2000
	s_add_u32 s0, s42, 0x160080
	v_lshl_add_u64 v[168:169], v[172:173], 0, s[76:77]
	s_addc_u32 s1, s43, 0
	s_add_i32 s2, s29, s49
	global_load_lds_dwordx4 v[168:169], off
	v_lshl_add_u64 v[168:169], s[0:1], 0, v[160:161]
	s_mov_b32 m0, s2
	s_nop 0
	global_load_lds_dwordx4 v[168:169], off
	v_lshl_add_u64 v[168:169], s[0:1], 0, v[156:157]
	s_add_i32 m0, s2, 0x2000
	s_nop 0
	global_load_lds_dwordx4 v[168:169], off
	v_lshl_add_u64 v[168:169], v[202:203], 0, s[76:77]
	s_mov_b32 m0, s60
	s_nop 0
	global_load_lds_dwordx4 v[168:169], off
	v_lshl_add_u64 v[168:169], v[212:213], 0, s[76:77]
	s_mov_b32 m0, s61
	s_nop 0
	global_load_lds_dwordx4 v[168:169], off
	s_waitcnt vmcnt(8)
	s_waitcnt lgkmcnt(0)
	s_setprio 1
	s_barrier
	v_mfma_f32_16x16x32_bf16 v[62:65], v[136:139], v[194:197], v[62:65]
	v_mfma_f32_16x16x32_bf16 v[62:65], v[140:143], v[198:201], v[62:65]
	v_mfma_f32_16x16x32_bf16 v[58:61], v[144:147], v[194:197], v[58:61]
	v_mfma_f32_16x16x32_bf16 v[58:61], v[148:151], v[198:201], v[58:61]
	v_mfma_f32_16x16x32_bf16 v[54:57], v[136:139], v[222:225], v[54:57]
	v_mfma_f32_16x16x32_bf16 v[54:57], v[140:143], v[226:229], v[54:57]
	v_mfma_f32_16x16x32_bf16 v[46:49], v[144:147], v[222:225], v[46:49]
	v_mfma_f32_16x16x32_bf16 v[46:49], v[148:151], v[226:229], v[46:49]
	v_mfma_f32_16x16x32_bf16 v[38:41], v[136:139], v[230:233], v[38:41]
	v_mfma_f32_16x16x32_bf16 v[38:41], v[140:143], v[234:237], v[38:41]
	v_mfma_f32_16x16x32_bf16 v[30:33], v[144:147], v[230:233], v[30:33]
	v_mfma_f32_16x16x32_bf16 v[30:33], v[148:151], v[234:237], v[30:33]
	v_mfma_f32_16x16x32_bf16 v[22:25], v[136:139], v[238:241], v[22:25]
	v_mfma_f32_16x16x32_bf16 v[22:25], v[140:143], v[242:245], v[22:25]
	v_mfma_f32_16x16x32_bf16 v[14:17], v[144:147], v[238:241], v[14:17]
	v_mfma_f32_16x16x32_bf16 v[14:17], v[148:151], v[242:245], v[14:17]
	s_setprio 0
	s_setprio 1
	v_mfma_f32_16x16x32_bf16 v[50:53], v[152:155], v[194:197], v[50:53]
	v_mfma_f32_16x16x32_bf16 v[50:53], v[180:183], v[198:201], v[50:53]
	v_mfma_f32_16x16x32_bf16 v[42:45], v[184:187], v[194:197], v[42:45]
	v_mfma_f32_16x16x32_bf16 v[42:45], v[190:193], v[198:201], v[42:45]
	v_mfma_f32_16x16x32_bf16 v[34:37], v[152:155], v[222:225], v[34:37]
	v_mfma_f32_16x16x32_bf16 v[34:37], v[180:183], v[226:229], v[34:37]
	v_mfma_f32_16x16x32_bf16 v[26:29], v[184:187], v[222:225], v[26:29]
	v_mfma_f32_16x16x32_bf16 v[26:29], v[190:193], v[226:229], v[26:29]
	v_mfma_f32_16x16x32_bf16 v[18:21], v[152:155], v[230:233], v[18:21]
	v_mfma_f32_16x16x32_bf16 v[18:21], v[180:183], v[234:237], v[18:21]
	v_mfma_f32_16x16x32_bf16 v[10:13], v[184:187], v[230:233], v[10:13]
	v_mfma_f32_16x16x32_bf16 v[10:13], v[190:193], v[234:237], v[10:13]
	v_mfma_f32_16x16x32_bf16 v[6:9], v[152:155], v[238:241], v[6:9]
	v_mfma_f32_16x16x32_bf16 v[6:9], v[180:183], v[242:245], v[6:9]
	s_setprio 2
	s_cmp_ge_i32 s83, s82
	s_cbranch_scc0 .Lq4b_1654l
	v_cmp_ne_u32_e64 vcc, s12, 0
	s_cbranch_vccz .Lq4s_1654l

;     __device__ __forceinline__ void operator()(const f32x4 (&acc)[2][2][4][2], const Unit& u, int wr, int wc, int fr, int fq) const {
;         const int col0 = u.pn * BM + wc * 32 + 8 * fq;
;         const bool part = u.slab >= 0;
; #pragma unroll
;         for (int ai = 0; ai < 2; ++ai) {
;             const int rb = u.pm * BM + ai * HALF + wr * 64;
;             const int cb = rb < 8192 ? (rb >> 11) : 4 + ((rb - 8192) >> 6);
;             const float* g = gmod + (size_t)cb * 12288 + col0;
;             f32x4 gv[2][2];
; #pragma unroll
;             for (int bj = 0; bj < 2; ++bj)
; #pragma unroll
;                 for (int n = 0; n < 2; ++n) gv[bj][n] = *(const GAS f32x4*)(g + bj * HALF + 4 * n);
; template <class Epi, class Sched, bool ALIGN_EPI = false, bool SP2 = false>
; __device__ __forceinline__ void gemm_phase(PG8_LAS unsigned char* lds, const Gemm g, const Sched& S, const Epi& E) {
;     ...
;             PG8_WAIT_V(8); PG8_WAIT_L(0); PG8_BAR; PG8_MMA(1, 0, At, B0); PG8_MMA(1, 1, At, B1); PG8_BAR; PG8_SCHED;
;             } else {
;             PG8_LDB(B0, 0, 0); PG8_SCHED; PG8_LDA(At, 0, 0); PG8_STAGE(PG8_SA(1, 1), a1 + hstep, voffA);
;             PG8_WAIT_L(8); PG8_BAR; PG8_WAIT_L(0); PG8_MMA(0, 0, At, B0); PG8_BAR; PG8_SCHED;
;             PG8_LDB(B1, 0, 1); PG8_STAGEB(PG8_SB(0, 0), b2, voffB);
;             PG8_BAR; PG8_WAIT_L(0); PG8_MMA(0, 1, At, B1); PG8_BAR;
;             PG8_LDA(At, 0, 1); PG8_STAGE(PG8_SA(0, 0), a2, voffA);
;             PG8_BAR; PG8_WAIT_L(0); PG8_MMA(1, 0, At, B0); PG8_BAR; PG8_SCHED;
;             PG8_STAGEB(PG8_SB(0, 1), b2 + hstep, voffB);
;             PG8_WAIT_V(6); PG8_BAR; PG8_MMA(1, 1, At, B1); PG8_BAR;
;             PG8_LDB(B0, 1, 0); PG8_SCHED; PG8_LDA(At, 1, 0); PG8_STAGE(PG8_SA(0, 1), a2 + hstep, voffA);
;             PG8_WAIT_L(8); PG8_BAR; PG8_WAIT_L(0); PG8_MMA(0, 0, At, B0); PG8_BAR; PG8_SCHED;
;             PG8_LDB(B1, 1, 1); PG8_STAGEB(PG8_SB(1, 0), b3, voffB);
;             PG8_BAR; PG8_WAIT_L(0); PG8_MMA(0, 1, At, B1); PG8_BAR;
;             PG8_LDA(At, 1, 1); PG8_STAGE(PG8_SA(1, 0), a3, voffA);
;             PG8_BAR; PG8_WAIT_L(0); PG8_MMA(1, 0, At, B0); PG8_BAR; PG8_SCHED;
;             PG8_STAGEB(PG8_SB(1, 1), b3 + hstep, voffB);
;             PG8_WAIT_V(6); PG8_BAR; PG8_MMA(1, 1, At, B1); PG8_BAR;
;             }
;         }
;         if constexpr (ALIGN_EPI) { if (wr == 0) PG8_BAR; }
.Lq4s_1654l:
	v_mfma_f32_16x16x32_bf16 v[2:5], v[184:187], v[238:241], v[2:5]
	v_mfma_f32_16x16x32_bf16 v[2:5], v[190:193], v[242:245], v[2:5]
	s_setprio 0
	s_add_i32 s0, s83, 2
	v_lshl_add_u64 v[132:133], v[132:133], 0, s[86:87]
	v_lshl_add_u64 v[134:135], v[134:135], 0, s[86:87]
	s_cmp_ge_i32 s83, s82
	s_mov_b32 s83, s0
	s_cbranch_scc0 .LBB0_1654
.Lpx_1654:
	s_and_b64 vcc, exec, s[12:13]
	s_cbranch_vccz .LBB0_1657
.LBB0_1657:
	s_cmp_lt_i32 s78, 0
	s_cselect_b64 s[34:35], -1, 0
	s_lshl_b32 s15, s71, 8
	s_add_i32 s15, s15, s59
	s_add_i32 s42, s15, 0xffffe000
	s_lshr_b32 s1, s42, 6
	s_ashr_i32 s0, s15, 11
	s_add_i32 s1, s1, 4
	s_cmpk_lt_i32 s15, 0x2000
	s_cselect_b32 s0, s0, s1
	s_mul_hi_i32 s1, s0, 0xc000
	s_mul_i32 s0, s0, 0xc000
	v_lshl_or_b32 v180, s75, 8, v188
	s_add_u32 s0, s55, s0
	v_ashrrev_i32_e32 v181, 31, v180
	s_addc_u32 s1, s56, s1
	v_lshl_add_u64 v[136:137], v[180:181], 2, s[0:1]
	global_load_dwordx4 v[140:143], v[136:137], off offset:16
	global_load_dwordx4 v[144:147], v[136:137], off
	global_load_dwordx4 v[132:135], v[136:137], off offset:528
	s_nop 0
	global_load_dwordx4 v[136:139], v[136:137], off offset:512
	v_cndmask_b32_e64 v148, 0, 1, s[8:9]
	s_mov_b64 s[40:41], -1
	s_and_b64 vcc, exec, s[34:35]
	v_cmp_ne_u32_e64 s[38:39], 1, v148
	s_cbranch_vccz .LBB0_1684
	v_or_b32_e32 v148, s15, v1
	v_ashrrev_i32_e32 v149, 31, v148
	v_lshlrev_b64 v[148:149], 11, v[148:149]
	v_lshl_add_u64 v[186:187], v[148:149], 0, v[180:181]
	v_lshl_add_u64 v[182:183], v[186:187], 1, s[10:11]
	global_load_dwordx4 v[222:225], v[182:183], off
	global_load_dwordx4 v[226:229], v[182:183], off offset:256
	v_add_co_u32_e32 v198, vcc, 0x10000, v182
	s_nop 1
	v_addc_co_u32_e32 v199, vcc, 0, v183, vcc
	global_load_dwordx4 v[230:233], v[198:199], off
	global_load_dwordx4 v[234:237], v[198:199], off offset:256
	v_add_co_u32_e32 v198, vcc, 0x20000, v182
	s_nop 1
	v_addc_co_u32_e32 v199, vcc, 0, v183, vcc
	global_load_dwordx4 v[238:241], v[198:199], off
	global_load_dwordx4 v[242:245], v[198:199], off offset:256
	v_add_co_u32_e32 v198, vcc, 0x30000, v182
	s_nop 1
	v_addc_co_u32_e32 v199, vcc, 0, v183, vcc
	global_load_dwordx4 v[190:193], v[198:199], off
	global_load_dwordx4 v[194:197], v[198:199], off offset:256
	s_and_b64 vcc, exec, s[38:39]
	v_lshl_add_u64 v[184:185], v[186:187], 2, s[6:7]
	s_waitcnt vmcnt(7)
	s_nop 1
	v_mov_b32_e32 v148, v222
	v_mov_b32_e32 v149, v223
	v_mov_b32_e32 v150, v224
	v_mov_b32_e32 v151, v225
	v_lshlrev_b32_e32 v152, 16, v148
	v_and_b32_e32 v153, 0xffff0000, v148
	v_lshlrev_b32_e32 v148, 16, v149
	v_and_b32_e32 v149, 0xffff0000, v149
	v_lshlrev_b32_e32 v168, 16, v150
	v_and_b32_e32 v169, 0xffff0000, v150
	v_lshlrev_b32_e32 v150, 16, v151
	v_and_b32_e32 v151, 0xffff0000, v151
	v_pk_fma_f32 v[154:155], v[130:131], v[146:147], v[148:149]
	v_pk_fma_f32 v[152:153], v[128:129], v[144:145], v[152:153]
	v_pk_fma_f32 v[150:151], v[126:127], v[142:143], v[150:151]
	v_pk_fma_f32 v[148:149], v[124:125], v[140:141], v[168:169]
	s_cbranch_vccnz .LBB0_1660
	s_mov_b64 s[40:41], 0
	global_store_dwordx4 v[184:185], v[152:155], off
	global_store_dwordx4 v[184:185], v[148:151], off offset:16
